# weight-conversion loops: the 6-VALU integer RNE bit trick per f32->bf16 pair replaced by v_cvt_pk_bf16_f32 (+ v_mov), 320 sites; same rounding for finite values (denorm mode preserve)
# speedup vs baseline: 1.0025x; 1.0008x over previous
.LBB0_668:
	s_lshl_b32 s13, s4, 1
	s_lshl_b32 s14, s5, 1
	v_or_b32_e32 v7, s13, v1
	v_or_b32_e32 v9, s14, v0
	s_add_i32 s15, s13, 4
	s_add_i32 s22, s14, 4
	s_add_i32 s23, s13, 8
	s_add_i32 s24, s14, 8
	s_add_i32 s25, s13, 12
	s_add_i32 s26, s14, 12
	s_add_i32 s27, s13, 16
	s_add_i32 s30, s14, 16
	s_add_i32 s36, s13, 20
	s_add_i32 s37, s14, 20
	s_add_i32 s40, s13, 24
	s_add_i32 s41, s14, 24
	s_add_i32 s13, s13, 28
	s_add_i32 s14, s14, 28
	v_add_u32_e32 v11, s1, v7
	v_add_u32_e32 v13, s8, v9
	v_or_b32_e32 v15, s15, v1
	v_or_b32_e32 v19, s22, v0
	v_or_b32_e32 v41, s23, v1
	v_or_b32_e32 v43, s24, v0
	v_or_b32_e32 v45, s25, v1
	v_or_b32_e32 v47, s26, v0
	v_or_b32_e32 v49, s27, v1
	v_or_b32_e32 v82, s30, v0
	v_or_b32_e32 v86, s36, v1
	v_or_b32_e32 v87, s37, v0
	v_or_b32_e32 v88, s40, v1
	v_or_b32_e32 v89, s41, v0
	v_or_b32_e32 v90, s13, v1
	v_or_b32_e32 v91, s14, v0
	v_mad_i64_i32 v[52:53], s[14:15], v13, s80, v[50:51]
	v_mad_i64_i32 v[54:55], s[14:15], v11, s80, v[50:51]
	v_add_u32_e32 v11, s1, v15
	v_add_u32_e32 v13, s8, v19
	v_add_u32_e32 v62, s1, v41
	v_add_u32_e32 v60, s8, v43
	v_add_u32_e32 v66, s1, v45
	v_add_u32_e32 v64, s8, v47
	v_add_u32_e32 v70, s1, v49
	v_add_u32_e32 v68, s8, v82
	v_add_u32_e32 v74, s1, v86
	v_add_u32_e32 v72, s8, v87
	v_add_u32_e32 v78, s1, v88
	v_add_u32_e32 v76, s8, v89
	v_add_u32_e32 v84, s1, v90
	v_add_u32_e32 v80, s8, v91
	v_mad_i64_i32 v[56:57], s[14:15], v13, s80, v[50:51]
	v_mad_i64_i32 v[58:59], s[14:15], v11, s80, v[50:51]
	v_mad_i64_i32 v[60:61], s[14:15], v60, s80, v[50:51]
	v_mad_i64_i32 v[62:63], s[14:15], v62, s80, v[50:51]
	v_mad_i64_i32 v[64:65], s[14:15], v64, s80, v[50:51]
	v_mad_i64_i32 v[66:67], s[14:15], v66, s80, v[50:51]
	v_mad_i64_i32 v[68:69], s[14:15], v68, s80, v[50:51]
	v_mad_i64_i32 v[70:71], s[14:15], v70, s80, v[50:51]
	v_mad_i64_i32 v[72:73], s[14:15], v72, s80, v[50:51]
	v_mad_i64_i32 v[74:75], s[14:15], v74, s80, v[50:51]
	v_mad_i64_i32 v[76:77], s[14:15], v76, s80, v[50:51]
	v_mad_i64_i32 v[78:79], s[14:15], v78, s80, v[50:51]
	v_mad_i64_i32 v[80:81], s[14:15], v80, s80, v[50:51]
	v_mad_i64_i32 v[84:85], s[14:15], v84, s80, v[50:51]
	global_load_dword v11, v[52:53], off
	global_load_dword v13, v[54:55], off
	global_load_dword v92, v[56:57], off
	global_load_dword v93, v[58:59], off
	global_load_dword v94, v[60:61], off
	global_load_dword v95, v[62:63], off
	global_load_dword v96, v[64:65], off
	global_load_dword v97, v[66:67], off
	global_load_dword v98, v[68:69], off
	global_load_dword v99, v[70:71], off
	global_load_dword v100, v[72:73], off
	global_load_dword v101, v[74:75], off
	global_load_dword v102, v[76:77], off
	global_load_dword v103, v[78:79], off
	global_load_dword v104, v[80:81], off
	global_load_dword v105, v[84:85], off
	s_add_i32 s5, s5, 16
	s_add_i32 s4, s4, 16
	s_lshl_b32 s13, s4, 1
	s_lshl_b32 s14, s5, 1
	v_or_b32_e32 v106, s13, v1
	v_or_b32_e32 v107, s14, v0
	s_add_i32 s15, s13, 4
	s_add_i32 s22, s14, 4
	s_add_i32 s23, s13, 8
	s_add_i32 s24, s14, 8
	s_add_i32 s25, s13, 12
	s_add_i32 s26, s14, 12
	s_add_i32 s27, s13, 16
	s_add_i32 s30, s14, 16
	s_add_i32 s36, s13, 20
	s_add_i32 s37, s14, 20
	s_add_i32 s40, s13, 24
	s_add_i32 s41, s14, 24
	s_add_i32 s13, s13, 28
	s_add_i32 s14, s14, 28
	v_add_u32_e32 v108, s1, v106
	v_add_u32_e32 v109, s8, v107
	v_or_b32_e32 v110, s15, v1
	v_or_b32_e32 v111, s22, v0
	v_or_b32_e32 v112, s23, v1
	v_or_b32_e32 v113, s24, v0
	v_or_b32_e32 v114, s25, v1
	v_or_b32_e32 v115, s26, v0
	v_or_b32_e32 v116, s27, v1
	v_or_b32_e32 v117, s30, v0
	v_or_b32_e32 v118, s36, v1
	v_or_b32_e32 v119, s37, v0
	v_or_b32_e32 v120, s40, v1
	v_or_b32_e32 v121, s41, v0
	v_or_b32_e32 v122, s13, v1
	v_or_b32_e32 v123, s14, v0
	v_mad_i64_i32 v[130:131], s[14:15], v109, s80, v[50:51]
	v_mad_i64_i32 v[132:133], s[14:15], v108, s80, v[50:51]
	v_add_u32_e32 v108, s1, v110
	v_add_u32_e32 v109, s8, v111
	v_add_u32_e32 v140, s1, v112
	v_add_u32_e32 v138, s8, v113
	v_add_u32_e32 v144, s1, v114
	v_add_u32_e32 v142, s8, v115
	v_add_u32_e32 v148, s1, v116
	v_add_u32_e32 v146, s8, v117
	v_add_u32_e32 v152, s1, v118
	v_add_u32_e32 v150, s8, v119
	v_add_u32_e32 v156, s1, v120
	v_add_u32_e32 v154, s8, v121
	v_add_u32_e32 v160, s1, v122
	v_add_u32_e32 v158, s8, v123
	v_mad_i64_i32 v[134:135], s[14:15], v109, s80, v[50:51]
	v_mad_i64_i32 v[136:137], s[14:15], v108, s80, v[50:51]
	v_mad_i64_i32 v[138:139], s[14:15], v138, s80, v[50:51]
	v_mad_i64_i32 v[140:141], s[14:15], v140, s80, v[50:51]
	v_mad_i64_i32 v[142:143], s[14:15], v142, s80, v[50:51]
	v_mad_i64_i32 v[144:145], s[14:15], v144, s80, v[50:51]
	v_mad_i64_i32 v[146:147], s[14:15], v146, s80, v[50:51]
	v_mad_i64_i32 v[148:149], s[14:15], v148, s80, v[50:51]
	v_mad_i64_i32 v[150:151], s[14:15], v150, s80, v[50:51]
	v_mad_i64_i32 v[152:153], s[14:15], v152, s80, v[50:51]
	v_mad_i64_i32 v[154:155], s[14:15], v154, s80, v[50:51]
	v_mad_i64_i32 v[156:157], s[14:15], v156, s80, v[50:51]
	v_mad_i64_i32 v[158:159], s[14:15], v158, s80, v[50:51]
	v_mad_i64_i32 v[160:161], s[14:15], v160, s80, v[50:51]
	global_load_dword v108, v[130:131], off
	global_load_dword v109, v[132:133], off
	global_load_dword v124, v[134:135], off
	global_load_dword v125, v[136:137], off
	global_load_dword v126, v[138:139], off
	global_load_dword v127, v[140:141], off
	global_load_dword v162, v[142:143], off
	global_load_dword v163, v[144:145], off
	global_load_dword v164, v[146:147], off
	global_load_dword v165, v[148:149], off
	global_load_dword v166, v[150:151], off
	global_load_dword v167, v[152:153], off
	global_load_dword v168, v[154:155], off
	global_load_dword v169, v[156:157], off
	global_load_dword v170, v[158:159], off
	global_load_dword v171, v[160:161], off
	v_mad_u64_u32 v[52:53], s[14:15], v9, s78, v[4:5]
	v_mad_u64_u32 v[54:55], s[14:15], v7, s78, v[4:5]
	v_mad_u64_u32 v[56:57], s[14:15], v19, s78, v[4:5]
	v_mad_u64_u32 v[58:59], s[14:15], v15, s78, v[4:5]
	v_mad_u64_u32 v[60:61], s[14:15], v43, s78, v[4:5]
	v_mad_u64_u32 v[62:63], s[14:15], v41, s78, v[4:5]
	v_mad_u64_u32 v[64:65], s[14:15], v47, s78, v[4:5]
	v_mad_u64_u32 v[66:67], s[14:15], v45, s78, v[4:5]
	v_mad_u64_u32 v[68:69], s[14:15], v82, s78, v[4:5]
	v_mad_u64_u32 v[70:71], s[14:15], v49, s78, v[4:5]
	v_mad_u64_u32 v[72:73], s[14:15], v87, s78, v[4:5]
	v_mad_u64_u32 v[74:75], s[14:15], v86, s78, v[4:5]
	v_mad_u64_u32 v[76:77], s[14:15], v89, s78, v[4:5]
	v_mad_u64_u32 v[78:79], s[14:15], v88, s78, v[4:5]
	v_mad_u64_u32 v[80:81], s[14:15], v91, s78, v[4:5]
	v_mad_u64_u32 v[84:85], s[14:15], v90, s78, v[4:5]
	s_waitcnt vmcnt(31)
	ds_write_b32 v52, v11
	s_waitcnt vmcnt(30)
	ds_write_b32 v54, v13
	s_waitcnt vmcnt(29)
	ds_write_b32 v56, v92
	s_waitcnt vmcnt(28)
	ds_write_b32 v58, v93
	s_waitcnt vmcnt(27)
	ds_write_b32 v60, v94
	s_waitcnt vmcnt(26)
	ds_write_b32 v62, v95
	s_waitcnt vmcnt(25)
	ds_write_b32 v64, v96
	s_waitcnt vmcnt(24)
	ds_write_b32 v66, v97
	s_waitcnt vmcnt(23)
	ds_write_b32 v68, v98
	s_waitcnt vmcnt(22)
	ds_write_b32 v70, v99
	s_waitcnt vmcnt(21)
	ds_write_b32 v72, v100
	s_waitcnt vmcnt(20)
	ds_write_b32 v74, v101
	s_waitcnt vmcnt(19)
	ds_write_b32 v76, v102
	s_waitcnt vmcnt(18)
	ds_write_b32 v78, v103
	s_waitcnt vmcnt(17)
	ds_write_b32 v80, v104
	s_waitcnt vmcnt(16)
	ds_write_b32 v84, v105
	v_mad_u64_u32 v[130:131], s[14:15], v107, s78, v[4:5]
	v_mad_u64_u32 v[132:133], s[14:15], v106, s78, v[4:5]
	v_mad_u64_u32 v[134:135], s[14:15], v111, s78, v[4:5]
	v_mad_u64_u32 v[136:137], s[14:15], v110, s78, v[4:5]
	v_mad_u64_u32 v[138:139], s[14:15], v113, s78, v[4:5]
	v_mad_u64_u32 v[140:141], s[14:15], v112, s78, v[4:5]
	v_mad_u64_u32 v[142:143], s[14:15], v115, s78, v[4:5]
	v_mad_u64_u32 v[144:145], s[14:15], v114, s78, v[4:5]
	v_mad_u64_u32 v[146:147], s[14:15], v117, s78, v[4:5]
	v_mad_u64_u32 v[148:149], s[14:15], v116, s78, v[4:5]
	v_mad_u64_u32 v[150:151], s[14:15], v119, s78, v[4:5]
	v_mad_u64_u32 v[152:153], s[14:15], v118, s78, v[4:5]
	v_mad_u64_u32 v[154:155], s[14:15], v121, s78, v[4:5]
	v_mad_u64_u32 v[156:157], s[14:15], v120, s78, v[4:5]
	v_mad_u64_u32 v[158:159], s[14:15], v123, s78, v[4:5]
	v_mad_u64_u32 v[160:161], s[14:15], v122, s78, v[4:5]
	s_waitcnt vmcnt(15)
	ds_write_b32 v130, v108
	s_waitcnt vmcnt(14)
	ds_write_b32 v132, v109
	s_waitcnt vmcnt(13)
	ds_write_b32 v134, v124
	s_waitcnt vmcnt(12)
	ds_write_b32 v136, v125
	s_waitcnt vmcnt(11)
	ds_write_b32 v138, v126
	s_waitcnt vmcnt(10)
	ds_write_b32 v140, v127
	s_waitcnt vmcnt(9)
	ds_write_b32 v142, v162
	s_waitcnt vmcnt(8)
	ds_write_b32 v144, v163
	s_waitcnt vmcnt(7)
	ds_write_b32 v146, v164
	s_waitcnt vmcnt(6)
	ds_write_b32 v148, v165
	s_waitcnt vmcnt(5)
	ds_write_b32 v150, v166
	s_waitcnt vmcnt(4)
	ds_write_b32 v152, v167
	s_waitcnt vmcnt(3)
	ds_write_b32 v154, v168
	s_waitcnt vmcnt(2)
	ds_write_b32 v156, v169
	s_waitcnt vmcnt(1)
	ds_write_b32 v158, v170
	s_waitcnt vmcnt(0)
	ds_write_b32 v160, v171
	s_add_i32 s5, s5, 16
	s_add_i32 s4, s4, 16
	s_add_i32 s9, s9, -16
	s_add_i32 s9, s9, -16
	s_cmp_lg_u32 s9, 0
	s_waitcnt lgkmcnt(0)
	s_add_i32 s1, s12, 0xf500
	ds_read2_b32 v[54:55], v5 offset1:8
	s_cmpk_lt_i32 s0, 0x58
	ds_read2_b32 v[58:59], v5 offset0:33 offset1:41
	s_cselect_b32 s0, s12, s1
	s_sext_i32_i16 s1, s0
	ds_read2_b32 v[60:61], v5 offset0:66 offset1:74
	s_cselect_b32 s4, 0, 0x80
	s_bfe_u32 s1, s1, 0x70018
	ds_read2_b32 v[62:63], v5 offset0:99 offset1:107
	s_add_i32 s1, s0, s1
	s_waitcnt lgkmcnt(3)
	s_sext_i32_i16 s5, s1
	s_and_b32 s1, s1, 0xff80
	s_waitcnt lgkmcnt(2)
	ds_read2_b32 v[64:65], v5 offset0:132 offset1:140
	s_sub_i32 s0, s0, s1
	v_cvt_pk_bf16_f32 v9, v54, v58
	ds_read2_b32 v[66:67], v5 offset0:165 offset1:173
	s_lshl_b32 s5, s5, 1
	s_sext_i32_i16 s0, s0
	v_mov_b32_e32 v50, v9
	s_waitcnt lgkmcnt(3)
	s_and_b32 s5, s5, 0xffffff00
	s_add_i32 s0, s4, s0
	s_waitcnt lgkmcnt(2)
	ds_read2_b32 v[68:69], v5 offset0:198 offset1:206
	s_add_i32 s0, s0, s5
	v_cvt_pk_bf16_f32 v9, v60, v62
	ds_read2_b32 v[70:71], v5 offset0:231 offset1:239
	s_ashr_i32 s1, s0, 31
	v_mov_b32_e32 v51, v9
	s_waitcnt lgkmcnt(3)
	s_lshl_b64 s[0:1], s[0:1], 11
	s_waitcnt lgkmcnt(2)
	s_add_u32 s4, s17, s0
	v_cvt_pk_bf16_f32 v9, v64, v66
	s_addc_u32 s5, s29, s1
	s_ashr_i32 s9, s8, 31
	v_mov_b32_e32 v52, v9
	s_waitcnt lgkmcnt(1)
	s_lshl_b64 s[0:1], s[8:9], 1
	s_waitcnt lgkmcnt(0)
	s_add_u32 s0, s4, s0
	v_cvt_pk_bf16_f32 v9, v68, v70
	s_addc_u32 s1, s5, s1
	v_lshlrev_b32_e32 v128, 1, v6
	v_mov_b32_e32 v53, v9
	v_lshl_add_u64 v[56:57], s[0:1], 0, v[128:129]
	v_lshlrev_b32_e32 v128, 1, v8
	v_lshl_add_u64 v[72:73], v[56:57], 0, v[128:129]
	v_cvt_pk_bf16_f32 v9, v55, v59
	global_store_dwordx4 v[72:73], v[50:53], off
	v_lshlrev_b32_e32 v128, 1, v10
	ds_read2_b32 v[54:55], v5 offset0:16 offset1:24
	v_mov_b32_e32 v50, v9
	v_cvt_pk_bf16_f32 v9, v61, v63
	v_mov_b32_e32 v51, v9
	v_cvt_pk_bf16_f32 v9, v65, v67
	v_mov_b32_e32 v52, v9
	v_cvt_pk_bf16_f32 v9, v69, v71
	v_mov_b32_e32 v53, v9
	v_lshl_add_u64 v[58:59], v[56:57], 0, v[128:129]
	global_store_dwordx4 v[58:59], v[50:53], off
	ds_read2_b32 v[58:59], v5 offset0:49 offset1:57
	ds_read2_b32 v[60:61], v5 offset0:82 offset1:90
	ds_read2_b32 v[62:63], v5 offset0:115 offset1:123
	s_waitcnt lgkmcnt(3)
	s_waitcnt lgkmcnt(2)
	ds_read2_b32 v[64:65], v5 offset0:148 offset1:156
	v_cvt_pk_bf16_f32 v9, v54, v58
	ds_read2_b32 v[66:67], v5 offset0:181 offset1:189
	v_mov_b32_e32 v50, v9
	s_waitcnt lgkmcnt(3)
	s_waitcnt lgkmcnt(2)
	ds_read2_b32 v[68:69], v5 offset0:214 offset1:222
	v_cvt_pk_bf16_f32 v9, v60, v62
	ds_read2_b32 v[70:71], v5 offset0:247 offset1:255
	v_mov_b32_e32 v51, v9
	s_waitcnt lgkmcnt(3)
	s_waitcnt lgkmcnt(2)
	v_cvt_pk_bf16_f32 v9, v64, v66
	v_mov_b32_e32 v52, v9
	s_waitcnt lgkmcnt(1)
	s_waitcnt lgkmcnt(0)
	v_cvt_pk_bf16_f32 v9, v68, v70
	v_mov_b32_e32 v53, v9
	v_lshlrev_b32_e32 v128, 1, v12
	v_lshl_add_u64 v[72:73], v[56:57], 0, v[128:129]
	v_cvt_pk_bf16_f32 v9, v55, v59
	global_store_dwordx4 v[72:73], v[50:53], off
	v_lshlrev_b32_e32 v128, 1, v14
	v_lshl_add_u64 v[54:55], v[56:57], 0, v[128:129]
	v_mov_b32_e32 v50, v9
	v_cvt_pk_bf16_f32 v9, v61, v63
	v_mov_b32_e32 v51, v9
	v_cvt_pk_bf16_f32 v9, v65, v67
	v_mov_b32_e32 v52, v9
	v_cvt_pk_bf16_f32 v9, v69, v71
	v_mov_b32_e32 v53, v9
	global_store_dwordx4 v[54:55], v[50:53], off
	s_waitcnt lgkmcnt(0)
	s_mov_b32 s0, s28
	s_mov_b64 s[8:9], -1
	s_andn2_b64 vcc, exec, s[10:11]
	s_mov_b64 s[10:11], -1
	s_cbranch_vccnz .LBB0_744

.LBB0_675:
	s_lshl_b32 s15, s1, 1
	s_lshl_b32 s22, s5, 1
	v_or_b32_e32 v7, s15, v1
	v_or_b32_e32 v9, s22, v0
	s_add_i32 s23, s15, 4
	s_add_i32 s24, s22, 4
	s_add_i32 s25, s15, 8
	s_add_i32 s26, s22, 8
	s_add_i32 s27, s15, 12
	s_add_i32 s30, s22, 12
	s_add_i32 s36, s15, 16
	s_add_i32 s37, s22, 16
	s_add_i32 s40, s15, 20
	s_add_i32 s41, s22, 20
	s_add_i32 s42, s15, 24
	s_add_i32 s43, s22, 24
	s_add_i32 s15, s15, 28
	s_add_i32 s22, s22, 28
	v_add_u32_e32 v54, s12, v9
	v_or_b32_e32 v11, s23, v1
	v_or_b32_e32 v13, s24, v0
	v_or_b32_e32 v15, s25, v1
	v_or_b32_e32 v19, s26, v0
	v_or_b32_e32 v41, s27, v1
	v_or_b32_e32 v43, s30, v0
	v_or_b32_e32 v45, s36, v1
	v_or_b32_e32 v47, s37, v0
	v_or_b32_e32 v49, s40, v1
	v_or_b32_e32 v82, s41, v0
	v_or_b32_e32 v86, s42, v1
	v_or_b32_e32 v87, s43, v0
	v_or_b32_e32 v88, s15, v1
	v_or_b32_e32 v89, s22, v0
	v_add_u32_e32 v52, s4, v7
	v_ashrrev_i32_e32 v55, 31, v54
	v_add_u32_e32 v56, s4, v11
	v_add_u32_e32 v58, s12, v13
	v_add_u32_e32 v60, s4, v15
	v_add_u32_e32 v62, s12, v19
	v_add_u32_e32 v64, s4, v41
	v_add_u32_e32 v66, s12, v43
	v_add_u32_e32 v68, s4, v45
	v_add_u32_e32 v70, s12, v47
	v_add_u32_e32 v72, s4, v49
	v_add_u32_e32 v74, s12, v82
	v_add_u32_e32 v76, s4, v86
	v_add_u32_e32 v78, s12, v87
	v_add_u32_e32 v80, s4, v88
	v_add_u32_e32 v84, s12, v89
	v_ashrrev_i32_e32 v53, 31, v52
	v_lshlrev_b64 v[54:55], 12, v[54:55]
	v_ashrrev_i32_e32 v59, 31, v58
	v_ashrrev_i32_e32 v57, 31, v56
	v_ashrrev_i32_e32 v63, 31, v62
	v_ashrrev_i32_e32 v61, 31, v60
	v_ashrrev_i32_e32 v67, 31, v66
	v_ashrrev_i32_e32 v65, 31, v64
	v_ashrrev_i32_e32 v71, 31, v70
	v_ashrrev_i32_e32 v69, 31, v68
	v_ashrrev_i32_e32 v75, 31, v74
	v_ashrrev_i32_e32 v73, 31, v72
	v_ashrrev_i32_e32 v79, 31, v78
	v_ashrrev_i32_e32 v77, 31, v76
	v_ashrrev_i32_e32 v85, 31, v84
	v_ashrrev_i32_e32 v81, 31, v80
	v_lshlrev_b64 v[52:53], 12, v[52:53]
	v_lshl_add_u64 v[54:55], v[50:51], 0, v[54:55]
	v_lshlrev_b64 v[56:57], 12, v[56:57]
	v_lshlrev_b64 v[58:59], 12, v[58:59]
	v_lshlrev_b64 v[60:61], 12, v[60:61]
	v_lshlrev_b64 v[62:63], 12, v[62:63]
	v_lshlrev_b64 v[64:65], 12, v[64:65]
	v_lshlrev_b64 v[66:67], 12, v[66:67]
	v_lshlrev_b64 v[68:69], 12, v[68:69]
	v_lshlrev_b64 v[70:71], 12, v[70:71]
	v_lshlrev_b64 v[72:73], 12, v[72:73]
	v_lshlrev_b64 v[74:75], 12, v[74:75]
	v_lshlrev_b64 v[76:77], 12, v[76:77]
	v_lshlrev_b64 v[78:79], 12, v[78:79]
	v_lshlrev_b64 v[80:81], 12, v[80:81]
	v_lshlrev_b64 v[84:85], 12, v[84:85]
	v_lshl_add_u64 v[52:53], v[50:51], 0, v[52:53]
	v_lshl_add_u64 v[58:59], v[50:51], 0, v[58:59]
	v_lshl_add_u64 v[56:57], v[50:51], 0, v[56:57]
	v_lshl_add_u64 v[62:63], v[50:51], 0, v[62:63]
	v_lshl_add_u64 v[60:61], v[50:51], 0, v[60:61]
	v_lshl_add_u64 v[66:67], v[50:51], 0, v[66:67]
	v_lshl_add_u64 v[64:65], v[50:51], 0, v[64:65]
	v_lshl_add_u64 v[70:71], v[50:51], 0, v[70:71]
	v_lshl_add_u64 v[68:69], v[50:51], 0, v[68:69]
	v_lshl_add_u64 v[74:75], v[50:51], 0, v[74:75]
	v_lshl_add_u64 v[72:73], v[50:51], 0, v[72:73]
	v_lshl_add_u64 v[78:79], v[50:51], 0, v[78:79]
	v_lshl_add_u64 v[76:77], v[50:51], 0, v[76:77]
	v_lshl_add_u64 v[84:85], v[50:51], 0, v[84:85]
	v_lshl_add_u64 v[80:81], v[50:51], 0, v[80:81]
	global_load_dword v90, v[54:55], off
	global_load_dword v91, v[52:53], off
	global_load_dword v92, v[58:59], off
	global_load_dword v93, v[56:57], off
	global_load_dword v94, v[62:63], off
	global_load_dword v95, v[60:61], off
	global_load_dword v96, v[66:67], off
	global_load_dword v97, v[64:65], off
	global_load_dword v98, v[70:71], off
	global_load_dword v99, v[68:69], off
	global_load_dword v100, v[74:75], off
	global_load_dword v101, v[72:73], off
	global_load_dword v102, v[78:79], off
	global_load_dword v103, v[76:77], off
	global_load_dword v104, v[84:85], off
	global_load_dword v105, v[80:81], off
	s_add_i32 s5, s5, 16
	s_add_i32 s1, s1, 16
	s_lshl_b32 s15, s1, 1
	s_lshl_b32 s22, s5, 1
	v_or_b32_e32 v106, s15, v1
	v_or_b32_e32 v107, s22, v0
	s_add_i32 s23, s15, 4
	s_add_i32 s24, s22, 4
	s_add_i32 s25, s15, 8
	s_add_i32 s26, s22, 8
	s_add_i32 s27, s15, 12
	s_add_i32 s30, s22, 12
	s_add_i32 s36, s15, 16
	s_add_i32 s37, s22, 16
	s_add_i32 s40, s15, 20
	s_add_i32 s41, s22, 20
	s_add_i32 s42, s15, 24
	s_add_i32 s43, s22, 24
	s_add_i32 s15, s15, 28
	s_add_i32 s22, s22, 28
	v_add_u32_e32 v132, s12, v107
	v_or_b32_e32 v108, s23, v1
	v_or_b32_e32 v109, s24, v0
	v_or_b32_e32 v110, s25, v1
	v_or_b32_e32 v111, s26, v0
	v_or_b32_e32 v112, s27, v1
	v_or_b32_e32 v113, s30, v0
	v_or_b32_e32 v114, s36, v1
	v_or_b32_e32 v115, s37, v0
	v_or_b32_e32 v116, s40, v1
	v_or_b32_e32 v117, s41, v0
	v_or_b32_e32 v118, s42, v1
	v_or_b32_e32 v119, s43, v0
	v_or_b32_e32 v120, s15, v1
	v_or_b32_e32 v121, s22, v0
	v_add_u32_e32 v130, s4, v106
	v_ashrrev_i32_e32 v133, 31, v132
	v_add_u32_e32 v134, s4, v108
	v_add_u32_e32 v136, s12, v109
	v_add_u32_e32 v138, s4, v110
	v_add_u32_e32 v140, s12, v111
	v_add_u32_e32 v142, s4, v112
	v_add_u32_e32 v144, s12, v113
	v_add_u32_e32 v146, s4, v114
	v_add_u32_e32 v148, s12, v115
	v_add_u32_e32 v150, s4, v116
	v_add_u32_e32 v152, s12, v117
	v_add_u32_e32 v154, s4, v118
	v_add_u32_e32 v156, s12, v119
	v_add_u32_e32 v158, s4, v120
	v_add_u32_e32 v160, s12, v121
	v_ashrrev_i32_e32 v131, 31, v130
	v_lshlrev_b64 v[132:133], 12, v[132:133]
	v_ashrrev_i32_e32 v137, 31, v136
	v_ashrrev_i32_e32 v135, 31, v134
	v_ashrrev_i32_e32 v141, 31, v140
	v_ashrrev_i32_e32 v139, 31, v138
	v_ashrrev_i32_e32 v145, 31, v144
	v_ashrrev_i32_e32 v143, 31, v142
	v_ashrrev_i32_e32 v149, 31, v148
	v_ashrrev_i32_e32 v147, 31, v146
	v_ashrrev_i32_e32 v153, 31, v152
	v_ashrrev_i32_e32 v151, 31, v150
	v_ashrrev_i32_e32 v157, 31, v156
	v_ashrrev_i32_e32 v155, 31, v154
	v_ashrrev_i32_e32 v161, 31, v160
	v_ashrrev_i32_e32 v159, 31, v158
	v_lshlrev_b64 v[130:131], 12, v[130:131]
	v_lshl_add_u64 v[132:133], v[50:51], 0, v[132:133]
	v_lshlrev_b64 v[134:135], 12, v[134:135]
	v_lshlrev_b64 v[136:137], 12, v[136:137]
	v_lshlrev_b64 v[138:139], 12, v[138:139]
	v_lshlrev_b64 v[140:141], 12, v[140:141]
	v_lshlrev_b64 v[142:143], 12, v[142:143]
	v_lshlrev_b64 v[144:145], 12, v[144:145]
	v_lshlrev_b64 v[146:147], 12, v[146:147]
	v_lshlrev_b64 v[148:149], 12, v[148:149]
	v_lshlrev_b64 v[150:151], 12, v[150:151]
	v_lshlrev_b64 v[152:153], 12, v[152:153]
	v_lshlrev_b64 v[154:155], 12, v[154:155]
	v_lshlrev_b64 v[156:157], 12, v[156:157]
	v_lshlrev_b64 v[158:159], 12, v[158:159]
	v_lshlrev_b64 v[160:161], 12, v[160:161]
	v_lshl_add_u64 v[130:131], v[50:51], 0, v[130:131]
	v_lshl_add_u64 v[136:137], v[50:51], 0, v[136:137]
	v_lshl_add_u64 v[134:135], v[50:51], 0, v[134:135]
	v_lshl_add_u64 v[140:141], v[50:51], 0, v[140:141]
	v_lshl_add_u64 v[138:139], v[50:51], 0, v[138:139]
	v_lshl_add_u64 v[144:145], v[50:51], 0, v[144:145]
	v_lshl_add_u64 v[142:143], v[50:51], 0, v[142:143]
	v_lshl_add_u64 v[148:149], v[50:51], 0, v[148:149]
	v_lshl_add_u64 v[146:147], v[50:51], 0, v[146:147]
	v_lshl_add_u64 v[152:153], v[50:51], 0, v[152:153]
	v_lshl_add_u64 v[150:151], v[50:51], 0, v[150:151]
	v_lshl_add_u64 v[156:157], v[50:51], 0, v[156:157]
	v_lshl_add_u64 v[154:155], v[50:51], 0, v[154:155]
	v_lshl_add_u64 v[160:161], v[50:51], 0, v[160:161]
	v_lshl_add_u64 v[158:159], v[50:51], 0, v[158:159]
	global_load_dword v122, v[132:133], off
	global_load_dword v123, v[130:131], off
	global_load_dword v124, v[136:137], off
	global_load_dword v125, v[134:135], off
	global_load_dword v126, v[140:141], off
	global_load_dword v127, v[138:139], off
	global_load_dword v162, v[144:145], off
	global_load_dword v163, v[142:143], off
	global_load_dword v164, v[148:149], off
	global_load_dword v165, v[146:147], off
	global_load_dword v166, v[152:153], off
	global_load_dword v167, v[150:151], off
	global_load_dword v168, v[156:157], off
	global_load_dword v169, v[154:155], off
	global_load_dword v170, v[160:161], off
	global_load_dword v171, v[158:159], off
	v_mad_u64_u32 v[52:53], s[22:23], v9, s78, v[4:5]
	v_mad_u64_u32 v[54:55], s[22:23], v7, s78, v[4:5]
	v_mad_u64_u32 v[56:57], s[22:23], v13, s78, v[4:5]
	v_mad_u64_u32 v[58:59], s[22:23], v11, s78, v[4:5]
	v_mad_u64_u32 v[60:61], s[22:23], v19, s78, v[4:5]
	v_mad_u64_u32 v[62:63], s[22:23], v15, s78, v[4:5]
	v_mad_u64_u32 v[64:65], s[22:23], v43, s78, v[4:5]
	v_mad_u64_u32 v[66:67], s[22:23], v41, s78, v[4:5]
	v_mad_u64_u32 v[68:69], s[22:23], v47, s78, v[4:5]
	v_mad_u64_u32 v[70:71], s[22:23], v45, s78, v[4:5]
	v_mad_u64_u32 v[72:73], s[22:23], v82, s78, v[4:5]
	v_mad_u64_u32 v[74:75], s[22:23], v49, s78, v[4:5]
	v_mad_u64_u32 v[76:77], s[22:23], v87, s78, v[4:5]
	v_mad_u64_u32 v[78:79], s[22:23], v86, s78, v[4:5]
	v_mad_u64_u32 v[80:81], s[22:23], v89, s78, v[4:5]
	v_mad_u64_u32 v[84:85], s[22:23], v88, s78, v[4:5]
	s_waitcnt vmcnt(31)
	ds_write_b32 v52, v90
	s_waitcnt vmcnt(30)
	ds_write_b32 v54, v91
	s_waitcnt vmcnt(29)
	ds_write_b32 v56, v92
	s_waitcnt vmcnt(28)
	ds_write_b32 v58, v93
	s_waitcnt vmcnt(27)
	ds_write_b32 v60, v94
	s_waitcnt vmcnt(26)
	ds_write_b32 v62, v95
	s_waitcnt vmcnt(25)
	ds_write_b32 v64, v96
	s_waitcnt vmcnt(24)
	ds_write_b32 v66, v97
	s_waitcnt vmcnt(23)
	ds_write_b32 v68, v98
	s_waitcnt vmcnt(22)
	ds_write_b32 v70, v99
	s_waitcnt vmcnt(21)
	ds_write_b32 v72, v100
	s_waitcnt vmcnt(20)
	ds_write_b32 v74, v101
	s_waitcnt vmcnt(19)
	ds_write_b32 v76, v102
	s_waitcnt vmcnt(18)
	ds_write_b32 v78, v103
	s_waitcnt vmcnt(17)
	ds_write_b32 v80, v104
	s_waitcnt vmcnt(16)
	ds_write_b32 v84, v105
	v_mad_u64_u32 v[130:131], s[22:23], v107, s78, v[4:5]
	v_mad_u64_u32 v[132:133], s[22:23], v106, s78, v[4:5]
	v_mad_u64_u32 v[134:135], s[22:23], v109, s78, v[4:5]
	v_mad_u64_u32 v[136:137], s[22:23], v108, s78, v[4:5]
	v_mad_u64_u32 v[138:139], s[22:23], v111, s78, v[4:5]
	v_mad_u64_u32 v[140:141], s[22:23], v110, s78, v[4:5]
	v_mad_u64_u32 v[142:143], s[22:23], v113, s78, v[4:5]
	v_mad_u64_u32 v[144:145], s[22:23], v112, s78, v[4:5]
	v_mad_u64_u32 v[146:147], s[22:23], v115, s78, v[4:5]
	v_mad_u64_u32 v[148:149], s[22:23], v114, s78, v[4:5]
	v_mad_u64_u32 v[150:151], s[22:23], v117, s78, v[4:5]
	v_mad_u64_u32 v[152:153], s[22:23], v116, s78, v[4:5]
	v_mad_u64_u32 v[154:155], s[22:23], v119, s78, v[4:5]
	v_mad_u64_u32 v[156:157], s[22:23], v118, s78, v[4:5]
	v_mad_u64_u32 v[158:159], s[22:23], v121, s78, v[4:5]
	v_mad_u64_u32 v[160:161], s[22:23], v120, s78, v[4:5]
	s_waitcnt vmcnt(15)
	ds_write_b32 v130, v122
	s_waitcnt vmcnt(14)
	ds_write_b32 v132, v123
	s_waitcnt vmcnt(13)
	ds_write_b32 v134, v124
	s_waitcnt vmcnt(12)
	ds_write_b32 v136, v125
	s_waitcnt vmcnt(11)
	ds_write_b32 v138, v126
	s_waitcnt vmcnt(10)
	ds_write_b32 v140, v127
	s_waitcnt vmcnt(9)
	ds_write_b32 v142, v162
	s_waitcnt vmcnt(8)
	ds_write_b32 v144, v163
	s_waitcnt vmcnt(7)
	ds_write_b32 v146, v164
	s_waitcnt vmcnt(6)
	ds_write_b32 v148, v165
	s_waitcnt vmcnt(5)
	ds_write_b32 v150, v166
	s_waitcnt vmcnt(4)
	ds_write_b32 v152, v167
	s_waitcnt vmcnt(3)
	ds_write_b32 v154, v168
	s_waitcnt vmcnt(2)
	ds_write_b32 v156, v169
	s_waitcnt vmcnt(1)
	ds_write_b32 v158, v170
	s_waitcnt vmcnt(0)
	ds_write_b32 v160, v171
	s_add_i32 s5, s5, 16
	s_add_i32 s1, s1, 16
	s_add_i32 s13, s13, -16
	s_add_i32 s13, s13, -16
	s_cmp_lg_u32 s13, 0
	s_waitcnt lgkmcnt(0)
	ds_read2_b32 v[54:55], v5 offset1:8
	ds_read2_b32 v[58:59], v5 offset0:33 offset1:41
	ds_read2_b32 v[60:61], v5 offset0:66 offset1:74
	ds_read2_b32 v[62:63], v5 offset0:99 offset1:107
	ds_read2_b32 v[64:65], v5 offset0:132 offset1:140
	s_waitcnt lgkmcnt(4)
	s_waitcnt lgkmcnt(3)
	v_cvt_pk_bf16_f32 v9, v54, v58
	ds_read2_b32 v[66:67], v5 offset0:165 offset1:173
	v_mov_b32_e32 v50, v9
	s_waitcnt lgkmcnt(3)
	s_waitcnt lgkmcnt(2)
	ds_read2_b32 v[68:69], v5 offset0:198 offset1:206
	v_cvt_pk_bf16_f32 v9, v60, v62
	ds_read2_b32 v[70:71], v5 offset0:231 offset1:239
	v_mov_b32_e32 v51, v9
	s_waitcnt lgkmcnt(3)
	s_mul_i32 s4, s14, 0x1600
	s_waitcnt lgkmcnt(2)
	s_mul_hi_i32 s1, s14, 0x1600
	s_add_u32 s14, s18, s4
	v_cvt_pk_bf16_f32 v9, v64, v66
	s_addc_u32 s1, s19, s1
	s_ashr_i32 s13, s12, 31
	v_mov_b32_e32 v52, v9
	s_waitcnt lgkmcnt(1)
	s_lshl_b64 s[4:5], s[12:13], 1
	s_waitcnt lgkmcnt(0)
	s_add_u32 s4, s14, s4
	v_cvt_pk_bf16_f32 v9, v68, v70
	s_addc_u32 s5, s1, s5
	v_lshlrev_b32_e32 v128, 1, v6
	v_mov_b32_e32 v53, v9
	v_lshl_add_u64 v[56:57], s[4:5], 0, v[128:129]
	v_lshlrev_b32_e32 v128, 1, v18
	v_lshl_add_u64 v[56:57], v[56:57], 0, v[128:129]
	v_cvt_pk_bf16_f32 v9, v55, v59
	global_store_dwordx4 v[56:57], v[50:53], off
	s_mov_b32 s1, 0xb000
	v_add_co_u32_e32 v58, vcc, s1, v56
	v_mov_b32_e32 v50, v9
	v_cvt_pk_bf16_f32 v9, v61, v63
	v_mov_b32_e32 v51, v9
	v_cvt_pk_bf16_f32 v9, v65, v67
	v_mov_b32_e32 v52, v9
	v_cvt_pk_bf16_f32 v9, v69, v71
	v_mov_b32_e32 v53, v9
	ds_read2_b32 v[54:55], v5 offset0:16 offset1:24
	v_addc_co_u32_e32 v59, vcc, 0, v57, vcc
	global_store_dwordx4 v[58:59], v[50:53], off
	ds_read2_b32 v[58:59], v5 offset0:49 offset1:57
	ds_read2_b32 v[60:61], v5 offset0:82 offset1:90
	ds_read2_b32 v[62:63], v5 offset0:115 offset1:123
	s_waitcnt lgkmcnt(3)
	s_waitcnt lgkmcnt(2)
	ds_read2_b32 v[64:65], v5 offset0:148 offset1:156
	v_cvt_pk_bf16_f32 v9, v54, v58
	ds_read2_b32 v[66:67], v5 offset0:181 offset1:189
	v_mov_b32_e32 v50, v9
	s_waitcnt lgkmcnt(3)
	s_waitcnt lgkmcnt(2)
	ds_read2_b32 v[68:69], v5 offset0:214 offset1:222
	v_cvt_pk_bf16_f32 v9, v60, v62
	ds_read2_b32 v[70:71], v5 offset0:247 offset1:255
	v_mov_b32_e32 v51, v9
	s_waitcnt lgkmcnt(3)
	s_waitcnt lgkmcnt(2)
	v_cvt_pk_bf16_f32 v9, v64, v66
	v_mov_b32_e32 v52, v9
	s_waitcnt lgkmcnt(1)
	s_waitcnt lgkmcnt(0)
	v_cvt_pk_bf16_f32 v9, v68, v70
	v_mov_b32_e32 v53, v9
	s_mov_b32 s1, 0x16000
	v_add_co_u32_e32 v72, vcc, s1, v56
	v_addc_co_u32_e32 v73, vcc, 0, v57, vcc
	v_cvt_pk_bf16_f32 v9, v55, v59
	global_store_dwordx4 v[72:73], v[50:53], off
	v_add_co_u32_e32 v54, vcc, 0x21000, v56
	s_nop 0
	v_mov_b32_e32 v50, v9
	v_cvt_pk_bf16_f32 v9, v61, v63
	v_mov_b32_e32 v51, v9
	v_cvt_pk_bf16_f32 v9, v65, v67
	v_mov_b32_e32 v52, v9
	v_cvt_pk_bf16_f32 v9, v69, v71
	v_mov_b32_e32 v53, v9
	v_addc_co_u32_e32 v55, vcc, 0, v57, vcc
	global_store_dwordx4 v[54:55], v[50:53], off
	s_waitcnt lgkmcnt(0)
	s_mov_b32 s4, s0
	s_andn2_b64 vcc, exec, s[10:11]
	s_mov_b64 s[10:11], -1
	s_cbranch_vccnz .LBB0_744

.LBB0_682:
	s_lshl_b32 s22, s5, 1
	s_lshl_b32 s23, s13, 1
	v_or_b32_e32 v7, s22, v1
	v_or_b32_e32 v9, s23, v0
	s_add_i32 s24, s22, 4
	s_add_i32 s25, s23, 4
	s_add_i32 s26, s22, 8
	s_add_i32 s27, s23, 8
	s_add_i32 s30, s22, 12
	s_add_i32 s36, s23, 12
	s_add_i32 s37, s22, 16
	s_add_i32 s40, s23, 16
	s_add_i32 s41, s22, 20
	s_add_i32 s42, s23, 20
	s_add_i32 s43, s22, 24
	s_add_i32 s52, s23, 24
	s_add_i32 s22, s22, 28
	s_add_i32 s23, s23, 28
	v_add_u32_e32 v11, s1, v7
	v_add_u32_e32 v13, s12, v9
	v_or_b32_e32 v15, s24, v1
	v_or_b32_e32 v19, s25, v0
	v_or_b32_e32 v41, s26, v1
	v_or_b32_e32 v43, s27, v0
	v_or_b32_e32 v45, s30, v1
	v_or_b32_e32 v47, s36, v0
	v_or_b32_e32 v49, s37, v1
	v_or_b32_e32 v82, s40, v0
	v_or_b32_e32 v86, s41, v1
	v_or_b32_e32 v87, s42, v0
	v_or_b32_e32 v88, s43, v1
	v_or_b32_e32 v89, s52, v0
	v_or_b32_e32 v90, s22, v1
	v_or_b32_e32 v91, s23, v0
	v_mad_i64_i32 v[52:53], s[22:23], v13, s80, v[50:51]
	v_mad_i64_i32 v[54:55], s[22:23], v11, s80, v[50:51]
	v_add_u32_e32 v11, s1, v15
	v_add_u32_e32 v13, s12, v19
	v_add_u32_e32 v62, s1, v41
	v_add_u32_e32 v60, s12, v43
	v_add_u32_e32 v66, s1, v45
	v_add_u32_e32 v64, s12, v47
	v_add_u32_e32 v70, s1, v49
	v_add_u32_e32 v68, s12, v82
	v_add_u32_e32 v74, s1, v86
	v_add_u32_e32 v72, s12, v87
	v_add_u32_e32 v78, s1, v88
	v_add_u32_e32 v76, s12, v89
	v_add_u32_e32 v84, s1, v90
	v_add_u32_e32 v80, s12, v91
	v_mad_i64_i32 v[56:57], s[22:23], v13, s80, v[50:51]
	v_mad_i64_i32 v[58:59], s[22:23], v11, s80, v[50:51]
	v_mad_i64_i32 v[60:61], s[22:23], v60, s80, v[50:51]
	v_mad_i64_i32 v[62:63], s[22:23], v62, s80, v[50:51]
	v_mad_i64_i32 v[64:65], s[22:23], v64, s80, v[50:51]
	v_mad_i64_i32 v[66:67], s[22:23], v66, s80, v[50:51]
	v_mad_i64_i32 v[68:69], s[22:23], v68, s80, v[50:51]
	v_mad_i64_i32 v[70:71], s[22:23], v70, s80, v[50:51]
	v_mad_i64_i32 v[72:73], s[22:23], v72, s80, v[50:51]
	v_mad_i64_i32 v[74:75], s[22:23], v74, s80, v[50:51]
	v_mad_i64_i32 v[76:77], s[22:23], v76, s80, v[50:51]
	v_mad_i64_i32 v[78:79], s[22:23], v78, s80, v[50:51]
	v_mad_i64_i32 v[80:81], s[22:23], v80, s80, v[50:51]
	v_mad_i64_i32 v[84:85], s[22:23], v84, s80, v[50:51]
	global_load_dword v11, v[52:53], off
	global_load_dword v13, v[54:55], off
	global_load_dword v92, v[56:57], off
	global_load_dword v93, v[58:59], off
	global_load_dword v94, v[60:61], off
	global_load_dword v95, v[62:63], off
	global_load_dword v96, v[64:65], off
	global_load_dword v97, v[66:67], off
	global_load_dword v98, v[68:69], off
	global_load_dword v99, v[70:71], off
	global_load_dword v100, v[72:73], off
	global_load_dword v101, v[74:75], off
	global_load_dword v102, v[76:77], off
	global_load_dword v103, v[78:79], off
	global_load_dword v104, v[80:81], off
	global_load_dword v105, v[84:85], off
	s_add_i32 s13, s13, 16
	s_add_i32 s5, s5, 16
	s_lshl_b32 s22, s5, 1
	s_lshl_b32 s23, s13, 1
	v_or_b32_e32 v106, s22, v1
	v_or_b32_e32 v107, s23, v0
	s_add_i32 s24, s22, 4
	s_add_i32 s25, s23, 4
	s_add_i32 s26, s22, 8
	s_add_i32 s27, s23, 8
	s_add_i32 s30, s22, 12
	s_add_i32 s36, s23, 12
	s_add_i32 s37, s22, 16
	s_add_i32 s40, s23, 16
	s_add_i32 s41, s22, 20
	s_add_i32 s42, s23, 20
	s_add_i32 s43, s22, 24
	s_add_i32 s52, s23, 24
	s_add_i32 s22, s22, 28
	s_add_i32 s23, s23, 28
	v_add_u32_e32 v108, s1, v106
	v_add_u32_e32 v109, s12, v107
	v_or_b32_e32 v110, s24, v1
	v_or_b32_e32 v111, s25, v0
	v_or_b32_e32 v112, s26, v1
	v_or_b32_e32 v113, s27, v0
	v_or_b32_e32 v114, s30, v1
	v_or_b32_e32 v115, s36, v0
	v_or_b32_e32 v116, s37, v1
	v_or_b32_e32 v117, s40, v0
	v_or_b32_e32 v118, s41, v1
	v_or_b32_e32 v119, s42, v0
	v_or_b32_e32 v120, s43, v1
	v_or_b32_e32 v121, s52, v0
	v_or_b32_e32 v122, s22, v1
	v_or_b32_e32 v123, s23, v0
	v_mad_i64_i32 v[130:131], s[22:23], v109, s80, v[50:51]
	v_mad_i64_i32 v[132:133], s[22:23], v108, s80, v[50:51]
	v_add_u32_e32 v108, s1, v110
	v_add_u32_e32 v109, s12, v111
	v_add_u32_e32 v140, s1, v112
	v_add_u32_e32 v138, s12, v113
	v_add_u32_e32 v144, s1, v114
	v_add_u32_e32 v142, s12, v115
	v_add_u32_e32 v148, s1, v116
	v_add_u32_e32 v146, s12, v117
	v_add_u32_e32 v152, s1, v118
	v_add_u32_e32 v150, s12, v119
	v_add_u32_e32 v156, s1, v120
	v_add_u32_e32 v154, s12, v121
	v_add_u32_e32 v160, s1, v122
	v_add_u32_e32 v158, s12, v123
	v_mad_i64_i32 v[134:135], s[22:23], v109, s80, v[50:51]
	v_mad_i64_i32 v[136:137], s[22:23], v108, s80, v[50:51]
	v_mad_i64_i32 v[138:139], s[22:23], v138, s80, v[50:51]
	v_mad_i64_i32 v[140:141], s[22:23], v140, s80, v[50:51]
	v_mad_i64_i32 v[142:143], s[22:23], v142, s80, v[50:51]
	v_mad_i64_i32 v[144:145], s[22:23], v144, s80, v[50:51]
	v_mad_i64_i32 v[146:147], s[22:23], v146, s80, v[50:51]
	v_mad_i64_i32 v[148:149], s[22:23], v148, s80, v[50:51]
	v_mad_i64_i32 v[150:151], s[22:23], v150, s80, v[50:51]
	v_mad_i64_i32 v[152:153], s[22:23], v152, s80, v[50:51]
	v_mad_i64_i32 v[154:155], s[22:23], v154, s80, v[50:51]
	v_mad_i64_i32 v[156:157], s[22:23], v156, s80, v[50:51]
	v_mad_i64_i32 v[158:159], s[22:23], v158, s80, v[50:51]
	v_mad_i64_i32 v[160:161], s[22:23], v160, s80, v[50:51]
	global_load_dword v108, v[130:131], off
	global_load_dword v109, v[132:133], off
	global_load_dword v124, v[134:135], off
	global_load_dword v125, v[136:137], off
	global_load_dword v126, v[138:139], off
	global_load_dword v127, v[140:141], off
	global_load_dword v162, v[142:143], off
	global_load_dword v163, v[144:145], off
	global_load_dword v164, v[146:147], off
	global_load_dword v165, v[148:149], off
	global_load_dword v166, v[150:151], off
	global_load_dword v167, v[152:153], off
	global_load_dword v168, v[154:155], off
	global_load_dword v169, v[156:157], off
	global_load_dword v170, v[158:159], off
	global_load_dword v171, v[160:161], off
	v_mad_u64_u32 v[52:53], s[22:23], v9, s78, v[4:5]
	v_mad_u64_u32 v[54:55], s[22:23], v7, s78, v[4:5]
	v_mad_u64_u32 v[56:57], s[22:23], v19, s78, v[4:5]
	v_mad_u64_u32 v[58:59], s[22:23], v15, s78, v[4:5]
	v_mad_u64_u32 v[60:61], s[22:23], v43, s78, v[4:5]
	v_mad_u64_u32 v[62:63], s[22:23], v41, s78, v[4:5]
	v_mad_u64_u32 v[64:65], s[22:23], v47, s78, v[4:5]
	v_mad_u64_u32 v[66:67], s[22:23], v45, s78, v[4:5]
	v_mad_u64_u32 v[68:69], s[22:23], v82, s78, v[4:5]
	v_mad_u64_u32 v[70:71], s[22:23], v49, s78, v[4:5]
	v_mad_u64_u32 v[72:73], s[22:23], v87, s78, v[4:5]
	v_mad_u64_u32 v[74:75], s[22:23], v86, s78, v[4:5]
	v_mad_u64_u32 v[76:77], s[22:23], v89, s78, v[4:5]
	v_mad_u64_u32 v[78:79], s[22:23], v88, s78, v[4:5]
	v_mad_u64_u32 v[80:81], s[22:23], v91, s78, v[4:5]
	v_mad_u64_u32 v[84:85], s[22:23], v90, s78, v[4:5]
	s_waitcnt vmcnt(31)
	ds_write_b32 v52, v11
	s_waitcnt vmcnt(30)
	ds_write_b32 v54, v13
	s_waitcnt vmcnt(29)
	ds_write_b32 v56, v92
	s_waitcnt vmcnt(28)
	ds_write_b32 v58, v93
	s_waitcnt vmcnt(27)
	ds_write_b32 v60, v94
	s_waitcnt vmcnt(26)
	ds_write_b32 v62, v95
	s_waitcnt vmcnt(25)
	ds_write_b32 v64, v96
	s_waitcnt vmcnt(24)
	ds_write_b32 v66, v97
	s_waitcnt vmcnt(23)
	ds_write_b32 v68, v98
	s_waitcnt vmcnt(22)
	ds_write_b32 v70, v99
	s_waitcnt vmcnt(21)
	ds_write_b32 v72, v100
	s_waitcnt vmcnt(20)
	ds_write_b32 v74, v101
	s_waitcnt vmcnt(19)
	ds_write_b32 v76, v102
	s_waitcnt vmcnt(18)
	ds_write_b32 v78, v103
	s_waitcnt vmcnt(17)
	ds_write_b32 v80, v104
	s_waitcnt vmcnt(16)
	ds_write_b32 v84, v105
	v_mad_u64_u32 v[130:131], s[22:23], v107, s78, v[4:5]
	v_mad_u64_u32 v[132:133], s[22:23], v106, s78, v[4:5]
	v_mad_u64_u32 v[134:135], s[22:23], v111, s78, v[4:5]
	v_mad_u64_u32 v[136:137], s[22:23], v110, s78, v[4:5]
	v_mad_u64_u32 v[138:139], s[22:23], v113, s78, v[4:5]
	v_mad_u64_u32 v[140:141], s[22:23], v112, s78, v[4:5]
	v_mad_u64_u32 v[142:143], s[22:23], v115, s78, v[4:5]
	v_mad_u64_u32 v[144:145], s[22:23], v114, s78, v[4:5]
	v_mad_u64_u32 v[146:147], s[22:23], v117, s78, v[4:5]
	v_mad_u64_u32 v[148:149], s[22:23], v116, s78, v[4:5]
	v_mad_u64_u32 v[150:151], s[22:23], v119, s78, v[4:5]
	v_mad_u64_u32 v[152:153], s[22:23], v118, s78, v[4:5]
	v_mad_u64_u32 v[154:155], s[22:23], v121, s78, v[4:5]
	v_mad_u64_u32 v[156:157], s[22:23], v120, s78, v[4:5]
	v_mad_u64_u32 v[158:159], s[22:23], v123, s78, v[4:5]
	v_mad_u64_u32 v[160:161], s[22:23], v122, s78, v[4:5]
	s_waitcnt vmcnt(15)
	ds_write_b32 v130, v108
	s_waitcnt vmcnt(14)
	ds_write_b32 v132, v109
	s_waitcnt vmcnt(13)
	ds_write_b32 v134, v124
	s_waitcnt vmcnt(12)
	ds_write_b32 v136, v125
	s_waitcnt vmcnt(11)
	ds_write_b32 v138, v126
	s_waitcnt vmcnt(10)
	ds_write_b32 v140, v127
	s_waitcnt vmcnt(9)
	ds_write_b32 v142, v162
	s_waitcnt vmcnt(8)
	ds_write_b32 v144, v163
	s_waitcnt vmcnt(7)
	ds_write_b32 v146, v164
	s_waitcnt vmcnt(6)
	ds_write_b32 v148, v165
	s_waitcnt vmcnt(5)
	ds_write_b32 v150, v166
	s_waitcnt vmcnt(4)
	ds_write_b32 v152, v167
	s_waitcnt vmcnt(3)
	ds_write_b32 v154, v168
	s_waitcnt vmcnt(2)
	ds_write_b32 v156, v169
	s_waitcnt vmcnt(1)
	ds_write_b32 v158, v170
	s_waitcnt vmcnt(0)
	ds_write_b32 v160, v171
	s_add_i32 s13, s13, 16
	s_add_i32 s5, s5, 16
	s_add_i32 s15, s15, -16
	s_add_i32 s15, s15, -16
	s_cmp_lg_u32 s15, 0
	s_waitcnt lgkmcnt(0)
	s_add_i32 s1, s14, 0xf500
	ds_read2_b32 v[54:55], v5 offset1:8
	s_cmpk_lt_i32 s0, 0x58
	ds_read2_b32 v[58:59], v5 offset0:33 offset1:41
	s_cselect_b32 s0, s14, s1
	s_sext_i32_i16 s1, s0
	ds_read2_b32 v[60:61], v5 offset0:66 offset1:74
	s_cselect_b32 s5, 0, 0x80
	s_bfe_u32 s1, s1, 0x70018
	ds_read2_b32 v[62:63], v5 offset0:99 offset1:107
	s_add_i32 s1, s0, s1
	s_waitcnt lgkmcnt(3)
	s_sext_i32_i16 s13, s1
	s_and_b32 s1, s1, 0xff80
	s_waitcnt lgkmcnt(2)
	ds_read2_b32 v[64:65], v5 offset0:132 offset1:140
	s_sub_i32 s0, s0, s1
	v_cvt_pk_bf16_f32 v9, v54, v58
	ds_read2_b32 v[66:67], v5 offset0:165 offset1:173
	s_lshl_b32 s13, s13, 1
	s_sext_i32_i16 s0, s0
	v_mov_b32_e32 v50, v9
	s_waitcnt lgkmcnt(3)
	s_and_b32 s13, s13, 0xffffff00
	s_add_i32 s0, s5, s0
	s_waitcnt lgkmcnt(2)
	ds_read2_b32 v[68:69], v5 offset0:198 offset1:206
	s_add_i32 s0, s0, s13
	v_cvt_pk_bf16_f32 v9, v60, v62
	ds_read2_b32 v[70:71], v5 offset0:231 offset1:239
	s_ashr_i32 s1, s0, 31
	v_mov_b32_e32 v51, v9
	s_waitcnt lgkmcnt(3)
	s_lshl_b64 s[0:1], s[0:1], 11
	s_waitcnt lgkmcnt(2)
	s_add_u32 s5, s20, s0
	v_cvt_pk_bf16_f32 v9, v64, v66
	s_addc_u32 s14, s21, s1
	s_ashr_i32 s13, s12, 31
	v_mov_b32_e32 v52, v9
	s_waitcnt lgkmcnt(1)
	s_lshl_b64 s[0:1], s[12:13], 1
	s_waitcnt lgkmcnt(0)
	s_add_u32 s0, s5, s0
	v_cvt_pk_bf16_f32 v9, v68, v70
	s_addc_u32 s1, s14, s1
	v_lshlrev_b32_e32 v128, 1, v6
	v_mov_b32_e32 v53, v9
	v_lshl_add_u64 v[56:57], s[0:1], 0, v[128:129]
	v_lshlrev_b32_e32 v128, 1, v8
	v_lshl_add_u64 v[72:73], v[56:57], 0, v[128:129]
	v_cvt_pk_bf16_f32 v9, v55, v59
	global_store_dwordx4 v[72:73], v[50:53], off
	v_lshlrev_b32_e32 v128, 1, v10
	ds_read2_b32 v[54:55], v5 offset0:16 offset1:24
	v_mov_b32_e32 v50, v9
	v_cvt_pk_bf16_f32 v9, v61, v63
	v_mov_b32_e32 v51, v9
	v_cvt_pk_bf16_f32 v9, v65, v67
	v_mov_b32_e32 v52, v9
	v_cvt_pk_bf16_f32 v9, v69, v71
	v_mov_b32_e32 v53, v9
	v_lshl_add_u64 v[58:59], v[56:57], 0, v[128:129]
	global_store_dwordx4 v[58:59], v[50:53], off
	ds_read2_b32 v[58:59], v5 offset0:49 offset1:57
	ds_read2_b32 v[60:61], v5 offset0:82 offset1:90
	ds_read2_b32 v[62:63], v5 offset0:115 offset1:123
	s_waitcnt lgkmcnt(3)
	s_waitcnt lgkmcnt(2)
	ds_read2_b32 v[64:65], v5 offset0:148 offset1:156
	v_cvt_pk_bf16_f32 v9, v54, v58
	ds_read2_b32 v[66:67], v5 offset0:181 offset1:189
	v_mov_b32_e32 v50, v9
	s_waitcnt lgkmcnt(3)
	s_waitcnt lgkmcnt(2)
	ds_read2_b32 v[68:69], v5 offset0:214 offset1:222
	v_cvt_pk_bf16_f32 v9, v60, v62
	ds_read2_b32 v[70:71], v5 offset0:247 offset1:255
	v_mov_b32_e32 v51, v9
	s_waitcnt lgkmcnt(3)
	s_waitcnt lgkmcnt(2)
	v_cvt_pk_bf16_f32 v9, v64, v66
	v_mov_b32_e32 v52, v9
	s_waitcnt lgkmcnt(1)
	s_waitcnt lgkmcnt(0)
	v_cvt_pk_bf16_f32 v9, v68, v70
	v_mov_b32_e32 v53, v9
	v_lshlrev_b32_e32 v128, 1, v12
	v_lshl_add_u64 v[72:73], v[56:57], 0, v[128:129]
	v_cvt_pk_bf16_f32 v9, v55, v59
	global_store_dwordx4 v[72:73], v[50:53], off
	v_lshlrev_b32_e32 v128, 1, v14
	v_lshl_add_u64 v[54:55], v[56:57], 0, v[128:129]
	v_mov_b32_e32 v50, v9
	v_cvt_pk_bf16_f32 v9, v61, v63
	v_mov_b32_e32 v51, v9
	v_cvt_pk_bf16_f32 v9, v65, v67
	v_mov_b32_e32 v52, v9
	v_cvt_pk_bf16_f32 v9, v69, v71
	v_mov_b32_e32 v53, v9
	global_store_dwordx4 v[54:55], v[50:53], off
	s_waitcnt lgkmcnt(0)
	s_mov_b32 s1, s4
	s_andn2_b64 vcc, exec, s[10:11]
	s_mov_b64 s[10:11], -1
	s_cbranch_vccnz .LBB0_744

.LBB0_689:
	s_lshl_b32 s15, s0, 1
	s_lshl_b32 s22, s5, 1
	v_or_b32_e32 v7, s15, v1
	v_or_b32_e32 v9, s22, v0
	s_add_i32 s23, s15, 4
	s_add_i32 s24, s22, 4
	s_add_i32 s25, s15, 8
	s_add_i32 s26, s22, 8
	s_add_i32 s27, s15, 12
	s_add_i32 s30, s22, 12
	s_add_i32 s36, s15, 16
	s_add_i32 s37, s22, 16
	s_add_i32 s40, s15, 20
	s_add_i32 s41, s22, 20
	s_add_i32 s42, s15, 24
	s_add_i32 s43, s22, 24
	s_add_i32 s15, s15, 28
	s_add_i32 s22, s22, 28
	v_add_u32_e32 v54, s12, v9
	v_or_b32_e32 v11, s23, v1
	v_or_b32_e32 v13, s24, v0
	v_or_b32_e32 v15, s25, v1
	v_or_b32_e32 v19, s26, v0
	v_or_b32_e32 v41, s27, v1
	v_or_b32_e32 v43, s30, v0
	v_or_b32_e32 v45, s36, v1
	v_or_b32_e32 v47, s37, v0
	v_or_b32_e32 v49, s40, v1
	v_or_b32_e32 v82, s41, v0
	v_or_b32_e32 v86, s42, v1
	v_or_b32_e32 v87, s43, v0
	v_or_b32_e32 v88, s15, v1
	v_or_b32_e32 v89, s22, v0
	v_add_u32_e32 v52, s4, v7
	v_ashrrev_i32_e32 v55, 31, v54
	v_add_u32_e32 v56, s4, v11
	v_add_u32_e32 v58, s12, v13
	v_add_u32_e32 v60, s4, v15
	v_add_u32_e32 v62, s12, v19
	v_add_u32_e32 v64, s4, v41
	v_add_u32_e32 v66, s12, v43
	v_add_u32_e32 v68, s4, v45
	v_add_u32_e32 v70, s12, v47
	v_add_u32_e32 v72, s4, v49
	v_add_u32_e32 v74, s12, v82
	v_add_u32_e32 v76, s4, v86
	v_add_u32_e32 v78, s12, v87
	v_add_u32_e32 v80, s4, v88
	v_add_u32_e32 v84, s12, v89
	v_ashrrev_i32_e32 v53, 31, v52
	v_lshlrev_b64 v[54:55], 12, v[54:55]
	v_ashrrev_i32_e32 v59, 31, v58
	v_ashrrev_i32_e32 v57, 31, v56
	v_ashrrev_i32_e32 v63, 31, v62
	v_ashrrev_i32_e32 v61, 31, v60
	v_ashrrev_i32_e32 v67, 31, v66
	v_ashrrev_i32_e32 v65, 31, v64
	v_ashrrev_i32_e32 v71, 31, v70
	v_ashrrev_i32_e32 v69, 31, v68
	v_ashrrev_i32_e32 v75, 31, v74
	v_ashrrev_i32_e32 v73, 31, v72
	v_ashrrev_i32_e32 v79, 31, v78
	v_ashrrev_i32_e32 v77, 31, v76
	v_ashrrev_i32_e32 v85, 31, v84
	v_ashrrev_i32_e32 v81, 31, v80
	v_lshlrev_b64 v[52:53], 12, v[52:53]
	v_lshl_add_u64 v[54:55], v[50:51], 0, v[54:55]
	v_lshlrev_b64 v[56:57], 12, v[56:57]
	v_lshlrev_b64 v[58:59], 12, v[58:59]
	v_lshlrev_b64 v[60:61], 12, v[60:61]
	v_lshlrev_b64 v[62:63], 12, v[62:63]
	v_lshlrev_b64 v[64:65], 12, v[64:65]
	v_lshlrev_b64 v[66:67], 12, v[66:67]
	v_lshlrev_b64 v[68:69], 12, v[68:69]
	v_lshlrev_b64 v[70:71], 12, v[70:71]
	v_lshlrev_b64 v[72:73], 12, v[72:73]
	v_lshlrev_b64 v[74:75], 12, v[74:75]
	v_lshlrev_b64 v[76:77], 12, v[76:77]
	v_lshlrev_b64 v[78:79], 12, v[78:79]
	v_lshlrev_b64 v[80:81], 12, v[80:81]
	v_lshlrev_b64 v[84:85], 12, v[84:85]
	v_lshl_add_u64 v[52:53], v[50:51], 0, v[52:53]
	v_lshl_add_u64 v[58:59], v[50:51], 0, v[58:59]
	v_lshl_add_u64 v[56:57], v[50:51], 0, v[56:57]
	v_lshl_add_u64 v[62:63], v[50:51], 0, v[62:63]
	v_lshl_add_u64 v[60:61], v[50:51], 0, v[60:61]
	v_lshl_add_u64 v[66:67], v[50:51], 0, v[66:67]
	v_lshl_add_u64 v[64:65], v[50:51], 0, v[64:65]
	v_lshl_add_u64 v[70:71], v[50:51], 0, v[70:71]
	v_lshl_add_u64 v[68:69], v[50:51], 0, v[68:69]
	v_lshl_add_u64 v[74:75], v[50:51], 0, v[74:75]
	v_lshl_add_u64 v[72:73], v[50:51], 0, v[72:73]
	v_lshl_add_u64 v[78:79], v[50:51], 0, v[78:79]
	v_lshl_add_u64 v[76:77], v[50:51], 0, v[76:77]
	v_lshl_add_u64 v[84:85], v[50:51], 0, v[84:85]
	v_lshl_add_u64 v[80:81], v[50:51], 0, v[80:81]
	global_load_dword v90, v[54:55], off
	global_load_dword v91, v[52:53], off
	global_load_dword v92, v[58:59], off
	global_load_dword v93, v[56:57], off
	global_load_dword v94, v[62:63], off
	global_load_dword v95, v[60:61], off
	global_load_dword v96, v[66:67], off
	global_load_dword v97, v[64:65], off
	global_load_dword v98, v[70:71], off
	global_load_dword v99, v[68:69], off
	global_load_dword v100, v[74:75], off
	global_load_dword v101, v[72:73], off
	global_load_dword v102, v[78:79], off
	global_load_dword v103, v[76:77], off
	global_load_dword v104, v[84:85], off
	global_load_dword v105, v[80:81], off
	s_add_i32 s5, s5, 16
	s_add_i32 s0, s0, 16
	s_lshl_b32 s15, s0, 1
	s_lshl_b32 s22, s5, 1
	v_or_b32_e32 v106, s15, v1
	v_or_b32_e32 v107, s22, v0
	s_add_i32 s23, s15, 4
	s_add_i32 s24, s22, 4
	s_add_i32 s25, s15, 8
	s_add_i32 s26, s22, 8
	s_add_i32 s27, s15, 12
	s_add_i32 s30, s22, 12
	s_add_i32 s36, s15, 16
	s_add_i32 s37, s22, 16
	s_add_i32 s40, s15, 20
	s_add_i32 s41, s22, 20
	s_add_i32 s42, s15, 24
	s_add_i32 s43, s22, 24
	s_add_i32 s15, s15, 28
	s_add_i32 s22, s22, 28
	v_add_u32_e32 v132, s12, v107
	v_or_b32_e32 v108, s23, v1
	v_or_b32_e32 v109, s24, v0
	v_or_b32_e32 v110, s25, v1
	v_or_b32_e32 v111, s26, v0
	v_or_b32_e32 v112, s27, v1
	v_or_b32_e32 v113, s30, v0
	v_or_b32_e32 v114, s36, v1
	v_or_b32_e32 v115, s37, v0
	v_or_b32_e32 v116, s40, v1
	v_or_b32_e32 v117, s41, v0
	v_or_b32_e32 v118, s42, v1
	v_or_b32_e32 v119, s43, v0
	v_or_b32_e32 v120, s15, v1
	v_or_b32_e32 v121, s22, v0
	v_add_u32_e32 v130, s4, v106
	v_ashrrev_i32_e32 v133, 31, v132
	v_add_u32_e32 v134, s4, v108
	v_add_u32_e32 v136, s12, v109
	v_add_u32_e32 v138, s4, v110
	v_add_u32_e32 v140, s12, v111
	v_add_u32_e32 v142, s4, v112
	v_add_u32_e32 v144, s12, v113
	v_add_u32_e32 v146, s4, v114
	v_add_u32_e32 v148, s12, v115
	v_add_u32_e32 v150, s4, v116
	v_add_u32_e32 v152, s12, v117
	v_add_u32_e32 v154, s4, v118
	v_add_u32_e32 v156, s12, v119
	v_add_u32_e32 v158, s4, v120
	v_add_u32_e32 v160, s12, v121
	v_ashrrev_i32_e32 v131, 31, v130
	v_lshlrev_b64 v[132:133], 12, v[132:133]
	v_ashrrev_i32_e32 v137, 31, v136
	v_ashrrev_i32_e32 v135, 31, v134
	v_ashrrev_i32_e32 v141, 31, v140
	v_ashrrev_i32_e32 v139, 31, v138
	v_ashrrev_i32_e32 v145, 31, v144
	v_ashrrev_i32_e32 v143, 31, v142
	v_ashrrev_i32_e32 v149, 31, v148
	v_ashrrev_i32_e32 v147, 31, v146
	v_ashrrev_i32_e32 v153, 31, v152
	v_ashrrev_i32_e32 v151, 31, v150
	v_ashrrev_i32_e32 v157, 31, v156
	v_ashrrev_i32_e32 v155, 31, v154
	v_ashrrev_i32_e32 v161, 31, v160
	v_ashrrev_i32_e32 v159, 31, v158
	v_lshlrev_b64 v[130:131], 12, v[130:131]
	v_lshl_add_u64 v[132:133], v[50:51], 0, v[132:133]
	v_lshlrev_b64 v[134:135], 12, v[134:135]
	v_lshlrev_b64 v[136:137], 12, v[136:137]
	v_lshlrev_b64 v[138:139], 12, v[138:139]
	v_lshlrev_b64 v[140:141], 12, v[140:141]
	v_lshlrev_b64 v[142:143], 12, v[142:143]
	v_lshlrev_b64 v[144:145], 12, v[144:145]
	v_lshlrev_b64 v[146:147], 12, v[146:147]
	v_lshlrev_b64 v[148:149], 12, v[148:149]
	v_lshlrev_b64 v[150:151], 12, v[150:151]
	v_lshlrev_b64 v[152:153], 12, v[152:153]
	v_lshlrev_b64 v[154:155], 12, v[154:155]
	v_lshlrev_b64 v[156:157], 12, v[156:157]
	v_lshlrev_b64 v[158:159], 12, v[158:159]
	v_lshlrev_b64 v[160:161], 12, v[160:161]
	v_lshl_add_u64 v[130:131], v[50:51], 0, v[130:131]
	v_lshl_add_u64 v[136:137], v[50:51], 0, v[136:137]
	v_lshl_add_u64 v[134:135], v[50:51], 0, v[134:135]
	v_lshl_add_u64 v[140:141], v[50:51], 0, v[140:141]
	v_lshl_add_u64 v[138:139], v[50:51], 0, v[138:139]
	v_lshl_add_u64 v[144:145], v[50:51], 0, v[144:145]
	v_lshl_add_u64 v[142:143], v[50:51], 0, v[142:143]
	v_lshl_add_u64 v[148:149], v[50:51], 0, v[148:149]
	v_lshl_add_u64 v[146:147], v[50:51], 0, v[146:147]
	v_lshl_add_u64 v[152:153], v[50:51], 0, v[152:153]
	v_lshl_add_u64 v[150:151], v[50:51], 0, v[150:151]
	v_lshl_add_u64 v[156:157], v[50:51], 0, v[156:157]
	v_lshl_add_u64 v[154:155], v[50:51], 0, v[154:155]
	v_lshl_add_u64 v[160:161], v[50:51], 0, v[160:161]
	v_lshl_add_u64 v[158:159], v[50:51], 0, v[158:159]
	global_load_dword v122, v[132:133], off
	global_load_dword v123, v[130:131], off
	global_load_dword v124, v[136:137], off
	global_load_dword v125, v[134:135], off
	global_load_dword v126, v[140:141], off
	global_load_dword v127, v[138:139], off
	global_load_dword v162, v[144:145], off
	global_load_dword v163, v[142:143], off
	global_load_dword v164, v[148:149], off
	global_load_dword v165, v[146:147], off
	global_load_dword v166, v[152:153], off
	global_load_dword v167, v[150:151], off
	global_load_dword v168, v[156:157], off
	global_load_dword v169, v[154:155], off
	global_load_dword v170, v[160:161], off
	global_load_dword v171, v[158:159], off
	v_mad_u64_u32 v[52:53], s[22:23], v9, s78, v[4:5]
	v_mad_u64_u32 v[54:55], s[22:23], v7, s78, v[4:5]
	v_mad_u64_u32 v[56:57], s[22:23], v13, s78, v[4:5]
	v_mad_u64_u32 v[58:59], s[22:23], v11, s78, v[4:5]
	v_mad_u64_u32 v[60:61], s[22:23], v19, s78, v[4:5]
	v_mad_u64_u32 v[62:63], s[22:23], v15, s78, v[4:5]
	v_mad_u64_u32 v[64:65], s[22:23], v43, s78, v[4:5]
	v_mad_u64_u32 v[66:67], s[22:23], v41, s78, v[4:5]
	v_mad_u64_u32 v[68:69], s[22:23], v47, s78, v[4:5]
	v_mad_u64_u32 v[70:71], s[22:23], v45, s78, v[4:5]
	v_mad_u64_u32 v[72:73], s[22:23], v82, s78, v[4:5]
	v_mad_u64_u32 v[74:75], s[22:23], v49, s78, v[4:5]
	v_mad_u64_u32 v[76:77], s[22:23], v87, s78, v[4:5]
	v_mad_u64_u32 v[78:79], s[22:23], v86, s78, v[4:5]
	v_mad_u64_u32 v[80:81], s[22:23], v89, s78, v[4:5]
	v_mad_u64_u32 v[84:85], s[22:23], v88, s78, v[4:5]
	s_waitcnt vmcnt(31)
	ds_write_b32 v52, v90
	s_waitcnt vmcnt(30)
	ds_write_b32 v54, v91
	s_waitcnt vmcnt(29)
	ds_write_b32 v56, v92
	s_waitcnt vmcnt(28)
	ds_write_b32 v58, v93
	s_waitcnt vmcnt(27)
	ds_write_b32 v60, v94
	s_waitcnt vmcnt(26)
	ds_write_b32 v62, v95
	s_waitcnt vmcnt(25)
	ds_write_b32 v64, v96
	s_waitcnt vmcnt(24)
	ds_write_b32 v66, v97
	s_waitcnt vmcnt(23)
	ds_write_b32 v68, v98
	s_waitcnt vmcnt(22)
	ds_write_b32 v70, v99
	s_waitcnt vmcnt(21)
	ds_write_b32 v72, v100
	s_waitcnt vmcnt(20)
	ds_write_b32 v74, v101
	s_waitcnt vmcnt(19)
	ds_write_b32 v76, v102
	s_waitcnt vmcnt(18)
	ds_write_b32 v78, v103
	s_waitcnt vmcnt(17)
	ds_write_b32 v80, v104
	s_waitcnt vmcnt(16)
	ds_write_b32 v84, v105
	v_mad_u64_u32 v[130:131], s[22:23], v107, s78, v[4:5]
	v_mad_u64_u32 v[132:133], s[22:23], v106, s78, v[4:5]
	v_mad_u64_u32 v[134:135], s[22:23], v109, s78, v[4:5]
	v_mad_u64_u32 v[136:137], s[22:23], v108, s78, v[4:5]
	v_mad_u64_u32 v[138:139], s[22:23], v111, s78, v[4:5]
	v_mad_u64_u32 v[140:141], s[22:23], v110, s78, v[4:5]
	v_mad_u64_u32 v[142:143], s[22:23], v113, s78, v[4:5]
	v_mad_u64_u32 v[144:145], s[22:23], v112, s78, v[4:5]
	v_mad_u64_u32 v[146:147], s[22:23], v115, s78, v[4:5]
	v_mad_u64_u32 v[148:149], s[22:23], v114, s78, v[4:5]
	v_mad_u64_u32 v[150:151], s[22:23], v117, s78, v[4:5]
	v_mad_u64_u32 v[152:153], s[22:23], v116, s78, v[4:5]
	v_mad_u64_u32 v[154:155], s[22:23], v119, s78, v[4:5]
	v_mad_u64_u32 v[156:157], s[22:23], v118, s78, v[4:5]
	v_mad_u64_u32 v[158:159], s[22:23], v121, s78, v[4:5]
	v_mad_u64_u32 v[160:161], s[22:23], v120, s78, v[4:5]
	s_waitcnt vmcnt(15)
	ds_write_b32 v130, v122
	s_waitcnt vmcnt(14)
	ds_write_b32 v132, v123
	s_waitcnt vmcnt(13)
	ds_write_b32 v134, v124
	s_waitcnt vmcnt(12)
	ds_write_b32 v136, v125
	s_waitcnt vmcnt(11)
	ds_write_b32 v138, v126
	s_waitcnt vmcnt(10)
	ds_write_b32 v140, v127
	s_waitcnt vmcnt(9)
	ds_write_b32 v142, v162
	s_waitcnt vmcnt(8)
	ds_write_b32 v144, v163
	s_waitcnt vmcnt(7)
	ds_write_b32 v146, v164
	s_waitcnt vmcnt(6)
	ds_write_b32 v148, v165
	s_waitcnt vmcnt(5)
	ds_write_b32 v150, v166
	s_waitcnt vmcnt(4)
	ds_write_b32 v152, v167
	s_waitcnt vmcnt(3)
	ds_write_b32 v154, v168
	s_waitcnt vmcnt(2)
	ds_write_b32 v156, v169
	s_waitcnt vmcnt(1)
	ds_write_b32 v158, v170
	s_waitcnt vmcnt(0)
	ds_write_b32 v160, v171
	s_add_i32 s5, s5, 16
	s_add_i32 s0, s0, 16
	s_add_i32 s13, s13, -16
	s_add_i32 s13, s13, -16
	s_cmp_lg_u32 s13, 0
	s_waitcnt lgkmcnt(0)
	ds_read2_b32 v[54:55], v5 offset1:8
	ds_read2_b32 v[58:59], v5 offset0:33 offset1:41
	ds_read2_b32 v[60:61], v5 offset0:66 offset1:74
	ds_read2_b32 v[62:63], v5 offset0:99 offset1:107
	ds_read2_b32 v[64:65], v5 offset0:132 offset1:140
	s_waitcnt lgkmcnt(4)
	s_waitcnt lgkmcnt(3)
	v_cvt_pk_bf16_f32 v9, v54, v58
	ds_read2_b32 v[66:67], v5 offset0:165 offset1:173
	v_mov_b32_e32 v50, v9
	s_waitcnt lgkmcnt(3)
	s_waitcnt lgkmcnt(2)
	ds_read2_b32 v[68:69], v5 offset0:198 offset1:206
	v_cvt_pk_bf16_f32 v9, v60, v62
	ds_read2_b32 v[70:71], v5 offset0:231 offset1:239
	v_mov_b32_e32 v51, v9
	s_waitcnt lgkmcnt(3)
	s_mul_i32 s4, s14, 0x1600
	s_waitcnt lgkmcnt(2)
	s_mul_hi_i32 s0, s14, 0x1600
	s_add_u32 s14, s39, s4
	v_cvt_pk_bf16_f32 v9, v64, v66
	s_addc_u32 s0, s44, s0
	s_ashr_i32 s13, s12, 31
	v_mov_b32_e32 v52, v9
	s_waitcnt lgkmcnt(1)
	s_lshl_b64 s[4:5], s[12:13], 1
	s_waitcnt lgkmcnt(0)
	s_add_u32 s4, s14, s4
	v_cvt_pk_bf16_f32 v9, v68, v70
	s_addc_u32 s5, s0, s5
	v_lshlrev_b32_e32 v128, 1, v6
	v_mov_b32_e32 v53, v9
	v_lshl_add_u64 v[56:57], s[4:5], 0, v[128:129]
	v_lshlrev_b32_e32 v128, 1, v18
	v_lshl_add_u64 v[56:57], v[56:57], 0, v[128:129]
	v_cvt_pk_bf16_f32 v9, v55, v59
	global_store_dwordx4 v[56:57], v[50:53], off
	s_mov_b32 s0, 0xb000
	v_add_co_u32_e32 v58, vcc, s0, v56
	v_mov_b32_e32 v50, v9
	v_cvt_pk_bf16_f32 v9, v61, v63
	v_mov_b32_e32 v51, v9
	v_cvt_pk_bf16_f32 v9, v65, v67
	v_mov_b32_e32 v52, v9
	v_cvt_pk_bf16_f32 v9, v69, v71
	v_mov_b32_e32 v53, v9
	ds_read2_b32 v[54:55], v5 offset0:16 offset1:24
	v_addc_co_u32_e32 v59, vcc, 0, v57, vcc
	global_store_dwordx4 v[58:59], v[50:53], off
	ds_read2_b32 v[58:59], v5 offset0:49 offset1:57
	ds_read2_b32 v[60:61], v5 offset0:82 offset1:90
	ds_read2_b32 v[62:63], v5 offset0:115 offset1:123
	s_waitcnt lgkmcnt(3)
	s_waitcnt lgkmcnt(2)
	ds_read2_b32 v[64:65], v5 offset0:148 offset1:156
	v_cvt_pk_bf16_f32 v9, v54, v58
	ds_read2_b32 v[66:67], v5 offset0:181 offset1:189
	v_mov_b32_e32 v50, v9
	s_waitcnt lgkmcnt(3)
	s_waitcnt lgkmcnt(2)
	ds_read2_b32 v[68:69], v5 offset0:214 offset1:222
	v_cvt_pk_bf16_f32 v9, v60, v62
	ds_read2_b32 v[70:71], v5 offset0:247 offset1:255
	v_mov_b32_e32 v51, v9
	s_waitcnt lgkmcnt(3)
	s_waitcnt lgkmcnt(2)
	v_cvt_pk_bf16_f32 v9, v64, v66
	v_mov_b32_e32 v52, v9
	s_waitcnt lgkmcnt(1)
	s_waitcnt lgkmcnt(0)
	v_cvt_pk_bf16_f32 v9, v68, v70
	v_mov_b32_e32 v53, v9
	s_mov_b32 s0, 0x16000
	v_add_co_u32_e32 v72, vcc, s0, v56
	v_addc_co_u32_e32 v73, vcc, 0, v57, vcc
	v_cvt_pk_bf16_f32 v9, v55, v59
	global_store_dwordx4 v[72:73], v[50:53], off
	v_add_co_u32_e32 v54, vcc, 0x21000, v56
	s_nop 0
	v_mov_b32_e32 v50, v9
	v_cvt_pk_bf16_f32 v9, v61, v63
	v_mov_b32_e32 v51, v9
	v_cvt_pk_bf16_f32 v9, v65, v67
	v_mov_b32_e32 v52, v9
	v_cvt_pk_bf16_f32 v9, v69, v71
	v_mov_b32_e32 v53, v9
	v_addc_co_u32_e32 v55, vcc, 0, v57, vcc
	global_store_dwordx4 v[54:55], v[50:53], off
	s_waitcnt lgkmcnt(0)
	s_mov_b32 s0, s1
	s_andn2_b64 vcc, exec, s[10:11]
	s_mov_b64 s[10:11], -1
	s_cbranch_vccnz .LBB0_744

.LBB0_700:
	s_lshl_b32 s23, s5, 1
	s_lshl_b32 s24, s13, 1
	v_or_b32_e32 v7, s23, v1
	v_or_b32_e32 v9, s24, v0
	s_add_i32 s25, s23, 4
	s_add_i32 s26, s24, 4
	s_add_i32 s27, s23, 8
	s_add_i32 s30, s24, 8
	s_add_i32 s36, s23, 12
	s_add_i32 s37, s24, 12
	s_add_i32 s40, s23, 16
	s_add_i32 s41, s24, 16
	s_add_i32 s42, s23, 20
	s_add_i32 s43, s24, 20
	s_add_i32 s52, s23, 24
	s_add_i32 s53, s24, 24
	s_add_i32 s23, s23, 28
	s_add_i32 s24, s24, 28
	v_add_u32_e32 v11, s4, v7
	v_add_u32_e32 v13, s12, v9
	v_or_b32_e32 v15, s25, v1
	v_or_b32_e32 v19, s26, v0
	v_or_b32_e32 v41, s27, v1
	v_or_b32_e32 v43, s30, v0
	v_or_b32_e32 v45, s36, v1
	v_or_b32_e32 v47, s37, v0
	v_or_b32_e32 v49, s40, v1
	v_or_b32_e32 v82, s41, v0
	v_or_b32_e32 v86, s42, v1
	v_or_b32_e32 v87, s43, v0
	v_or_b32_e32 v88, s52, v1
	v_or_b32_e32 v89, s53, v0
	v_or_b32_e32 v90, s23, v1
	v_or_b32_e32 v91, s24, v0
	v_mad_i64_i32 v[52:53], s[24:25], v13, s68, v[50:51]
	v_mad_i64_i32 v[54:55], s[24:25], v11, s68, v[50:51]
	v_add_u32_e32 v11, s4, v15
	v_add_u32_e32 v13, s12, v19
	v_add_u32_e32 v62, s4, v41
	v_add_u32_e32 v60, s12, v43
	v_add_u32_e32 v66, s4, v45
	v_add_u32_e32 v64, s12, v47
	v_add_u32_e32 v70, s4, v49
	v_add_u32_e32 v68, s12, v82
	v_add_u32_e32 v74, s4, v86
	v_add_u32_e32 v72, s12, v87
	v_add_u32_e32 v78, s4, v88
	v_add_u32_e32 v76, s12, v89
	v_add_u32_e32 v84, s4, v90
	v_add_u32_e32 v80, s12, v91
	v_mad_i64_i32 v[56:57], s[24:25], v13, s68, v[50:51]
	v_mad_i64_i32 v[58:59], s[24:25], v11, s68, v[50:51]
	v_mad_i64_i32 v[60:61], s[24:25], v60, s68, v[50:51]
	v_mad_i64_i32 v[62:63], s[24:25], v62, s68, v[50:51]
	v_mad_i64_i32 v[64:65], s[24:25], v64, s68, v[50:51]
	v_mad_i64_i32 v[66:67], s[24:25], v66, s68, v[50:51]
	v_mad_i64_i32 v[68:69], s[24:25], v68, s68, v[50:51]
	v_mad_i64_i32 v[70:71], s[24:25], v70, s68, v[50:51]
	v_mad_i64_i32 v[72:73], s[24:25], v72, s68, v[50:51]
	v_mad_i64_i32 v[74:75], s[24:25], v74, s68, v[50:51]
	v_mad_i64_i32 v[76:77], s[24:25], v76, s68, v[50:51]
	v_mad_i64_i32 v[78:79], s[24:25], v78, s68, v[50:51]
	v_mad_i64_i32 v[80:81], s[24:25], v80, s68, v[50:51]
	v_mad_i64_i32 v[84:85], s[24:25], v84, s68, v[50:51]
	global_load_dword v11, v[52:53], off
	global_load_dword v13, v[54:55], off
	global_load_dword v92, v[56:57], off
	global_load_dword v93, v[58:59], off
	global_load_dword v94, v[60:61], off
	global_load_dword v95, v[62:63], off
	global_load_dword v96, v[64:65], off
	global_load_dword v97, v[66:67], off
	global_load_dword v98, v[68:69], off
	global_load_dword v99, v[70:71], off
	global_load_dword v100, v[72:73], off
	global_load_dword v101, v[74:75], off
	global_load_dword v102, v[76:77], off
	global_load_dword v103, v[78:79], off
	global_load_dword v104, v[80:81], off
	global_load_dword v105, v[84:85], off
	s_add_i32 s13, s13, 16
	s_add_i32 s5, s5, 16
	s_lshl_b32 s23, s5, 1
	s_lshl_b32 s24, s13, 1
	v_or_b32_e32 v106, s23, v1
	v_or_b32_e32 v107, s24, v0
	s_add_i32 s25, s23, 4
	s_add_i32 s26, s24, 4
	s_add_i32 s27, s23, 8
	s_add_i32 s30, s24, 8
	s_add_i32 s36, s23, 12
	s_add_i32 s37, s24, 12
	s_add_i32 s40, s23, 16
	s_add_i32 s41, s24, 16
	s_add_i32 s42, s23, 20
	s_add_i32 s43, s24, 20
	s_add_i32 s52, s23, 24
	s_add_i32 s53, s24, 24
	s_add_i32 s23, s23, 28
	s_add_i32 s24, s24, 28
	v_add_u32_e32 v108, s4, v106
	v_add_u32_e32 v109, s12, v107
	v_or_b32_e32 v110, s25, v1
	v_or_b32_e32 v111, s26, v0
	v_or_b32_e32 v112, s27, v1
	v_or_b32_e32 v113, s30, v0
	v_or_b32_e32 v114, s36, v1
	v_or_b32_e32 v115, s37, v0
	v_or_b32_e32 v116, s40, v1
	v_or_b32_e32 v117, s41, v0
	v_or_b32_e32 v118, s42, v1
	v_or_b32_e32 v119, s43, v0
	v_or_b32_e32 v120, s52, v1
	v_or_b32_e32 v121, s53, v0
	v_or_b32_e32 v122, s23, v1
	v_or_b32_e32 v123, s24, v0
	v_mad_i64_i32 v[130:131], s[24:25], v109, s68, v[50:51]
	v_mad_i64_i32 v[132:133], s[24:25], v108, s68, v[50:51]
	v_add_u32_e32 v108, s4, v110
	v_add_u32_e32 v109, s12, v111
	v_add_u32_e32 v140, s4, v112
	v_add_u32_e32 v138, s12, v113
	v_add_u32_e32 v144, s4, v114
	v_add_u32_e32 v142, s12, v115
	v_add_u32_e32 v148, s4, v116
	v_add_u32_e32 v146, s12, v117
	v_add_u32_e32 v152, s4, v118
	v_add_u32_e32 v150, s12, v119
	v_add_u32_e32 v156, s4, v120
	v_add_u32_e32 v154, s12, v121
	v_add_u32_e32 v160, s4, v122
	v_add_u32_e32 v158, s12, v123
	v_mad_i64_i32 v[134:135], s[24:25], v109, s68, v[50:51]
	v_mad_i64_i32 v[136:137], s[24:25], v108, s68, v[50:51]
	v_mad_i64_i32 v[138:139], s[24:25], v138, s68, v[50:51]
	v_mad_i64_i32 v[140:141], s[24:25], v140, s68, v[50:51]
	v_mad_i64_i32 v[142:143], s[24:25], v142, s68, v[50:51]
	v_mad_i64_i32 v[144:145], s[24:25], v144, s68, v[50:51]
	v_mad_i64_i32 v[146:147], s[24:25], v146, s68, v[50:51]
	v_mad_i64_i32 v[148:149], s[24:25], v148, s68, v[50:51]
	v_mad_i64_i32 v[150:151], s[24:25], v150, s68, v[50:51]
	v_mad_i64_i32 v[152:153], s[24:25], v152, s68, v[50:51]
	v_mad_i64_i32 v[154:155], s[24:25], v154, s68, v[50:51]
	v_mad_i64_i32 v[156:157], s[24:25], v156, s68, v[50:51]
	v_mad_i64_i32 v[158:159], s[24:25], v158, s68, v[50:51]
	v_mad_i64_i32 v[160:161], s[24:25], v160, s68, v[50:51]
	global_load_dword v108, v[130:131], off
	global_load_dword v109, v[132:133], off
	global_load_dword v124, v[134:135], off
	global_load_dword v125, v[136:137], off
	global_load_dword v126, v[138:139], off
	global_load_dword v127, v[140:141], off
	global_load_dword v162, v[142:143], off
	global_load_dword v163, v[144:145], off
	global_load_dword v164, v[146:147], off
	global_load_dword v165, v[148:149], off
	global_load_dword v166, v[150:151], off
	global_load_dword v167, v[152:153], off
	global_load_dword v168, v[154:155], off
	global_load_dword v169, v[156:157], off
	global_load_dword v170, v[158:159], off
	global_load_dword v171, v[160:161], off
	v_mad_u64_u32 v[52:53], s[24:25], v9, s78, v[4:5]
	v_mad_u64_u32 v[54:55], s[24:25], v7, s78, v[4:5]
	v_mad_u64_u32 v[56:57], s[24:25], v19, s78, v[4:5]
	v_mad_u64_u32 v[58:59], s[24:25], v15, s78, v[4:5]
	v_mad_u64_u32 v[60:61], s[24:25], v43, s78, v[4:5]
	v_mad_u64_u32 v[62:63], s[24:25], v41, s78, v[4:5]
	v_mad_u64_u32 v[64:65], s[24:25], v47, s78, v[4:5]
	v_mad_u64_u32 v[66:67], s[24:25], v45, s78, v[4:5]
	v_mad_u64_u32 v[68:69], s[24:25], v82, s78, v[4:5]
	v_mad_u64_u32 v[70:71], s[24:25], v49, s78, v[4:5]
	v_mad_u64_u32 v[72:73], s[24:25], v87, s78, v[4:5]
	v_mad_u64_u32 v[74:75], s[24:25], v86, s78, v[4:5]
	v_mad_u64_u32 v[76:77], s[24:25], v89, s78, v[4:5]
	v_mad_u64_u32 v[78:79], s[24:25], v88, s78, v[4:5]
	v_mad_u64_u32 v[80:81], s[24:25], v91, s78, v[4:5]
	v_mad_u64_u32 v[84:85], s[24:25], v90, s78, v[4:5]
	s_waitcnt vmcnt(31)
	ds_write_b32 v52, v11
	s_waitcnt vmcnt(30)
	ds_write_b32 v54, v13
	s_waitcnt vmcnt(29)
	ds_write_b32 v56, v92
	s_waitcnt vmcnt(28)
	ds_write_b32 v58, v93
	s_waitcnt vmcnt(27)
	ds_write_b32 v60, v94
	s_waitcnt vmcnt(26)
	ds_write_b32 v62, v95
	s_waitcnt vmcnt(25)
	ds_write_b32 v64, v96
	s_waitcnt vmcnt(24)
	ds_write_b32 v66, v97
	s_waitcnt vmcnt(23)
	ds_write_b32 v68, v98
	s_waitcnt vmcnt(22)
	ds_write_b32 v70, v99
	s_waitcnt vmcnt(21)
	ds_write_b32 v72, v100
	s_waitcnt vmcnt(20)
	ds_write_b32 v74, v101
	s_waitcnt vmcnt(19)
	ds_write_b32 v76, v102
	s_waitcnt vmcnt(18)
	ds_write_b32 v78, v103
	s_waitcnt vmcnt(17)
	ds_write_b32 v80, v104
	s_waitcnt vmcnt(16)
	ds_write_b32 v84, v105
	v_mad_u64_u32 v[130:131], s[24:25], v107, s78, v[4:5]
	v_mad_u64_u32 v[132:133], s[24:25], v106, s78, v[4:5]
	v_mad_u64_u32 v[134:135], s[24:25], v111, s78, v[4:5]
	v_mad_u64_u32 v[136:137], s[24:25], v110, s78, v[4:5]
	v_mad_u64_u32 v[138:139], s[24:25], v113, s78, v[4:5]
	v_mad_u64_u32 v[140:141], s[24:25], v112, s78, v[4:5]
	v_mad_u64_u32 v[142:143], s[24:25], v115, s78, v[4:5]
	v_mad_u64_u32 v[144:145], s[24:25], v114, s78, v[4:5]
	v_mad_u64_u32 v[146:147], s[24:25], v117, s78, v[4:5]
	v_mad_u64_u32 v[148:149], s[24:25], v116, s78, v[4:5]
	v_mad_u64_u32 v[150:151], s[24:25], v119, s78, v[4:5]
	v_mad_u64_u32 v[152:153], s[24:25], v118, s78, v[4:5]
	v_mad_u64_u32 v[154:155], s[24:25], v121, s78, v[4:5]
	v_mad_u64_u32 v[156:157], s[24:25], v120, s78, v[4:5]
	v_mad_u64_u32 v[158:159], s[24:25], v123, s78, v[4:5]
	v_mad_u64_u32 v[160:161], s[24:25], v122, s78, v[4:5]
	s_waitcnt vmcnt(15)
	ds_write_b32 v130, v108
	s_waitcnt vmcnt(14)
	ds_write_b32 v132, v109
	s_waitcnt vmcnt(13)
	ds_write_b32 v134, v124
	s_waitcnt vmcnt(12)
	ds_write_b32 v136, v125
	s_waitcnt vmcnt(11)
	ds_write_b32 v138, v126
	s_waitcnt vmcnt(10)
	ds_write_b32 v140, v127
	s_waitcnt vmcnt(9)
	ds_write_b32 v142, v162
	s_waitcnt vmcnt(8)
	ds_write_b32 v144, v163
	s_waitcnt vmcnt(7)
	ds_write_b32 v146, v164
	s_waitcnt vmcnt(6)
	ds_write_b32 v148, v165
	s_waitcnt vmcnt(5)
	ds_write_b32 v150, v166
	s_waitcnt vmcnt(4)
	ds_write_b32 v152, v167
	s_waitcnt vmcnt(3)
	ds_write_b32 v154, v168
	s_waitcnt vmcnt(2)
	ds_write_b32 v156, v169
	s_waitcnt vmcnt(1)
	ds_write_b32 v158, v170
	s_waitcnt vmcnt(0)
	ds_write_b32 v160, v171
	s_add_i32 s13, s13, 16
	s_add_i32 s5, s5, 16
	s_add_i32 s22, s22, -16
	s_add_i32 s22, s22, -16
	s_cmp_lg_u32 s22, 0
	s_waitcnt lgkmcnt(0)
	ds_read2_b32 v[54:55], v5 offset1:8
	ds_read2_b32 v[58:59], v5 offset0:33 offset1:41
	ds_read2_b32 v[60:61], v5 offset0:66 offset1:74
	ds_read2_b32 v[62:63], v5 offset0:99 offset1:107
	ds_read2_b32 v[64:65], v5 offset0:132 offset1:140
	s_waitcnt lgkmcnt(4)
	s_waitcnt lgkmcnt(3)
	v_cvt_pk_bf16_f32 v9, v54, v58
	ds_read2_b32 v[66:67], v5 offset0:165 offset1:173
	v_mov_b32_e32 v50, v9
	s_waitcnt lgkmcnt(3)
	s_add_i32 s4, s14, 0xfffffb00
	s_waitcnt lgkmcnt(2)
	ds_read2_b32 v[68:69], v5 offset0:198 offset1:206
	s_cmp_lt_i32 s1, 40
	v_cvt_pk_bf16_f32 v9, v60, v62
	ds_read2_b32 v[70:71], v5 offset0:231 offset1:239
	s_cselect_b32 s5, s15, 0
	s_cselect_b32 s4, s14, s4
	v_mov_b32_e32 v51, v9
	s_waitcnt lgkmcnt(3)
	s_cselect_b32 s1, s35, s62
	s_cselect_b32 s13, s38, s63
	s_lshl_b64 s[4:5], s[4:5], 11
	s_waitcnt lgkmcnt(2)
	s_add_u32 s1, s1, s4
	v_cvt_pk_bf16_f32 v9, v64, v66
	s_addc_u32 s14, s13, s5
	s_ashr_i32 s13, s12, 31
	v_mov_b32_e32 v52, v9
	s_waitcnt lgkmcnt(1)
	s_lshl_b64 s[4:5], s[12:13], 1
	s_waitcnt lgkmcnt(0)
	s_add_u32 s4, s1, s4
	v_cvt_pk_bf16_f32 v9, v68, v70
	s_addc_u32 s5, s14, s5
	v_lshlrev_b32_e32 v128, 1, v6
	v_mov_b32_e32 v53, v9
	v_lshl_add_u64 v[56:57], s[4:5], 0, v[128:129]
	v_lshlrev_b32_e32 v128, 1, v8
	v_lshl_add_u64 v[72:73], v[56:57], 0, v[128:129]
	v_cvt_pk_bf16_f32 v9, v55, v59
	global_store_dwordx4 v[72:73], v[50:53], off
	v_lshlrev_b32_e32 v128, 1, v10
	ds_read2_b32 v[54:55], v5 offset0:16 offset1:24
	v_mov_b32_e32 v50, v9
	v_cvt_pk_bf16_f32 v9, v61, v63
	v_mov_b32_e32 v51, v9
	v_cvt_pk_bf16_f32 v9, v65, v67
	v_mov_b32_e32 v52, v9
	v_cvt_pk_bf16_f32 v9, v69, v71
	v_mov_b32_e32 v53, v9
	v_lshl_add_u64 v[58:59], v[56:57], 0, v[128:129]
	global_store_dwordx4 v[58:59], v[50:53], off
	ds_read2_b32 v[58:59], v5 offset0:49 offset1:57
	ds_read2_b32 v[60:61], v5 offset0:82 offset1:90
	ds_read2_b32 v[62:63], v5 offset0:115 offset1:123
	s_waitcnt lgkmcnt(3)
	s_waitcnt lgkmcnt(2)
	ds_read2_b32 v[64:65], v5 offset0:148 offset1:156
	v_cvt_pk_bf16_f32 v9, v54, v58
	ds_read2_b32 v[66:67], v5 offset0:181 offset1:189
	v_mov_b32_e32 v50, v9
	s_waitcnt lgkmcnt(3)
	s_waitcnt lgkmcnt(2)
	ds_read2_b32 v[68:69], v5 offset0:214 offset1:222
	v_cvt_pk_bf16_f32 v9, v60, v62
	ds_read2_b32 v[70:71], v5 offset0:247 offset1:255
	v_mov_b32_e32 v51, v9
	s_waitcnt lgkmcnt(3)
	s_waitcnt lgkmcnt(2)
	v_cvt_pk_bf16_f32 v9, v64, v66
	v_mov_b32_e32 v52, v9
	s_waitcnt lgkmcnt(1)
	s_waitcnt lgkmcnt(0)
	v_cvt_pk_bf16_f32 v9, v68, v70
	v_mov_b32_e32 v53, v9
	v_lshlrev_b32_e32 v128, 1, v12
	v_lshl_add_u64 v[72:73], v[56:57], 0, v[128:129]
	v_cvt_pk_bf16_f32 v9, v55, v59
	global_store_dwordx4 v[72:73], v[50:53], off
	v_lshlrev_b32_e32 v128, 1, v14
	v_lshl_add_u64 v[54:55], v[56:57], 0, v[128:129]
	v_mov_b32_e32 v50, v9
	v_cvt_pk_bf16_f32 v9, v61, v63
	v_mov_b32_e32 v51, v9
	v_cvt_pk_bf16_f32 v9, v65, v67
	v_mov_b32_e32 v52, v9
	v_cvt_pk_bf16_f32 v9, v69, v71
	v_mov_b32_e32 v53, v9
	global_store_dwordx4 v[54:55], v[50:53], off
	s_waitcnt lgkmcnt(0)
	s_mov_b32 s1, s0
	s_andn2_b64 vcc, exec, s[10:11]
	s_mov_b64 s[10:11], -1
	s_cbranch_vccnz .LBB0_706

.LBB0_704:
	s_lshl_b32 s14, s1, 1
	s_lshl_b32 s15, s5, 1
	v_or_b32_e32 v7, s14, v1
	v_or_b32_e32 v9, s15, v0
	s_add_i32 s22, s14, 4
	s_add_i32 s23, s15, 4
	s_add_i32 s24, s14, 8
	s_add_i32 s25, s15, 8
	s_add_i32 s26, s14, 12
	s_add_i32 s27, s15, 12
	s_add_i32 s30, s14, 16
	s_add_i32 s36, s15, 16
	s_add_i32 s37, s14, 20
	s_add_i32 s40, s15, 20
	s_add_i32 s41, s14, 24
	s_add_i32 s42, s15, 24
	s_add_i32 s14, s14, 28
	s_add_i32 s15, s15, 28
	v_add_u32_e32 v54, s10, v9
	v_or_b32_e32 v11, s22, v1
	v_or_b32_e32 v13, s23, v0
	v_or_b32_e32 v15, s24, v1
	v_or_b32_e32 v19, s25, v0
	v_or_b32_e32 v41, s26, v1
	v_or_b32_e32 v43, s27, v0
	v_or_b32_e32 v45, s30, v1
	v_or_b32_e32 v47, s36, v0
	v_or_b32_e32 v49, s37, v1
	v_or_b32_e32 v82, s40, v0
	v_or_b32_e32 v86, s41, v1
	v_or_b32_e32 v87, s42, v0
	v_or_b32_e32 v88, s14, v1
	v_or_b32_e32 v89, s15, v0
	v_add_u32_e32 v52, s4, v7
	v_ashrrev_i32_e32 v55, 31, v54
	v_add_u32_e32 v56, s4, v11
	v_add_u32_e32 v58, s10, v13
	v_add_u32_e32 v60, s4, v15
	v_add_u32_e32 v62, s10, v19
	v_add_u32_e32 v64, s4, v41
	v_add_u32_e32 v66, s10, v43
	v_add_u32_e32 v68, s4, v45
	v_add_u32_e32 v70, s10, v47
	v_add_u32_e32 v72, s4, v49
	v_add_u32_e32 v74, s10, v82
	v_add_u32_e32 v76, s4, v86
	v_add_u32_e32 v78, s10, v87
	v_add_u32_e32 v80, s4, v88
	v_add_u32_e32 v84, s10, v89
	v_ashrrev_i32_e32 v53, 31, v52
	v_lshlrev_b64 v[54:55], 12, v[54:55]
	v_ashrrev_i32_e32 v59, 31, v58
	v_ashrrev_i32_e32 v57, 31, v56
	v_ashrrev_i32_e32 v63, 31, v62
	v_ashrrev_i32_e32 v61, 31, v60
	v_ashrrev_i32_e32 v67, 31, v66
	v_ashrrev_i32_e32 v65, 31, v64
	v_ashrrev_i32_e32 v71, 31, v70
	v_ashrrev_i32_e32 v69, 31, v68
	v_ashrrev_i32_e32 v75, 31, v74
	v_ashrrev_i32_e32 v73, 31, v72
	v_ashrrev_i32_e32 v79, 31, v78
	v_ashrrev_i32_e32 v77, 31, v76
	v_ashrrev_i32_e32 v85, 31, v84
	v_ashrrev_i32_e32 v81, 31, v80
	v_lshlrev_b64 v[52:53], 12, v[52:53]
	v_lshl_add_u64 v[54:55], v[50:51], 0, v[54:55]
	v_lshlrev_b64 v[56:57], 12, v[56:57]
	v_lshlrev_b64 v[58:59], 12, v[58:59]
	v_lshlrev_b64 v[60:61], 12, v[60:61]
	v_lshlrev_b64 v[62:63], 12, v[62:63]
	v_lshlrev_b64 v[64:65], 12, v[64:65]
	v_lshlrev_b64 v[66:67], 12, v[66:67]
	v_lshlrev_b64 v[68:69], 12, v[68:69]
	v_lshlrev_b64 v[70:71], 12, v[70:71]
	v_lshlrev_b64 v[72:73], 12, v[72:73]
	v_lshlrev_b64 v[74:75], 12, v[74:75]
	v_lshlrev_b64 v[76:77], 12, v[76:77]
	v_lshlrev_b64 v[78:79], 12, v[78:79]
	v_lshlrev_b64 v[80:81], 12, v[80:81]
	v_lshlrev_b64 v[84:85], 12, v[84:85]
	v_lshl_add_u64 v[52:53], v[50:51], 0, v[52:53]
	v_lshl_add_u64 v[58:59], v[50:51], 0, v[58:59]
	v_lshl_add_u64 v[56:57], v[50:51], 0, v[56:57]
	v_lshl_add_u64 v[62:63], v[50:51], 0, v[62:63]
	v_lshl_add_u64 v[60:61], v[50:51], 0, v[60:61]
	v_lshl_add_u64 v[66:67], v[50:51], 0, v[66:67]
	v_lshl_add_u64 v[64:65], v[50:51], 0, v[64:65]
	v_lshl_add_u64 v[70:71], v[50:51], 0, v[70:71]
	v_lshl_add_u64 v[68:69], v[50:51], 0, v[68:69]
	v_lshl_add_u64 v[74:75], v[50:51], 0, v[74:75]
	v_lshl_add_u64 v[72:73], v[50:51], 0, v[72:73]
	v_lshl_add_u64 v[78:79], v[50:51], 0, v[78:79]
	v_lshl_add_u64 v[76:77], v[50:51], 0, v[76:77]
	v_lshl_add_u64 v[84:85], v[50:51], 0, v[84:85]
	v_lshl_add_u64 v[80:81], v[50:51], 0, v[80:81]
	global_load_dword v90, v[54:55], off
	global_load_dword v91, v[52:53], off
	global_load_dword v92, v[58:59], off
	global_load_dword v93, v[56:57], off
	global_load_dword v94, v[62:63], off
	global_load_dword v95, v[60:61], off
	global_load_dword v96, v[66:67], off
	global_load_dword v97, v[64:65], off
	global_load_dword v98, v[70:71], off
	global_load_dword v99, v[68:69], off
	global_load_dword v100, v[74:75], off
	global_load_dword v101, v[72:73], off
	global_load_dword v102, v[78:79], off
	global_load_dword v103, v[76:77], off
	global_load_dword v104, v[84:85], off
	global_load_dword v105, v[80:81], off
	s_add_i32 s5, s5, 16
	s_add_i32 s1, s1, 16
	s_lshl_b32 s14, s1, 1
	s_lshl_b32 s15, s5, 1
	v_or_b32_e32 v106, s14, v1
	v_or_b32_e32 v107, s15, v0
	s_add_i32 s22, s14, 4
	s_add_i32 s23, s15, 4
	s_add_i32 s24, s14, 8
	s_add_i32 s25, s15, 8
	s_add_i32 s26, s14, 12
	s_add_i32 s27, s15, 12
	s_add_i32 s30, s14, 16
	s_add_i32 s36, s15, 16
	s_add_i32 s37, s14, 20
	s_add_i32 s40, s15, 20
	s_add_i32 s41, s14, 24
	s_add_i32 s42, s15, 24
	s_add_i32 s14, s14, 28
	s_add_i32 s15, s15, 28
	v_add_u32_e32 v132, s10, v107
	v_or_b32_e32 v108, s22, v1
	v_or_b32_e32 v109, s23, v0
	v_or_b32_e32 v110, s24, v1
	v_or_b32_e32 v111, s25, v0
	v_or_b32_e32 v112, s26, v1
	v_or_b32_e32 v113, s27, v0
	v_or_b32_e32 v114, s30, v1
	v_or_b32_e32 v115, s36, v0
	v_or_b32_e32 v116, s37, v1
	v_or_b32_e32 v117, s40, v0
	v_or_b32_e32 v118, s41, v1
	v_or_b32_e32 v119, s42, v0
	v_or_b32_e32 v120, s14, v1
	v_or_b32_e32 v121, s15, v0
	v_add_u32_e32 v130, s4, v106
	v_ashrrev_i32_e32 v133, 31, v132
	v_add_u32_e32 v134, s4, v108
	v_add_u32_e32 v136, s10, v109
	v_add_u32_e32 v138, s4, v110
	v_add_u32_e32 v140, s10, v111
	v_add_u32_e32 v142, s4, v112
	v_add_u32_e32 v144, s10, v113
	v_add_u32_e32 v146, s4, v114
	v_add_u32_e32 v148, s10, v115
	v_add_u32_e32 v150, s4, v116
	v_add_u32_e32 v152, s10, v117
	v_add_u32_e32 v154, s4, v118
	v_add_u32_e32 v156, s10, v119
	v_add_u32_e32 v158, s4, v120
	v_add_u32_e32 v160, s10, v121
	v_ashrrev_i32_e32 v131, 31, v130
	v_lshlrev_b64 v[132:133], 12, v[132:133]
	v_ashrrev_i32_e32 v137, 31, v136
	v_ashrrev_i32_e32 v135, 31, v134
	v_ashrrev_i32_e32 v141, 31, v140
	v_ashrrev_i32_e32 v139, 31, v138
	v_ashrrev_i32_e32 v145, 31, v144
	v_ashrrev_i32_e32 v143, 31, v142
	v_ashrrev_i32_e32 v149, 31, v148
	v_ashrrev_i32_e32 v147, 31, v146
	v_ashrrev_i32_e32 v153, 31, v152
	v_ashrrev_i32_e32 v151, 31, v150
	v_ashrrev_i32_e32 v157, 31, v156
	v_ashrrev_i32_e32 v155, 31, v154
	v_ashrrev_i32_e32 v161, 31, v160
	v_ashrrev_i32_e32 v159, 31, v158
	v_lshlrev_b64 v[130:131], 12, v[130:131]
	v_lshl_add_u64 v[132:133], v[50:51], 0, v[132:133]
	v_lshlrev_b64 v[134:135], 12, v[134:135]
	v_lshlrev_b64 v[136:137], 12, v[136:137]
	v_lshlrev_b64 v[138:139], 12, v[138:139]
	v_lshlrev_b64 v[140:141], 12, v[140:141]
	v_lshlrev_b64 v[142:143], 12, v[142:143]
	v_lshlrev_b64 v[144:145], 12, v[144:145]
	v_lshlrev_b64 v[146:147], 12, v[146:147]
	v_lshlrev_b64 v[148:149], 12, v[148:149]
	v_lshlrev_b64 v[150:151], 12, v[150:151]
	v_lshlrev_b64 v[152:153], 12, v[152:153]
	v_lshlrev_b64 v[154:155], 12, v[154:155]
	v_lshlrev_b64 v[156:157], 12, v[156:157]
	v_lshlrev_b64 v[158:159], 12, v[158:159]
	v_lshlrev_b64 v[160:161], 12, v[160:161]
	v_lshl_add_u64 v[130:131], v[50:51], 0, v[130:131]
	v_lshl_add_u64 v[136:137], v[50:51], 0, v[136:137]
	v_lshl_add_u64 v[134:135], v[50:51], 0, v[134:135]
	v_lshl_add_u64 v[140:141], v[50:51], 0, v[140:141]
	v_lshl_add_u64 v[138:139], v[50:51], 0, v[138:139]
	v_lshl_add_u64 v[144:145], v[50:51], 0, v[144:145]
	v_lshl_add_u64 v[142:143], v[50:51], 0, v[142:143]
	v_lshl_add_u64 v[148:149], v[50:51], 0, v[148:149]
	v_lshl_add_u64 v[146:147], v[50:51], 0, v[146:147]
	v_lshl_add_u64 v[152:153], v[50:51], 0, v[152:153]
	v_lshl_add_u64 v[150:151], v[50:51], 0, v[150:151]
	v_lshl_add_u64 v[156:157], v[50:51], 0, v[156:157]
	v_lshl_add_u64 v[154:155], v[50:51], 0, v[154:155]
	v_lshl_add_u64 v[160:161], v[50:51], 0, v[160:161]
	v_lshl_add_u64 v[158:159], v[50:51], 0, v[158:159]
	global_load_dword v122, v[132:133], off
	global_load_dword v123, v[130:131], off
	global_load_dword v124, v[136:137], off
	global_load_dword v125, v[134:135], off
	global_load_dword v126, v[140:141], off
	global_load_dword v127, v[138:139], off
	global_load_dword v162, v[144:145], off
	global_load_dword v163, v[142:143], off
	global_load_dword v164, v[148:149], off
	global_load_dword v165, v[146:147], off
	global_load_dword v166, v[152:153], off
	global_load_dword v167, v[150:151], off
	global_load_dword v168, v[156:157], off
	global_load_dword v169, v[154:155], off
	global_load_dword v170, v[160:161], off
	global_load_dword v171, v[158:159], off
	v_mad_u64_u32 v[52:53], s[14:15], v9, s78, v[4:5]
	v_mad_u64_u32 v[54:55], s[14:15], v7, s78, v[4:5]
	v_mad_u64_u32 v[56:57], s[14:15], v13, s78, v[4:5]
	v_mad_u64_u32 v[58:59], s[14:15], v11, s78, v[4:5]
	v_mad_u64_u32 v[60:61], s[14:15], v19, s78, v[4:5]
	v_mad_u64_u32 v[62:63], s[14:15], v15, s78, v[4:5]
	v_mad_u64_u32 v[64:65], s[14:15], v43, s78, v[4:5]
	v_mad_u64_u32 v[66:67], s[14:15], v41, s78, v[4:5]
	v_mad_u64_u32 v[68:69], s[14:15], v47, s78, v[4:5]
	v_mad_u64_u32 v[70:71], s[14:15], v45, s78, v[4:5]
	v_mad_u64_u32 v[72:73], s[14:15], v82, s78, v[4:5]
	v_mad_u64_u32 v[74:75], s[14:15], v49, s78, v[4:5]
	v_mad_u64_u32 v[76:77], s[14:15], v87, s78, v[4:5]
	v_mad_u64_u32 v[78:79], s[14:15], v86, s78, v[4:5]
	v_mad_u64_u32 v[80:81], s[14:15], v89, s78, v[4:5]
	v_mad_u64_u32 v[84:85], s[14:15], v88, s78, v[4:5]
	s_waitcnt vmcnt(31)
	ds_write_b32 v52, v90
	s_waitcnt vmcnt(30)
	ds_write_b32 v54, v91
	s_waitcnt vmcnt(29)
	ds_write_b32 v56, v92
	s_waitcnt vmcnt(28)
	ds_write_b32 v58, v93
	s_waitcnt vmcnt(27)
	ds_write_b32 v60, v94
	s_waitcnt vmcnt(26)
	ds_write_b32 v62, v95
	s_waitcnt vmcnt(25)
	ds_write_b32 v64, v96
	s_waitcnt vmcnt(24)
	ds_write_b32 v66, v97
	s_waitcnt vmcnt(23)
	ds_write_b32 v68, v98
	s_waitcnt vmcnt(22)
	ds_write_b32 v70, v99
	s_waitcnt vmcnt(21)
	ds_write_b32 v72, v100
	s_waitcnt vmcnt(20)
	ds_write_b32 v74, v101
	s_waitcnt vmcnt(19)
	ds_write_b32 v76, v102
	s_waitcnt vmcnt(18)
	ds_write_b32 v78, v103
	s_waitcnt vmcnt(17)
	ds_write_b32 v80, v104
	s_waitcnt vmcnt(16)
	ds_write_b32 v84, v105
	v_mad_u64_u32 v[130:131], s[14:15], v107, s78, v[4:5]
	v_mad_u64_u32 v[132:133], s[14:15], v106, s78, v[4:5]
	v_mad_u64_u32 v[134:135], s[14:15], v109, s78, v[4:5]
	v_mad_u64_u32 v[136:137], s[14:15], v108, s78, v[4:5]
	v_mad_u64_u32 v[138:139], s[14:15], v111, s78, v[4:5]
	v_mad_u64_u32 v[140:141], s[14:15], v110, s78, v[4:5]
	v_mad_u64_u32 v[142:143], s[14:15], v113, s78, v[4:5]
	v_mad_u64_u32 v[144:145], s[14:15], v112, s78, v[4:5]
	v_mad_u64_u32 v[146:147], s[14:15], v115, s78, v[4:5]
	v_mad_u64_u32 v[148:149], s[14:15], v114, s78, v[4:5]
	v_mad_u64_u32 v[150:151], s[14:15], v117, s78, v[4:5]
	v_mad_u64_u32 v[152:153], s[14:15], v116, s78, v[4:5]
	v_mad_u64_u32 v[154:155], s[14:15], v119, s78, v[4:5]
	v_mad_u64_u32 v[156:157], s[14:15], v118, s78, v[4:5]
	v_mad_u64_u32 v[158:159], s[14:15], v121, s78, v[4:5]
	v_mad_u64_u32 v[160:161], s[14:15], v120, s78, v[4:5]
	s_waitcnt vmcnt(15)
	ds_write_b32 v130, v122
	s_waitcnt vmcnt(14)
	ds_write_b32 v132, v123
	s_waitcnt vmcnt(13)
	ds_write_b32 v134, v124
	s_waitcnt vmcnt(12)
	ds_write_b32 v136, v125
	s_waitcnt vmcnt(11)
	ds_write_b32 v138, v126
	s_waitcnt vmcnt(10)
	ds_write_b32 v140, v127
	s_waitcnt vmcnt(9)
	ds_write_b32 v142, v162
	s_waitcnt vmcnt(8)
	ds_write_b32 v144, v163
	s_waitcnt vmcnt(7)
	ds_write_b32 v146, v164
	s_waitcnt vmcnt(6)
	ds_write_b32 v148, v165
	s_waitcnt vmcnt(5)
	ds_write_b32 v150, v166
	s_waitcnt vmcnt(4)
	ds_write_b32 v152, v167
	s_waitcnt vmcnt(3)
	ds_write_b32 v154, v168
	s_waitcnt vmcnt(2)
	ds_write_b32 v156, v169
	s_waitcnt vmcnt(1)
	ds_write_b32 v158, v170
	s_waitcnt vmcnt(0)
	ds_write_b32 v160, v171
	s_add_i32 s5, s5, 16
	s_add_i32 s1, s1, 16
	s_add_i32 s11, s11, -16
	s_add_i32 s11, s11, -16
	s_cmp_lg_u32 s11, 0
	s_waitcnt lgkmcnt(0)
	ds_read2_b32 v[54:55], v5 offset1:8
	ds_read2_b32 v[58:59], v5 offset0:33 offset1:41
	ds_read2_b32 v[60:61], v5 offset0:66 offset1:74
	ds_read2_b32 v[62:63], v5 offset0:99 offset1:107
	ds_read2_b32 v[64:65], v5 offset0:132 offset1:140
	s_waitcnt lgkmcnt(4)
	s_waitcnt lgkmcnt(3)
	v_cvt_pk_bf16_f32 v9, v54, v58
	ds_read2_b32 v[66:67], v5 offset0:165 offset1:173
	v_mov_b32_e32 v50, v9
	s_waitcnt lgkmcnt(3)
	s_waitcnt lgkmcnt(2)
	ds_read2_b32 v[68:69], v5 offset0:198 offset1:206
	v_cvt_pk_bf16_f32 v9, v60, v62
	ds_read2_b32 v[70:71], v5 offset0:231 offset1:239
	v_mov_b32_e32 v51, v9
	s_waitcnt lgkmcnt(3)
	s_lshl_b64 s[4:5], s[12:13], 11
	s_waitcnt lgkmcnt(2)
	s_add_u32 s1, s64, s4
	v_cvt_pk_bf16_f32 v9, v64, v66
	s_addc_u32 s12, s65, s5
	s_ashr_i32 s11, s10, 31
	v_mov_b32_e32 v52, v9
	s_waitcnt lgkmcnt(1)
	s_lshl_b64 s[4:5], s[10:11], 1
	s_waitcnt lgkmcnt(0)
	s_add_u32 s4, s1, s4
	v_cvt_pk_bf16_f32 v9, v68, v70
	s_addc_u32 s5, s12, s5
	v_lshlrev_b32_e32 v128, 1, v6
	v_mov_b32_e32 v53, v9
	v_lshl_add_u64 v[56:57], s[4:5], 0, v[128:129]
	v_lshlrev_b32_e32 v128, 1, v8
	v_lshl_add_u64 v[72:73], v[56:57], 0, v[128:129]
	v_cvt_pk_bf16_f32 v9, v55, v59
	global_store_dwordx4 v[72:73], v[50:53], off
	v_lshlrev_b32_e32 v128, 1, v10
	ds_read2_b32 v[54:55], v5 offset0:16 offset1:24
	v_mov_b32_e32 v50, v9
	v_cvt_pk_bf16_f32 v9, v61, v63
	v_mov_b32_e32 v51, v9
	v_cvt_pk_bf16_f32 v9, v65, v67
	v_mov_b32_e32 v52, v9
	v_cvt_pk_bf16_f32 v9, v69, v71
	v_mov_b32_e32 v53, v9
	v_lshl_add_u64 v[58:59], v[56:57], 0, v[128:129]
	global_store_dwordx4 v[58:59], v[50:53], off
	ds_read2_b32 v[58:59], v5 offset0:49 offset1:57
	ds_read2_b32 v[60:61], v5 offset0:82 offset1:90
	ds_read2_b32 v[62:63], v5 offset0:115 offset1:123
	s_waitcnt lgkmcnt(3)
	s_waitcnt lgkmcnt(2)
	ds_read2_b32 v[64:65], v5 offset0:148 offset1:156
	v_cvt_pk_bf16_f32 v9, v54, v58
	ds_read2_b32 v[66:67], v5 offset0:181 offset1:189
	v_mov_b32_e32 v50, v9
	s_waitcnt lgkmcnt(3)
	s_waitcnt lgkmcnt(2)
	ds_read2_b32 v[68:69], v5 offset0:214 offset1:222
	v_cvt_pk_bf16_f32 v9, v60, v62
	ds_read2_b32 v[70:71], v5 offset0:247 offset1:255
	v_mov_b32_e32 v51, v9
	s_waitcnt lgkmcnt(3)
	s_waitcnt lgkmcnt(2)
	v_cvt_pk_bf16_f32 v9, v64, v66
	v_mov_b32_e32 v52, v9
	s_waitcnt lgkmcnt(1)
	s_waitcnt lgkmcnt(0)
	v_cvt_pk_bf16_f32 v9, v68, v70
	v_mov_b32_e32 v53, v9
	v_lshlrev_b32_e32 v128, 1, v12
	v_lshl_add_u64 v[72:73], v[56:57], 0, v[128:129]
	v_cvt_pk_bf16_f32 v9, v55, v59
	global_store_dwordx4 v[72:73], v[50:53], off
	v_lshlrev_b32_e32 v128, 1, v14
	v_lshl_add_u64 v[54:55], v[56:57], 0, v[128:129]
	v_mov_b32_e32 v50, v9
	v_cvt_pk_bf16_f32 v9, v61, v63
	v_mov_b32_e32 v51, v9
	v_cvt_pk_bf16_f32 v9, v65, v67
	v_mov_b32_e32 v52, v9
	v_cvt_pk_bf16_f32 v9, v69, v71
	v_mov_b32_e32 v53, v9
	global_store_dwordx4 v[54:55], v[50:53], off
	s_waitcnt lgkmcnt(0)
	s_mov_b64 s[10:11], -1

.LBB0_712:
	s_lshl_b32 s23, s5, 1
	s_lshl_b32 s24, s13, 1
	v_or_b32_e32 v7, s23, v1
	v_or_b32_e32 v9, s24, v0
	s_add_i32 s25, s23, 4
	s_add_i32 s26, s24, 4
	s_add_i32 s27, s23, 8
	s_add_i32 s30, s24, 8
	s_add_i32 s36, s23, 12
	s_add_i32 s37, s24, 12
	s_add_i32 s40, s23, 16
	s_add_i32 s41, s24, 16
	s_add_i32 s42, s23, 20
	s_add_i32 s43, s24, 20
	s_add_i32 s52, s23, 24
	s_add_i32 s53, s24, 24
	s_add_i32 s23, s23, 28
	s_add_i32 s24, s24, 28
	v_add_u32_e32 v11, s4, v7
	v_add_u32_e32 v13, s12, v9
	v_or_b32_e32 v15, s25, v1
	v_or_b32_e32 v19, s26, v0
	v_or_b32_e32 v41, s27, v1
	v_or_b32_e32 v43, s30, v0
	v_or_b32_e32 v45, s36, v1
	v_or_b32_e32 v47, s37, v0
	v_or_b32_e32 v49, s40, v1
	v_or_b32_e32 v82, s41, v0
	v_or_b32_e32 v86, s42, v1
	v_or_b32_e32 v87, s43, v0
	v_or_b32_e32 v88, s52, v1
	v_or_b32_e32 v89, s53, v0
	v_or_b32_e32 v90, s23, v1
	v_or_b32_e32 v91, s24, v0
	v_mad_i64_i32 v[52:53], s[24:25], v13, s55, v[50:51]
	v_mad_i64_i32 v[54:55], s[24:25], v11, s55, v[50:51]
	v_add_u32_e32 v11, s4, v15
	v_add_u32_e32 v13, s12, v19
	v_add_u32_e32 v62, s4, v41
	v_add_u32_e32 v60, s12, v43
	v_add_u32_e32 v66, s4, v45
	v_add_u32_e32 v64, s12, v47
	v_add_u32_e32 v70, s4, v49
	v_add_u32_e32 v68, s12, v82
	v_add_u32_e32 v74, s4, v86
	v_add_u32_e32 v72, s12, v87
	v_add_u32_e32 v78, s4, v88
	v_add_u32_e32 v76, s12, v89
	v_add_u32_e32 v84, s4, v90
	v_add_u32_e32 v80, s12, v91
	v_mad_i64_i32 v[56:57], s[24:25], v13, s55, v[50:51]
	v_mad_i64_i32 v[58:59], s[24:25], v11, s55, v[50:51]
	v_mad_i64_i32 v[60:61], s[24:25], v60, s55, v[50:51]
	v_mad_i64_i32 v[62:63], s[24:25], v62, s55, v[50:51]
	v_mad_i64_i32 v[64:65], s[24:25], v64, s55, v[50:51]
	v_mad_i64_i32 v[66:67], s[24:25], v66, s55, v[50:51]
	v_mad_i64_i32 v[68:69], s[24:25], v68, s55, v[50:51]
	v_mad_i64_i32 v[70:71], s[24:25], v70, s55, v[50:51]
	v_mad_i64_i32 v[72:73], s[24:25], v72, s55, v[50:51]
	v_mad_i64_i32 v[74:75], s[24:25], v74, s55, v[50:51]
	v_mad_i64_i32 v[76:77], s[24:25], v76, s55, v[50:51]
	v_mad_i64_i32 v[78:79], s[24:25], v78, s55, v[50:51]
	v_mad_i64_i32 v[80:81], s[24:25], v80, s55, v[50:51]
	v_mad_i64_i32 v[84:85], s[24:25], v84, s55, v[50:51]
	global_load_dword v11, v[52:53], off
	global_load_dword v13, v[54:55], off
	global_load_dword v92, v[56:57], off
	global_load_dword v93, v[58:59], off
	global_load_dword v94, v[60:61], off
	global_load_dword v95, v[62:63], off
	global_load_dword v96, v[64:65], off
	global_load_dword v97, v[66:67], off
	global_load_dword v98, v[68:69], off
	global_load_dword v99, v[70:71], off
	global_load_dword v100, v[72:73], off
	global_load_dword v101, v[74:75], off
	global_load_dword v102, v[76:77], off
	global_load_dword v103, v[78:79], off
	global_load_dword v104, v[80:81], off
	global_load_dword v105, v[84:85], off
	s_add_i32 s13, s13, 16
	s_add_i32 s5, s5, 16
	s_lshl_b32 s23, s5, 1
	s_lshl_b32 s24, s13, 1
	v_or_b32_e32 v106, s23, v1
	v_or_b32_e32 v107, s24, v0
	s_add_i32 s25, s23, 4
	s_add_i32 s26, s24, 4
	s_add_i32 s27, s23, 8
	s_add_i32 s30, s24, 8
	s_add_i32 s36, s23, 12
	s_add_i32 s37, s24, 12
	s_add_i32 s40, s23, 16
	s_add_i32 s41, s24, 16
	s_add_i32 s42, s23, 20
	s_add_i32 s43, s24, 20
	s_add_i32 s52, s23, 24
	s_add_i32 s53, s24, 24
	s_add_i32 s23, s23, 28
	s_add_i32 s24, s24, 28
	v_add_u32_e32 v108, s4, v106
	v_add_u32_e32 v109, s12, v107
	v_or_b32_e32 v110, s25, v1
	v_or_b32_e32 v111, s26, v0
	v_or_b32_e32 v112, s27, v1
	v_or_b32_e32 v113, s30, v0
	v_or_b32_e32 v114, s36, v1
	v_or_b32_e32 v115, s37, v0
	v_or_b32_e32 v116, s40, v1
	v_or_b32_e32 v117, s41, v0
	v_or_b32_e32 v118, s42, v1
	v_or_b32_e32 v119, s43, v0
	v_or_b32_e32 v120, s52, v1
	v_or_b32_e32 v121, s53, v0
	v_or_b32_e32 v122, s23, v1
	v_or_b32_e32 v123, s24, v0
	v_mad_i64_i32 v[130:131], s[24:25], v109, s55, v[50:51]
	v_mad_i64_i32 v[132:133], s[24:25], v108, s55, v[50:51]
	v_add_u32_e32 v108, s4, v110
	v_add_u32_e32 v109, s12, v111
	v_add_u32_e32 v140, s4, v112
	v_add_u32_e32 v138, s12, v113
	v_add_u32_e32 v144, s4, v114
	v_add_u32_e32 v142, s12, v115
	v_add_u32_e32 v148, s4, v116
	v_add_u32_e32 v146, s12, v117
	v_add_u32_e32 v152, s4, v118
	v_add_u32_e32 v150, s12, v119
	v_add_u32_e32 v156, s4, v120
	v_add_u32_e32 v154, s12, v121
	v_add_u32_e32 v160, s4, v122
	v_add_u32_e32 v158, s12, v123
	v_mad_i64_i32 v[134:135], s[24:25], v109, s55, v[50:51]
	v_mad_i64_i32 v[136:137], s[24:25], v108, s55, v[50:51]
	v_mad_i64_i32 v[138:139], s[24:25], v138, s55, v[50:51]
	v_mad_i64_i32 v[140:141], s[24:25], v140, s55, v[50:51]
	v_mad_i64_i32 v[142:143], s[24:25], v142, s55, v[50:51]
	v_mad_i64_i32 v[144:145], s[24:25], v144, s55, v[50:51]
	v_mad_i64_i32 v[146:147], s[24:25], v146, s55, v[50:51]
	v_mad_i64_i32 v[148:149], s[24:25], v148, s55, v[50:51]
	v_mad_i64_i32 v[150:151], s[24:25], v150, s55, v[50:51]
	v_mad_i64_i32 v[152:153], s[24:25], v152, s55, v[50:51]
	v_mad_i64_i32 v[154:155], s[24:25], v154, s55, v[50:51]
	v_mad_i64_i32 v[156:157], s[24:25], v156, s55, v[50:51]
	v_mad_i64_i32 v[158:159], s[24:25], v158, s55, v[50:51]
	v_mad_i64_i32 v[160:161], s[24:25], v160, s55, v[50:51]
	global_load_dword v108, v[130:131], off
	global_load_dword v109, v[132:133], off
	global_load_dword v124, v[134:135], off
	global_load_dword v125, v[136:137], off
	global_load_dword v126, v[138:139], off
	global_load_dword v127, v[140:141], off
	global_load_dword v162, v[142:143], off
	global_load_dword v163, v[144:145], off
	global_load_dword v164, v[146:147], off
	global_load_dword v165, v[148:149], off
	global_load_dword v166, v[150:151], off
	global_load_dword v167, v[152:153], off
	global_load_dword v168, v[154:155], off
	global_load_dword v169, v[156:157], off
	global_load_dword v170, v[158:159], off
	global_load_dword v171, v[160:161], off
	v_mad_u64_u32 v[52:53], s[24:25], v9, s78, v[4:5]
	v_mad_u64_u32 v[54:55], s[24:25], v7, s78, v[4:5]
	v_mad_u64_u32 v[56:57], s[24:25], v19, s78, v[4:5]
	v_mad_u64_u32 v[58:59], s[24:25], v15, s78, v[4:5]
	v_mad_u64_u32 v[60:61], s[24:25], v43, s78, v[4:5]
	v_mad_u64_u32 v[62:63], s[24:25], v41, s78, v[4:5]
	v_mad_u64_u32 v[64:65], s[24:25], v47, s78, v[4:5]
	v_mad_u64_u32 v[66:67], s[24:25], v45, s78, v[4:5]
	v_mad_u64_u32 v[68:69], s[24:25], v82, s78, v[4:5]
	v_mad_u64_u32 v[70:71], s[24:25], v49, s78, v[4:5]
	v_mad_u64_u32 v[72:73], s[24:25], v87, s78, v[4:5]
	v_mad_u64_u32 v[74:75], s[24:25], v86, s78, v[4:5]
	v_mad_u64_u32 v[76:77], s[24:25], v89, s78, v[4:5]
	v_mad_u64_u32 v[78:79], s[24:25], v88, s78, v[4:5]
	v_mad_u64_u32 v[80:81], s[24:25], v91, s78, v[4:5]
	v_mad_u64_u32 v[84:85], s[24:25], v90, s78, v[4:5]
	s_waitcnt vmcnt(31)
	ds_write_b32 v52, v11
	s_waitcnt vmcnt(30)
	ds_write_b32 v54, v13
	s_waitcnt vmcnt(29)
	ds_write_b32 v56, v92
	s_waitcnt vmcnt(28)
	ds_write_b32 v58, v93
	s_waitcnt vmcnt(27)
	ds_write_b32 v60, v94
	s_waitcnt vmcnt(26)
	ds_write_b32 v62, v95
	s_waitcnt vmcnt(25)
	ds_write_b32 v64, v96
	s_waitcnt vmcnt(24)
	ds_write_b32 v66, v97
	s_waitcnt vmcnt(23)
	ds_write_b32 v68, v98
	s_waitcnt vmcnt(22)
	ds_write_b32 v70, v99
	s_waitcnt vmcnt(21)
	ds_write_b32 v72, v100
	s_waitcnt vmcnt(20)
	ds_write_b32 v74, v101
	s_waitcnt vmcnt(19)
	ds_write_b32 v76, v102
	s_waitcnt vmcnt(18)
	ds_write_b32 v78, v103
	s_waitcnt vmcnt(17)
	ds_write_b32 v80, v104
	s_waitcnt vmcnt(16)
	ds_write_b32 v84, v105
	v_mad_u64_u32 v[130:131], s[24:25], v107, s78, v[4:5]
	v_mad_u64_u32 v[132:133], s[24:25], v106, s78, v[4:5]
	v_mad_u64_u32 v[134:135], s[24:25], v111, s78, v[4:5]
	v_mad_u64_u32 v[136:137], s[24:25], v110, s78, v[4:5]
	v_mad_u64_u32 v[138:139], s[24:25], v113, s78, v[4:5]
	v_mad_u64_u32 v[140:141], s[24:25], v112, s78, v[4:5]
	v_mad_u64_u32 v[142:143], s[24:25], v115, s78, v[4:5]
	v_mad_u64_u32 v[144:145], s[24:25], v114, s78, v[4:5]
	v_mad_u64_u32 v[146:147], s[24:25], v117, s78, v[4:5]
	v_mad_u64_u32 v[148:149], s[24:25], v116, s78, v[4:5]
	v_mad_u64_u32 v[150:151], s[24:25], v119, s78, v[4:5]
	v_mad_u64_u32 v[152:153], s[24:25], v118, s78, v[4:5]
	v_mad_u64_u32 v[154:155], s[24:25], v121, s78, v[4:5]
	v_mad_u64_u32 v[156:157], s[24:25], v120, s78, v[4:5]
	v_mad_u64_u32 v[158:159], s[24:25], v123, s78, v[4:5]
	v_mad_u64_u32 v[160:161], s[24:25], v122, s78, v[4:5]
	s_waitcnt vmcnt(15)
	ds_write_b32 v130, v108
	s_waitcnt vmcnt(14)
	ds_write_b32 v132, v109
	s_waitcnt vmcnt(13)
	ds_write_b32 v134, v124
	s_waitcnt vmcnt(12)
	ds_write_b32 v136, v125
	s_waitcnt vmcnt(11)
	ds_write_b32 v138, v126
	s_waitcnt vmcnt(10)
	ds_write_b32 v140, v127
	s_waitcnt vmcnt(9)
	ds_write_b32 v142, v162
	s_waitcnt vmcnt(8)
	ds_write_b32 v144, v163
	s_waitcnt vmcnt(7)
	ds_write_b32 v146, v164
	s_waitcnt vmcnt(6)
	ds_write_b32 v148, v165
	s_waitcnt vmcnt(5)
	ds_write_b32 v150, v166
	s_waitcnt vmcnt(4)
	ds_write_b32 v152, v167
	s_waitcnt vmcnt(3)
	ds_write_b32 v154, v168
	s_waitcnt vmcnt(2)
	ds_write_b32 v156, v169
	s_waitcnt vmcnt(1)
	ds_write_b32 v158, v170
	s_waitcnt vmcnt(0)
	ds_write_b32 v160, v171
	s_add_i32 s13, s13, 16
	s_add_i32 s5, s5, 16
	s_add_i32 s22, s22, -16
	s_add_i32 s22, s22, -16
	s_cmp_lg_u32 s22, 0
	s_waitcnt lgkmcnt(0)
	ds_read2_b32 v[54:55], v5 offset1:8
	ds_read2_b32 v[58:59], v5 offset0:33 offset1:41
	ds_read2_b32 v[60:61], v5 offset0:66 offset1:74
	ds_read2_b32 v[62:63], v5 offset0:99 offset1:107
	ds_read2_b32 v[64:65], v5 offset0:132 offset1:140
	s_waitcnt lgkmcnt(4)
	s_waitcnt lgkmcnt(3)
	v_cvt_pk_bf16_f32 v9, v54, v58
	ds_read2_b32 v[66:67], v5 offset0:165 offset1:173
	v_mov_b32_e32 v50, v9
	s_waitcnt lgkmcnt(3)
	s_add_i32 s4, s14, 0xfffff800
	s_waitcnt lgkmcnt(2)
	ds_read2_b32 v[68:69], v5 offset0:198 offset1:206
	s_cmp_lt_i32 s1, 64
	v_cvt_pk_bf16_f32 v9, v60, v62
	ds_read2_b32 v[70:71], v5 offset0:231 offset1:239
	s_cselect_b32 s5, s15, 0
	s_cselect_b32 s4, s14, s4
	v_mov_b32_e32 v51, v9
	s_waitcnt lgkmcnt(3)
	s_cselect_b32 s1, s35, s45
	s_cselect_b32 s13, s38, s46
	s_lshl_b64 s[4:5], s[4:5], 11
	s_waitcnt lgkmcnt(2)
	s_add_u32 s1, s1, s4
	v_cvt_pk_bf16_f32 v9, v64, v66
	s_addc_u32 s14, s13, s5
	s_ashr_i32 s13, s12, 31
	v_mov_b32_e32 v52, v9
	s_waitcnt lgkmcnt(1)
	s_lshl_b64 s[4:5], s[12:13], 1
	s_waitcnt lgkmcnt(0)
	s_add_u32 s4, s1, s4
	v_cvt_pk_bf16_f32 v9, v68, v70
	s_addc_u32 s5, s14, s5
	v_lshlrev_b32_e32 v128, 1, v6
	v_mov_b32_e32 v53, v9
	v_lshl_add_u64 v[56:57], s[4:5], 0, v[128:129]
	v_lshlrev_b32_e32 v128, 1, v8
	v_lshl_add_u64 v[72:73], v[56:57], 0, v[128:129]
	v_cvt_pk_bf16_f32 v9, v55, v59
	global_store_dwordx4 v[72:73], v[50:53], off
	v_lshlrev_b32_e32 v128, 1, v10
	ds_read2_b32 v[54:55], v5 offset0:16 offset1:24
	v_mov_b32_e32 v50, v9
	v_cvt_pk_bf16_f32 v9, v61, v63
	v_mov_b32_e32 v51, v9
	v_cvt_pk_bf16_f32 v9, v65, v67
	v_mov_b32_e32 v52, v9
	v_cvt_pk_bf16_f32 v9, v69, v71
	v_mov_b32_e32 v53, v9
	v_lshl_add_u64 v[58:59], v[56:57], 0, v[128:129]
	global_store_dwordx4 v[58:59], v[50:53], off
	ds_read2_b32 v[58:59], v5 offset0:49 offset1:57
	ds_read2_b32 v[60:61], v5 offset0:82 offset1:90
	ds_read2_b32 v[62:63], v5 offset0:115 offset1:123
	s_waitcnt lgkmcnt(3)
	s_waitcnt lgkmcnt(2)
	ds_read2_b32 v[64:65], v5 offset0:148 offset1:156
	v_cvt_pk_bf16_f32 v9, v54, v58
	ds_read2_b32 v[66:67], v5 offset0:181 offset1:189
	v_mov_b32_e32 v50, v9
	s_waitcnt lgkmcnt(3)
	s_waitcnt lgkmcnt(2)
	ds_read2_b32 v[68:69], v5 offset0:214 offset1:222
	v_cvt_pk_bf16_f32 v9, v60, v62
	ds_read2_b32 v[70:71], v5 offset0:247 offset1:255
	v_mov_b32_e32 v51, v9
	s_waitcnt lgkmcnt(3)
	s_waitcnt lgkmcnt(2)
	v_cvt_pk_bf16_f32 v9, v64, v66
	v_mov_b32_e32 v52, v9
	s_waitcnt lgkmcnt(1)
	s_waitcnt lgkmcnt(0)
	v_cvt_pk_bf16_f32 v9, v68, v70
	v_mov_b32_e32 v53, v9
	v_lshlrev_b32_e32 v128, 1, v12
	v_lshl_add_u64 v[72:73], v[56:57], 0, v[128:129]
	v_cvt_pk_bf16_f32 v9, v55, v59
	global_store_dwordx4 v[72:73], v[50:53], off
	v_lshlrev_b32_e32 v128, 1, v14
	v_lshl_add_u64 v[54:55], v[56:57], 0, v[128:129]
	v_mov_b32_e32 v50, v9
	v_cvt_pk_bf16_f32 v9, v61, v63
	v_mov_b32_e32 v51, v9
	v_cvt_pk_bf16_f32 v9, v65, v67
	v_mov_b32_e32 v52, v9
	v_cvt_pk_bf16_f32 v9, v69, v71
	v_mov_b32_e32 v53, v9
	global_store_dwordx4 v[54:55], v[50:53], off
	s_waitcnt lgkmcnt(0)
	s_mov_b32 s1, s0
	s_andn2_b64 vcc, exec, s[10:11]
	s_mov_b64 s[10:11], -1
	s_cbranch_vccnz .LBB0_718

.LBB0_716:
	s_lshl_b32 s14, s1, 1
	s_lshl_b32 s15, s5, 1
	v_or_b32_e32 v7, s14, v1
	v_or_b32_e32 v9, s15, v0
	s_add_i32 s22, s14, 4
	s_add_i32 s23, s15, 4
	s_add_i32 s24, s14, 8
	s_add_i32 s25, s15, 8
	s_add_i32 s26, s14, 12
	s_add_i32 s27, s15, 12
	s_add_i32 s30, s14, 16
	s_add_i32 s36, s15, 16
	s_add_i32 s37, s14, 20
	s_add_i32 s40, s15, 20
	s_add_i32 s41, s14, 24
	s_add_i32 s42, s15, 24
	s_add_i32 s14, s14, 28
	s_add_i32 s15, s15, 28
	v_add_u32_e32 v54, s10, v9
	v_or_b32_e32 v11, s22, v1
	v_or_b32_e32 v13, s23, v0
	v_or_b32_e32 v15, s24, v1
	v_or_b32_e32 v19, s25, v0
	v_or_b32_e32 v41, s26, v1
	v_or_b32_e32 v43, s27, v0
	v_or_b32_e32 v45, s30, v1
	v_or_b32_e32 v47, s36, v0
	v_or_b32_e32 v49, s37, v1
	v_or_b32_e32 v82, s40, v0
	v_or_b32_e32 v86, s41, v1
	v_or_b32_e32 v87, s42, v0
	v_or_b32_e32 v88, s14, v1
	v_or_b32_e32 v89, s15, v0
	v_add_u32_e32 v52, s4, v7
	v_ashrrev_i32_e32 v55, 31, v54
	v_add_u32_e32 v56, s4, v11
	v_add_u32_e32 v58, s10, v13
	v_add_u32_e32 v60, s4, v15
	v_add_u32_e32 v62, s10, v19
	v_add_u32_e32 v64, s4, v41
	v_add_u32_e32 v66, s10, v43
	v_add_u32_e32 v68, s4, v45
	v_add_u32_e32 v70, s10, v47
	v_add_u32_e32 v72, s4, v49
	v_add_u32_e32 v74, s10, v82
	v_add_u32_e32 v76, s4, v86
	v_add_u32_e32 v78, s10, v87
	v_add_u32_e32 v80, s4, v88
	v_add_u32_e32 v84, s10, v89
	v_ashrrev_i32_e32 v53, 31, v52
	v_lshlrev_b64 v[54:55], 12, v[54:55]
	v_ashrrev_i32_e32 v59, 31, v58
	v_ashrrev_i32_e32 v57, 31, v56
	v_ashrrev_i32_e32 v63, 31, v62
	v_ashrrev_i32_e32 v61, 31, v60
	v_ashrrev_i32_e32 v67, 31, v66
	v_ashrrev_i32_e32 v65, 31, v64
	v_ashrrev_i32_e32 v71, 31, v70
	v_ashrrev_i32_e32 v69, 31, v68
	v_ashrrev_i32_e32 v75, 31, v74
	v_ashrrev_i32_e32 v73, 31, v72
	v_ashrrev_i32_e32 v79, 31, v78
	v_ashrrev_i32_e32 v77, 31, v76
	v_ashrrev_i32_e32 v85, 31, v84
	v_ashrrev_i32_e32 v81, 31, v80
	v_lshlrev_b64 v[52:53], 12, v[52:53]
	v_lshl_add_u64 v[54:55], v[50:51], 0, v[54:55]
	v_lshlrev_b64 v[56:57], 12, v[56:57]
	v_lshlrev_b64 v[58:59], 12, v[58:59]
	v_lshlrev_b64 v[60:61], 12, v[60:61]
	v_lshlrev_b64 v[62:63], 12, v[62:63]
	v_lshlrev_b64 v[64:65], 12, v[64:65]
	v_lshlrev_b64 v[66:67], 12, v[66:67]
	v_lshlrev_b64 v[68:69], 12, v[68:69]
	v_lshlrev_b64 v[70:71], 12, v[70:71]
	v_lshlrev_b64 v[72:73], 12, v[72:73]
	v_lshlrev_b64 v[74:75], 12, v[74:75]
	v_lshlrev_b64 v[76:77], 12, v[76:77]
	v_lshlrev_b64 v[78:79], 12, v[78:79]
	v_lshlrev_b64 v[80:81], 12, v[80:81]
	v_lshlrev_b64 v[84:85], 12, v[84:85]
	v_lshl_add_u64 v[52:53], v[50:51], 0, v[52:53]
	v_lshl_add_u64 v[58:59], v[50:51], 0, v[58:59]
	v_lshl_add_u64 v[56:57], v[50:51], 0, v[56:57]
	v_lshl_add_u64 v[62:63], v[50:51], 0, v[62:63]
	v_lshl_add_u64 v[60:61], v[50:51], 0, v[60:61]
	v_lshl_add_u64 v[66:67], v[50:51], 0, v[66:67]
	v_lshl_add_u64 v[64:65], v[50:51], 0, v[64:65]
	v_lshl_add_u64 v[70:71], v[50:51], 0, v[70:71]
	v_lshl_add_u64 v[68:69], v[50:51], 0, v[68:69]
	v_lshl_add_u64 v[74:75], v[50:51], 0, v[74:75]
	v_lshl_add_u64 v[72:73], v[50:51], 0, v[72:73]
	v_lshl_add_u64 v[78:79], v[50:51], 0, v[78:79]
	v_lshl_add_u64 v[76:77], v[50:51], 0, v[76:77]
	v_lshl_add_u64 v[84:85], v[50:51], 0, v[84:85]
	v_lshl_add_u64 v[80:81], v[50:51], 0, v[80:81]
	global_load_dword v90, v[54:55], off
	global_load_dword v91, v[52:53], off
	global_load_dword v92, v[58:59], off
	global_load_dword v93, v[56:57], off
	global_load_dword v94, v[62:63], off
	global_load_dword v95, v[60:61], off
	global_load_dword v96, v[66:67], off
	global_load_dword v97, v[64:65], off
	global_load_dword v98, v[70:71], off
	global_load_dword v99, v[68:69], off
	global_load_dword v100, v[74:75], off
	global_load_dword v101, v[72:73], off
	global_load_dword v102, v[78:79], off
	global_load_dword v103, v[76:77], off
	global_load_dword v104, v[84:85], off
	global_load_dword v105, v[80:81], off
	s_add_i32 s5, s5, 16
	s_add_i32 s1, s1, 16
	s_lshl_b32 s14, s1, 1
	s_lshl_b32 s15, s5, 1
	v_or_b32_e32 v106, s14, v1
	v_or_b32_e32 v107, s15, v0
	s_add_i32 s22, s14, 4
	s_add_i32 s23, s15, 4
	s_add_i32 s24, s14, 8
	s_add_i32 s25, s15, 8
	s_add_i32 s26, s14, 12
	s_add_i32 s27, s15, 12
	s_add_i32 s30, s14, 16
	s_add_i32 s36, s15, 16
	s_add_i32 s37, s14, 20
	s_add_i32 s40, s15, 20
	s_add_i32 s41, s14, 24
	s_add_i32 s42, s15, 24
	s_add_i32 s14, s14, 28
	s_add_i32 s15, s15, 28
	v_add_u32_e32 v132, s10, v107
	v_or_b32_e32 v108, s22, v1
	v_or_b32_e32 v109, s23, v0
	v_or_b32_e32 v110, s24, v1
	v_or_b32_e32 v111, s25, v0
	v_or_b32_e32 v112, s26, v1
	v_or_b32_e32 v113, s27, v0
	v_or_b32_e32 v114, s30, v1
	v_or_b32_e32 v115, s36, v0
	v_or_b32_e32 v116, s37, v1
	v_or_b32_e32 v117, s40, v0
	v_or_b32_e32 v118, s41, v1
	v_or_b32_e32 v119, s42, v0
	v_or_b32_e32 v120, s14, v1
	v_or_b32_e32 v121, s15, v0
	v_add_u32_e32 v130, s4, v106
	v_ashrrev_i32_e32 v133, 31, v132
	v_add_u32_e32 v134, s4, v108
	v_add_u32_e32 v136, s10, v109
	v_add_u32_e32 v138, s4, v110
	v_add_u32_e32 v140, s10, v111
	v_add_u32_e32 v142, s4, v112
	v_add_u32_e32 v144, s10, v113
	v_add_u32_e32 v146, s4, v114
	v_add_u32_e32 v148, s10, v115
	v_add_u32_e32 v150, s4, v116
	v_add_u32_e32 v152, s10, v117
	v_add_u32_e32 v154, s4, v118
	v_add_u32_e32 v156, s10, v119
	v_add_u32_e32 v158, s4, v120
	v_add_u32_e32 v160, s10, v121
	v_ashrrev_i32_e32 v131, 31, v130
	v_lshlrev_b64 v[132:133], 12, v[132:133]
	v_ashrrev_i32_e32 v137, 31, v136
	v_ashrrev_i32_e32 v135, 31, v134
	v_ashrrev_i32_e32 v141, 31, v140
	v_ashrrev_i32_e32 v139, 31, v138
	v_ashrrev_i32_e32 v145, 31, v144
	v_ashrrev_i32_e32 v143, 31, v142
	v_ashrrev_i32_e32 v149, 31, v148
	v_ashrrev_i32_e32 v147, 31, v146
	v_ashrrev_i32_e32 v153, 31, v152
	v_ashrrev_i32_e32 v151, 31, v150
	v_ashrrev_i32_e32 v157, 31, v156
	v_ashrrev_i32_e32 v155, 31, v154
	v_ashrrev_i32_e32 v161, 31, v160
	v_ashrrev_i32_e32 v159, 31, v158
	v_lshlrev_b64 v[130:131], 12, v[130:131]
	v_lshl_add_u64 v[132:133], v[50:51], 0, v[132:133]
	v_lshlrev_b64 v[134:135], 12, v[134:135]
	v_lshlrev_b64 v[136:137], 12, v[136:137]
	v_lshlrev_b64 v[138:139], 12, v[138:139]
	v_lshlrev_b64 v[140:141], 12, v[140:141]
	v_lshlrev_b64 v[142:143], 12, v[142:143]
	v_lshlrev_b64 v[144:145], 12, v[144:145]
	v_lshlrev_b64 v[146:147], 12, v[146:147]
	v_lshlrev_b64 v[148:149], 12, v[148:149]
	v_lshlrev_b64 v[150:151], 12, v[150:151]
	v_lshlrev_b64 v[152:153], 12, v[152:153]
	v_lshlrev_b64 v[154:155], 12, v[154:155]
	v_lshlrev_b64 v[156:157], 12, v[156:157]
	v_lshlrev_b64 v[158:159], 12, v[158:159]
	v_lshlrev_b64 v[160:161], 12, v[160:161]
	v_lshl_add_u64 v[130:131], v[50:51], 0, v[130:131]
	v_lshl_add_u64 v[136:137], v[50:51], 0, v[136:137]
	v_lshl_add_u64 v[134:135], v[50:51], 0, v[134:135]
	v_lshl_add_u64 v[140:141], v[50:51], 0, v[140:141]
	v_lshl_add_u64 v[138:139], v[50:51], 0, v[138:139]
	v_lshl_add_u64 v[144:145], v[50:51], 0, v[144:145]
	v_lshl_add_u64 v[142:143], v[50:51], 0, v[142:143]
	v_lshl_add_u64 v[148:149], v[50:51], 0, v[148:149]
	v_lshl_add_u64 v[146:147], v[50:51], 0, v[146:147]
	v_lshl_add_u64 v[152:153], v[50:51], 0, v[152:153]
	v_lshl_add_u64 v[150:151], v[50:51], 0, v[150:151]
	v_lshl_add_u64 v[156:157], v[50:51], 0, v[156:157]
	v_lshl_add_u64 v[154:155], v[50:51], 0, v[154:155]
	v_lshl_add_u64 v[160:161], v[50:51], 0, v[160:161]
	v_lshl_add_u64 v[158:159], v[50:51], 0, v[158:159]
	global_load_dword v122, v[132:133], off
	global_load_dword v123, v[130:131], off
	global_load_dword v124, v[136:137], off
	global_load_dword v125, v[134:135], off
	global_load_dword v126, v[140:141], off
	global_load_dword v127, v[138:139], off
	global_load_dword v162, v[144:145], off
	global_load_dword v163, v[142:143], off
	global_load_dword v164, v[148:149], off
	global_load_dword v165, v[146:147], off
	global_load_dword v166, v[152:153], off
	global_load_dword v167, v[150:151], off
	global_load_dword v168, v[156:157], off
	global_load_dword v169, v[154:155], off
	global_load_dword v170, v[160:161], off
	global_load_dword v171, v[158:159], off
	v_mad_u64_u32 v[52:53], s[14:15], v9, s78, v[4:5]
	v_mad_u64_u32 v[54:55], s[14:15], v7, s78, v[4:5]
	v_mad_u64_u32 v[56:57], s[14:15], v13, s78, v[4:5]
	v_mad_u64_u32 v[58:59], s[14:15], v11, s78, v[4:5]
	v_mad_u64_u32 v[60:61], s[14:15], v19, s78, v[4:5]
	v_mad_u64_u32 v[62:63], s[14:15], v15, s78, v[4:5]
	v_mad_u64_u32 v[64:65], s[14:15], v43, s78, v[4:5]
	v_mad_u64_u32 v[66:67], s[14:15], v41, s78, v[4:5]
	v_mad_u64_u32 v[68:69], s[14:15], v47, s78, v[4:5]
	v_mad_u64_u32 v[70:71], s[14:15], v45, s78, v[4:5]
	v_mad_u64_u32 v[72:73], s[14:15], v82, s78, v[4:5]
	v_mad_u64_u32 v[74:75], s[14:15], v49, s78, v[4:5]
	v_mad_u64_u32 v[76:77], s[14:15], v87, s78, v[4:5]
	v_mad_u64_u32 v[78:79], s[14:15], v86, s78, v[4:5]
	v_mad_u64_u32 v[80:81], s[14:15], v89, s78, v[4:5]
	v_mad_u64_u32 v[84:85], s[14:15], v88, s78, v[4:5]
	s_waitcnt vmcnt(31)
	ds_write_b32 v52, v90
	s_waitcnt vmcnt(30)
	ds_write_b32 v54, v91
	s_waitcnt vmcnt(29)
	ds_write_b32 v56, v92
	s_waitcnt vmcnt(28)
	ds_write_b32 v58, v93
	s_waitcnt vmcnt(27)
	ds_write_b32 v60, v94
	s_waitcnt vmcnt(26)
	ds_write_b32 v62, v95
	s_waitcnt vmcnt(25)
	ds_write_b32 v64, v96
	s_waitcnt vmcnt(24)
	ds_write_b32 v66, v97
	s_waitcnt vmcnt(23)
	ds_write_b32 v68, v98
	s_waitcnt vmcnt(22)
	ds_write_b32 v70, v99
	s_waitcnt vmcnt(21)
	ds_write_b32 v72, v100
	s_waitcnt vmcnt(20)
	ds_write_b32 v74, v101
	s_waitcnt vmcnt(19)
	ds_write_b32 v76, v102
	s_waitcnt vmcnt(18)
	ds_write_b32 v78, v103
	s_waitcnt vmcnt(17)
	ds_write_b32 v80, v104
	s_waitcnt vmcnt(16)
	ds_write_b32 v84, v105
	v_mad_u64_u32 v[130:131], s[14:15], v107, s78, v[4:5]
	v_mad_u64_u32 v[132:133], s[14:15], v106, s78, v[4:5]
	v_mad_u64_u32 v[134:135], s[14:15], v109, s78, v[4:5]
	v_mad_u64_u32 v[136:137], s[14:15], v108, s78, v[4:5]
	v_mad_u64_u32 v[138:139], s[14:15], v111, s78, v[4:5]
	v_mad_u64_u32 v[140:141], s[14:15], v110, s78, v[4:5]
	v_mad_u64_u32 v[142:143], s[14:15], v113, s78, v[4:5]
	v_mad_u64_u32 v[144:145], s[14:15], v112, s78, v[4:5]
	v_mad_u64_u32 v[146:147], s[14:15], v115, s78, v[4:5]
	v_mad_u64_u32 v[148:149], s[14:15], v114, s78, v[4:5]
	v_mad_u64_u32 v[150:151], s[14:15], v117, s78, v[4:5]
	v_mad_u64_u32 v[152:153], s[14:15], v116, s78, v[4:5]
	v_mad_u64_u32 v[154:155], s[14:15], v119, s78, v[4:5]
	v_mad_u64_u32 v[156:157], s[14:15], v118, s78, v[4:5]
	v_mad_u64_u32 v[158:159], s[14:15], v121, s78, v[4:5]
	v_mad_u64_u32 v[160:161], s[14:15], v120, s78, v[4:5]
	s_waitcnt vmcnt(15)
	ds_write_b32 v130, v122
	s_waitcnt vmcnt(14)
	ds_write_b32 v132, v123
	s_waitcnt vmcnt(13)
	ds_write_b32 v134, v124
	s_waitcnt vmcnt(12)
	ds_write_b32 v136, v125
	s_waitcnt vmcnt(11)
	ds_write_b32 v138, v126
	s_waitcnt vmcnt(10)
	ds_write_b32 v140, v127
	s_waitcnt vmcnt(9)
	ds_write_b32 v142, v162
	s_waitcnt vmcnt(8)
	ds_write_b32 v144, v163
	s_waitcnt vmcnt(7)
	ds_write_b32 v146, v164
	s_waitcnt vmcnt(6)
	ds_write_b32 v148, v165
	s_waitcnt vmcnt(5)
	ds_write_b32 v150, v166
	s_waitcnt vmcnt(4)
	ds_write_b32 v152, v167
	s_waitcnt vmcnt(3)
	ds_write_b32 v154, v168
	s_waitcnt vmcnt(2)
	ds_write_b32 v156, v169
	s_waitcnt vmcnt(1)
	ds_write_b32 v158, v170
	s_waitcnt vmcnt(0)
	ds_write_b32 v160, v171
	s_add_i32 s5, s5, 16
	s_add_i32 s1, s1, 16
	s_add_i32 s11, s11, -16
	s_add_i32 s11, s11, -16
	s_cmp_lg_u32 s11, 0
	s_waitcnt lgkmcnt(0)
	ds_read2_b32 v[54:55], v5 offset1:8
	ds_read2_b32 v[58:59], v5 offset0:33 offset1:41
	ds_read2_b32 v[60:61], v5 offset0:66 offset1:74
	ds_read2_b32 v[62:63], v5 offset0:99 offset1:107
	ds_read2_b32 v[64:65], v5 offset0:132 offset1:140
	s_waitcnt lgkmcnt(4)
	s_waitcnt lgkmcnt(3)
	v_cvt_pk_bf16_f32 v9, v54, v58
	ds_read2_b32 v[66:67], v5 offset0:165 offset1:173
	v_mov_b32_e32 v50, v9
	s_waitcnt lgkmcnt(3)
	s_waitcnt lgkmcnt(2)
	ds_read2_b32 v[68:69], v5 offset0:198 offset1:206
	v_cvt_pk_bf16_f32 v9, v60, v62
	ds_read2_b32 v[70:71], v5 offset0:231 offset1:239
	v_mov_b32_e32 v51, v9
	s_waitcnt lgkmcnt(3)
	s_lshl_b64 s[4:5], s[12:13], 11
	s_waitcnt lgkmcnt(2)
	s_add_u32 s1, s47, s4
	v_cvt_pk_bf16_f32 v9, v64, v66
	s_addc_u32 s12, s48, s5
	s_ashr_i32 s11, s10, 31
	v_mov_b32_e32 v52, v9
	s_waitcnt lgkmcnt(1)
	s_lshl_b64 s[4:5], s[10:11], 1
	s_waitcnt lgkmcnt(0)
	s_add_u32 s4, s1, s4
	v_cvt_pk_bf16_f32 v9, v68, v70
	s_addc_u32 s5, s12, s5
	v_lshlrev_b32_e32 v128, 1, v6
	v_mov_b32_e32 v53, v9
	v_lshl_add_u64 v[56:57], s[4:5], 0, v[128:129]
	v_lshlrev_b32_e32 v128, 1, v8
	v_lshl_add_u64 v[72:73], v[56:57], 0, v[128:129]
	v_cvt_pk_bf16_f32 v9, v55, v59
	global_store_dwordx4 v[72:73], v[50:53], off
	v_lshlrev_b32_e32 v128, 1, v10
	ds_read2_b32 v[54:55], v5 offset0:16 offset1:24
	v_mov_b32_e32 v50, v9
	v_cvt_pk_bf16_f32 v9, v61, v63
	v_mov_b32_e32 v51, v9
	v_cvt_pk_bf16_f32 v9, v65, v67
	v_mov_b32_e32 v52, v9
	v_cvt_pk_bf16_f32 v9, v69, v71
	v_mov_b32_e32 v53, v9
	v_lshl_add_u64 v[58:59], v[56:57], 0, v[128:129]
	global_store_dwordx4 v[58:59], v[50:53], off
	ds_read2_b32 v[58:59], v5 offset0:49 offset1:57
	ds_read2_b32 v[60:61], v5 offset0:82 offset1:90
	ds_read2_b32 v[62:63], v5 offset0:115 offset1:123
	s_waitcnt lgkmcnt(3)
	s_waitcnt lgkmcnt(2)
	ds_read2_b32 v[64:65], v5 offset0:148 offset1:156
	v_cvt_pk_bf16_f32 v9, v54, v58
	ds_read2_b32 v[66:67], v5 offset0:181 offset1:189
	v_mov_b32_e32 v50, v9
	s_waitcnt lgkmcnt(3)
	s_waitcnt lgkmcnt(2)
	ds_read2_b32 v[68:69], v5 offset0:214 offset1:222
	v_cvt_pk_bf16_f32 v9, v60, v62
	ds_read2_b32 v[70:71], v5 offset0:247 offset1:255
	v_mov_b32_e32 v51, v9
	s_waitcnt lgkmcnt(3)
	s_waitcnt lgkmcnt(2)
	v_cvt_pk_bf16_f32 v9, v64, v66
	v_mov_b32_e32 v52, v9
	s_waitcnt lgkmcnt(1)
	s_waitcnt lgkmcnt(0)
	v_cvt_pk_bf16_f32 v9, v68, v70
	v_mov_b32_e32 v53, v9
	v_lshlrev_b32_e32 v128, 1, v12
	v_lshl_add_u64 v[72:73], v[56:57], 0, v[128:129]
	v_cvt_pk_bf16_f32 v9, v55, v59
	global_store_dwordx4 v[72:73], v[50:53], off
	v_lshlrev_b32_e32 v128, 1, v14
	v_lshl_add_u64 v[54:55], v[56:57], 0, v[128:129]
	v_mov_b32_e32 v50, v9
	v_cvt_pk_bf16_f32 v9, v61, v63
	v_mov_b32_e32 v51, v9
	v_cvt_pk_bf16_f32 v9, v65, v67
	v_mov_b32_e32 v52, v9
	v_cvt_pk_bf16_f32 v9, v69, v71
	v_mov_b32_e32 v53, v9
	global_store_dwordx4 v[54:55], v[50:53], off
	s_waitcnt lgkmcnt(0)
	s_mov_b64 s[10:11], -1

.LBB0_724:
	s_lshl_b32 s22, s4, 1
	s_lshl_b32 s23, s5, 1
	v_or_b32_e32 v7, s22, v1
	v_or_b32_e32 v9, s23, v0
	s_add_i32 s24, s22, 4
	s_add_i32 s25, s23, 4
	s_add_i32 s26, s22, 8
	s_add_i32 s27, s23, 8
	s_add_i32 s30, s22, 12
	s_add_i32 s36, s23, 12
	s_add_i32 s37, s22, 16
	s_add_i32 s40, s23, 16
	s_add_i32 s41, s22, 20
	s_add_i32 s42, s23, 20
	s_add_i32 s43, s22, 24
	s_add_i32 s52, s23, 24
	s_add_i32 s22, s22, 28
	s_add_i32 s23, s23, 28
	v_add_u32_e32 v11, s1, v7
	v_add_u32_e32 v13, s12, v9
	v_or_b32_e32 v15, s24, v1
	v_or_b32_e32 v19, s25, v0
	v_or_b32_e32 v41, s26, v1
	v_or_b32_e32 v43, s27, v0
	v_or_b32_e32 v45, s30, v1
	v_or_b32_e32 v47, s36, v0
	v_or_b32_e32 v49, s37, v1
	v_or_b32_e32 v82, s40, v0
	v_or_b32_e32 v86, s41, v1
	v_or_b32_e32 v87, s42, v0
	v_or_b32_e32 v88, s43, v1
	v_or_b32_e32 v89, s52, v0
	v_or_b32_e32 v90, s22, v1
	v_or_b32_e32 v91, s23, v0
	v_mad_i64_i32 v[52:53], s[22:23], v13, s79, v[50:51]
	v_mad_i64_i32 v[54:55], s[22:23], v11, s79, v[50:51]
	v_add_u32_e32 v11, s1, v15
	v_add_u32_e32 v13, s12, v19
	v_add_u32_e32 v62, s1, v41
	v_add_u32_e32 v60, s12, v43
	v_add_u32_e32 v66, s1, v45
	v_add_u32_e32 v64, s12, v47
	v_add_u32_e32 v70, s1, v49
	v_add_u32_e32 v68, s12, v82
	v_add_u32_e32 v74, s1, v86
	v_add_u32_e32 v72, s12, v87
	v_add_u32_e32 v78, s1, v88
	v_add_u32_e32 v76, s12, v89
	v_add_u32_e32 v84, s1, v90
	v_add_u32_e32 v80, s12, v91
	v_mad_i64_i32 v[56:57], s[22:23], v13, s79, v[50:51]
	v_mad_i64_i32 v[58:59], s[22:23], v11, s79, v[50:51]
	v_mad_i64_i32 v[60:61], s[22:23], v60, s79, v[50:51]
	v_mad_i64_i32 v[62:63], s[22:23], v62, s79, v[50:51]
	v_mad_i64_i32 v[64:65], s[22:23], v64, s79, v[50:51]
	v_mad_i64_i32 v[66:67], s[22:23], v66, s79, v[50:51]
	v_mad_i64_i32 v[68:69], s[22:23], v68, s79, v[50:51]
	v_mad_i64_i32 v[70:71], s[22:23], v70, s79, v[50:51]
	v_mad_i64_i32 v[72:73], s[22:23], v72, s79, v[50:51]
	v_mad_i64_i32 v[74:75], s[22:23], v74, s79, v[50:51]
	v_mad_i64_i32 v[76:77], s[22:23], v76, s79, v[50:51]
	v_mad_i64_i32 v[78:79], s[22:23], v78, s79, v[50:51]
	v_mad_i64_i32 v[80:81], s[22:23], v80, s79, v[50:51]
	v_mad_i64_i32 v[84:85], s[22:23], v84, s79, v[50:51]
	global_load_dword v11, v[52:53], off
	global_load_dword v13, v[54:55], off
	global_load_dword v92, v[56:57], off
	global_load_dword v93, v[58:59], off
	global_load_dword v94, v[60:61], off
	global_load_dword v95, v[62:63], off
	global_load_dword v96, v[64:65], off
	global_load_dword v97, v[66:67], off
	global_load_dword v98, v[68:69], off
	global_load_dword v99, v[70:71], off
	global_load_dword v100, v[72:73], off
	global_load_dword v101, v[74:75], off
	global_load_dword v102, v[76:77], off
	global_load_dword v103, v[78:79], off
	global_load_dword v104, v[80:81], off
	global_load_dword v105, v[84:85], off
	s_add_i32 s5, s5, 16
	s_add_i32 s4, s4, 16
	s_lshl_b32 s22, s4, 1
	s_lshl_b32 s23, s5, 1
	v_or_b32_e32 v106, s22, v1
	v_or_b32_e32 v107, s23, v0
	s_add_i32 s24, s22, 4
	s_add_i32 s25, s23, 4
	s_add_i32 s26, s22, 8
	s_add_i32 s27, s23, 8
	s_add_i32 s30, s22, 12
	s_add_i32 s36, s23, 12
	s_add_i32 s37, s22, 16
	s_add_i32 s40, s23, 16
	s_add_i32 s41, s22, 20
	s_add_i32 s42, s23, 20
	s_add_i32 s43, s22, 24
	s_add_i32 s52, s23, 24
	s_add_i32 s22, s22, 28
	s_add_i32 s23, s23, 28
	v_add_u32_e32 v108, s1, v106
	v_add_u32_e32 v109, s12, v107
	v_or_b32_e32 v110, s24, v1
	v_or_b32_e32 v111, s25, v0
	v_or_b32_e32 v112, s26, v1
	v_or_b32_e32 v113, s27, v0
	v_or_b32_e32 v114, s30, v1
	v_or_b32_e32 v115, s36, v0
	v_or_b32_e32 v116, s37, v1
	v_or_b32_e32 v117, s40, v0
	v_or_b32_e32 v118, s41, v1
	v_or_b32_e32 v119, s42, v0
	v_or_b32_e32 v120, s43, v1
	v_or_b32_e32 v121, s52, v0
	v_or_b32_e32 v122, s22, v1
	v_or_b32_e32 v123, s23, v0
	v_mad_i64_i32 v[130:131], s[22:23], v109, s79, v[50:51]
	v_mad_i64_i32 v[132:133], s[22:23], v108, s79, v[50:51]
	v_add_u32_e32 v108, s1, v110
	v_add_u32_e32 v109, s12, v111
	v_add_u32_e32 v140, s1, v112
	v_add_u32_e32 v138, s12, v113
	v_add_u32_e32 v144, s1, v114
	v_add_u32_e32 v142, s12, v115
	v_add_u32_e32 v148, s1, v116
	v_add_u32_e32 v146, s12, v117
	v_add_u32_e32 v152, s1, v118
	v_add_u32_e32 v150, s12, v119
	v_add_u32_e32 v156, s1, v120
	v_add_u32_e32 v154, s12, v121
	v_add_u32_e32 v160, s1, v122
	v_add_u32_e32 v158, s12, v123
	v_mad_i64_i32 v[134:135], s[22:23], v109, s79, v[50:51]
	v_mad_i64_i32 v[136:137], s[22:23], v108, s79, v[50:51]
	v_mad_i64_i32 v[138:139], s[22:23], v138, s79, v[50:51]
	v_mad_i64_i32 v[140:141], s[22:23], v140, s79, v[50:51]
	v_mad_i64_i32 v[142:143], s[22:23], v142, s79, v[50:51]
	v_mad_i64_i32 v[144:145], s[22:23], v144, s79, v[50:51]
	v_mad_i64_i32 v[146:147], s[22:23], v146, s79, v[50:51]
	v_mad_i64_i32 v[148:149], s[22:23], v148, s79, v[50:51]
	v_mad_i64_i32 v[150:151], s[22:23], v150, s79, v[50:51]
	v_mad_i64_i32 v[152:153], s[22:23], v152, s79, v[50:51]
	v_mad_i64_i32 v[154:155], s[22:23], v154, s79, v[50:51]
	v_mad_i64_i32 v[156:157], s[22:23], v156, s79, v[50:51]
	v_mad_i64_i32 v[158:159], s[22:23], v158, s79, v[50:51]
	v_mad_i64_i32 v[160:161], s[22:23], v160, s79, v[50:51]
	global_load_dword v108, v[130:131], off
	global_load_dword v109, v[132:133], off
	global_load_dword v124, v[134:135], off
	global_load_dword v125, v[136:137], off
	global_load_dword v126, v[138:139], off
	global_load_dword v127, v[140:141], off
	global_load_dword v162, v[142:143], off
	global_load_dword v163, v[144:145], off
	global_load_dword v164, v[146:147], off
	global_load_dword v165, v[148:149], off
	global_load_dword v166, v[150:151], off
	global_load_dword v167, v[152:153], off
	global_load_dword v168, v[154:155], off
	global_load_dword v169, v[156:157], off
	global_load_dword v170, v[158:159], off
	global_load_dword v171, v[160:161], off
	v_mad_u64_u32 v[52:53], s[22:23], v9, s78, v[4:5]
	v_mad_u64_u32 v[54:55], s[22:23], v7, s78, v[4:5]
	v_mad_u64_u32 v[56:57], s[22:23], v19, s78, v[4:5]
	v_mad_u64_u32 v[58:59], s[22:23], v15, s78, v[4:5]
	v_mad_u64_u32 v[60:61], s[22:23], v43, s78, v[4:5]
	v_mad_u64_u32 v[62:63], s[22:23], v41, s78, v[4:5]
	v_mad_u64_u32 v[64:65], s[22:23], v47, s78, v[4:5]
	v_mad_u64_u32 v[66:67], s[22:23], v45, s78, v[4:5]
	v_mad_u64_u32 v[68:69], s[22:23], v82, s78, v[4:5]
	v_mad_u64_u32 v[70:71], s[22:23], v49, s78, v[4:5]
	v_mad_u64_u32 v[72:73], s[22:23], v87, s78, v[4:5]
	v_mad_u64_u32 v[74:75], s[22:23], v86, s78, v[4:5]
	v_mad_u64_u32 v[76:77], s[22:23], v89, s78, v[4:5]
	v_mad_u64_u32 v[78:79], s[22:23], v88, s78, v[4:5]
	v_mad_u64_u32 v[80:81], s[22:23], v91, s78, v[4:5]
	v_mad_u64_u32 v[84:85], s[22:23], v90, s78, v[4:5]
	s_waitcnt vmcnt(31)
	ds_write_b32 v52, v11
	s_waitcnt vmcnt(30)
	ds_write_b32 v54, v13
	s_waitcnt vmcnt(29)
	ds_write_b32 v56, v92
	s_waitcnt vmcnt(28)
	ds_write_b32 v58, v93
	s_waitcnt vmcnt(27)
	ds_write_b32 v60, v94
	s_waitcnt vmcnt(26)
	ds_write_b32 v62, v95
	s_waitcnt vmcnt(25)
	ds_write_b32 v64, v96
	s_waitcnt vmcnt(24)
	ds_write_b32 v66, v97
	s_waitcnt vmcnt(23)
	ds_write_b32 v68, v98
	s_waitcnt vmcnt(22)
	ds_write_b32 v70, v99
	s_waitcnt vmcnt(21)
	ds_write_b32 v72, v100
	s_waitcnt vmcnt(20)
	ds_write_b32 v74, v101
	s_waitcnt vmcnt(19)
	ds_write_b32 v76, v102
	s_waitcnt vmcnt(18)
	ds_write_b32 v78, v103
	s_waitcnt vmcnt(17)
	ds_write_b32 v80, v104
	s_waitcnt vmcnt(16)
	ds_write_b32 v84, v105
	v_mad_u64_u32 v[130:131], s[22:23], v107, s78, v[4:5]
	v_mad_u64_u32 v[132:133], s[22:23], v106, s78, v[4:5]
	v_mad_u64_u32 v[134:135], s[22:23], v111, s78, v[4:5]
	v_mad_u64_u32 v[136:137], s[22:23], v110, s78, v[4:5]
	v_mad_u64_u32 v[138:139], s[22:23], v113, s78, v[4:5]
	v_mad_u64_u32 v[140:141], s[22:23], v112, s78, v[4:5]
	v_mad_u64_u32 v[142:143], s[22:23], v115, s78, v[4:5]
	v_mad_u64_u32 v[144:145], s[22:23], v114, s78, v[4:5]
	v_mad_u64_u32 v[146:147], s[22:23], v117, s78, v[4:5]
	v_mad_u64_u32 v[148:149], s[22:23], v116, s78, v[4:5]
	v_mad_u64_u32 v[150:151], s[22:23], v119, s78, v[4:5]
	v_mad_u64_u32 v[152:153], s[22:23], v118, s78, v[4:5]
	v_mad_u64_u32 v[154:155], s[22:23], v121, s78, v[4:5]
	v_mad_u64_u32 v[156:157], s[22:23], v120, s78, v[4:5]
	v_mad_u64_u32 v[158:159], s[22:23], v123, s78, v[4:5]
	v_mad_u64_u32 v[160:161], s[22:23], v122, s78, v[4:5]
	s_waitcnt vmcnt(15)
	ds_write_b32 v130, v108
	s_waitcnt vmcnt(14)
	ds_write_b32 v132, v109
	s_waitcnt vmcnt(13)
	ds_write_b32 v134, v124
	s_waitcnt vmcnt(12)
	ds_write_b32 v136, v125
	s_waitcnt vmcnt(11)
	ds_write_b32 v138, v126
	s_waitcnt vmcnt(10)
	ds_write_b32 v140, v127
	s_waitcnt vmcnt(9)
	ds_write_b32 v142, v162
	s_waitcnt vmcnt(8)
	ds_write_b32 v144, v163
	s_waitcnt vmcnt(7)
	ds_write_b32 v146, v164
	s_waitcnt vmcnt(6)
	ds_write_b32 v148, v165
	s_waitcnt vmcnt(5)
	ds_write_b32 v150, v166
	s_waitcnt vmcnt(4)
	ds_write_b32 v152, v167
	s_waitcnt vmcnt(3)
	ds_write_b32 v154, v168
	s_waitcnt vmcnt(2)
	ds_write_b32 v156, v169
	s_waitcnt vmcnt(1)
	ds_write_b32 v158, v170
	s_waitcnt vmcnt(0)
	ds_write_b32 v160, v171
	s_add_i32 s5, s5, 16
	s_add_i32 s4, s4, 16
	s_add_i32 s13, s13, -16
	s_add_i32 s13, s13, -16
	s_cmp_lg_u32 s13, 0
	s_waitcnt lgkmcnt(0)
	ds_read2_b32 v[54:55], v5 offset1:8
	ds_read2_b32 v[58:59], v5 offset0:33 offset1:41
	ds_read2_b32 v[60:61], v5 offset0:66 offset1:74
	ds_read2_b32 v[62:63], v5 offset0:99 offset1:107
	ds_read2_b32 v[64:65], v5 offset0:132 offset1:140
	s_waitcnt lgkmcnt(4)
	s_waitcnt lgkmcnt(3)
	v_cvt_pk_bf16_f32 v9, v54, v58
	ds_read2_b32 v[66:67], v5 offset0:165 offset1:173
	v_mov_b32_e32 v50, v9
	s_waitcnt lgkmcnt(3)
	s_waitcnt lgkmcnt(2)
	ds_read2_b32 v[68:69], v5 offset0:198 offset1:206
	v_cvt_pk_bf16_f32 v9, v60, v62
	ds_read2_b32 v[70:71], v5 offset0:231 offset1:239
	v_mov_b32_e32 v51, v9
	s_waitcnt lgkmcnt(3)
	s_lshl_b64 s[4:5], s[14:15], 11
	s_waitcnt lgkmcnt(2)
	s_add_u32 s1, s35, s4
	v_cvt_pk_bf16_f32 v9, v64, v66
	s_addc_u32 s14, s38, s5
	s_ashr_i32 s13, s12, 31
	v_mov_b32_e32 v52, v9
	s_waitcnt lgkmcnt(1)
	s_lshl_b64 s[4:5], s[12:13], 1
	s_waitcnt lgkmcnt(0)
	s_add_u32 s4, s1, s4
	v_cvt_pk_bf16_f32 v9, v68, v70
	s_addc_u32 s5, s14, s5
	v_lshlrev_b32_e32 v128, 1, v6
	v_mov_b32_e32 v53, v9
	v_lshl_add_u64 v[56:57], s[4:5], 0, v[128:129]
	v_lshlrev_b32_e32 v128, 1, v8
	v_lshl_add_u64 v[72:73], v[56:57], 0, v[128:129]
	v_cvt_pk_bf16_f32 v9, v55, v59
	global_store_dwordx4 v[72:73], v[50:53], off
	v_lshlrev_b32_e32 v128, 1, v10
	ds_read2_b32 v[54:55], v5 offset0:16 offset1:24
	v_mov_b32_e32 v50, v9
	v_cvt_pk_bf16_f32 v9, v61, v63
	v_mov_b32_e32 v51, v9
	v_cvt_pk_bf16_f32 v9, v65, v67
	v_mov_b32_e32 v52, v9
	v_cvt_pk_bf16_f32 v9, v69, v71
	v_mov_b32_e32 v53, v9
	v_lshl_add_u64 v[58:59], v[56:57], 0, v[128:129]
	global_store_dwordx4 v[58:59], v[50:53], off
	ds_read2_b32 v[58:59], v5 offset0:49 offset1:57
	ds_read2_b32 v[60:61], v5 offset0:82 offset1:90
	ds_read2_b32 v[62:63], v5 offset0:115 offset1:123
	s_waitcnt lgkmcnt(3)
	s_waitcnt lgkmcnt(2)
	ds_read2_b32 v[64:65], v5 offset0:148 offset1:156
	v_cvt_pk_bf16_f32 v9, v54, v58
	ds_read2_b32 v[66:67], v5 offset0:181 offset1:189
	v_mov_b32_e32 v50, v9
	s_waitcnt lgkmcnt(3)
	s_waitcnt lgkmcnt(2)
	ds_read2_b32 v[68:69], v5 offset0:214 offset1:222
	v_cvt_pk_bf16_f32 v9, v60, v62
	ds_read2_b32 v[70:71], v5 offset0:247 offset1:255
	v_mov_b32_e32 v51, v9
	s_waitcnt lgkmcnt(3)
	s_waitcnt lgkmcnt(2)
	v_cvt_pk_bf16_f32 v9, v64, v66
	v_mov_b32_e32 v52, v9
	s_waitcnt lgkmcnt(1)
	s_waitcnt lgkmcnt(0)
	v_cvt_pk_bf16_f32 v9, v68, v70
	v_mov_b32_e32 v53, v9
	v_lshlrev_b32_e32 v128, 1, v12
	v_lshl_add_u64 v[72:73], v[56:57], 0, v[128:129]
	v_cvt_pk_bf16_f32 v9, v55, v59
	global_store_dwordx4 v[72:73], v[50:53], off
	v_lshlrev_b32_e32 v128, 1, v14
	v_lshl_add_u64 v[54:55], v[56:57], 0, v[128:129]
	v_mov_b32_e32 v50, v9
	v_cvt_pk_bf16_f32 v9, v61, v63
	v_mov_b32_e32 v51, v9
	v_cvt_pk_bf16_f32 v9, v65, v67
	v_mov_b32_e32 v52, v9
	v_cvt_pk_bf16_f32 v9, v69, v71
	v_mov_b32_e32 v53, v9
	global_store_dwordx4 v[54:55], v[50:53], off
	s_waitcnt lgkmcnt(0)
	s_mov_b32 s1, s0
	s_andn2_b64 vcc, exec, s[10:11]
	s_mov_b64 s[10:11], -1
	s_cbranch_vccnz .LBB0_744

.LBB0_731:
	s_lshl_b32 s15, s4, 1
	s_lshl_b32 s22, s5, 1
	v_or_b32_e32 v7, s15, v1
	v_or_b32_e32 v9, s22, v0
	s_add_i32 s23, s15, 4
	s_add_i32 s24, s22, 4
	s_add_i32 s25, s15, 8
	s_add_i32 s26, s22, 8
	s_add_i32 s27, s15, 12
	s_add_i32 s30, s22, 12
	s_add_i32 s36, s15, 16
	s_add_i32 s37, s22, 16
	s_add_i32 s40, s15, 20
	s_add_i32 s41, s22, 20
	s_add_i32 s42, s15, 24
	s_add_i32 s43, s22, 24
	s_add_i32 s15, s15, 28
	s_add_i32 s22, s22, 28
	v_add_u32_e32 v11, s0, v7
	v_add_u32_e32 v13, s12, v9
	v_or_b32_e32 v15, s23, v1
	v_or_b32_e32 v19, s24, v0
	v_or_b32_e32 v41, s25, v1
	v_or_b32_e32 v43, s26, v0
	v_or_b32_e32 v45, s27, v1
	v_or_b32_e32 v47, s30, v0
	v_or_b32_e32 v49, s36, v1
	v_or_b32_e32 v82, s37, v0
	v_or_b32_e32 v86, s40, v1
	v_or_b32_e32 v87, s41, v0
	v_or_b32_e32 v88, s42, v1
	v_or_b32_e32 v89, s43, v0
	v_or_b32_e32 v90, s15, v1
	v_or_b32_e32 v91, s22, v0
	v_mad_i64_i32 v[52:53], s[22:23], v13, s68, v[50:51]
	v_mad_i64_i32 v[54:55], s[22:23], v11, s68, v[50:51]
	v_add_u32_e32 v11, s0, v15
	v_add_u32_e32 v13, s12, v19
	v_add_u32_e32 v62, s0, v41
	v_add_u32_e32 v60, s12, v43
	v_add_u32_e32 v66, s0, v45
	v_add_u32_e32 v64, s12, v47
	v_add_u32_e32 v70, s0, v49
	v_add_u32_e32 v68, s12, v82
	v_add_u32_e32 v74, s0, v86
	v_add_u32_e32 v72, s12, v87
	v_add_u32_e32 v78, s0, v88
	v_add_u32_e32 v76, s12, v89
	v_add_u32_e32 v84, s0, v90
	v_add_u32_e32 v80, s12, v91
	v_mad_i64_i32 v[56:57], s[22:23], v13, s68, v[50:51]
	v_mad_i64_i32 v[58:59], s[22:23], v11, s68, v[50:51]
	v_mad_i64_i32 v[60:61], s[22:23], v60, s68, v[50:51]
	v_mad_i64_i32 v[62:63], s[22:23], v62, s68, v[50:51]
	v_mad_i64_i32 v[64:65], s[22:23], v64, s68, v[50:51]
	v_mad_i64_i32 v[66:67], s[22:23], v66, s68, v[50:51]
	v_mad_i64_i32 v[68:69], s[22:23], v68, s68, v[50:51]
	v_mad_i64_i32 v[70:71], s[22:23], v70, s68, v[50:51]
	v_mad_i64_i32 v[72:73], s[22:23], v72, s68, v[50:51]
	v_mad_i64_i32 v[74:75], s[22:23], v74, s68, v[50:51]
	v_mad_i64_i32 v[76:77], s[22:23], v76, s68, v[50:51]
	v_mad_i64_i32 v[78:79], s[22:23], v78, s68, v[50:51]
	v_mad_i64_i32 v[80:81], s[22:23], v80, s68, v[50:51]
	v_mad_i64_i32 v[84:85], s[22:23], v84, s68, v[50:51]
	global_load_dword v11, v[52:53], off
	global_load_dword v13, v[54:55], off
	global_load_dword v92, v[56:57], off
	global_load_dword v93, v[58:59], off
	global_load_dword v94, v[60:61], off
	global_load_dword v95, v[62:63], off
	global_load_dword v96, v[64:65], off
	global_load_dword v97, v[66:67], off
	global_load_dword v98, v[68:69], off
	global_load_dword v99, v[70:71], off
	global_load_dword v100, v[72:73], off
	global_load_dword v101, v[74:75], off
	global_load_dword v102, v[76:77], off
	global_load_dword v103, v[78:79], off
	global_load_dword v104, v[80:81], off
	global_load_dword v105, v[84:85], off
	s_add_i32 s5, s5, 16
	s_add_i32 s4, s4, 16
	s_lshl_b32 s15, s4, 1
	s_lshl_b32 s22, s5, 1
	v_or_b32_e32 v106, s15, v1
	v_or_b32_e32 v107, s22, v0
	s_add_i32 s23, s15, 4
	s_add_i32 s24, s22, 4
	s_add_i32 s25, s15, 8
	s_add_i32 s26, s22, 8
	s_add_i32 s27, s15, 12
	s_add_i32 s30, s22, 12
	s_add_i32 s36, s15, 16
	s_add_i32 s37, s22, 16
	s_add_i32 s40, s15, 20
	s_add_i32 s41, s22, 20
	s_add_i32 s42, s15, 24
	s_add_i32 s43, s22, 24
	s_add_i32 s15, s15, 28
	s_add_i32 s22, s22, 28
	v_add_u32_e32 v108, s0, v106
	v_add_u32_e32 v109, s12, v107
	v_or_b32_e32 v110, s23, v1
	v_or_b32_e32 v111, s24, v0
	v_or_b32_e32 v112, s25, v1
	v_or_b32_e32 v113, s26, v0
	v_or_b32_e32 v114, s27, v1
	v_or_b32_e32 v115, s30, v0
	v_or_b32_e32 v116, s36, v1
	v_or_b32_e32 v117, s37, v0
	v_or_b32_e32 v118, s40, v1
	v_or_b32_e32 v119, s41, v0
	v_or_b32_e32 v120, s42, v1
	v_or_b32_e32 v121, s43, v0
	v_or_b32_e32 v122, s15, v1
	v_or_b32_e32 v123, s22, v0
	v_mad_i64_i32 v[130:131], s[22:23], v109, s68, v[50:51]
	v_mad_i64_i32 v[132:133], s[22:23], v108, s68, v[50:51]
	v_add_u32_e32 v108, s0, v110
	v_add_u32_e32 v109, s12, v111
	v_add_u32_e32 v140, s0, v112
	v_add_u32_e32 v138, s12, v113
	v_add_u32_e32 v144, s0, v114
	v_add_u32_e32 v142, s12, v115
	v_add_u32_e32 v148, s0, v116
	v_add_u32_e32 v146, s12, v117
	v_add_u32_e32 v152, s0, v118
	v_add_u32_e32 v150, s12, v119
	v_add_u32_e32 v156, s0, v120
	v_add_u32_e32 v154, s12, v121
	v_add_u32_e32 v160, s0, v122
	v_add_u32_e32 v158, s12, v123
	v_mad_i64_i32 v[134:135], s[22:23], v109, s68, v[50:51]
	v_mad_i64_i32 v[136:137], s[22:23], v108, s68, v[50:51]
	v_mad_i64_i32 v[138:139], s[22:23], v138, s68, v[50:51]
	v_mad_i64_i32 v[140:141], s[22:23], v140, s68, v[50:51]
	v_mad_i64_i32 v[142:143], s[22:23], v142, s68, v[50:51]
	v_mad_i64_i32 v[144:145], s[22:23], v144, s68, v[50:51]
	v_mad_i64_i32 v[146:147], s[22:23], v146, s68, v[50:51]
	v_mad_i64_i32 v[148:149], s[22:23], v148, s68, v[50:51]
	v_mad_i64_i32 v[150:151], s[22:23], v150, s68, v[50:51]
	v_mad_i64_i32 v[152:153], s[22:23], v152, s68, v[50:51]
	v_mad_i64_i32 v[154:155], s[22:23], v154, s68, v[50:51]
	v_mad_i64_i32 v[156:157], s[22:23], v156, s68, v[50:51]
	v_mad_i64_i32 v[158:159], s[22:23], v158, s68, v[50:51]
	v_mad_i64_i32 v[160:161], s[22:23], v160, s68, v[50:51]
	global_load_dword v108, v[130:131], off
	global_load_dword v109, v[132:133], off
	global_load_dword v124, v[134:135], off
	global_load_dword v125, v[136:137], off
	global_load_dword v126, v[138:139], off
	global_load_dword v127, v[140:141], off
	global_load_dword v162, v[142:143], off
	global_load_dword v163, v[144:145], off
	global_load_dword v164, v[146:147], off
	global_load_dword v165, v[148:149], off
	global_load_dword v166, v[150:151], off
	global_load_dword v167, v[152:153], off
	global_load_dword v168, v[154:155], off
	global_load_dword v169, v[156:157], off
	global_load_dword v170, v[158:159], off
	global_load_dword v171, v[160:161], off
	v_mad_u64_u32 v[52:53], s[22:23], v9, s78, v[4:5]
	v_mad_u64_u32 v[54:55], s[22:23], v7, s78, v[4:5]
	v_mad_u64_u32 v[56:57], s[22:23], v19, s78, v[4:5]
	v_mad_u64_u32 v[58:59], s[22:23], v15, s78, v[4:5]
	v_mad_u64_u32 v[60:61], s[22:23], v43, s78, v[4:5]
	v_mad_u64_u32 v[62:63], s[22:23], v41, s78, v[4:5]
	v_mad_u64_u32 v[64:65], s[22:23], v47, s78, v[4:5]
	v_mad_u64_u32 v[66:67], s[22:23], v45, s78, v[4:5]
	v_mad_u64_u32 v[68:69], s[22:23], v82, s78, v[4:5]
	v_mad_u64_u32 v[70:71], s[22:23], v49, s78, v[4:5]
	v_mad_u64_u32 v[72:73], s[22:23], v87, s78, v[4:5]
	v_mad_u64_u32 v[74:75], s[22:23], v86, s78, v[4:5]
	v_mad_u64_u32 v[76:77], s[22:23], v89, s78, v[4:5]
	v_mad_u64_u32 v[78:79], s[22:23], v88, s78, v[4:5]
	v_mad_u64_u32 v[80:81], s[22:23], v91, s78, v[4:5]
	v_mad_u64_u32 v[84:85], s[22:23], v90, s78, v[4:5]
	s_waitcnt vmcnt(31)
	ds_write_b32 v52, v11
	s_waitcnt vmcnt(30)
	ds_write_b32 v54, v13
	s_waitcnt vmcnt(29)
	ds_write_b32 v56, v92
	s_waitcnt vmcnt(28)
	ds_write_b32 v58, v93
	s_waitcnt vmcnt(27)
	ds_write_b32 v60, v94
	s_waitcnt vmcnt(26)
	ds_write_b32 v62, v95
	s_waitcnt vmcnt(25)
	ds_write_b32 v64, v96
	s_waitcnt vmcnt(24)
	ds_write_b32 v66, v97
	s_waitcnt vmcnt(23)
	ds_write_b32 v68, v98
	s_waitcnt vmcnt(22)
	ds_write_b32 v70, v99
	s_waitcnt vmcnt(21)
	ds_write_b32 v72, v100
	s_waitcnt vmcnt(20)
	ds_write_b32 v74, v101
	s_waitcnt vmcnt(19)
	ds_write_b32 v76, v102
	s_waitcnt vmcnt(18)
	ds_write_b32 v78, v103
	s_waitcnt vmcnt(17)
	ds_write_b32 v80, v104
	s_waitcnt vmcnt(16)
	ds_write_b32 v84, v105
	v_mad_u64_u32 v[130:131], s[22:23], v107, s78, v[4:5]
	v_mad_u64_u32 v[132:133], s[22:23], v106, s78, v[4:5]
	v_mad_u64_u32 v[134:135], s[22:23], v111, s78, v[4:5]
	v_mad_u64_u32 v[136:137], s[22:23], v110, s78, v[4:5]
	v_mad_u64_u32 v[138:139], s[22:23], v113, s78, v[4:5]
	v_mad_u64_u32 v[140:141], s[22:23], v112, s78, v[4:5]
	v_mad_u64_u32 v[142:143], s[22:23], v115, s78, v[4:5]
	v_mad_u64_u32 v[144:145], s[22:23], v114, s78, v[4:5]
	v_mad_u64_u32 v[146:147], s[22:23], v117, s78, v[4:5]
	v_mad_u64_u32 v[148:149], s[22:23], v116, s78, v[4:5]
	v_mad_u64_u32 v[150:151], s[22:23], v119, s78, v[4:5]
	v_mad_u64_u32 v[152:153], s[22:23], v118, s78, v[4:5]
	v_mad_u64_u32 v[154:155], s[22:23], v121, s78, v[4:5]
	v_mad_u64_u32 v[156:157], s[22:23], v120, s78, v[4:5]
	v_mad_u64_u32 v[158:159], s[22:23], v123, s78, v[4:5]
	v_mad_u64_u32 v[160:161], s[22:23], v122, s78, v[4:5]
	s_waitcnt vmcnt(15)
	ds_write_b32 v130, v108
	s_waitcnt vmcnt(14)
	ds_write_b32 v132, v109
	s_waitcnt vmcnt(13)
	ds_write_b32 v134, v124
	s_waitcnt vmcnt(12)
	ds_write_b32 v136, v125
	s_waitcnt vmcnt(11)
	ds_write_b32 v138, v126
	s_waitcnt vmcnt(10)
	ds_write_b32 v140, v127
	s_waitcnt vmcnt(9)
	ds_write_b32 v142, v162
	s_waitcnt vmcnt(8)
	ds_write_b32 v144, v163
	s_waitcnt vmcnt(7)
	ds_write_b32 v146, v164
	s_waitcnt vmcnt(6)
	ds_write_b32 v148, v165
	s_waitcnt vmcnt(5)
	ds_write_b32 v150, v166
	s_waitcnt vmcnt(4)
	ds_write_b32 v152, v167
	s_waitcnt vmcnt(3)
	ds_write_b32 v154, v168
	s_waitcnt vmcnt(2)
	ds_write_b32 v156, v169
	s_waitcnt vmcnt(1)
	ds_write_b32 v158, v170
	s_waitcnt vmcnt(0)
	ds_write_b32 v160, v171
	s_add_i32 s5, s5, 16
	s_add_i32 s4, s4, 16
	s_add_i32 s13, s13, -16
	s_add_i32 s13, s13, -16
	s_cmp_lg_u32 s13, 0
	s_waitcnt lgkmcnt(0)
	ds_read2_b32 v[54:55], v5 offset1:8
	ds_read2_b32 v[58:59], v5 offset0:33 offset1:41
	ds_read2_b32 v[60:61], v5 offset0:66 offset1:74
	ds_read2_b32 v[62:63], v5 offset0:99 offset1:107
	ds_read2_b32 v[64:65], v5 offset0:132 offset1:140
	s_waitcnt lgkmcnt(4)
	s_waitcnt lgkmcnt(3)
	v_cvt_pk_bf16_f32 v9, v54, v58
	ds_read2_b32 v[66:67], v5 offset0:165 offset1:173
	v_mov_b32_e32 v50, v9
	s_waitcnt lgkmcnt(3)
	s_waitcnt lgkmcnt(2)
	ds_read2_b32 v[68:69], v5 offset0:198 offset1:206
	v_cvt_pk_bf16_f32 v9, v60, v62
	ds_read2_b32 v[70:71], v5 offset0:231 offset1:239
	v_mov_b32_e32 v51, v9
	s_waitcnt lgkmcnt(3)
	s_mul_i32 s4, s14, 0x300
	s_waitcnt lgkmcnt(2)
	s_mul_hi_i32 s0, s14, 0x300
	s_add_u32 s14, s49, s4
	v_cvt_pk_bf16_f32 v9, v64, v66
	s_addc_u32 s0, s50, s0
	s_ashr_i32 s13, s12, 31
	v_mov_b32_e32 v52, v9
	s_waitcnt lgkmcnt(1)
	s_lshl_b64 s[4:5], s[12:13], 1
	s_waitcnt lgkmcnt(0)
	s_add_u32 s4, s14, s4
	v_cvt_pk_bf16_f32 v9, v68, v70
	s_addc_u32 s5, s0, s5
	v_lshlrev_b32_e32 v128, 1, v6
	v_mov_b32_e32 v53, v9
	v_lshl_add_u64 v[56:57], s[4:5], 0, v[128:129]
	v_mov_b32_e32 v41, v129
	v_lshl_add_u64 v[56:57], v[56:57], 0, v[40:41]
	v_cvt_pk_bf16_f32 v9, v55, v59
	global_store_dwordx4 v[56:57], v[50:53], off
	s_movk_i32 s0, 0x1000
	v_add_co_u32_e32 v58, vcc, s0, v56
	v_mov_b32_e32 v50, v9
	v_cvt_pk_bf16_f32 v9, v61, v63
	v_mov_b32_e32 v51, v9
	v_cvt_pk_bf16_f32 v9, v65, v67
	v_mov_b32_e32 v52, v9
	v_cvt_pk_bf16_f32 v9, v69, v71
	v_mov_b32_e32 v53, v9
	ds_read2_b32 v[54:55], v5 offset0:16 offset1:24
	v_addc_co_u32_e32 v59, vcc, 0, v57, vcc
	global_store_dwordx4 v[58:59], v[50:53], off offset:2048
	ds_read2_b32 v[58:59], v5 offset0:49 offset1:57
	ds_read2_b32 v[60:61], v5 offset0:82 offset1:90
	ds_read2_b32 v[62:63], v5 offset0:115 offset1:123
	s_waitcnt lgkmcnt(3)
	s_waitcnt lgkmcnt(2)
	ds_read2_b32 v[64:65], v5 offset0:148 offset1:156
	v_cvt_pk_bf16_f32 v9, v54, v58
	ds_read2_b32 v[66:67], v5 offset0:181 offset1:189
	v_mov_b32_e32 v50, v9
	s_waitcnt lgkmcnt(3)
	s_waitcnt lgkmcnt(2)
	ds_read2_b32 v[68:69], v5 offset0:214 offset1:222
	v_cvt_pk_bf16_f32 v9, v60, v62
	ds_read2_b32 v[70:71], v5 offset0:247 offset1:255
	v_mov_b32_e32 v51, v9
	s_waitcnt lgkmcnt(3)
	s_waitcnt lgkmcnt(2)
	v_cvt_pk_bf16_f32 v9, v64, v66
	v_mov_b32_e32 v52, v9
	s_waitcnt lgkmcnt(1)
	s_waitcnt lgkmcnt(0)
	v_cvt_pk_bf16_f32 v9, v68, v70
	v_mov_b32_e32 v53, v9
	s_movk_i32 s0, 0x3000
	v_add_co_u32_e32 v72, vcc, s0, v56
	v_addc_co_u32_e32 v73, vcc, 0, v57, vcc
	v_cvt_pk_bf16_f32 v9, v55, v59
	global_store_dwordx4 v[72:73], v[50:53], off
	v_add_co_u32_e32 v54, vcc, 0x4000, v56
	s_nop 0
	v_mov_b32_e32 v50, v9
	v_cvt_pk_bf16_f32 v9, v61, v63
	v_mov_b32_e32 v51, v9
	v_cvt_pk_bf16_f32 v9, v65, v67
	v_mov_b32_e32 v52, v9
	v_cvt_pk_bf16_f32 v9, v69, v71
	v_mov_b32_e32 v53, v9
	v_addc_co_u32_e32 v55, vcc, 0, v57, vcc
	global_store_dwordx4 v[54:55], v[50:53], off offset:2048
	s_waitcnt lgkmcnt(0)
	s_mov_b32 s0, s1
	s_andn2_b64 vcc, exec, s[10:11]
	s_mov_b64 s[10:11], -1
	s_cbranch_vccnz .LBB0_744

.LBB0_738:
	s_lshl_b32 s22, s5, 1
	s_lshl_b32 s23, s13, 1
	v_or_b32_e32 v7, s22, v1
	v_or_b32_e32 v9, s23, v0
	s_add_i32 s24, s22, 4
	s_add_i32 s25, s23, 4
	s_add_i32 s26, s22, 8
	s_add_i32 s27, s23, 8
	s_add_i32 s30, s22, 12
	s_add_i32 s36, s23, 12
	s_add_i32 s37, s22, 16
	s_add_i32 s40, s23, 16
	s_add_i32 s41, s22, 20
	s_add_i32 s42, s23, 20
	s_add_i32 s43, s22, 24
	s_add_i32 s52, s23, 24
	s_add_i32 s22, s22, 28
	s_add_i32 s23, s23, 28
	v_add_u32_e32 v54, s12, v9
	v_or_b32_e32 v11, s24, v1
	v_or_b32_e32 v13, s25, v0
	v_or_b32_e32 v15, s26, v1
	v_or_b32_e32 v19, s27, v0
	v_or_b32_e32 v41, s30, v1
	v_or_b32_e32 v43, s36, v0
	v_or_b32_e32 v45, s37, v1
	v_or_b32_e32 v47, s40, v0
	v_or_b32_e32 v49, s41, v1
	v_or_b32_e32 v82, s42, v0
	v_or_b32_e32 v86, s43, v1
	v_or_b32_e32 v87, s52, v0
	v_or_b32_e32 v88, s22, v1
	v_or_b32_e32 v89, s23, v0
	v_add_u32_e32 v52, s4, v7
	v_ashrrev_i32_e32 v55, 31, v54
	v_add_u32_e32 v56, s4, v11
	v_add_u32_e32 v58, s12, v13
	v_add_u32_e32 v60, s4, v15
	v_add_u32_e32 v62, s12, v19
	v_add_u32_e32 v64, s4, v41
	v_add_u32_e32 v66, s12, v43
	v_add_u32_e32 v68, s4, v45
	v_add_u32_e32 v70, s12, v47
	v_add_u32_e32 v72, s4, v49
	v_add_u32_e32 v74, s12, v82
	v_add_u32_e32 v76, s4, v86
	v_add_u32_e32 v78, s12, v87
	v_add_u32_e32 v80, s4, v88
	v_add_u32_e32 v84, s12, v89
	v_ashrrev_i32_e32 v53, 31, v52
	v_lshlrev_b64 v[54:55], 13, v[54:55]
	v_ashrrev_i32_e32 v59, 31, v58
	v_ashrrev_i32_e32 v57, 31, v56
	v_ashrrev_i32_e32 v63, 31, v62
	v_ashrrev_i32_e32 v61, 31, v60
	v_ashrrev_i32_e32 v67, 31, v66
	v_ashrrev_i32_e32 v65, 31, v64
	v_ashrrev_i32_e32 v71, 31, v70
	v_ashrrev_i32_e32 v69, 31, v68
	v_ashrrev_i32_e32 v75, 31, v74
	v_ashrrev_i32_e32 v73, 31, v72
	v_ashrrev_i32_e32 v79, 31, v78
	v_ashrrev_i32_e32 v77, 31, v76
	v_ashrrev_i32_e32 v85, 31, v84
	v_ashrrev_i32_e32 v81, 31, v80
	v_lshlrev_b64 v[52:53], 13, v[52:53]
	v_lshl_add_u64 v[54:55], v[50:51], 0, v[54:55]
	v_lshlrev_b64 v[56:57], 13, v[56:57]
	v_lshlrev_b64 v[58:59], 13, v[58:59]
	v_lshlrev_b64 v[60:61], 13, v[60:61]
	v_lshlrev_b64 v[62:63], 13, v[62:63]
	v_lshlrev_b64 v[64:65], 13, v[64:65]
	v_lshlrev_b64 v[66:67], 13, v[66:67]
	v_lshlrev_b64 v[68:69], 13, v[68:69]
	v_lshlrev_b64 v[70:71], 13, v[70:71]
	v_lshlrev_b64 v[72:73], 13, v[72:73]
	v_lshlrev_b64 v[74:75], 13, v[74:75]
	v_lshlrev_b64 v[76:77], 13, v[76:77]
	v_lshlrev_b64 v[78:79], 13, v[78:79]
	v_lshlrev_b64 v[80:81], 13, v[80:81]
	v_lshlrev_b64 v[84:85], 13, v[84:85]
	v_lshl_add_u64 v[52:53], v[50:51], 0, v[52:53]
	v_lshl_add_u64 v[58:59], v[50:51], 0, v[58:59]
	v_lshl_add_u64 v[56:57], v[50:51], 0, v[56:57]
	v_lshl_add_u64 v[62:63], v[50:51], 0, v[62:63]
	v_lshl_add_u64 v[60:61], v[50:51], 0, v[60:61]
	v_lshl_add_u64 v[66:67], v[50:51], 0, v[66:67]
	v_lshl_add_u64 v[64:65], v[50:51], 0, v[64:65]
	v_lshl_add_u64 v[70:71], v[50:51], 0, v[70:71]
	v_lshl_add_u64 v[68:69], v[50:51], 0, v[68:69]
	v_lshl_add_u64 v[74:75], v[50:51], 0, v[74:75]
	v_lshl_add_u64 v[72:73], v[50:51], 0, v[72:73]
	v_lshl_add_u64 v[78:79], v[50:51], 0, v[78:79]
	v_lshl_add_u64 v[76:77], v[50:51], 0, v[76:77]
	v_lshl_add_u64 v[84:85], v[50:51], 0, v[84:85]
	v_lshl_add_u64 v[80:81], v[50:51], 0, v[80:81]
	global_load_dword v90, v[54:55], off
	global_load_dword v91, v[52:53], off
	global_load_dword v92, v[58:59], off
	global_load_dword v93, v[56:57], off
	global_load_dword v94, v[62:63], off
	global_load_dword v95, v[60:61], off
	global_load_dword v96, v[66:67], off
	global_load_dword v97, v[64:65], off
	global_load_dword v98, v[70:71], off
	global_load_dword v99, v[68:69], off
	global_load_dword v100, v[74:75], off
	global_load_dword v101, v[72:73], off
	global_load_dword v102, v[78:79], off
	global_load_dword v103, v[76:77], off
	global_load_dword v104, v[84:85], off
	global_load_dword v105, v[80:81], off
	s_add_i32 s13, s13, 16
	s_add_i32 s5, s5, 16
	s_lshl_b32 s22, s5, 1
	s_lshl_b32 s23, s13, 1
	v_or_b32_e32 v106, s22, v1
	v_or_b32_e32 v107, s23, v0
	s_add_i32 s24, s22, 4
	s_add_i32 s25, s23, 4
	s_add_i32 s26, s22, 8
	s_add_i32 s27, s23, 8
	s_add_i32 s30, s22, 12
	s_add_i32 s36, s23, 12
	s_add_i32 s37, s22, 16
	s_add_i32 s40, s23, 16
	s_add_i32 s41, s22, 20
	s_add_i32 s42, s23, 20
	s_add_i32 s43, s22, 24
	s_add_i32 s52, s23, 24
	s_add_i32 s22, s22, 28
	s_add_i32 s23, s23, 28
	v_add_u32_e32 v132, s12, v107
	v_or_b32_e32 v108, s24, v1
	v_or_b32_e32 v109, s25, v0
	v_or_b32_e32 v110, s26, v1
	v_or_b32_e32 v111, s27, v0
	v_or_b32_e32 v112, s30, v1
	v_or_b32_e32 v113, s36, v0
	v_or_b32_e32 v114, s37, v1
	v_or_b32_e32 v115, s40, v0
	v_or_b32_e32 v116, s41, v1
	v_or_b32_e32 v117, s42, v0
	v_or_b32_e32 v118, s43, v1
	v_or_b32_e32 v119, s52, v0
	v_or_b32_e32 v120, s22, v1
	v_or_b32_e32 v121, s23, v0
	v_add_u32_e32 v130, s4, v106
	v_ashrrev_i32_e32 v133, 31, v132
	v_add_u32_e32 v134, s4, v108
	v_add_u32_e32 v136, s12, v109
	v_add_u32_e32 v138, s4, v110
	v_add_u32_e32 v140, s12, v111
	v_add_u32_e32 v142, s4, v112
	v_add_u32_e32 v144, s12, v113
	v_add_u32_e32 v146, s4, v114
	v_add_u32_e32 v148, s12, v115
	v_add_u32_e32 v150, s4, v116
	v_add_u32_e32 v152, s12, v117
	v_add_u32_e32 v154, s4, v118
	v_add_u32_e32 v156, s12, v119
	v_add_u32_e32 v158, s4, v120
	v_add_u32_e32 v160, s12, v121
	v_ashrrev_i32_e32 v131, 31, v130
	v_lshlrev_b64 v[132:133], 13, v[132:133]
	v_ashrrev_i32_e32 v137, 31, v136
	v_ashrrev_i32_e32 v135, 31, v134
	v_ashrrev_i32_e32 v141, 31, v140
	v_ashrrev_i32_e32 v139, 31, v138
	v_ashrrev_i32_e32 v145, 31, v144
	v_ashrrev_i32_e32 v143, 31, v142
	v_ashrrev_i32_e32 v149, 31, v148
	v_ashrrev_i32_e32 v147, 31, v146
	v_ashrrev_i32_e32 v153, 31, v152
	v_ashrrev_i32_e32 v151, 31, v150
	v_ashrrev_i32_e32 v157, 31, v156
	v_ashrrev_i32_e32 v155, 31, v154
	v_ashrrev_i32_e32 v161, 31, v160
	v_ashrrev_i32_e32 v159, 31, v158
	v_lshlrev_b64 v[130:131], 13, v[130:131]
	v_lshl_add_u64 v[132:133], v[50:51], 0, v[132:133]
	v_lshlrev_b64 v[134:135], 13, v[134:135]
	v_lshlrev_b64 v[136:137], 13, v[136:137]
	v_lshlrev_b64 v[138:139], 13, v[138:139]
	v_lshlrev_b64 v[140:141], 13, v[140:141]
	v_lshlrev_b64 v[142:143], 13, v[142:143]
	v_lshlrev_b64 v[144:145], 13, v[144:145]
	v_lshlrev_b64 v[146:147], 13, v[146:147]
	v_lshlrev_b64 v[148:149], 13, v[148:149]
	v_lshlrev_b64 v[150:151], 13, v[150:151]
	v_lshlrev_b64 v[152:153], 13, v[152:153]
	v_lshlrev_b64 v[154:155], 13, v[154:155]
	v_lshlrev_b64 v[156:157], 13, v[156:157]
	v_lshlrev_b64 v[158:159], 13, v[158:159]
	v_lshlrev_b64 v[160:161], 13, v[160:161]
	v_lshl_add_u64 v[130:131], v[50:51], 0, v[130:131]
	v_lshl_add_u64 v[136:137], v[50:51], 0, v[136:137]
	v_lshl_add_u64 v[134:135], v[50:51], 0, v[134:135]
	v_lshl_add_u64 v[140:141], v[50:51], 0, v[140:141]
	v_lshl_add_u64 v[138:139], v[50:51], 0, v[138:139]
	v_lshl_add_u64 v[144:145], v[50:51], 0, v[144:145]
	v_lshl_add_u64 v[142:143], v[50:51], 0, v[142:143]
	v_lshl_add_u64 v[148:149], v[50:51], 0, v[148:149]
	v_lshl_add_u64 v[146:147], v[50:51], 0, v[146:147]
	v_lshl_add_u64 v[152:153], v[50:51], 0, v[152:153]
	v_lshl_add_u64 v[150:151], v[50:51], 0, v[150:151]
	v_lshl_add_u64 v[156:157], v[50:51], 0, v[156:157]
	v_lshl_add_u64 v[154:155], v[50:51], 0, v[154:155]
	v_lshl_add_u64 v[160:161], v[50:51], 0, v[160:161]
	v_lshl_add_u64 v[158:159], v[50:51], 0, v[158:159]
	global_load_dword v122, v[132:133], off
	global_load_dword v123, v[130:131], off
	global_load_dword v124, v[136:137], off
	global_load_dword v125, v[134:135], off
	global_load_dword v126, v[140:141], off
	global_load_dword v127, v[138:139], off
	global_load_dword v162, v[144:145], off
	global_load_dword v163, v[142:143], off
	global_load_dword v164, v[148:149], off
	global_load_dword v165, v[146:147], off
	global_load_dword v166, v[152:153], off
	global_load_dword v167, v[150:151], off
	global_load_dword v168, v[156:157], off
	global_load_dword v169, v[154:155], off
	global_load_dword v170, v[160:161], off
	global_load_dword v171, v[158:159], off
	v_mad_u64_u32 v[52:53], s[22:23], v9, s78, v[4:5]
	v_mad_u64_u32 v[54:55], s[22:23], v7, s78, v[4:5]
	v_mad_u64_u32 v[56:57], s[22:23], v13, s78, v[4:5]
	v_mad_u64_u32 v[58:59], s[22:23], v11, s78, v[4:5]
	v_mad_u64_u32 v[60:61], s[22:23], v19, s78, v[4:5]
	v_mad_u64_u32 v[62:63], s[22:23], v15, s78, v[4:5]
	v_mad_u64_u32 v[64:65], s[22:23], v43, s78, v[4:5]
	v_mad_u64_u32 v[66:67], s[22:23], v41, s78, v[4:5]
	v_mad_u64_u32 v[68:69], s[22:23], v47, s78, v[4:5]
	v_mad_u64_u32 v[70:71], s[22:23], v45, s78, v[4:5]
	v_mad_u64_u32 v[72:73], s[22:23], v82, s78, v[4:5]
	v_mad_u64_u32 v[74:75], s[22:23], v49, s78, v[4:5]
	v_mad_u64_u32 v[76:77], s[22:23], v87, s78, v[4:5]
	v_mad_u64_u32 v[78:79], s[22:23], v86, s78, v[4:5]
	v_mad_u64_u32 v[80:81], s[22:23], v89, s78, v[4:5]
	v_mad_u64_u32 v[84:85], s[22:23], v88, s78, v[4:5]
	s_waitcnt vmcnt(31)
	ds_write_b32 v52, v90
	s_waitcnt vmcnt(30)
	ds_write_b32 v54, v91
	s_waitcnt vmcnt(29)
	ds_write_b32 v56, v92
	s_waitcnt vmcnt(28)
	ds_write_b32 v58, v93
	s_waitcnt vmcnt(27)
	ds_write_b32 v60, v94
	s_waitcnt vmcnt(26)
	ds_write_b32 v62, v95
	s_waitcnt vmcnt(25)
	ds_write_b32 v64, v96
	s_waitcnt vmcnt(24)
	ds_write_b32 v66, v97
	s_waitcnt vmcnt(23)
	ds_write_b32 v68, v98
	s_waitcnt vmcnt(22)
	ds_write_b32 v70, v99
	s_waitcnt vmcnt(21)
	ds_write_b32 v72, v100
	s_waitcnt vmcnt(20)
	ds_write_b32 v74, v101
	s_waitcnt vmcnt(19)
	ds_write_b32 v76, v102
	s_waitcnt vmcnt(18)
	ds_write_b32 v78, v103
	s_waitcnt vmcnt(17)
	ds_write_b32 v80, v104
	s_waitcnt vmcnt(16)
	ds_write_b32 v84, v105
	v_mad_u64_u32 v[130:131], s[22:23], v107, s78, v[4:5]
	v_mad_u64_u32 v[132:133], s[22:23], v106, s78, v[4:5]
	v_mad_u64_u32 v[134:135], s[22:23], v109, s78, v[4:5]
	v_mad_u64_u32 v[136:137], s[22:23], v108, s78, v[4:5]
	v_mad_u64_u32 v[138:139], s[22:23], v111, s78, v[4:5]
	v_mad_u64_u32 v[140:141], s[22:23], v110, s78, v[4:5]
	v_mad_u64_u32 v[142:143], s[22:23], v113, s78, v[4:5]
	v_mad_u64_u32 v[144:145], s[22:23], v112, s78, v[4:5]
	v_mad_u64_u32 v[146:147], s[22:23], v115, s78, v[4:5]
	v_mad_u64_u32 v[148:149], s[22:23], v114, s78, v[4:5]
	v_mad_u64_u32 v[150:151], s[22:23], v117, s78, v[4:5]
	v_mad_u64_u32 v[152:153], s[22:23], v116, s78, v[4:5]
	v_mad_u64_u32 v[154:155], s[22:23], v119, s78, v[4:5]
	v_mad_u64_u32 v[156:157], s[22:23], v118, s78, v[4:5]
	v_mad_u64_u32 v[158:159], s[22:23], v121, s78, v[4:5]
	v_mad_u64_u32 v[160:161], s[22:23], v120, s78, v[4:5]
	s_waitcnt vmcnt(15)
	ds_write_b32 v130, v122
	s_waitcnt vmcnt(14)
	ds_write_b32 v132, v123
	s_waitcnt vmcnt(13)
	ds_write_b32 v134, v124
	s_waitcnt vmcnt(12)
	ds_write_b32 v136, v125
	s_waitcnt vmcnt(11)
	ds_write_b32 v138, v126
	s_waitcnt vmcnt(10)
	ds_write_b32 v140, v127
	s_waitcnt vmcnt(9)
	ds_write_b32 v142, v162
	s_waitcnt vmcnt(8)
	ds_write_b32 v144, v163
	s_waitcnt vmcnt(7)
	ds_write_b32 v146, v164
	s_waitcnt vmcnt(6)
	ds_write_b32 v148, v165
	s_waitcnt vmcnt(5)
	ds_write_b32 v150, v166
	s_waitcnt vmcnt(4)
	ds_write_b32 v152, v167
	s_waitcnt vmcnt(3)
	ds_write_b32 v154, v168
	s_waitcnt vmcnt(2)
	ds_write_b32 v156, v169
	s_waitcnt vmcnt(1)
	ds_write_b32 v158, v170
	s_waitcnt vmcnt(0)
	ds_write_b32 v160, v171
	s_add_i32 s13, s13, 16
	s_add_i32 s5, s5, 16
	s_add_i32 s15, s15, -16
	s_add_i32 s15, s15, -16
	s_cmp_lg_u32 s15, 0
	s_bfe_i32 s4, s1, 0x80000
	s_bfe_u32 s4, s4, 0x3000c
	s_waitcnt lgkmcnt(0)
	s_add_i32 s1, s1, s4
	s_bfe_u32 s4, s14, 0x80017
	ds_read2_b32 v[54:55], v5 offset1:8
	s_bfe_i32 s1, s1, 0x80000
	s_add_i32 s4, s14, s4
	ds_read2_b32 v[58:59], v5 offset0:33 offset1:41
	s_sext_i32_i16 s1, s1
	s_and_b32 s4, s4, 0xff00
	s_sub_i32 s4, s14, s4
	s_lshl_b32 s1, s1, 4
	ds_read2_b32 v[60:61], v5 offset0:66 offset1:74
	s_sext_i32_i16 s4, s4
	s_and_b32 s1, s1, 0xffffff80
	ds_read2_b32 v[62:63], v5 offset0:99 offset1:107
	s_add_i32 s1, s1, s4
	s_waitcnt lgkmcnt(3)
	s_add_i32 s5, s1, 0xffffff80
	s_waitcnt lgkmcnt(2)
	ds_read2_b32 v[64:65], v5 offset0:132 offset1:140
	s_cmpk_lt_i32 s4, 0x80
	v_cvt_pk_bf16_f32 v9, v54, v58
	ds_read2_b32 v[66:67], v5 offset0:165 offset1:173
	s_cselect_b32 s4, s1, s5
	s_mov_b32 s1, 0x23a0000
	v_mov_b32_e32 v50, v9
	s_waitcnt lgkmcnt(3)
	s_cselect_b32 s1, s1, 0x2420000
	s_ashr_i32 s5, s4, 31
	s_waitcnt lgkmcnt(2)
	ds_read2_b32 v[68:69], v5 offset0:198 offset1:206
	s_lshl_b64 s[4:5], s[4:5], 9
	v_cvt_pk_bf16_f32 v9, v60, v62
	ds_read2_b32 v[70:71], v5 offset0:231 offset1:239
	s_add_u32 s1, s17, s1
	v_mov_b32_e32 v51, v9
	s_waitcnt lgkmcnt(3)
	s_addc_u32 s13, s29, 0
	s_waitcnt lgkmcnt(2)
	s_add_u32 s1, s1, s4
	v_cvt_pk_bf16_f32 v9, v64, v66
	s_addc_u32 s14, s13, s5
	s_ashr_i32 s13, s12, 31
	v_mov_b32_e32 v52, v9
	s_waitcnt lgkmcnt(1)
	s_lshl_b64 s[4:5], s[12:13], 1
	s_waitcnt lgkmcnt(0)
	s_add_u32 s4, s1, s4
	v_cvt_pk_bf16_f32 v9, v68, v70
	s_addc_u32 s5, s14, s5
	v_lshlrev_b32_e32 v128, 1, v6
	v_mov_b32_e32 v53, v9
	v_lshl_add_u64 v[56:57], s[4:5], 0, v[128:129]
	v_mov_b32_e32 v43, v129
	v_lshl_add_u64 v[72:73], v[56:57], 0, v[42:43]
	v_cvt_pk_bf16_f32 v9, v55, v59
	global_store_dwordx4 v[72:73], v[50:53], off
	v_mov_b32_e32 v45, v129
	ds_read2_b32 v[54:55], v5 offset0:16 offset1:24
	v_mov_b32_e32 v50, v9
	v_cvt_pk_bf16_f32 v9, v61, v63
	v_mov_b32_e32 v51, v9
	v_cvt_pk_bf16_f32 v9, v65, v67
	v_mov_b32_e32 v52, v9
	v_cvt_pk_bf16_f32 v9, v69, v71
	v_mov_b32_e32 v53, v9
	v_lshl_add_u64 v[58:59], v[56:57], 0, v[44:45]
	global_store_dwordx4 v[58:59], v[50:53], off
	ds_read2_b32 v[58:59], v5 offset0:49 offset1:57
	ds_read2_b32 v[60:61], v5 offset0:82 offset1:90
	ds_read2_b32 v[62:63], v5 offset0:115 offset1:123
	s_waitcnt lgkmcnt(3)
	s_waitcnt lgkmcnt(2)
	ds_read2_b32 v[64:65], v5 offset0:148 offset1:156
	v_cvt_pk_bf16_f32 v9, v54, v58
	ds_read2_b32 v[66:67], v5 offset0:181 offset1:189
	v_mov_b32_e32 v50, v9
	s_waitcnt lgkmcnt(3)
	s_waitcnt lgkmcnt(2)
	ds_read2_b32 v[68:69], v5 offset0:214 offset1:222
	v_cvt_pk_bf16_f32 v9, v60, v62
	ds_read2_b32 v[70:71], v5 offset0:247 offset1:255
	v_mov_b32_e32 v51, v9
	s_waitcnt lgkmcnt(3)
	s_waitcnt lgkmcnt(2)
	v_cvt_pk_bf16_f32 v9, v64, v66
	v_mov_b32_e32 v52, v9
	s_waitcnt lgkmcnt(1)
	s_waitcnt lgkmcnt(0)
	v_cvt_pk_bf16_f32 v9, v68, v70
	v_mov_b32_e32 v53, v9
	v_mov_b32_e32 v47, v129
	v_lshl_add_u64 v[72:73], v[56:57], 0, v[46:47]
	v_cvt_pk_bf16_f32 v9, v55, v59
	global_store_dwordx4 v[72:73], v[50:53], off
	v_mov_b32_e32 v49, v129
	v_lshl_add_u64 v[54:55], v[56:57], 0, v[48:49]
	v_mov_b32_e32 v50, v9
	v_cvt_pk_bf16_f32 v9, v61, v63
	v_mov_b32_e32 v51, v9
	v_cvt_pk_bf16_f32 v9, v65, v67
	v_mov_b32_e32 v52, v9
	v_cvt_pk_bf16_f32 v9, v69, v71
	v_mov_b32_e32 v53, v9
	global_store_dwordx4 v[54:55], v[50:53], off
	s_waitcnt lgkmcnt(0)
	s_mov_b32 s1, s0
	s_andn2_b64 vcc, exec, s[10:11]
	s_mov_b64 s[10:11], -1
	s_cbranch_vccnz .LBB0_744

.LBB0_742:
	s_lshl_b32 s11, s0, 1
	s_lshl_b32 s14, s4, 1
	v_or_b32_e32 v7, s11, v1
	v_or_b32_e32 v9, s14, v0
	s_add_i32 s15, s11, 4
	s_add_i32 s22, s14, 4
	s_add_i32 s23, s11, 8
	s_add_i32 s24, s14, 8
	s_add_i32 s25, s11, 12
	s_add_i32 s26, s14, 12
	s_add_i32 s27, s11, 16
	s_add_i32 s30, s14, 16
	s_add_i32 s36, s11, 20
	s_add_i32 s37, s14, 20
	s_add_i32 s40, s11, 24
	s_add_i32 s41, s14, 24
	s_add_i32 s11, s11, 28
	s_add_i32 s14, s14, 28
	v_add_u32_e32 v54, s10, v9
	v_or_b32_e32 v11, s15, v1
	v_or_b32_e32 v13, s22, v0
	v_or_b32_e32 v15, s23, v1
	v_or_b32_e32 v19, s24, v0
	v_or_b32_e32 v41, s25, v1
	v_or_b32_e32 v43, s26, v0
	v_or_b32_e32 v45, s27, v1
	v_or_b32_e32 v47, s30, v0
	v_or_b32_e32 v49, s36, v1
	v_or_b32_e32 v82, s37, v0
	v_or_b32_e32 v86, s40, v1
	v_or_b32_e32 v87, s41, v0
	v_or_b32_e32 v88, s11, v1
	v_or_b32_e32 v89, s14, v0
	v_add_u32_e32 v52, s1, v7
	v_ashrrev_i32_e32 v55, 31, v54
	v_add_u32_e32 v56, s1, v11
	v_add_u32_e32 v58, s10, v13
	v_add_u32_e32 v60, s1, v15
	v_add_u32_e32 v62, s10, v19
	v_add_u32_e32 v64, s1, v41
	v_add_u32_e32 v66, s10, v43
	v_add_u32_e32 v68, s1, v45
	v_add_u32_e32 v70, s10, v47
	v_add_u32_e32 v72, s1, v49
	v_add_u32_e32 v74, s10, v82
	v_add_u32_e32 v76, s1, v86
	v_add_u32_e32 v78, s10, v87
	v_add_u32_e32 v80, s1, v88
	v_add_u32_e32 v84, s10, v89
	v_ashrrev_i32_e32 v53, 31, v52
	v_lshlrev_b64 v[54:55], 12, v[54:55]
	v_ashrrev_i32_e32 v59, 31, v58
	v_ashrrev_i32_e32 v57, 31, v56
	v_ashrrev_i32_e32 v63, 31, v62
	v_ashrrev_i32_e32 v61, 31, v60
	v_ashrrev_i32_e32 v67, 31, v66
	v_ashrrev_i32_e32 v65, 31, v64
	v_ashrrev_i32_e32 v71, 31, v70
	v_ashrrev_i32_e32 v69, 31, v68
	v_ashrrev_i32_e32 v75, 31, v74
	v_ashrrev_i32_e32 v73, 31, v72
	v_ashrrev_i32_e32 v79, 31, v78
	v_ashrrev_i32_e32 v77, 31, v76
	v_ashrrev_i32_e32 v85, 31, v84
	v_ashrrev_i32_e32 v81, 31, v80
	v_lshlrev_b64 v[52:53], 12, v[52:53]
	v_lshl_add_u64 v[54:55], v[50:51], 0, v[54:55]
	v_lshlrev_b64 v[56:57], 12, v[56:57]
	v_lshlrev_b64 v[58:59], 12, v[58:59]
	v_lshlrev_b64 v[60:61], 12, v[60:61]
	v_lshlrev_b64 v[62:63], 12, v[62:63]
	v_lshlrev_b64 v[64:65], 12, v[64:65]
	v_lshlrev_b64 v[66:67], 12, v[66:67]
	v_lshlrev_b64 v[68:69], 12, v[68:69]
	v_lshlrev_b64 v[70:71], 12, v[70:71]
	v_lshlrev_b64 v[72:73], 12, v[72:73]
	v_lshlrev_b64 v[74:75], 12, v[74:75]
	v_lshlrev_b64 v[76:77], 12, v[76:77]
	v_lshlrev_b64 v[78:79], 12, v[78:79]
	v_lshlrev_b64 v[80:81], 12, v[80:81]
	v_lshlrev_b64 v[84:85], 12, v[84:85]
	v_lshl_add_u64 v[52:53], v[50:51], 0, v[52:53]
	v_lshl_add_u64 v[58:59], v[50:51], 0, v[58:59]
	v_lshl_add_u64 v[56:57], v[50:51], 0, v[56:57]
	v_lshl_add_u64 v[62:63], v[50:51], 0, v[62:63]
	v_lshl_add_u64 v[60:61], v[50:51], 0, v[60:61]
	v_lshl_add_u64 v[66:67], v[50:51], 0, v[66:67]
	v_lshl_add_u64 v[64:65], v[50:51], 0, v[64:65]
	v_lshl_add_u64 v[70:71], v[50:51], 0, v[70:71]
	v_lshl_add_u64 v[68:69], v[50:51], 0, v[68:69]
	v_lshl_add_u64 v[74:75], v[50:51], 0, v[74:75]
	v_lshl_add_u64 v[72:73], v[50:51], 0, v[72:73]
	v_lshl_add_u64 v[78:79], v[50:51], 0, v[78:79]
	v_lshl_add_u64 v[76:77], v[50:51], 0, v[76:77]
	v_lshl_add_u64 v[84:85], v[50:51], 0, v[84:85]
	v_lshl_add_u64 v[80:81], v[50:51], 0, v[80:81]
	global_load_dword v90, v[54:55], off
	global_load_dword v91, v[52:53], off
	global_load_dword v92, v[58:59], off
	global_load_dword v93, v[56:57], off
	global_load_dword v94, v[62:63], off
	global_load_dword v95, v[60:61], off
	global_load_dword v96, v[66:67], off
	global_load_dword v97, v[64:65], off
	global_load_dword v98, v[70:71], off
	global_load_dword v99, v[68:69], off
	global_load_dword v100, v[74:75], off
	global_load_dword v101, v[72:73], off
	global_load_dword v102, v[78:79], off
	global_load_dword v103, v[76:77], off
	global_load_dword v104, v[84:85], off
	global_load_dword v105, v[80:81], off
	s_add_i32 s4, s4, 16
	s_add_i32 s0, s0, 16
	s_lshl_b32 s11, s0, 1
	s_lshl_b32 s14, s4, 1
	v_or_b32_e32 v106, s11, v1
	v_or_b32_e32 v107, s14, v0
	s_add_i32 s15, s11, 4
	s_add_i32 s22, s14, 4
	s_add_i32 s23, s11, 8
	s_add_i32 s24, s14, 8
	s_add_i32 s25, s11, 12
	s_add_i32 s26, s14, 12
	s_add_i32 s27, s11, 16
	s_add_i32 s30, s14, 16
	s_add_i32 s36, s11, 20
	s_add_i32 s37, s14, 20
	s_add_i32 s40, s11, 24
	s_add_i32 s41, s14, 24
	s_add_i32 s11, s11, 28
	s_add_i32 s14, s14, 28
	v_add_u32_e32 v132, s10, v107
	v_or_b32_e32 v108, s15, v1
	v_or_b32_e32 v109, s22, v0
	v_or_b32_e32 v110, s23, v1
	v_or_b32_e32 v111, s24, v0
	v_or_b32_e32 v112, s25, v1
	v_or_b32_e32 v113, s26, v0
	v_or_b32_e32 v114, s27, v1
	v_or_b32_e32 v115, s30, v0
	v_or_b32_e32 v116, s36, v1
	v_or_b32_e32 v117, s37, v0
	v_or_b32_e32 v118, s40, v1
	v_or_b32_e32 v119, s41, v0
	v_or_b32_e32 v120, s11, v1
	v_or_b32_e32 v121, s14, v0
	v_add_u32_e32 v130, s1, v106
	v_ashrrev_i32_e32 v133, 31, v132
	v_add_u32_e32 v134, s1, v108
	v_add_u32_e32 v136, s10, v109
	v_add_u32_e32 v138, s1, v110
	v_add_u32_e32 v140, s10, v111
	v_add_u32_e32 v142, s1, v112
	v_add_u32_e32 v144, s10, v113
	v_add_u32_e32 v146, s1, v114
	v_add_u32_e32 v148, s10, v115
	v_add_u32_e32 v150, s1, v116
	v_add_u32_e32 v152, s10, v117
	v_add_u32_e32 v154, s1, v118
	v_add_u32_e32 v156, s10, v119
	v_add_u32_e32 v158, s1, v120
	v_add_u32_e32 v160, s10, v121
	v_ashrrev_i32_e32 v131, 31, v130
	v_lshlrev_b64 v[132:133], 12, v[132:133]
	v_ashrrev_i32_e32 v137, 31, v136
	v_ashrrev_i32_e32 v135, 31, v134
	v_ashrrev_i32_e32 v141, 31, v140
	v_ashrrev_i32_e32 v139, 31, v138
	v_ashrrev_i32_e32 v145, 31, v144
	v_ashrrev_i32_e32 v143, 31, v142
	v_ashrrev_i32_e32 v149, 31, v148
	v_ashrrev_i32_e32 v147, 31, v146
	v_ashrrev_i32_e32 v153, 31, v152
	v_ashrrev_i32_e32 v151, 31, v150
	v_ashrrev_i32_e32 v157, 31, v156
	v_ashrrev_i32_e32 v155, 31, v154
	v_ashrrev_i32_e32 v161, 31, v160
	v_ashrrev_i32_e32 v159, 31, v158
	v_lshlrev_b64 v[130:131], 12, v[130:131]
	v_lshl_add_u64 v[132:133], v[50:51], 0, v[132:133]
	v_lshlrev_b64 v[134:135], 12, v[134:135]
	v_lshlrev_b64 v[136:137], 12, v[136:137]
	v_lshlrev_b64 v[138:139], 12, v[138:139]
	v_lshlrev_b64 v[140:141], 12, v[140:141]
	v_lshlrev_b64 v[142:143], 12, v[142:143]
	v_lshlrev_b64 v[144:145], 12, v[144:145]
	v_lshlrev_b64 v[146:147], 12, v[146:147]
	v_lshlrev_b64 v[148:149], 12, v[148:149]
	v_lshlrev_b64 v[150:151], 12, v[150:151]
	v_lshlrev_b64 v[152:153], 12, v[152:153]
	v_lshlrev_b64 v[154:155], 12, v[154:155]
	v_lshlrev_b64 v[156:157], 12, v[156:157]
	v_lshlrev_b64 v[158:159], 12, v[158:159]
	v_lshlrev_b64 v[160:161], 12, v[160:161]
	v_lshl_add_u64 v[130:131], v[50:51], 0, v[130:131]
	v_lshl_add_u64 v[136:137], v[50:51], 0, v[136:137]
	v_lshl_add_u64 v[134:135], v[50:51], 0, v[134:135]
	v_lshl_add_u64 v[140:141], v[50:51], 0, v[140:141]
	v_lshl_add_u64 v[138:139], v[50:51], 0, v[138:139]
	v_lshl_add_u64 v[144:145], v[50:51], 0, v[144:145]
	v_lshl_add_u64 v[142:143], v[50:51], 0, v[142:143]
	v_lshl_add_u64 v[148:149], v[50:51], 0, v[148:149]
	v_lshl_add_u64 v[146:147], v[50:51], 0, v[146:147]
	v_lshl_add_u64 v[152:153], v[50:51], 0, v[152:153]
	v_lshl_add_u64 v[150:151], v[50:51], 0, v[150:151]
	v_lshl_add_u64 v[156:157], v[50:51], 0, v[156:157]
	v_lshl_add_u64 v[154:155], v[50:51], 0, v[154:155]
	v_lshl_add_u64 v[160:161], v[50:51], 0, v[160:161]
	v_lshl_add_u64 v[158:159], v[50:51], 0, v[158:159]
	global_load_dword v122, v[132:133], off
	global_load_dword v123, v[130:131], off
	global_load_dword v124, v[136:137], off
	global_load_dword v125, v[134:135], off
	global_load_dword v126, v[140:141], off
	global_load_dword v127, v[138:139], off
	global_load_dword v162, v[144:145], off
	global_load_dword v163, v[142:143], off
	global_load_dword v164, v[148:149], off
	global_load_dword v165, v[146:147], off
	global_load_dword v166, v[152:153], off
	global_load_dword v167, v[150:151], off
	global_load_dword v168, v[156:157], off
	global_load_dword v169, v[154:155], off
	global_load_dword v170, v[160:161], off
	global_load_dword v171, v[158:159], off
	v_mad_u64_u32 v[52:53], s[14:15], v9, s78, v[4:5]
	v_mad_u64_u32 v[54:55], s[14:15], v7, s78, v[4:5]
	v_mad_u64_u32 v[56:57], s[14:15], v13, s78, v[4:5]
	v_mad_u64_u32 v[58:59], s[14:15], v11, s78, v[4:5]
	v_mad_u64_u32 v[60:61], s[14:15], v19, s78, v[4:5]
	v_mad_u64_u32 v[62:63], s[14:15], v15, s78, v[4:5]
	v_mad_u64_u32 v[64:65], s[14:15], v43, s78, v[4:5]
	v_mad_u64_u32 v[66:67], s[14:15], v41, s78, v[4:5]
	v_mad_u64_u32 v[68:69], s[14:15], v47, s78, v[4:5]
	v_mad_u64_u32 v[70:71], s[14:15], v45, s78, v[4:5]
	v_mad_u64_u32 v[72:73], s[14:15], v82, s78, v[4:5]
	v_mad_u64_u32 v[74:75], s[14:15], v49, s78, v[4:5]
	v_mad_u64_u32 v[76:77], s[14:15], v87, s78, v[4:5]
	v_mad_u64_u32 v[78:79], s[14:15], v86, s78, v[4:5]
	v_mad_u64_u32 v[80:81], s[14:15], v89, s78, v[4:5]
	v_mad_u64_u32 v[84:85], s[14:15], v88, s78, v[4:5]
	s_waitcnt vmcnt(31)
	ds_write_b32 v52, v90
	s_waitcnt vmcnt(30)
	ds_write_b32 v54, v91
	s_waitcnt vmcnt(29)
	ds_write_b32 v56, v92
	s_waitcnt vmcnt(28)
	ds_write_b32 v58, v93
	s_waitcnt vmcnt(27)
	ds_write_b32 v60, v94
	s_waitcnt vmcnt(26)
	ds_write_b32 v62, v95
	s_waitcnt vmcnt(25)
	ds_write_b32 v64, v96
	s_waitcnt vmcnt(24)
	ds_write_b32 v66, v97
	s_waitcnt vmcnt(23)
	ds_write_b32 v68, v98
	s_waitcnt vmcnt(22)
	ds_write_b32 v70, v99
	s_waitcnt vmcnt(21)
	ds_write_b32 v72, v100
	s_waitcnt vmcnt(20)
	ds_write_b32 v74, v101
	s_waitcnt vmcnt(19)
	ds_write_b32 v76, v102
	s_waitcnt vmcnt(18)
	ds_write_b32 v78, v103
	s_waitcnt vmcnt(17)
	ds_write_b32 v80, v104
	s_waitcnt vmcnt(16)
	ds_write_b32 v84, v105
	v_mad_u64_u32 v[130:131], s[14:15], v107, s78, v[4:5]
	v_mad_u64_u32 v[132:133], s[14:15], v106, s78, v[4:5]
	v_mad_u64_u32 v[134:135], s[14:15], v109, s78, v[4:5]
	v_mad_u64_u32 v[136:137], s[14:15], v108, s78, v[4:5]
	v_mad_u64_u32 v[138:139], s[14:15], v111, s78, v[4:5]
	v_mad_u64_u32 v[140:141], s[14:15], v110, s78, v[4:5]
	v_mad_u64_u32 v[142:143], s[14:15], v113, s78, v[4:5]
	v_mad_u64_u32 v[144:145], s[14:15], v112, s78, v[4:5]
	v_mad_u64_u32 v[146:147], s[14:15], v115, s78, v[4:5]
	v_mad_u64_u32 v[148:149], s[14:15], v114, s78, v[4:5]
	v_mad_u64_u32 v[150:151], s[14:15], v117, s78, v[4:5]
	v_mad_u64_u32 v[152:153], s[14:15], v116, s78, v[4:5]
	v_mad_u64_u32 v[154:155], s[14:15], v119, s78, v[4:5]
	v_mad_u64_u32 v[156:157], s[14:15], v118, s78, v[4:5]
	v_mad_u64_u32 v[158:159], s[14:15], v121, s78, v[4:5]
	v_mad_u64_u32 v[160:161], s[14:15], v120, s78, v[4:5]
	s_waitcnt vmcnt(15)
	ds_write_b32 v130, v122
	s_waitcnt vmcnt(14)
	ds_write_b32 v132, v123
	s_waitcnt vmcnt(13)
	ds_write_b32 v134, v124
	s_waitcnt vmcnt(12)
	ds_write_b32 v136, v125
	s_waitcnt vmcnt(11)
	ds_write_b32 v138, v126
	s_waitcnt vmcnt(10)
	ds_write_b32 v140, v127
	s_waitcnt vmcnt(9)
	ds_write_b32 v142, v162
	s_waitcnt vmcnt(8)
	ds_write_b32 v144, v163
	s_waitcnt vmcnt(7)
	ds_write_b32 v146, v164
	s_waitcnt vmcnt(6)
	ds_write_b32 v148, v165
	s_waitcnt vmcnt(5)
	ds_write_b32 v150, v166
	s_waitcnt vmcnt(4)
	ds_write_b32 v152, v167
	s_waitcnt vmcnt(3)
	ds_write_b32 v154, v168
	s_waitcnt vmcnt(2)
	ds_write_b32 v156, v169
	s_waitcnt vmcnt(1)
	ds_write_b32 v158, v170
	s_waitcnt vmcnt(0)
	ds_write_b32 v160, v171
	s_add_i32 s4, s4, 16
	s_add_i32 s0, s0, 16
	s_add_i32 s5, s5, -16
	s_add_i32 s5, s5, -16
	s_cmp_lg_u32 s5, 0
	s_waitcnt lgkmcnt(0)
	ds_read2_b32 v[54:55], v5 offset1:8
	ds_read2_b32 v[58:59], v5 offset0:33 offset1:41
	ds_read2_b32 v[60:61], v5 offset0:66 offset1:74
	ds_read2_b32 v[62:63], v5 offset0:99 offset1:107
	ds_read2_b32 v[64:65], v5 offset0:132 offset1:140
	s_waitcnt lgkmcnt(4)
	s_waitcnt lgkmcnt(3)
	v_cvt_pk_bf16_f32 v9, v54, v58
	ds_read2_b32 v[66:67], v5 offset0:165 offset1:173
	v_mov_b32_e32 v50, v9
	s_waitcnt lgkmcnt(3)
	s_waitcnt lgkmcnt(2)
	ds_read2_b32 v[68:69], v5 offset0:198 offset1:206
	v_cvt_pk_bf16_f32 v9, v60, v62
	ds_read2_b32 v[70:71], v5 offset0:231 offset1:239
	v_mov_b32_e32 v51, v9
	s_waitcnt lgkmcnt(3)
	s_lshl_b64 s[0:1], s[12:13], 11
	s_waitcnt lgkmcnt(2)
	s_add_u32 s4, s51, s0
	v_cvt_pk_bf16_f32 v9, v64, v66
	s_addc_u32 s5, s61, s1
	s_ashr_i32 s11, s10, 31
	v_mov_b32_e32 v52, v9
	s_waitcnt lgkmcnt(1)
	s_lshl_b64 s[0:1], s[10:11], 1
	s_waitcnt lgkmcnt(0)
	s_add_u32 s0, s4, s0
	v_cvt_pk_bf16_f32 v9, v68, v70
	s_addc_u32 s1, s5, s1
	v_lshlrev_b32_e32 v128, 1, v6
	v_mov_b32_e32 v53, v9
	v_lshl_add_u64 v[56:57], s[0:1], 0, v[128:129]
	v_lshlrev_b32_e32 v128, 1, v8
	v_lshl_add_u64 v[72:73], v[56:57], 0, v[128:129]
	v_cvt_pk_bf16_f32 v9, v55, v59
	global_store_dwordx4 v[72:73], v[50:53], off
	v_lshlrev_b32_e32 v128, 1, v10
	ds_read2_b32 v[54:55], v5 offset0:16 offset1:24
	v_mov_b32_e32 v50, v9
	v_cvt_pk_bf16_f32 v9, v61, v63
	v_mov_b32_e32 v51, v9
	v_cvt_pk_bf16_f32 v9, v65, v67
	v_mov_b32_e32 v52, v9
	v_cvt_pk_bf16_f32 v9, v69, v71
	v_mov_b32_e32 v53, v9
	v_lshl_add_u64 v[58:59], v[56:57], 0, v[128:129]
	global_store_dwordx4 v[58:59], v[50:53], off
	ds_read2_b32 v[58:59], v5 offset0:49 offset1:57
	ds_read2_b32 v[60:61], v5 offset0:82 offset1:90
	ds_read2_b32 v[62:63], v5 offset0:115 offset1:123
	s_waitcnt lgkmcnt(3)
	s_waitcnt lgkmcnt(2)
	ds_read2_b32 v[64:65], v5 offset0:148 offset1:156
	v_cvt_pk_bf16_f32 v9, v54, v58
	ds_read2_b32 v[66:67], v5 offset0:181 offset1:189
	v_mov_b32_e32 v50, v9
	s_waitcnt lgkmcnt(3)
	s_waitcnt lgkmcnt(2)
	ds_read2_b32 v[68:69], v5 offset0:214 offset1:222
	v_cvt_pk_bf16_f32 v9, v60, v62
	ds_read2_b32 v[70:71], v5 offset0:247 offset1:255
	v_mov_b32_e32 v51, v9
	s_waitcnt lgkmcnt(3)
	s_waitcnt lgkmcnt(2)
	v_cvt_pk_bf16_f32 v9, v64, v66
	v_mov_b32_e32 v52, v9
	s_waitcnt lgkmcnt(1)
	s_waitcnt lgkmcnt(0)
	v_cvt_pk_bf16_f32 v9, v68, v70
	v_mov_b32_e32 v53, v9
	v_lshlrev_b32_e32 v128, 1, v12
	v_lshl_add_u64 v[72:73], v[56:57], 0, v[128:129]
	v_cvt_pk_bf16_f32 v9, v55, v59
	global_store_dwordx4 v[72:73], v[50:53], off
	v_lshlrev_b32_e32 v128, 1, v14
	v_lshl_add_u64 v[54:55], v[56:57], 0, v[128:129]
	v_mov_b32_e32 v50, v9
	v_cvt_pk_bf16_f32 v9, v61, v63
	v_mov_b32_e32 v51, v9
	v_cvt_pk_bf16_f32 v9, v65, v67
	v_mov_b32_e32 v52, v9
	v_cvt_pk_bf16_f32 v9, v69, v71
	v_mov_b32_e32 v53, v9
	global_store_dwordx4 v[54:55], v[50:53], off
	s_waitcnt lgkmcnt(0)
	s_mov_b64 s[10:11], -1

.LBB0_784:
	s_lshl_b32 s9, s3, 1
	s_lshl_b32 s10, s4, 1
	v_or_b32_e32 v7, s9, v1
	v_or_b32_e32 v9, s10, v2
	s_add_i32 s11, s9, 4
	s_add_i32 s28, s10, 4
	s_add_i32 s29, s9, 8
	s_add_i32 s30, s10, 8
	s_add_i32 s36, s9, 12
	s_add_i32 s37, s10, 12
	s_add_i32 s38, s9, 16
	s_add_i32 s39, s10, 16
	s_add_i32 s40, s9, 20
	s_add_i32 s41, s10, 20
	s_add_i32 s42, s9, 24
	s_add_i32 s43, s10, 24
	s_add_i32 s9, s9, 28
	s_add_i32 s10, s10, 28
	v_add_u32_e32 v11, s1, v7
	v_add_u32_e32 v13, s2, v9
	v_or_b32_e32 v15, s11, v1
	v_or_b32_e32 v17, s28, v2
	v_or_b32_e32 v21, s29, v1
	v_or_b32_e32 v35, s30, v2
	v_or_b32_e32 v37, s36, v1
	v_or_b32_e32 v39, s37, v2
	v_or_b32_e32 v41, s38, v1
	v_or_b32_e32 v43, s39, v2
	v_or_b32_e32 v78, s40, v1
	v_or_b32_e32 v79, s41, v2
	v_or_b32_e32 v80, s42, v1
	v_or_b32_e32 v81, s43, v2
	v_or_b32_e32 v82, s9, v1
	v_or_b32_e32 v83, s10, v2
	v_mad_i64_i32 v[46:47], s[10:11], v13, s80, v[44:45]
	v_mad_i64_i32 v[48:49], s[10:11], v11, s80, v[44:45]
	v_add_u32_e32 v11, s1, v15
	v_add_u32_e32 v13, s2, v17
	v_add_u32_e32 v56, s1, v21
	v_add_u32_e32 v54, s2, v35
	v_add_u32_e32 v60, s1, v37
	v_add_u32_e32 v58, s2, v39
	v_add_u32_e32 v64, s1, v41
	v_add_u32_e32 v62, s2, v43
	v_add_u32_e32 v68, s1, v78
	v_add_u32_e32 v66, s2, v79
	v_add_u32_e32 v72, s1, v80
	v_add_u32_e32 v70, s2, v81
	v_add_u32_e32 v76, s1, v82
	v_add_u32_e32 v74, s2, v83
	v_mad_i64_i32 v[50:51], s[10:11], v13, s80, v[44:45]
	v_mad_i64_i32 v[52:53], s[10:11], v11, s80, v[44:45]
	v_mad_i64_i32 v[54:55], s[10:11], v54, s80, v[44:45]
	v_mad_i64_i32 v[56:57], s[10:11], v56, s80, v[44:45]
	v_mad_i64_i32 v[58:59], s[10:11], v58, s80, v[44:45]
	v_mad_i64_i32 v[60:61], s[10:11], v60, s80, v[44:45]
	v_mad_i64_i32 v[62:63], s[10:11], v62, s80, v[44:45]
	v_mad_i64_i32 v[64:65], s[10:11], v64, s80, v[44:45]
	v_mad_i64_i32 v[66:67], s[10:11], v66, s80, v[44:45]
	v_mad_i64_i32 v[68:69], s[10:11], v68, s80, v[44:45]
	v_mad_i64_i32 v[70:71], s[10:11], v70, s80, v[44:45]
	v_mad_i64_i32 v[72:73], s[10:11], v72, s80, v[44:45]
	v_mad_i64_i32 v[74:75], s[10:11], v74, s80, v[44:45]
	v_mad_i64_i32 v[76:77], s[10:11], v76, s80, v[44:45]
	global_load_dword v11, v[46:47], off
	global_load_dword v13, v[48:49], off
	global_load_dword v84, v[50:51], off
	global_load_dword v85, v[52:53], off
	global_load_dword v86, v[54:55], off
	global_load_dword v87, v[56:57], off
	global_load_dword v88, v[58:59], off
	global_load_dword v89, v[60:61], off
	global_load_dword v90, v[62:63], off
	global_load_dword v91, v[64:65], off
	global_load_dword v92, v[66:67], off
	global_load_dword v93, v[68:69], off
	global_load_dword v94, v[70:71], off
	global_load_dword v95, v[72:73], off
	global_load_dword v96, v[74:75], off
	global_load_dword v97, v[76:77], off
	s_add_i32 s4, s4, 16
	s_add_i32 s3, s3, 16
	s_lshl_b32 s9, s3, 1
	s_lshl_b32 s10, s4, 1
	v_or_b32_e32 v106, s9, v1
	v_or_b32_e32 v107, s10, v2
	s_add_i32 s11, s9, 4
	s_add_i32 s28, s10, 4
	s_add_i32 s29, s9, 8
	s_add_i32 s30, s10, 8
	s_add_i32 s36, s9, 12
	s_add_i32 s37, s10, 12
	s_add_i32 s38, s9, 16
	s_add_i32 s39, s10, 16
	s_add_i32 s40, s9, 20
	s_add_i32 s41, s10, 20
	s_add_i32 s42, s9, 24
	s_add_i32 s43, s10, 24
	s_add_i32 s9, s9, 28
	s_add_i32 s10, s10, 28
	v_add_u32_e32 v108, s1, v106
	v_add_u32_e32 v109, s2, v107
	v_or_b32_e32 v110, s11, v1
	v_or_b32_e32 v111, s28, v2
	v_or_b32_e32 v112, s29, v1
	v_or_b32_e32 v113, s30, v2
	v_or_b32_e32 v114, s36, v1
	v_or_b32_e32 v115, s37, v2
	v_or_b32_e32 v116, s38, v1
	v_or_b32_e32 v117, s39, v2
	v_or_b32_e32 v118, s40, v1
	v_or_b32_e32 v119, s41, v2
	v_or_b32_e32 v120, s42, v1
	v_or_b32_e32 v121, s43, v2
	v_or_b32_e32 v122, s9, v1
	v_or_b32_e32 v123, s10, v2
	v_mad_i64_i32 v[130:131], s[10:11], v109, s80, v[44:45]
	v_mad_i64_i32 v[132:133], s[10:11], v108, s80, v[44:45]
	v_add_u32_e32 v108, s1, v110
	v_add_u32_e32 v109, s2, v111
	v_add_u32_e32 v140, s1, v112
	v_add_u32_e32 v138, s2, v113
	v_add_u32_e32 v144, s1, v114
	v_add_u32_e32 v142, s2, v115
	v_add_u32_e32 v148, s1, v116
	v_add_u32_e32 v146, s2, v117
	v_add_u32_e32 v152, s1, v118
	v_add_u32_e32 v150, s2, v119
	v_add_u32_e32 v156, s1, v120
	v_add_u32_e32 v154, s2, v121
	v_add_u32_e32 v160, s1, v122
	v_add_u32_e32 v158, s2, v123
	v_mad_i64_i32 v[134:135], s[10:11], v109, s80, v[44:45]
	v_mad_i64_i32 v[136:137], s[10:11], v108, s80, v[44:45]
	v_mad_i64_i32 v[138:139], s[10:11], v138, s80, v[44:45]
	v_mad_i64_i32 v[140:141], s[10:11], v140, s80, v[44:45]
	v_mad_i64_i32 v[142:143], s[10:11], v142, s80, v[44:45]
	v_mad_i64_i32 v[144:145], s[10:11], v144, s80, v[44:45]
	v_mad_i64_i32 v[146:147], s[10:11], v146, s80, v[44:45]
	v_mad_i64_i32 v[148:149], s[10:11], v148, s80, v[44:45]
	v_mad_i64_i32 v[150:151], s[10:11], v150, s80, v[44:45]
	v_mad_i64_i32 v[152:153], s[10:11], v152, s80, v[44:45]
	v_mad_i64_i32 v[154:155], s[10:11], v154, s80, v[44:45]
	v_mad_i64_i32 v[156:157], s[10:11], v156, s80, v[44:45]
	v_mad_i64_i32 v[158:159], s[10:11], v158, s80, v[44:45]
	v_mad_i64_i32 v[160:161], s[10:11], v160, s80, v[44:45]
	global_load_dword v108, v[130:131], off
	global_load_dword v109, v[132:133], off
	global_load_dword v124, v[134:135], off
	global_load_dword v125, v[136:137], off
	global_load_dword v126, v[138:139], off
	global_load_dword v127, v[140:141], off
	global_load_dword v162, v[142:143], off
	global_load_dword v163, v[144:145], off
	global_load_dword v164, v[146:147], off
	global_load_dword v165, v[148:149], off
	global_load_dword v166, v[150:151], off
	global_load_dword v167, v[152:153], off
	global_load_dword v168, v[154:155], off
	global_load_dword v169, v[156:157], off
	global_load_dword v170, v[158:159], off
	global_load_dword v171, v[160:161], off
	v_mad_u64_u32 v[46:47], s[10:11], v9, s78, v[6:7]
	v_mad_u64_u32 v[48:49], s[10:11], v7, s78, v[6:7]
	v_mad_u64_u32 v[50:51], s[10:11], v17, s78, v[6:7]
	v_mad_u64_u32 v[52:53], s[10:11], v15, s78, v[6:7]
	v_mad_u64_u32 v[54:55], s[10:11], v35, s78, v[6:7]
	v_mad_u64_u32 v[56:57], s[10:11], v21, s78, v[6:7]
	v_mad_u64_u32 v[58:59], s[10:11], v39, s78, v[6:7]
	v_mad_u64_u32 v[60:61], s[10:11], v37, s78, v[6:7]
	v_mad_u64_u32 v[62:63], s[10:11], v43, s78, v[6:7]
	v_mad_u64_u32 v[64:65], s[10:11], v41, s78, v[6:7]
	v_mad_u64_u32 v[66:67], s[10:11], v79, s78, v[6:7]
	v_mad_u64_u32 v[68:69], s[10:11], v78, s78, v[6:7]
	v_mad_u64_u32 v[70:71], s[10:11], v81, s78, v[6:7]
	v_mad_u64_u32 v[72:73], s[10:11], v80, s78, v[6:7]
	v_mad_u64_u32 v[74:75], s[10:11], v83, s78, v[6:7]
	v_mad_u64_u32 v[76:77], s[10:11], v82, s78, v[6:7]
	s_waitcnt vmcnt(31)
	ds_write_b32 v46, v11
	s_waitcnt vmcnt(30)
	ds_write_b32 v48, v13
	s_waitcnt vmcnt(29)
	ds_write_b32 v50, v84
	s_waitcnt vmcnt(28)
	ds_write_b32 v52, v85
	s_waitcnt vmcnt(27)
	ds_write_b32 v54, v86
	s_waitcnt vmcnt(26)
	ds_write_b32 v56, v87
	s_waitcnt vmcnt(25)
	ds_write_b32 v58, v88
	s_waitcnt vmcnt(24)
	ds_write_b32 v60, v89
	s_waitcnt vmcnt(23)
	ds_write_b32 v62, v90
	s_waitcnt vmcnt(22)
	ds_write_b32 v64, v91
	s_waitcnt vmcnt(21)
	ds_write_b32 v66, v92
	s_waitcnt vmcnt(20)
	ds_write_b32 v68, v93
	s_waitcnt vmcnt(19)
	ds_write_b32 v70, v94
	s_waitcnt vmcnt(18)
	ds_write_b32 v72, v95
	s_waitcnt vmcnt(17)
	ds_write_b32 v74, v96
	s_waitcnt vmcnt(16)
	ds_write_b32 v76, v97
	v_mad_u64_u32 v[130:131], s[10:11], v107, s78, v[6:7]
	v_mad_u64_u32 v[132:133], s[10:11], v106, s78, v[6:7]
	v_mad_u64_u32 v[134:135], s[10:11], v111, s78, v[6:7]
	v_mad_u64_u32 v[136:137], s[10:11], v110, s78, v[6:7]
	v_mad_u64_u32 v[138:139], s[10:11], v113, s78, v[6:7]
	v_mad_u64_u32 v[140:141], s[10:11], v112, s78, v[6:7]
	v_mad_u64_u32 v[142:143], s[10:11], v115, s78, v[6:7]
	v_mad_u64_u32 v[144:145], s[10:11], v114, s78, v[6:7]
	v_mad_u64_u32 v[146:147], s[10:11], v117, s78, v[6:7]
	v_mad_u64_u32 v[148:149], s[10:11], v116, s78, v[6:7]
	v_mad_u64_u32 v[150:151], s[10:11], v119, s78, v[6:7]
	v_mad_u64_u32 v[152:153], s[10:11], v118, s78, v[6:7]
	v_mad_u64_u32 v[154:155], s[10:11], v121, s78, v[6:7]
	v_mad_u64_u32 v[156:157], s[10:11], v120, s78, v[6:7]
	v_mad_u64_u32 v[158:159], s[10:11], v123, s78, v[6:7]
	v_mad_u64_u32 v[160:161], s[10:11], v122, s78, v[6:7]
	s_waitcnt vmcnt(15)
	ds_write_b32 v130, v108
	s_waitcnt vmcnt(14)
	ds_write_b32 v132, v109
	s_waitcnt vmcnt(13)
	ds_write_b32 v134, v124
	s_waitcnt vmcnt(12)
	ds_write_b32 v136, v125
	s_waitcnt vmcnt(11)
	ds_write_b32 v138, v126
	s_waitcnt vmcnt(10)
	ds_write_b32 v140, v127
	s_waitcnt vmcnt(9)
	ds_write_b32 v142, v162
	s_waitcnt vmcnt(8)
	ds_write_b32 v144, v163
	s_waitcnt vmcnt(7)
	ds_write_b32 v146, v164
	s_waitcnt vmcnt(6)
	ds_write_b32 v148, v165
	s_waitcnt vmcnt(5)
	ds_write_b32 v150, v166
	s_waitcnt vmcnt(4)
	ds_write_b32 v152, v167
	s_waitcnt vmcnt(3)
	ds_write_b32 v154, v168
	s_waitcnt vmcnt(2)
	ds_write_b32 v156, v169
	s_waitcnt vmcnt(1)
	ds_write_b32 v158, v170
	s_waitcnt vmcnt(0)
	ds_write_b32 v160, v171
	s_add_i32 s4, s4, 16
	s_add_i32 s3, s3, 16
	s_add_i32 s5, s5, -16
	s_add_i32 s5, s5, -16
	s_cmp_lg_u32 s5, 0
	s_waitcnt lgkmcnt(0)
	s_add_i32 s1, s8, 0xf500
	ds_read2_b32 v[48:49], v3 offset1:8
	s_cmpk_lt_i32 s0, 0x58
	ds_read2_b32 v[52:53], v3 offset0:33 offset1:41
	s_cselect_b32 s0, s8, s1
	s_sext_i32_i16 s1, s0
	ds_read2_b32 v[54:55], v3 offset0:66 offset1:74
	s_cselect_b32 s3, 0, 0x80
	s_bfe_u32 s1, s1, 0x70018
	ds_read2_b32 v[56:57], v3 offset0:99 offset1:107
	s_add_i32 s1, s0, s1
	s_waitcnt lgkmcnt(3)
	s_sext_i32_i16 s4, s1
	s_and_b32 s1, s1, 0xff80
	s_waitcnt lgkmcnt(2)
	ds_read2_b32 v[58:59], v3 offset0:132 offset1:140
	s_sub_i32 s0, s0, s1
	v_cvt_pk_bf16_f32 v9, v48, v52
	ds_read2_b32 v[60:61], v3 offset0:165 offset1:173
	s_lshl_b32 s4, s4, 1
	s_sext_i32_i16 s0, s0
	v_mov_b32_e32 v44, v9
	s_waitcnt lgkmcnt(3)
	s_and_b32 s4, s4, 0xffffff00
	s_add_i32 s0, s3, s0
	s_waitcnt lgkmcnt(2)
	ds_read2_b32 v[62:63], v3 offset0:198 offset1:206
	s_add_i32 s0, s0, s4
	v_cvt_pk_bf16_f32 v9, v54, v56
	ds_read2_b32 v[64:65], v3 offset0:231 offset1:239
	s_ashr_i32 s1, s0, 31
	v_mov_b32_e32 v45, v9
	s_waitcnt lgkmcnt(3)
	s_lshl_b64 s[0:1], s[0:1], 11
	s_waitcnt lgkmcnt(2)
	s_add_u32 s4, s13, s0
	v_cvt_pk_bf16_f32 v9, v58, v60
	s_addc_u32 s5, s14, s1
	s_ashr_i32 s3, s2, 31
	v_mov_b32_e32 v46, v9
	s_waitcnt lgkmcnt(1)
	s_lshl_b64 s[0:1], s[2:3], 1
	s_waitcnt lgkmcnt(0)
	s_add_u32 s0, s4, s0
	v_cvt_pk_bf16_f32 v9, v62, v64
	s_addc_u32 s1, s5, s1
	v_lshlrev_b32_e32 v128, 1, v8
	v_mov_b32_e32 v47, v9
	v_lshl_add_u64 v[50:51], s[0:1], 0, v[128:129]
	v_lshlrev_b32_e32 v128, 1, v10
	v_lshl_add_u64 v[66:67], v[50:51], 0, v[128:129]
	v_cvt_pk_bf16_f32 v9, v49, v53
	global_store_dwordx4 v[66:67], v[44:47], off
	v_lshlrev_b32_e32 v128, 1, v12
	ds_read2_b32 v[48:49], v3 offset0:16 offset1:24
	v_mov_b32_e32 v44, v9
	v_cvt_pk_bf16_f32 v9, v55, v57
	v_mov_b32_e32 v45, v9
	v_cvt_pk_bf16_f32 v9, v59, v61
	v_mov_b32_e32 v46, v9
	v_cvt_pk_bf16_f32 v9, v63, v65
	v_mov_b32_e32 v47, v9
	v_lshl_add_u64 v[52:53], v[50:51], 0, v[128:129]
	global_store_dwordx4 v[52:53], v[44:47], off
	ds_read2_b32 v[52:53], v3 offset0:49 offset1:57
	ds_read2_b32 v[54:55], v3 offset0:82 offset1:90
	ds_read2_b32 v[56:57], v3 offset0:115 offset1:123
	s_waitcnt lgkmcnt(3)
	s_waitcnt lgkmcnt(2)
	ds_read2_b32 v[58:59], v3 offset0:148 offset1:156
	v_cvt_pk_bf16_f32 v9, v48, v52
	ds_read2_b32 v[60:61], v3 offset0:181 offset1:189
	v_mov_b32_e32 v44, v9
	s_waitcnt lgkmcnt(3)
	s_waitcnt lgkmcnt(2)
	ds_read2_b32 v[62:63], v3 offset0:214 offset1:222
	v_cvt_pk_bf16_f32 v9, v54, v56
	ds_read2_b32 v[64:65], v3 offset0:247 offset1:255
	v_mov_b32_e32 v45, v9
	s_waitcnt lgkmcnt(3)
	s_waitcnt lgkmcnt(2)
	v_cvt_pk_bf16_f32 v9, v58, v60
	v_mov_b32_e32 v46, v9
	s_waitcnt lgkmcnt(1)
	s_waitcnt lgkmcnt(0)
	v_cvt_pk_bf16_f32 v9, v62, v64
	v_mov_b32_e32 v47, v9
	v_lshlrev_b32_e32 v128, 1, v14
	v_lshl_add_u64 v[66:67], v[50:51], 0, v[128:129]
	v_cvt_pk_bf16_f32 v9, v49, v53
	global_store_dwordx4 v[66:67], v[44:47], off
	v_lshlrev_b32_e32 v128, 1, v16
	v_lshl_add_u64 v[48:49], v[50:51], 0, v[128:129]
	v_mov_b32_e32 v44, v9
	v_cvt_pk_bf16_f32 v9, v55, v57
	v_mov_b32_e32 v45, v9
	v_cvt_pk_bf16_f32 v9, v59, v61
	v_mov_b32_e32 v46, v9
	v_cvt_pk_bf16_f32 v9, v63, v65
	v_mov_b32_e32 v47, v9
	global_store_dwordx4 v[48:49], v[44:47], off
	s_waitcnt lgkmcnt(0)
	s_mov_b32 s0, s12
	s_mov_b64 s[2:3], -1
	s_andn2_b64 vcc, exec, s[6:7]
	s_mov_b64 s[6:7], -1
	s_cbranch_vccnz .LBB0_832

.LBB0_791:
	s_lshl_b32 s11, s1, 1
	s_lshl_b32 s28, s5, 1
	v_or_b32_e32 v7, s11, v1
	v_or_b32_e32 v9, s28, v2
	s_add_i32 s29, s11, 4
	s_add_i32 s30, s28, 4
	s_add_i32 s36, s11, 8
	s_add_i32 s37, s28, 8
	s_add_i32 s38, s11, 12
	s_add_i32 s39, s28, 12
	s_add_i32 s40, s11, 16
	s_add_i32 s41, s28, 16
	s_add_i32 s42, s11, 20
	s_add_i32 s43, s28, 20
	s_add_i32 s44, s11, 24
	s_add_i32 s45, s28, 24
	s_add_i32 s11, s11, 28
	s_add_i32 s28, s28, 28
	v_add_u32_e32 v48, s8, v9
	v_or_b32_e32 v11, s29, v1
	v_or_b32_e32 v13, s30, v2
	v_or_b32_e32 v15, s36, v1
	v_or_b32_e32 v17, s37, v2
	v_or_b32_e32 v21, s38, v1
	v_or_b32_e32 v35, s39, v2
	v_or_b32_e32 v37, s40, v1
	v_or_b32_e32 v39, s41, v2
	v_or_b32_e32 v41, s42, v1
	v_or_b32_e32 v43, s43, v2
	v_or_b32_e32 v78, s44, v1
	v_or_b32_e32 v79, s45, v2
	v_or_b32_e32 v80, s11, v1
	v_or_b32_e32 v81, s28, v2
	v_add_u32_e32 v46, s4, v7
	v_ashrrev_i32_e32 v49, 31, v48
	v_add_u32_e32 v50, s4, v11
	v_add_u32_e32 v52, s8, v13
	v_add_u32_e32 v54, s4, v15
	v_add_u32_e32 v56, s8, v17
	v_add_u32_e32 v58, s4, v21
	v_add_u32_e32 v60, s8, v35
	v_add_u32_e32 v62, s4, v37
	v_add_u32_e32 v64, s8, v39
	v_add_u32_e32 v66, s4, v41
	v_add_u32_e32 v68, s8, v43
	v_add_u32_e32 v70, s4, v78
	v_add_u32_e32 v72, s8, v79
	v_add_u32_e32 v74, s4, v80
	v_add_u32_e32 v76, s8, v81
	v_ashrrev_i32_e32 v47, 31, v46
	v_lshlrev_b64 v[48:49], 12, v[48:49]
	v_ashrrev_i32_e32 v53, 31, v52
	v_ashrrev_i32_e32 v51, 31, v50
	v_ashrrev_i32_e32 v57, 31, v56
	v_ashrrev_i32_e32 v55, 31, v54
	v_ashrrev_i32_e32 v61, 31, v60
	v_ashrrev_i32_e32 v59, 31, v58
	v_ashrrev_i32_e32 v65, 31, v64
	v_ashrrev_i32_e32 v63, 31, v62
	v_ashrrev_i32_e32 v69, 31, v68
	v_ashrrev_i32_e32 v67, 31, v66
	v_ashrrev_i32_e32 v73, 31, v72
	v_ashrrev_i32_e32 v71, 31, v70
	v_ashrrev_i32_e32 v77, 31, v76
	v_ashrrev_i32_e32 v75, 31, v74
	v_lshlrev_b64 v[46:47], 12, v[46:47]
	v_lshl_add_u64 v[48:49], v[44:45], 0, v[48:49]
	v_lshlrev_b64 v[50:51], 12, v[50:51]
	v_lshlrev_b64 v[52:53], 12, v[52:53]
	v_lshlrev_b64 v[54:55], 12, v[54:55]
	v_lshlrev_b64 v[56:57], 12, v[56:57]
	v_lshlrev_b64 v[58:59], 12, v[58:59]
	v_lshlrev_b64 v[60:61], 12, v[60:61]
	v_lshlrev_b64 v[62:63], 12, v[62:63]
	v_lshlrev_b64 v[64:65], 12, v[64:65]
	v_lshlrev_b64 v[66:67], 12, v[66:67]
	v_lshlrev_b64 v[68:69], 12, v[68:69]
	v_lshlrev_b64 v[70:71], 12, v[70:71]
	v_lshlrev_b64 v[72:73], 12, v[72:73]
	v_lshlrev_b64 v[74:75], 12, v[74:75]
	v_lshlrev_b64 v[76:77], 12, v[76:77]
	v_lshl_add_u64 v[46:47], v[44:45], 0, v[46:47]
	v_lshl_add_u64 v[52:53], v[44:45], 0, v[52:53]
	v_lshl_add_u64 v[50:51], v[44:45], 0, v[50:51]
	v_lshl_add_u64 v[56:57], v[44:45], 0, v[56:57]
	v_lshl_add_u64 v[54:55], v[44:45], 0, v[54:55]
	v_lshl_add_u64 v[60:61], v[44:45], 0, v[60:61]
	v_lshl_add_u64 v[58:59], v[44:45], 0, v[58:59]
	v_lshl_add_u64 v[64:65], v[44:45], 0, v[64:65]
	v_lshl_add_u64 v[62:63], v[44:45], 0, v[62:63]
	v_lshl_add_u64 v[68:69], v[44:45], 0, v[68:69]
	v_lshl_add_u64 v[66:67], v[44:45], 0, v[66:67]
	v_lshl_add_u64 v[72:73], v[44:45], 0, v[72:73]
	v_lshl_add_u64 v[70:71], v[44:45], 0, v[70:71]
	v_lshl_add_u64 v[76:77], v[44:45], 0, v[76:77]
	v_lshl_add_u64 v[74:75], v[44:45], 0, v[74:75]
	global_load_dword v82, v[48:49], off
	global_load_dword v83, v[46:47], off
	global_load_dword v84, v[52:53], off
	global_load_dword v85, v[50:51], off
	global_load_dword v86, v[56:57], off
	global_load_dword v87, v[54:55], off
	global_load_dword v88, v[60:61], off
	global_load_dword v89, v[58:59], off
	global_load_dword v90, v[64:65], off
	global_load_dword v91, v[62:63], off
	global_load_dword v92, v[68:69], off
	global_load_dword v93, v[66:67], off
	global_load_dword v94, v[72:73], off
	global_load_dword v95, v[70:71], off
	global_load_dword v96, v[76:77], off
	global_load_dword v97, v[74:75], off
	s_add_i32 s5, s5, 16
	s_add_i32 s1, s1, 16
	s_lshl_b32 s11, s1, 1
	s_lshl_b32 s28, s5, 1
	v_or_b32_e32 v106, s11, v1
	v_or_b32_e32 v107, s28, v2
	s_add_i32 s29, s11, 4
	s_add_i32 s30, s28, 4
	s_add_i32 s36, s11, 8
	s_add_i32 s37, s28, 8
	s_add_i32 s38, s11, 12
	s_add_i32 s39, s28, 12
	s_add_i32 s40, s11, 16
	s_add_i32 s41, s28, 16
	s_add_i32 s42, s11, 20
	s_add_i32 s43, s28, 20
	s_add_i32 s44, s11, 24
	s_add_i32 s45, s28, 24
	s_add_i32 s11, s11, 28
	s_add_i32 s28, s28, 28
	v_add_u32_e32 v132, s8, v107
	v_or_b32_e32 v108, s29, v1
	v_or_b32_e32 v109, s30, v2
	v_or_b32_e32 v110, s36, v1
	v_or_b32_e32 v111, s37, v2
	v_or_b32_e32 v112, s38, v1
	v_or_b32_e32 v113, s39, v2
	v_or_b32_e32 v114, s40, v1
	v_or_b32_e32 v115, s41, v2
	v_or_b32_e32 v116, s42, v1
	v_or_b32_e32 v117, s43, v2
	v_or_b32_e32 v118, s44, v1
	v_or_b32_e32 v119, s45, v2
	v_or_b32_e32 v120, s11, v1
	v_or_b32_e32 v121, s28, v2
	v_add_u32_e32 v130, s4, v106
	v_ashrrev_i32_e32 v133, 31, v132
	v_add_u32_e32 v134, s4, v108
	v_add_u32_e32 v136, s8, v109
	v_add_u32_e32 v138, s4, v110
	v_add_u32_e32 v140, s8, v111
	v_add_u32_e32 v142, s4, v112
	v_add_u32_e32 v144, s8, v113
	v_add_u32_e32 v146, s4, v114
	v_add_u32_e32 v148, s8, v115
	v_add_u32_e32 v150, s4, v116
	v_add_u32_e32 v152, s8, v117
	v_add_u32_e32 v154, s4, v118
	v_add_u32_e32 v156, s8, v119
	v_add_u32_e32 v158, s4, v120
	v_add_u32_e32 v160, s8, v121
	v_ashrrev_i32_e32 v131, 31, v130
	v_lshlrev_b64 v[132:133], 12, v[132:133]
	v_ashrrev_i32_e32 v137, 31, v136
	v_ashrrev_i32_e32 v135, 31, v134
	v_ashrrev_i32_e32 v141, 31, v140
	v_ashrrev_i32_e32 v139, 31, v138
	v_ashrrev_i32_e32 v145, 31, v144
	v_ashrrev_i32_e32 v143, 31, v142
	v_ashrrev_i32_e32 v149, 31, v148
	v_ashrrev_i32_e32 v147, 31, v146
	v_ashrrev_i32_e32 v153, 31, v152
	v_ashrrev_i32_e32 v151, 31, v150
	v_ashrrev_i32_e32 v157, 31, v156
	v_ashrrev_i32_e32 v155, 31, v154
	v_ashrrev_i32_e32 v161, 31, v160
	v_ashrrev_i32_e32 v159, 31, v158
	v_lshlrev_b64 v[130:131], 12, v[130:131]
	v_lshl_add_u64 v[132:133], v[44:45], 0, v[132:133]
	v_lshlrev_b64 v[134:135], 12, v[134:135]
	v_lshlrev_b64 v[136:137], 12, v[136:137]
	v_lshlrev_b64 v[138:139], 12, v[138:139]
	v_lshlrev_b64 v[140:141], 12, v[140:141]
	v_lshlrev_b64 v[142:143], 12, v[142:143]
	v_lshlrev_b64 v[144:145], 12, v[144:145]
	v_lshlrev_b64 v[146:147], 12, v[146:147]
	v_lshlrev_b64 v[148:149], 12, v[148:149]
	v_lshlrev_b64 v[150:151], 12, v[150:151]
	v_lshlrev_b64 v[152:153], 12, v[152:153]
	v_lshlrev_b64 v[154:155], 12, v[154:155]
	v_lshlrev_b64 v[156:157], 12, v[156:157]
	v_lshlrev_b64 v[158:159], 12, v[158:159]
	v_lshlrev_b64 v[160:161], 12, v[160:161]
	v_lshl_add_u64 v[130:131], v[44:45], 0, v[130:131]
	v_lshl_add_u64 v[136:137], v[44:45], 0, v[136:137]
	v_lshl_add_u64 v[134:135], v[44:45], 0, v[134:135]
	v_lshl_add_u64 v[140:141], v[44:45], 0, v[140:141]
	v_lshl_add_u64 v[138:139], v[44:45], 0, v[138:139]
	v_lshl_add_u64 v[144:145], v[44:45], 0, v[144:145]
	v_lshl_add_u64 v[142:143], v[44:45], 0, v[142:143]
	v_lshl_add_u64 v[148:149], v[44:45], 0, v[148:149]
	v_lshl_add_u64 v[146:147], v[44:45], 0, v[146:147]
	v_lshl_add_u64 v[152:153], v[44:45], 0, v[152:153]
	v_lshl_add_u64 v[150:151], v[44:45], 0, v[150:151]
	v_lshl_add_u64 v[156:157], v[44:45], 0, v[156:157]
	v_lshl_add_u64 v[154:155], v[44:45], 0, v[154:155]
	v_lshl_add_u64 v[160:161], v[44:45], 0, v[160:161]
	v_lshl_add_u64 v[158:159], v[44:45], 0, v[158:159]
	global_load_dword v122, v[132:133], off
	global_load_dword v123, v[130:131], off
	global_load_dword v124, v[136:137], off
	global_load_dword v125, v[134:135], off
	global_load_dword v126, v[140:141], off
	global_load_dword v127, v[138:139], off
	global_load_dword v162, v[144:145], off
	global_load_dword v163, v[142:143], off
	global_load_dword v164, v[148:149], off
	global_load_dword v165, v[146:147], off
	global_load_dword v166, v[152:153], off
	global_load_dword v167, v[150:151], off
	global_load_dword v168, v[156:157], off
	global_load_dword v169, v[154:155], off
	global_load_dword v170, v[160:161], off
	global_load_dword v171, v[158:159], off
	v_mad_u64_u32 v[46:47], s[28:29], v9, s78, v[6:7]
	v_mad_u64_u32 v[48:49], s[28:29], v7, s78, v[6:7]
	v_mad_u64_u32 v[50:51], s[28:29], v13, s78, v[6:7]
	v_mad_u64_u32 v[52:53], s[28:29], v11, s78, v[6:7]
	v_mad_u64_u32 v[54:55], s[28:29], v17, s78, v[6:7]
	v_mad_u64_u32 v[56:57], s[28:29], v15, s78, v[6:7]
	v_mad_u64_u32 v[58:59], s[28:29], v35, s78, v[6:7]
	v_mad_u64_u32 v[60:61], s[28:29], v21, s78, v[6:7]
	v_mad_u64_u32 v[62:63], s[28:29], v39, s78, v[6:7]
	v_mad_u64_u32 v[64:65], s[28:29], v37, s78, v[6:7]
	v_mad_u64_u32 v[66:67], s[28:29], v43, s78, v[6:7]
	v_mad_u64_u32 v[68:69], s[28:29], v41, s78, v[6:7]
	v_mad_u64_u32 v[70:71], s[28:29], v79, s78, v[6:7]
	v_mad_u64_u32 v[72:73], s[28:29], v78, s78, v[6:7]
	v_mad_u64_u32 v[74:75], s[28:29], v81, s78, v[6:7]
	v_mad_u64_u32 v[76:77], s[28:29], v80, s78, v[6:7]
	s_waitcnt vmcnt(31)
	ds_write_b32 v46, v82
	s_waitcnt vmcnt(30)
	ds_write_b32 v48, v83
	s_waitcnt vmcnt(29)
	ds_write_b32 v50, v84
	s_waitcnt vmcnt(28)
	ds_write_b32 v52, v85
	s_waitcnt vmcnt(27)
	ds_write_b32 v54, v86
	s_waitcnt vmcnt(26)
	ds_write_b32 v56, v87
	s_waitcnt vmcnt(25)
	ds_write_b32 v58, v88
	s_waitcnt vmcnt(24)
	ds_write_b32 v60, v89
	s_waitcnt vmcnt(23)
	ds_write_b32 v62, v90
	s_waitcnt vmcnt(22)
	ds_write_b32 v64, v91
	s_waitcnt vmcnt(21)
	ds_write_b32 v66, v92
	s_waitcnt vmcnt(20)
	ds_write_b32 v68, v93
	s_waitcnt vmcnt(19)
	ds_write_b32 v70, v94
	s_waitcnt vmcnt(18)
	ds_write_b32 v72, v95
	s_waitcnt vmcnt(17)
	ds_write_b32 v74, v96
	s_waitcnt vmcnt(16)
	ds_write_b32 v76, v97
	v_mad_u64_u32 v[130:131], s[28:29], v107, s78, v[6:7]
	v_mad_u64_u32 v[132:133], s[28:29], v106, s78, v[6:7]
	v_mad_u64_u32 v[134:135], s[28:29], v109, s78, v[6:7]
	v_mad_u64_u32 v[136:137], s[28:29], v108, s78, v[6:7]
	v_mad_u64_u32 v[138:139], s[28:29], v111, s78, v[6:7]
	v_mad_u64_u32 v[140:141], s[28:29], v110, s78, v[6:7]
	v_mad_u64_u32 v[142:143], s[28:29], v113, s78, v[6:7]
	v_mad_u64_u32 v[144:145], s[28:29], v112, s78, v[6:7]
	v_mad_u64_u32 v[146:147], s[28:29], v115, s78, v[6:7]
	v_mad_u64_u32 v[148:149], s[28:29], v114, s78, v[6:7]
	v_mad_u64_u32 v[150:151], s[28:29], v117, s78, v[6:7]
	v_mad_u64_u32 v[152:153], s[28:29], v116, s78, v[6:7]
	v_mad_u64_u32 v[154:155], s[28:29], v119, s78, v[6:7]
	v_mad_u64_u32 v[156:157], s[28:29], v118, s78, v[6:7]
	v_mad_u64_u32 v[158:159], s[28:29], v121, s78, v[6:7]
	v_mad_u64_u32 v[160:161], s[28:29], v120, s78, v[6:7]
	s_waitcnt vmcnt(15)
	ds_write_b32 v130, v122
	s_waitcnt vmcnt(14)
	ds_write_b32 v132, v123
	s_waitcnt vmcnt(13)
	ds_write_b32 v134, v124
	s_waitcnt vmcnt(12)
	ds_write_b32 v136, v125
	s_waitcnt vmcnt(11)
	ds_write_b32 v138, v126
	s_waitcnt vmcnt(10)
	ds_write_b32 v140, v127
	s_waitcnt vmcnt(9)
	ds_write_b32 v142, v162
	s_waitcnt vmcnt(8)
	ds_write_b32 v144, v163
	s_waitcnt vmcnt(7)
	ds_write_b32 v146, v164
	s_waitcnt vmcnt(6)
	ds_write_b32 v148, v165
	s_waitcnt vmcnt(5)
	ds_write_b32 v150, v166
	s_waitcnt vmcnt(4)
	ds_write_b32 v152, v167
	s_waitcnt vmcnt(3)
	ds_write_b32 v154, v168
	s_waitcnt vmcnt(2)
	ds_write_b32 v156, v169
	s_waitcnt vmcnt(1)
	ds_write_b32 v158, v170
	s_waitcnt vmcnt(0)
	ds_write_b32 v160, v171
	s_add_i32 s5, s5, 16
	s_add_i32 s1, s1, 16
	s_add_i32 s9, s9, -16
	s_add_i32 s9, s9, -16
	s_cmp_lg_u32 s9, 0
	s_waitcnt lgkmcnt(0)
	ds_read2_b32 v[48:49], v3 offset1:8
	ds_read2_b32 v[52:53], v3 offset0:33 offset1:41
	ds_read2_b32 v[54:55], v3 offset0:66 offset1:74
	ds_read2_b32 v[56:57], v3 offset0:99 offset1:107
	ds_read2_b32 v[58:59], v3 offset0:132 offset1:140
	s_waitcnt lgkmcnt(4)
	s_waitcnt lgkmcnt(3)
	v_cvt_pk_bf16_f32 v9, v48, v52
	ds_read2_b32 v[60:61], v3 offset0:165 offset1:173
	v_mov_b32_e32 v44, v9
	s_waitcnt lgkmcnt(3)
	s_waitcnt lgkmcnt(2)
	ds_read2_b32 v[62:63], v3 offset0:198 offset1:206
	v_cvt_pk_bf16_f32 v9, v54, v56
	ds_read2_b32 v[64:65], v3 offset0:231 offset1:239
	v_mov_b32_e32 v45, v9
	s_waitcnt lgkmcnt(3)
	s_mul_i32 s4, s10, 0x1600
	s_waitcnt lgkmcnt(2)
	s_mul_hi_i32 s1, s10, 0x1600
	s_add_u32 s10, s18, s4
	v_cvt_pk_bf16_f32 v9, v58, v60
	s_addc_u32 s1, s19, s1
	s_ashr_i32 s9, s8, 31
	v_mov_b32_e32 v46, v9
	s_waitcnt lgkmcnt(1)
	s_lshl_b64 s[4:5], s[8:9], 1
	s_waitcnt lgkmcnt(0)
	s_add_u32 s4, s10, s4
	v_cvt_pk_bf16_f32 v9, v62, v64
	s_addc_u32 s5, s1, s5
	v_lshlrev_b32_e32 v128, 1, v8
	v_mov_b32_e32 v47, v9
	v_lshl_add_u64 v[50:51], s[4:5], 0, v[128:129]
	v_lshlrev_b32_e32 v128, 1, v20
	v_lshl_add_u64 v[50:51], v[50:51], 0, v[128:129]
	v_cvt_pk_bf16_f32 v9, v49, v53
	global_store_dwordx4 v[50:51], v[44:47], off
	v_add_co_u32_e32 v52, vcc, s47, v50
	s_nop 0
	v_mov_b32_e32 v44, v9
	v_cvt_pk_bf16_f32 v9, v55, v57
	v_mov_b32_e32 v45, v9
	v_cvt_pk_bf16_f32 v9, v59, v61
	v_mov_b32_e32 v46, v9
	v_cvt_pk_bf16_f32 v9, v63, v65
	v_mov_b32_e32 v47, v9
	ds_read2_b32 v[48:49], v3 offset0:16 offset1:24
	v_addc_co_u32_e32 v53, vcc, 0, v51, vcc
	global_store_dwordx4 v[52:53], v[44:47], off
	ds_read2_b32 v[52:53], v3 offset0:49 offset1:57
	ds_read2_b32 v[54:55], v3 offset0:82 offset1:90
	ds_read2_b32 v[56:57], v3 offset0:115 offset1:123
	s_waitcnt lgkmcnt(3)
	s_waitcnt lgkmcnt(2)
	ds_read2_b32 v[58:59], v3 offset0:148 offset1:156
	v_cvt_pk_bf16_f32 v9, v48, v52
	ds_read2_b32 v[60:61], v3 offset0:181 offset1:189
	v_mov_b32_e32 v44, v9
	s_waitcnt lgkmcnt(3)
	s_waitcnt lgkmcnt(2)
	ds_read2_b32 v[62:63], v3 offset0:214 offset1:222
	v_cvt_pk_bf16_f32 v9, v54, v56
	ds_read2_b32 v[64:65], v3 offset0:247 offset1:255
	v_mov_b32_e32 v45, v9
	s_waitcnt lgkmcnt(3)
	s_waitcnt lgkmcnt(2)
	v_cvt_pk_bf16_f32 v9, v58, v60
	v_mov_b32_e32 v46, v9
	s_waitcnt lgkmcnt(1)
	s_waitcnt lgkmcnt(0)
	v_cvt_pk_bf16_f32 v9, v62, v64
	v_mov_b32_e32 v47, v9
	v_add_co_u32_e32 v66, vcc, s48, v50
	v_addc_co_u32_e32 v67, vcc, 0, v51, vcc
	v_cvt_pk_bf16_f32 v9, v49, v53
	global_store_dwordx4 v[66:67], v[44:47], off
	v_add_co_u32_e32 v48, vcc, 0x21000, v50
	s_nop 0
	v_mov_b32_e32 v44, v9
	v_cvt_pk_bf16_f32 v9, v55, v57
	v_mov_b32_e32 v45, v9
	v_cvt_pk_bf16_f32 v9, v59, v61
	v_mov_b32_e32 v46, v9
	v_cvt_pk_bf16_f32 v9, v63, v65
	v_mov_b32_e32 v47, v9
	v_addc_co_u32_e32 v49, vcc, 0, v51, vcc
	global_store_dwordx4 v[48:49], v[44:47], off
	s_waitcnt lgkmcnt(0)
	s_mov_b32 s1, s0
	s_andn2_b64 vcc, exec, s[6:7]
	s_mov_b64 s[6:7], -1
	s_cbranch_vccnz .LBB0_832

.LBB0_798:
	s_lshl_b32 s28, s5, 1
	s_lshl_b32 s29, s9, 1
	v_or_b32_e32 v7, s28, v1
	v_or_b32_e32 v9, s29, v2
	s_add_i32 s30, s28, 4
	s_add_i32 s36, s29, 4
	s_add_i32 s37, s28, 8
	s_add_i32 s38, s29, 8
	s_add_i32 s39, s28, 12
	s_add_i32 s40, s29, 12
	s_add_i32 s41, s28, 16
	s_add_i32 s42, s29, 16
	s_add_i32 s43, s28, 20
	s_add_i32 s44, s29, 20
	s_add_i32 s45, s28, 24
	s_add_i32 s46, s29, 24
	s_add_i32 s28, s28, 28
	s_add_i32 s29, s29, 28
	v_add_u32_e32 v11, s4, v7
	v_add_u32_e32 v13, s8, v9
	v_or_b32_e32 v15, s30, v1
	v_or_b32_e32 v17, s36, v2
	v_or_b32_e32 v21, s37, v1
	v_or_b32_e32 v35, s38, v2
	v_or_b32_e32 v37, s39, v1
	v_or_b32_e32 v39, s40, v2
	v_or_b32_e32 v41, s41, v1
	v_or_b32_e32 v43, s42, v2
	v_or_b32_e32 v78, s43, v1
	v_or_b32_e32 v79, s44, v2
	v_or_b32_e32 v80, s45, v1
	v_or_b32_e32 v81, s46, v2
	v_or_b32_e32 v82, s28, v1
	v_or_b32_e32 v83, s29, v2
	v_mad_i64_i32 v[46:47], s[28:29], v13, s80, v[44:45]
	v_mad_i64_i32 v[48:49], s[28:29], v11, s80, v[44:45]
	v_add_u32_e32 v11, s4, v15
	v_add_u32_e32 v13, s8, v17
	v_add_u32_e32 v56, s4, v21
	v_add_u32_e32 v54, s8, v35
	v_add_u32_e32 v60, s4, v37
	v_add_u32_e32 v58, s8, v39
	v_add_u32_e32 v64, s4, v41
	v_add_u32_e32 v62, s8, v43
	v_add_u32_e32 v68, s4, v78
	v_add_u32_e32 v66, s8, v79
	v_add_u32_e32 v72, s4, v80
	v_add_u32_e32 v70, s8, v81
	v_add_u32_e32 v76, s4, v82
	v_add_u32_e32 v74, s8, v83
	v_mad_i64_i32 v[50:51], s[28:29], v13, s80, v[44:45]
	v_mad_i64_i32 v[52:53], s[28:29], v11, s80, v[44:45]
	v_mad_i64_i32 v[54:55], s[28:29], v54, s80, v[44:45]
	v_mad_i64_i32 v[56:57], s[28:29], v56, s80, v[44:45]
	v_mad_i64_i32 v[58:59], s[28:29], v58, s80, v[44:45]
	v_mad_i64_i32 v[60:61], s[28:29], v60, s80, v[44:45]
	v_mad_i64_i32 v[62:63], s[28:29], v62, s80, v[44:45]
	v_mad_i64_i32 v[64:65], s[28:29], v64, s80, v[44:45]
	v_mad_i64_i32 v[66:67], s[28:29], v66, s80, v[44:45]
	v_mad_i64_i32 v[68:69], s[28:29], v68, s80, v[44:45]
	v_mad_i64_i32 v[70:71], s[28:29], v70, s80, v[44:45]
	v_mad_i64_i32 v[72:73], s[28:29], v72, s80, v[44:45]
	v_mad_i64_i32 v[74:75], s[28:29], v74, s80, v[44:45]
	v_mad_i64_i32 v[76:77], s[28:29], v76, s80, v[44:45]
	global_load_dword v11, v[46:47], off
	global_load_dword v13, v[48:49], off
	global_load_dword v84, v[50:51], off
	global_load_dword v85, v[52:53], off
	global_load_dword v86, v[54:55], off
	global_load_dword v87, v[56:57], off
	global_load_dword v88, v[58:59], off
	global_load_dword v89, v[60:61], off
	global_load_dword v90, v[62:63], off
	global_load_dword v91, v[64:65], off
	global_load_dword v92, v[66:67], off
	global_load_dword v93, v[68:69], off
	global_load_dword v94, v[70:71], off
	global_load_dword v95, v[72:73], off
	global_load_dword v96, v[74:75], off
	global_load_dword v97, v[76:77], off
	s_add_i32 s9, s9, 16
	s_add_i32 s5, s5, 16
	s_lshl_b32 s28, s5, 1
	s_lshl_b32 s29, s9, 1
	v_or_b32_e32 v106, s28, v1
	v_or_b32_e32 v107, s29, v2
	s_add_i32 s30, s28, 4
	s_add_i32 s36, s29, 4
	s_add_i32 s37, s28, 8
	s_add_i32 s38, s29, 8
	s_add_i32 s39, s28, 12
	s_add_i32 s40, s29, 12
	s_add_i32 s41, s28, 16
	s_add_i32 s42, s29, 16
	s_add_i32 s43, s28, 20
	s_add_i32 s44, s29, 20
	s_add_i32 s45, s28, 24
	s_add_i32 s46, s29, 24
	s_add_i32 s28, s28, 28
	s_add_i32 s29, s29, 28
	v_add_u32_e32 v108, s4, v106
	v_add_u32_e32 v109, s8, v107
	v_or_b32_e32 v110, s30, v1
	v_or_b32_e32 v111, s36, v2
	v_or_b32_e32 v112, s37, v1
	v_or_b32_e32 v113, s38, v2
	v_or_b32_e32 v114, s39, v1
	v_or_b32_e32 v115, s40, v2
	v_or_b32_e32 v116, s41, v1
	v_or_b32_e32 v117, s42, v2
	v_or_b32_e32 v118, s43, v1
	v_or_b32_e32 v119, s44, v2
	v_or_b32_e32 v120, s45, v1
	v_or_b32_e32 v121, s46, v2
	v_or_b32_e32 v122, s28, v1
	v_or_b32_e32 v123, s29, v2
	v_mad_i64_i32 v[130:131], s[28:29], v109, s80, v[44:45]
	v_mad_i64_i32 v[132:133], s[28:29], v108, s80, v[44:45]
	v_add_u32_e32 v108, s4, v110
	v_add_u32_e32 v109, s8, v111
	v_add_u32_e32 v140, s4, v112
	v_add_u32_e32 v138, s8, v113
	v_add_u32_e32 v144, s4, v114
	v_add_u32_e32 v142, s8, v115
	v_add_u32_e32 v148, s4, v116
	v_add_u32_e32 v146, s8, v117
	v_add_u32_e32 v152, s4, v118
	v_add_u32_e32 v150, s8, v119
	v_add_u32_e32 v156, s4, v120
	v_add_u32_e32 v154, s8, v121
	v_add_u32_e32 v160, s4, v122
	v_add_u32_e32 v158, s8, v123
	v_mad_i64_i32 v[134:135], s[28:29], v109, s80, v[44:45]
	v_mad_i64_i32 v[136:137], s[28:29], v108, s80, v[44:45]
	v_mad_i64_i32 v[138:139], s[28:29], v138, s80, v[44:45]
	v_mad_i64_i32 v[140:141], s[28:29], v140, s80, v[44:45]
	v_mad_i64_i32 v[142:143], s[28:29], v142, s80, v[44:45]
	v_mad_i64_i32 v[144:145], s[28:29], v144, s80, v[44:45]
	v_mad_i64_i32 v[146:147], s[28:29], v146, s80, v[44:45]
	v_mad_i64_i32 v[148:149], s[28:29], v148, s80, v[44:45]
	v_mad_i64_i32 v[150:151], s[28:29], v150, s80, v[44:45]
	v_mad_i64_i32 v[152:153], s[28:29], v152, s80, v[44:45]
	v_mad_i64_i32 v[154:155], s[28:29], v154, s80, v[44:45]
	v_mad_i64_i32 v[156:157], s[28:29], v156, s80, v[44:45]
	v_mad_i64_i32 v[158:159], s[28:29], v158, s80, v[44:45]
	v_mad_i64_i32 v[160:161], s[28:29], v160, s80, v[44:45]
	global_load_dword v108, v[130:131], off
	global_load_dword v109, v[132:133], off
	global_load_dword v124, v[134:135], off
	global_load_dword v125, v[136:137], off
	global_load_dword v126, v[138:139], off
	global_load_dword v127, v[140:141], off
	global_load_dword v162, v[142:143], off
	global_load_dword v163, v[144:145], off
	global_load_dword v164, v[146:147], off
	global_load_dword v165, v[148:149], off
	global_load_dword v166, v[150:151], off
	global_load_dword v167, v[152:153], off
	global_load_dword v168, v[154:155], off
	global_load_dword v169, v[156:157], off
	global_load_dword v170, v[158:159], off
	global_load_dword v171, v[160:161], off
	v_mad_u64_u32 v[46:47], s[28:29], v9, s78, v[6:7]
	v_mad_u64_u32 v[48:49], s[28:29], v7, s78, v[6:7]
	v_mad_u64_u32 v[50:51], s[28:29], v17, s78, v[6:7]
	v_mad_u64_u32 v[52:53], s[28:29], v15, s78, v[6:7]
	v_mad_u64_u32 v[54:55], s[28:29], v35, s78, v[6:7]
	v_mad_u64_u32 v[56:57], s[28:29], v21, s78, v[6:7]
	v_mad_u64_u32 v[58:59], s[28:29], v39, s78, v[6:7]
	v_mad_u64_u32 v[60:61], s[28:29], v37, s78, v[6:7]
	v_mad_u64_u32 v[62:63], s[28:29], v43, s78, v[6:7]
	v_mad_u64_u32 v[64:65], s[28:29], v41, s78, v[6:7]
	v_mad_u64_u32 v[66:67], s[28:29], v79, s78, v[6:7]
	v_mad_u64_u32 v[68:69], s[28:29], v78, s78, v[6:7]
	v_mad_u64_u32 v[70:71], s[28:29], v81, s78, v[6:7]
	v_mad_u64_u32 v[72:73], s[28:29], v80, s78, v[6:7]
	v_mad_u64_u32 v[74:75], s[28:29], v83, s78, v[6:7]
	v_mad_u64_u32 v[76:77], s[28:29], v82, s78, v[6:7]
	s_waitcnt vmcnt(31)
	ds_write_b32 v46, v11
	s_waitcnt vmcnt(30)
	ds_write_b32 v48, v13
	s_waitcnt vmcnt(29)
	ds_write_b32 v50, v84
	s_waitcnt vmcnt(28)
	ds_write_b32 v52, v85
	s_waitcnt vmcnt(27)
	ds_write_b32 v54, v86
	s_waitcnt vmcnt(26)
	ds_write_b32 v56, v87
	s_waitcnt vmcnt(25)
	ds_write_b32 v58, v88
	s_waitcnt vmcnt(24)
	ds_write_b32 v60, v89
	s_waitcnt vmcnt(23)
	ds_write_b32 v62, v90
	s_waitcnt vmcnt(22)
	ds_write_b32 v64, v91
	s_waitcnt vmcnt(21)
	ds_write_b32 v66, v92
	s_waitcnt vmcnt(20)
	ds_write_b32 v68, v93
	s_waitcnt vmcnt(19)
	ds_write_b32 v70, v94
	s_waitcnt vmcnt(18)
	ds_write_b32 v72, v95
	s_waitcnt vmcnt(17)
	ds_write_b32 v74, v96
	s_waitcnt vmcnt(16)
	ds_write_b32 v76, v97
	v_mad_u64_u32 v[130:131], s[28:29], v107, s78, v[6:7]
	v_mad_u64_u32 v[132:133], s[28:29], v106, s78, v[6:7]
	v_mad_u64_u32 v[134:135], s[28:29], v111, s78, v[6:7]
	v_mad_u64_u32 v[136:137], s[28:29], v110, s78, v[6:7]
	v_mad_u64_u32 v[138:139], s[28:29], v113, s78, v[6:7]
	v_mad_u64_u32 v[140:141], s[28:29], v112, s78, v[6:7]
	v_mad_u64_u32 v[142:143], s[28:29], v115, s78, v[6:7]
	v_mad_u64_u32 v[144:145], s[28:29], v114, s78, v[6:7]
	v_mad_u64_u32 v[146:147], s[28:29], v117, s78, v[6:7]
	v_mad_u64_u32 v[148:149], s[28:29], v116, s78, v[6:7]
	v_mad_u64_u32 v[150:151], s[28:29], v119, s78, v[6:7]
	v_mad_u64_u32 v[152:153], s[28:29], v118, s78, v[6:7]
	v_mad_u64_u32 v[154:155], s[28:29], v121, s78, v[6:7]
	v_mad_u64_u32 v[156:157], s[28:29], v120, s78, v[6:7]
	v_mad_u64_u32 v[158:159], s[28:29], v123, s78, v[6:7]
	v_mad_u64_u32 v[160:161], s[28:29], v122, s78, v[6:7]
	s_waitcnt vmcnt(15)
	ds_write_b32 v130, v108
	s_waitcnt vmcnt(14)
	ds_write_b32 v132, v109
	s_waitcnt vmcnt(13)
	ds_write_b32 v134, v124
	s_waitcnt vmcnt(12)
	ds_write_b32 v136, v125
	s_waitcnt vmcnt(11)
	ds_write_b32 v138, v126
	s_waitcnt vmcnt(10)
	ds_write_b32 v140, v127
	s_waitcnt vmcnt(9)
	ds_write_b32 v142, v162
	s_waitcnt vmcnt(8)
	ds_write_b32 v144, v163
	s_waitcnt vmcnt(7)
	ds_write_b32 v146, v164
	s_waitcnt vmcnt(6)
	ds_write_b32 v148, v165
	s_waitcnt vmcnt(5)
	ds_write_b32 v150, v166
	s_waitcnt vmcnt(4)
	ds_write_b32 v152, v167
	s_waitcnt vmcnt(3)
	ds_write_b32 v154, v168
	s_waitcnt vmcnt(2)
	ds_write_b32 v156, v169
	s_waitcnt vmcnt(1)
	ds_write_b32 v158, v170
	s_waitcnt vmcnt(0)
	ds_write_b32 v160, v171
	s_add_i32 s9, s9, 16
	s_add_i32 s5, s5, 16
	s_add_i32 s11, s11, -16
	s_add_i32 s11, s11, -16
	s_cmp_lg_u32 s11, 0
	s_waitcnt lgkmcnt(0)
	s_add_i32 s4, s10, 0xf500
	ds_read2_b32 v[48:49], v3 offset1:8
	s_cmpk_lt_i32 s0, 0x58
	ds_read2_b32 v[52:53], v3 offset0:33 offset1:41
	s_cselect_b32 s0, s10, s4
	s_sext_i32_i16 s4, s0
	ds_read2_b32 v[54:55], v3 offset0:66 offset1:74
	s_cselect_b32 s5, 0, 0x80
	s_bfe_u32 s4, s4, 0x70018
	ds_read2_b32 v[56:57], v3 offset0:99 offset1:107
	s_add_i32 s4, s0, s4
	s_waitcnt lgkmcnt(3)
	s_sext_i32_i16 s9, s4
	s_and_b32 s4, s4, 0xff80
	s_waitcnt lgkmcnt(2)
	ds_read2_b32 v[58:59], v3 offset0:132 offset1:140
	s_sub_i32 s0, s0, s4
	v_cvt_pk_bf16_f32 v9, v48, v52
	ds_read2_b32 v[60:61], v3 offset0:165 offset1:173
	s_lshl_b32 s9, s9, 1
	s_sext_i32_i16 s0, s0
	v_mov_b32_e32 v44, v9
	s_waitcnt lgkmcnt(3)
	s_and_b32 s9, s9, 0xffffff00
	s_add_i32 s0, s5, s0
	s_waitcnt lgkmcnt(2)
	ds_read2_b32 v[62:63], v3 offset0:198 offset1:206
	s_add_i32 s4, s0, s9
	v_cvt_pk_bf16_f32 v9, v54, v56
	ds_read2_b32 v[64:65], v3 offset0:231 offset1:239
	s_ashr_i32 s5, s4, 31
	v_mov_b32_e32 v45, v9
	s_waitcnt lgkmcnt(3)
	s_lshl_b64 s[4:5], s[4:5], 11
	s_waitcnt lgkmcnt(2)
	s_add_u32 s0, s20, s4
	v_cvt_pk_bf16_f32 v9, v58, v60
	s_addc_u32 s10, s21, s5
	s_ashr_i32 s9, s8, 31
	v_mov_b32_e32 v46, v9
	s_waitcnt lgkmcnt(1)
	s_lshl_b64 s[4:5], s[8:9], 1
	s_waitcnt lgkmcnt(0)
	s_add_u32 s4, s0, s4
	v_cvt_pk_bf16_f32 v9, v62, v64
	s_addc_u32 s5, s10, s5
	v_lshlrev_b32_e32 v128, 1, v8
	v_mov_b32_e32 v47, v9
	v_lshl_add_u64 v[50:51], s[4:5], 0, v[128:129]
	v_lshlrev_b32_e32 v128, 1, v10
	v_lshl_add_u64 v[66:67], v[50:51], 0, v[128:129]
	v_cvt_pk_bf16_f32 v9, v49, v53
	global_store_dwordx4 v[66:67], v[44:47], off
	v_lshlrev_b32_e32 v128, 1, v12
	ds_read2_b32 v[48:49], v3 offset0:16 offset1:24
	v_mov_b32_e32 v44, v9
	v_cvt_pk_bf16_f32 v9, v55, v57
	v_mov_b32_e32 v45, v9
	v_cvt_pk_bf16_f32 v9, v59, v61
	v_mov_b32_e32 v46, v9
	v_cvt_pk_bf16_f32 v9, v63, v65
	v_mov_b32_e32 v47, v9
	v_lshl_add_u64 v[52:53], v[50:51], 0, v[128:129]
	global_store_dwordx4 v[52:53], v[44:47], off
	ds_read2_b32 v[52:53], v3 offset0:49 offset1:57
	ds_read2_b32 v[54:55], v3 offset0:82 offset1:90
	ds_read2_b32 v[56:57], v3 offset0:115 offset1:123
	s_waitcnt lgkmcnt(3)
	s_waitcnt lgkmcnt(2)
	ds_read2_b32 v[58:59], v3 offset0:148 offset1:156
	v_cvt_pk_bf16_f32 v9, v48, v52
	ds_read2_b32 v[60:61], v3 offset0:181 offset1:189
	v_mov_b32_e32 v44, v9
	s_waitcnt lgkmcnt(3)
	s_waitcnt lgkmcnt(2)
	ds_read2_b32 v[62:63], v3 offset0:214 offset1:222
	v_cvt_pk_bf16_f32 v9, v54, v56
	ds_read2_b32 v[64:65], v3 offset0:247 offset1:255
	v_mov_b32_e32 v45, v9
	s_waitcnt lgkmcnt(3)
	s_waitcnt lgkmcnt(2)
	v_cvt_pk_bf16_f32 v9, v58, v60
	v_mov_b32_e32 v46, v9
	s_waitcnt lgkmcnt(1)
	s_waitcnt lgkmcnt(0)
	v_cvt_pk_bf16_f32 v9, v62, v64
	v_mov_b32_e32 v47, v9
	v_lshlrev_b32_e32 v128, 1, v14
	v_lshl_add_u64 v[66:67], v[50:51], 0, v[128:129]
	v_cvt_pk_bf16_f32 v9, v49, v53
	global_store_dwordx4 v[66:67], v[44:47], off
	v_lshlrev_b32_e32 v128, 1, v16
	v_lshl_add_u64 v[48:49], v[50:51], 0, v[128:129]
	v_mov_b32_e32 v44, v9
	v_cvt_pk_bf16_f32 v9, v55, v57
	v_mov_b32_e32 v45, v9
	v_cvt_pk_bf16_f32 v9, v59, v61
	v_mov_b32_e32 v46, v9
	v_cvt_pk_bf16_f32 v9, v63, v65
	v_mov_b32_e32 v47, v9
	global_store_dwordx4 v[48:49], v[44:47], off
	s_waitcnt lgkmcnt(0)
	s_mov_b32 s0, s1
	s_andn2_b64 vcc, exec, s[6:7]
	s_mov_b64 s[6:7], -1
	s_cbranch_vccnz .LBB0_832

.LBB0_805:
	s_lshl_b32 s11, s1, 1
	s_lshl_b32 s28, s5, 1
	v_or_b32_e32 v7, s11, v1
	v_or_b32_e32 v9, s28, v2
	s_add_i32 s29, s11, 4
	s_add_i32 s30, s28, 4
	s_add_i32 s36, s11, 8
	s_add_i32 s37, s28, 8
	s_add_i32 s38, s11, 12
	s_add_i32 s39, s28, 12
	s_add_i32 s40, s11, 16
	s_add_i32 s41, s28, 16
	s_add_i32 s42, s11, 20
	s_add_i32 s43, s28, 20
	s_add_i32 s44, s11, 24
	s_add_i32 s45, s28, 24
	s_add_i32 s11, s11, 28
	s_add_i32 s28, s28, 28
	v_add_u32_e32 v48, s8, v9
	v_or_b32_e32 v11, s29, v1
	v_or_b32_e32 v13, s30, v2
	v_or_b32_e32 v15, s36, v1
	v_or_b32_e32 v17, s37, v2
	v_or_b32_e32 v21, s38, v1
	v_or_b32_e32 v35, s39, v2
	v_or_b32_e32 v37, s40, v1
	v_or_b32_e32 v39, s41, v2
	v_or_b32_e32 v41, s42, v1
	v_or_b32_e32 v43, s43, v2
	v_or_b32_e32 v78, s44, v1
	v_or_b32_e32 v79, s45, v2
	v_or_b32_e32 v80, s11, v1
	v_or_b32_e32 v81, s28, v2
	v_add_u32_e32 v46, s4, v7
	v_ashrrev_i32_e32 v49, 31, v48
	v_add_u32_e32 v50, s4, v11
	v_add_u32_e32 v52, s8, v13
	v_add_u32_e32 v54, s4, v15
	v_add_u32_e32 v56, s8, v17
	v_add_u32_e32 v58, s4, v21
	v_add_u32_e32 v60, s8, v35
	v_add_u32_e32 v62, s4, v37
	v_add_u32_e32 v64, s8, v39
	v_add_u32_e32 v66, s4, v41
	v_add_u32_e32 v68, s8, v43
	v_add_u32_e32 v70, s4, v78
	v_add_u32_e32 v72, s8, v79
	v_add_u32_e32 v74, s4, v80
	v_add_u32_e32 v76, s8, v81
	v_ashrrev_i32_e32 v47, 31, v46
	v_lshlrev_b64 v[48:49], 12, v[48:49]
	v_ashrrev_i32_e32 v53, 31, v52
	v_ashrrev_i32_e32 v51, 31, v50
	v_ashrrev_i32_e32 v57, 31, v56
	v_ashrrev_i32_e32 v55, 31, v54
	v_ashrrev_i32_e32 v61, 31, v60
	v_ashrrev_i32_e32 v59, 31, v58
	v_ashrrev_i32_e32 v65, 31, v64
	v_ashrrev_i32_e32 v63, 31, v62
	v_ashrrev_i32_e32 v69, 31, v68
	v_ashrrev_i32_e32 v67, 31, v66
	v_ashrrev_i32_e32 v73, 31, v72
	v_ashrrev_i32_e32 v71, 31, v70
	v_ashrrev_i32_e32 v77, 31, v76
	v_ashrrev_i32_e32 v75, 31, v74
	v_lshlrev_b64 v[46:47], 12, v[46:47]
	v_lshl_add_u64 v[48:49], v[44:45], 0, v[48:49]
	v_lshlrev_b64 v[50:51], 12, v[50:51]
	v_lshlrev_b64 v[52:53], 12, v[52:53]
	v_lshlrev_b64 v[54:55], 12, v[54:55]
	v_lshlrev_b64 v[56:57], 12, v[56:57]
	v_lshlrev_b64 v[58:59], 12, v[58:59]
	v_lshlrev_b64 v[60:61], 12, v[60:61]
	v_lshlrev_b64 v[62:63], 12, v[62:63]
	v_lshlrev_b64 v[64:65], 12, v[64:65]
	v_lshlrev_b64 v[66:67], 12, v[66:67]
	v_lshlrev_b64 v[68:69], 12, v[68:69]
	v_lshlrev_b64 v[70:71], 12, v[70:71]
	v_lshlrev_b64 v[72:73], 12, v[72:73]
	v_lshlrev_b64 v[74:75], 12, v[74:75]
	v_lshlrev_b64 v[76:77], 12, v[76:77]
	v_lshl_add_u64 v[46:47], v[44:45], 0, v[46:47]
	v_lshl_add_u64 v[52:53], v[44:45], 0, v[52:53]
	v_lshl_add_u64 v[50:51], v[44:45], 0, v[50:51]
	v_lshl_add_u64 v[56:57], v[44:45], 0, v[56:57]
	v_lshl_add_u64 v[54:55], v[44:45], 0, v[54:55]
	v_lshl_add_u64 v[60:61], v[44:45], 0, v[60:61]
	v_lshl_add_u64 v[58:59], v[44:45], 0, v[58:59]
	v_lshl_add_u64 v[64:65], v[44:45], 0, v[64:65]
	v_lshl_add_u64 v[62:63], v[44:45], 0, v[62:63]
	v_lshl_add_u64 v[68:69], v[44:45], 0, v[68:69]
	v_lshl_add_u64 v[66:67], v[44:45], 0, v[66:67]
	v_lshl_add_u64 v[72:73], v[44:45], 0, v[72:73]
	v_lshl_add_u64 v[70:71], v[44:45], 0, v[70:71]
	v_lshl_add_u64 v[76:77], v[44:45], 0, v[76:77]
	v_lshl_add_u64 v[74:75], v[44:45], 0, v[74:75]
	global_load_dword v82, v[48:49], off
	global_load_dword v83, v[46:47], off
	global_load_dword v84, v[52:53], off
	global_load_dword v85, v[50:51], off
	global_load_dword v86, v[56:57], off
	global_load_dword v87, v[54:55], off
	global_load_dword v88, v[60:61], off
	global_load_dword v89, v[58:59], off
	global_load_dword v90, v[64:65], off
	global_load_dword v91, v[62:63], off
	global_load_dword v92, v[68:69], off
	global_load_dword v93, v[66:67], off
	global_load_dword v94, v[72:73], off
	global_load_dword v95, v[70:71], off
	global_load_dword v96, v[76:77], off
	global_load_dword v97, v[74:75], off
	s_add_i32 s5, s5, 16
	s_add_i32 s1, s1, 16
	s_lshl_b32 s11, s1, 1
	s_lshl_b32 s28, s5, 1
	v_or_b32_e32 v106, s11, v1
	v_or_b32_e32 v107, s28, v2
	s_add_i32 s29, s11, 4
	s_add_i32 s30, s28, 4
	s_add_i32 s36, s11, 8
	s_add_i32 s37, s28, 8
	s_add_i32 s38, s11, 12
	s_add_i32 s39, s28, 12
	s_add_i32 s40, s11, 16
	s_add_i32 s41, s28, 16
	s_add_i32 s42, s11, 20
	s_add_i32 s43, s28, 20
	s_add_i32 s44, s11, 24
	s_add_i32 s45, s28, 24
	s_add_i32 s11, s11, 28
	s_add_i32 s28, s28, 28
	v_add_u32_e32 v132, s8, v107
	v_or_b32_e32 v108, s29, v1
	v_or_b32_e32 v109, s30, v2
	v_or_b32_e32 v110, s36, v1
	v_or_b32_e32 v111, s37, v2
	v_or_b32_e32 v112, s38, v1
	v_or_b32_e32 v113, s39, v2
	v_or_b32_e32 v114, s40, v1
	v_or_b32_e32 v115, s41, v2
	v_or_b32_e32 v116, s42, v1
	v_or_b32_e32 v117, s43, v2
	v_or_b32_e32 v118, s44, v1
	v_or_b32_e32 v119, s45, v2
	v_or_b32_e32 v120, s11, v1
	v_or_b32_e32 v121, s28, v2
	v_add_u32_e32 v130, s4, v106
	v_ashrrev_i32_e32 v133, 31, v132
	v_add_u32_e32 v134, s4, v108
	v_add_u32_e32 v136, s8, v109
	v_add_u32_e32 v138, s4, v110
	v_add_u32_e32 v140, s8, v111
	v_add_u32_e32 v142, s4, v112
	v_add_u32_e32 v144, s8, v113
	v_add_u32_e32 v146, s4, v114
	v_add_u32_e32 v148, s8, v115
	v_add_u32_e32 v150, s4, v116
	v_add_u32_e32 v152, s8, v117
	v_add_u32_e32 v154, s4, v118
	v_add_u32_e32 v156, s8, v119
	v_add_u32_e32 v158, s4, v120
	v_add_u32_e32 v160, s8, v121
	v_ashrrev_i32_e32 v131, 31, v130
	v_lshlrev_b64 v[132:133], 12, v[132:133]
	v_ashrrev_i32_e32 v137, 31, v136
	v_ashrrev_i32_e32 v135, 31, v134
	v_ashrrev_i32_e32 v141, 31, v140
	v_ashrrev_i32_e32 v139, 31, v138
	v_ashrrev_i32_e32 v145, 31, v144
	v_ashrrev_i32_e32 v143, 31, v142
	v_ashrrev_i32_e32 v149, 31, v148
	v_ashrrev_i32_e32 v147, 31, v146
	v_ashrrev_i32_e32 v153, 31, v152
	v_ashrrev_i32_e32 v151, 31, v150
	v_ashrrev_i32_e32 v157, 31, v156
	v_ashrrev_i32_e32 v155, 31, v154
	v_ashrrev_i32_e32 v161, 31, v160
	v_ashrrev_i32_e32 v159, 31, v158
	v_lshlrev_b64 v[130:131], 12, v[130:131]
	v_lshl_add_u64 v[132:133], v[44:45], 0, v[132:133]
	v_lshlrev_b64 v[134:135], 12, v[134:135]
	v_lshlrev_b64 v[136:137], 12, v[136:137]
	v_lshlrev_b64 v[138:139], 12, v[138:139]
	v_lshlrev_b64 v[140:141], 12, v[140:141]
	v_lshlrev_b64 v[142:143], 12, v[142:143]
	v_lshlrev_b64 v[144:145], 12, v[144:145]
	v_lshlrev_b64 v[146:147], 12, v[146:147]
	v_lshlrev_b64 v[148:149], 12, v[148:149]
	v_lshlrev_b64 v[150:151], 12, v[150:151]
	v_lshlrev_b64 v[152:153], 12, v[152:153]
	v_lshlrev_b64 v[154:155], 12, v[154:155]
	v_lshlrev_b64 v[156:157], 12, v[156:157]
	v_lshlrev_b64 v[158:159], 12, v[158:159]
	v_lshlrev_b64 v[160:161], 12, v[160:161]
	v_lshl_add_u64 v[130:131], v[44:45], 0, v[130:131]
	v_lshl_add_u64 v[136:137], v[44:45], 0, v[136:137]
	v_lshl_add_u64 v[134:135], v[44:45], 0, v[134:135]
	v_lshl_add_u64 v[140:141], v[44:45], 0, v[140:141]
	v_lshl_add_u64 v[138:139], v[44:45], 0, v[138:139]
	v_lshl_add_u64 v[144:145], v[44:45], 0, v[144:145]
	v_lshl_add_u64 v[142:143], v[44:45], 0, v[142:143]
	v_lshl_add_u64 v[148:149], v[44:45], 0, v[148:149]
	v_lshl_add_u64 v[146:147], v[44:45], 0, v[146:147]
	v_lshl_add_u64 v[152:153], v[44:45], 0, v[152:153]
	v_lshl_add_u64 v[150:151], v[44:45], 0, v[150:151]
	v_lshl_add_u64 v[156:157], v[44:45], 0, v[156:157]
	v_lshl_add_u64 v[154:155], v[44:45], 0, v[154:155]
	v_lshl_add_u64 v[160:161], v[44:45], 0, v[160:161]
	v_lshl_add_u64 v[158:159], v[44:45], 0, v[158:159]
	global_load_dword v122, v[132:133], off
	global_load_dword v123, v[130:131], off
	global_load_dword v124, v[136:137], off
	global_load_dword v125, v[134:135], off
	global_load_dword v126, v[140:141], off
	global_load_dword v127, v[138:139], off
	global_load_dword v162, v[144:145], off
	global_load_dword v163, v[142:143], off
	global_load_dword v164, v[148:149], off
	global_load_dword v165, v[146:147], off
	global_load_dword v166, v[152:153], off
	global_load_dword v167, v[150:151], off
	global_load_dword v168, v[156:157], off
	global_load_dword v169, v[154:155], off
	global_load_dword v170, v[160:161], off
	global_load_dword v171, v[158:159], off
	v_mad_u64_u32 v[46:47], s[28:29], v9, s78, v[6:7]
	v_mad_u64_u32 v[48:49], s[28:29], v7, s78, v[6:7]
	v_mad_u64_u32 v[50:51], s[28:29], v13, s78, v[6:7]
	v_mad_u64_u32 v[52:53], s[28:29], v11, s78, v[6:7]
	v_mad_u64_u32 v[54:55], s[28:29], v17, s78, v[6:7]
	v_mad_u64_u32 v[56:57], s[28:29], v15, s78, v[6:7]
	v_mad_u64_u32 v[58:59], s[28:29], v35, s78, v[6:7]
	v_mad_u64_u32 v[60:61], s[28:29], v21, s78, v[6:7]
	v_mad_u64_u32 v[62:63], s[28:29], v39, s78, v[6:7]
	v_mad_u64_u32 v[64:65], s[28:29], v37, s78, v[6:7]
	v_mad_u64_u32 v[66:67], s[28:29], v43, s78, v[6:7]
	v_mad_u64_u32 v[68:69], s[28:29], v41, s78, v[6:7]
	v_mad_u64_u32 v[70:71], s[28:29], v79, s78, v[6:7]
	v_mad_u64_u32 v[72:73], s[28:29], v78, s78, v[6:7]
	v_mad_u64_u32 v[74:75], s[28:29], v81, s78, v[6:7]
	v_mad_u64_u32 v[76:77], s[28:29], v80, s78, v[6:7]
	s_waitcnt vmcnt(31)
	ds_write_b32 v46, v82
	s_waitcnt vmcnt(30)
	ds_write_b32 v48, v83
	s_waitcnt vmcnt(29)
	ds_write_b32 v50, v84
	s_waitcnt vmcnt(28)
	ds_write_b32 v52, v85
	s_waitcnt vmcnt(27)
	ds_write_b32 v54, v86
	s_waitcnt vmcnt(26)
	ds_write_b32 v56, v87
	s_waitcnt vmcnt(25)
	ds_write_b32 v58, v88
	s_waitcnt vmcnt(24)
	ds_write_b32 v60, v89
	s_waitcnt vmcnt(23)
	ds_write_b32 v62, v90
	s_waitcnt vmcnt(22)
	ds_write_b32 v64, v91
	s_waitcnt vmcnt(21)
	ds_write_b32 v66, v92
	s_waitcnt vmcnt(20)
	ds_write_b32 v68, v93
	s_waitcnt vmcnt(19)
	ds_write_b32 v70, v94
	s_waitcnt vmcnt(18)
	ds_write_b32 v72, v95
	s_waitcnt vmcnt(17)
	ds_write_b32 v74, v96
	s_waitcnt vmcnt(16)
	ds_write_b32 v76, v97
	v_mad_u64_u32 v[130:131], s[28:29], v107, s78, v[6:7]
	v_mad_u64_u32 v[132:133], s[28:29], v106, s78, v[6:7]
	v_mad_u64_u32 v[134:135], s[28:29], v109, s78, v[6:7]
	v_mad_u64_u32 v[136:137], s[28:29], v108, s78, v[6:7]
	v_mad_u64_u32 v[138:139], s[28:29], v111, s78, v[6:7]
	v_mad_u64_u32 v[140:141], s[28:29], v110, s78, v[6:7]
	v_mad_u64_u32 v[142:143], s[28:29], v113, s78, v[6:7]
	v_mad_u64_u32 v[144:145], s[28:29], v112, s78, v[6:7]
	v_mad_u64_u32 v[146:147], s[28:29], v115, s78, v[6:7]
	v_mad_u64_u32 v[148:149], s[28:29], v114, s78, v[6:7]
	v_mad_u64_u32 v[150:151], s[28:29], v117, s78, v[6:7]
	v_mad_u64_u32 v[152:153], s[28:29], v116, s78, v[6:7]
	v_mad_u64_u32 v[154:155], s[28:29], v119, s78, v[6:7]
	v_mad_u64_u32 v[156:157], s[28:29], v118, s78, v[6:7]
	v_mad_u64_u32 v[158:159], s[28:29], v121, s78, v[6:7]
	v_mad_u64_u32 v[160:161], s[28:29], v120, s78, v[6:7]
	s_waitcnt vmcnt(15)
	ds_write_b32 v130, v122
	s_waitcnt vmcnt(14)
	ds_write_b32 v132, v123
	s_waitcnt vmcnt(13)
	ds_write_b32 v134, v124
	s_waitcnt vmcnt(12)
	ds_write_b32 v136, v125
	s_waitcnt vmcnt(11)
	ds_write_b32 v138, v126
	s_waitcnt vmcnt(10)
	ds_write_b32 v140, v127
	s_waitcnt vmcnt(9)
	ds_write_b32 v142, v162
	s_waitcnt vmcnt(8)
	ds_write_b32 v144, v163
	s_waitcnt vmcnt(7)
	ds_write_b32 v146, v164
	s_waitcnt vmcnt(6)
	ds_write_b32 v148, v165
	s_waitcnt vmcnt(5)
	ds_write_b32 v150, v166
	s_waitcnt vmcnt(4)
	ds_write_b32 v152, v167
	s_waitcnt vmcnt(3)
	ds_write_b32 v154, v168
	s_waitcnt vmcnt(2)
	ds_write_b32 v156, v169
	s_waitcnt vmcnt(1)
	ds_write_b32 v158, v170
	s_waitcnt vmcnt(0)
	ds_write_b32 v160, v171
	s_add_i32 s5, s5, 16
	s_add_i32 s1, s1, 16
	s_add_i32 s9, s9, -16
	s_add_i32 s9, s9, -16
	s_cmp_lg_u32 s9, 0
	s_waitcnt lgkmcnt(0)
	ds_read2_b32 v[48:49], v3 offset1:8
	ds_read2_b32 v[52:53], v3 offset0:33 offset1:41
	ds_read2_b32 v[54:55], v3 offset0:66 offset1:74
	ds_read2_b32 v[56:57], v3 offset0:99 offset1:107
	ds_read2_b32 v[58:59], v3 offset0:132 offset1:140
	s_waitcnt lgkmcnt(4)
	s_waitcnt lgkmcnt(3)
	v_cvt_pk_bf16_f32 v9, v48, v52
	ds_read2_b32 v[60:61], v3 offset0:165 offset1:173
	v_mov_b32_e32 v44, v9
	s_waitcnt lgkmcnt(3)
	s_waitcnt lgkmcnt(2)
	ds_read2_b32 v[62:63], v3 offset0:198 offset1:206
	v_cvt_pk_bf16_f32 v9, v54, v56
	ds_read2_b32 v[64:65], v3 offset0:231 offset1:239
	v_mov_b32_e32 v45, v9
	s_waitcnt lgkmcnt(3)
	s_mul_i32 s4, s10, 0x1600
	s_waitcnt lgkmcnt(2)
	s_mul_hi_i32 s1, s10, 0x1600
	s_add_u32 s10, s22, s4
	v_cvt_pk_bf16_f32 v9, v58, v60
	s_addc_u32 s1, s23, s1
	s_ashr_i32 s9, s8, 31
	v_mov_b32_e32 v46, v9
	s_waitcnt lgkmcnt(1)
	s_lshl_b64 s[4:5], s[8:9], 1
	s_waitcnt lgkmcnt(0)
	s_add_u32 s4, s10, s4
	v_cvt_pk_bf16_f32 v9, v62, v64
	s_addc_u32 s5, s1, s5
	v_lshlrev_b32_e32 v128, 1, v8
	v_mov_b32_e32 v47, v9
	v_lshl_add_u64 v[50:51], s[4:5], 0, v[128:129]
	v_lshlrev_b32_e32 v128, 1, v20
	v_lshl_add_u64 v[50:51], v[50:51], 0, v[128:129]
	v_cvt_pk_bf16_f32 v9, v49, v53
	global_store_dwordx4 v[50:51], v[44:47], off
	v_add_co_u32_e32 v52, vcc, s47, v50
	s_nop 0
	v_mov_b32_e32 v44, v9
	v_cvt_pk_bf16_f32 v9, v55, v57
	v_mov_b32_e32 v45, v9
	v_cvt_pk_bf16_f32 v9, v59, v61
	v_mov_b32_e32 v46, v9
	v_cvt_pk_bf16_f32 v9, v63, v65
	v_mov_b32_e32 v47, v9
	ds_read2_b32 v[48:49], v3 offset0:16 offset1:24
	v_addc_co_u32_e32 v53, vcc, 0, v51, vcc
	global_store_dwordx4 v[52:53], v[44:47], off
	ds_read2_b32 v[52:53], v3 offset0:49 offset1:57
	ds_read2_b32 v[54:55], v3 offset0:82 offset1:90
	ds_read2_b32 v[56:57], v3 offset0:115 offset1:123
	s_waitcnt lgkmcnt(3)
	s_waitcnt lgkmcnt(2)
	ds_read2_b32 v[58:59], v3 offset0:148 offset1:156
	v_cvt_pk_bf16_f32 v9, v48, v52
	ds_read2_b32 v[60:61], v3 offset0:181 offset1:189
	v_mov_b32_e32 v44, v9
	s_waitcnt lgkmcnt(3)
	s_waitcnt lgkmcnt(2)
	ds_read2_b32 v[62:63], v3 offset0:214 offset1:222
	v_cvt_pk_bf16_f32 v9, v54, v56
	ds_read2_b32 v[64:65], v3 offset0:247 offset1:255
	v_mov_b32_e32 v45, v9
	s_waitcnt lgkmcnt(3)
	s_waitcnt lgkmcnt(2)
	v_cvt_pk_bf16_f32 v9, v58, v60
	v_mov_b32_e32 v46, v9
	s_waitcnt lgkmcnt(1)
	s_waitcnt lgkmcnt(0)
	v_cvt_pk_bf16_f32 v9, v62, v64
	v_mov_b32_e32 v47, v9
	v_add_co_u32_e32 v66, vcc, s48, v50
	v_addc_co_u32_e32 v67, vcc, 0, v51, vcc
	v_cvt_pk_bf16_f32 v9, v49, v53
	global_store_dwordx4 v[66:67], v[44:47], off
	v_add_co_u32_e32 v48, vcc, 0x21000, v50
	s_nop 0
	v_mov_b32_e32 v44, v9
	v_cvt_pk_bf16_f32 v9, v55, v57
	v_mov_b32_e32 v45, v9
	v_cvt_pk_bf16_f32 v9, v59, v61
	v_mov_b32_e32 v46, v9
	v_cvt_pk_bf16_f32 v9, v63, v65
	v_mov_b32_e32 v47, v9
	v_addc_co_u32_e32 v49, vcc, 0, v51, vcc
	global_store_dwordx4 v[48:49], v[44:47], off
	s_waitcnt lgkmcnt(0)
	s_mov_b32 s4, s0
	s_andn2_b64 vcc, exec, s[6:7]
	s_mov_b64 s[6:7], -1
	s_cbranch_vccnz .LBB0_832

.LBB0_812:
	s_lshl_b32 s28, s1, 1
	s_lshl_b32 s29, s5, 1
	v_or_b32_e32 v7, s28, v1
	v_or_b32_e32 v9, s29, v2
	s_add_i32 s30, s28, 4
	s_add_i32 s36, s29, 4
	s_add_i32 s37, s28, 8
	s_add_i32 s38, s29, 8
	s_add_i32 s39, s28, 12
	s_add_i32 s40, s29, 12
	s_add_i32 s41, s28, 16
	s_add_i32 s42, s29, 16
	s_add_i32 s43, s28, 20
	s_add_i32 s44, s29, 20
	s_add_i32 s45, s28, 24
	s_add_i32 s46, s29, 24
	s_add_i32 s28, s28, 28
	s_add_i32 s29, s29, 28
	v_add_u32_e32 v11, s0, v7
	v_add_u32_e32 v13, s8, v9
	v_or_b32_e32 v15, s30, v1
	v_or_b32_e32 v17, s36, v2
	v_or_b32_e32 v21, s37, v1
	v_or_b32_e32 v35, s38, v2
	v_or_b32_e32 v37, s39, v1
	v_or_b32_e32 v39, s40, v2
	v_or_b32_e32 v41, s41, v1
	v_or_b32_e32 v43, s42, v2
	v_or_b32_e32 v78, s43, v1
	v_or_b32_e32 v79, s44, v2
	v_or_b32_e32 v80, s45, v1
	v_or_b32_e32 v81, s46, v2
	v_or_b32_e32 v82, s28, v1
	v_or_b32_e32 v83, s29, v2
	v_mad_i64_i32 v[46:47], s[28:29], v13, s79, v[44:45]
	v_mad_i64_i32 v[48:49], s[28:29], v11, s79, v[44:45]
	v_add_u32_e32 v11, s0, v15
	v_add_u32_e32 v13, s8, v17
	v_add_u32_e32 v56, s0, v21
	v_add_u32_e32 v54, s8, v35
	v_add_u32_e32 v60, s0, v37
	v_add_u32_e32 v58, s8, v39
	v_add_u32_e32 v64, s0, v41
	v_add_u32_e32 v62, s8, v43
	v_add_u32_e32 v68, s0, v78
	v_add_u32_e32 v66, s8, v79
	v_add_u32_e32 v72, s0, v80
	v_add_u32_e32 v70, s8, v81
	v_add_u32_e32 v76, s0, v82
	v_add_u32_e32 v74, s8, v83
	v_mad_i64_i32 v[50:51], s[28:29], v13, s79, v[44:45]
	v_mad_i64_i32 v[52:53], s[28:29], v11, s79, v[44:45]
	v_mad_i64_i32 v[54:55], s[28:29], v54, s79, v[44:45]
	v_mad_i64_i32 v[56:57], s[28:29], v56, s79, v[44:45]
	v_mad_i64_i32 v[58:59], s[28:29], v58, s79, v[44:45]
	v_mad_i64_i32 v[60:61], s[28:29], v60, s79, v[44:45]
	v_mad_i64_i32 v[62:63], s[28:29], v62, s79, v[44:45]
	v_mad_i64_i32 v[64:65], s[28:29], v64, s79, v[44:45]
	v_mad_i64_i32 v[66:67], s[28:29], v66, s79, v[44:45]
	v_mad_i64_i32 v[68:69], s[28:29], v68, s79, v[44:45]
	v_mad_i64_i32 v[70:71], s[28:29], v70, s79, v[44:45]
	v_mad_i64_i32 v[72:73], s[28:29], v72, s79, v[44:45]
	v_mad_i64_i32 v[74:75], s[28:29], v74, s79, v[44:45]
	v_mad_i64_i32 v[76:77], s[28:29], v76, s79, v[44:45]
	global_load_dword v11, v[46:47], off
	global_load_dword v13, v[48:49], off
	global_load_dword v84, v[50:51], off
	global_load_dword v85, v[52:53], off
	global_load_dword v86, v[54:55], off
	global_load_dword v87, v[56:57], off
	global_load_dword v88, v[58:59], off
	global_load_dword v89, v[60:61], off
	global_load_dword v90, v[62:63], off
	global_load_dword v91, v[64:65], off
	global_load_dword v92, v[66:67], off
	global_load_dword v93, v[68:69], off
	global_load_dword v94, v[70:71], off
	global_load_dword v95, v[72:73], off
	global_load_dword v96, v[74:75], off
	global_load_dword v97, v[76:77], off
	s_add_i32 s5, s5, 16
	s_add_i32 s1, s1, 16
	s_lshl_b32 s28, s1, 1
	s_lshl_b32 s29, s5, 1
	v_or_b32_e32 v106, s28, v1
	v_or_b32_e32 v107, s29, v2
	s_add_i32 s30, s28, 4
	s_add_i32 s36, s29, 4
	s_add_i32 s37, s28, 8
	s_add_i32 s38, s29, 8
	s_add_i32 s39, s28, 12
	s_add_i32 s40, s29, 12
	s_add_i32 s41, s28, 16
	s_add_i32 s42, s29, 16
	s_add_i32 s43, s28, 20
	s_add_i32 s44, s29, 20
	s_add_i32 s45, s28, 24
	s_add_i32 s46, s29, 24
	s_add_i32 s28, s28, 28
	s_add_i32 s29, s29, 28
	v_add_u32_e32 v108, s0, v106
	v_add_u32_e32 v109, s8, v107
	v_or_b32_e32 v110, s30, v1
	v_or_b32_e32 v111, s36, v2
	v_or_b32_e32 v112, s37, v1
	v_or_b32_e32 v113, s38, v2
	v_or_b32_e32 v114, s39, v1
	v_or_b32_e32 v115, s40, v2
	v_or_b32_e32 v116, s41, v1
	v_or_b32_e32 v117, s42, v2
	v_or_b32_e32 v118, s43, v1
	v_or_b32_e32 v119, s44, v2
	v_or_b32_e32 v120, s45, v1
	v_or_b32_e32 v121, s46, v2
	v_or_b32_e32 v122, s28, v1
	v_or_b32_e32 v123, s29, v2
	v_mad_i64_i32 v[130:131], s[28:29], v109, s79, v[44:45]
	v_mad_i64_i32 v[132:133], s[28:29], v108, s79, v[44:45]
	v_add_u32_e32 v108, s0, v110
	v_add_u32_e32 v109, s8, v111
	v_add_u32_e32 v140, s0, v112
	v_add_u32_e32 v138, s8, v113
	v_add_u32_e32 v144, s0, v114
	v_add_u32_e32 v142, s8, v115
	v_add_u32_e32 v148, s0, v116
	v_add_u32_e32 v146, s8, v117
	v_add_u32_e32 v152, s0, v118
	v_add_u32_e32 v150, s8, v119
	v_add_u32_e32 v156, s0, v120
	v_add_u32_e32 v154, s8, v121
	v_add_u32_e32 v160, s0, v122
	v_add_u32_e32 v158, s8, v123
	v_mad_i64_i32 v[134:135], s[28:29], v109, s79, v[44:45]
	v_mad_i64_i32 v[136:137], s[28:29], v108, s79, v[44:45]
	v_mad_i64_i32 v[138:139], s[28:29], v138, s79, v[44:45]
	v_mad_i64_i32 v[140:141], s[28:29], v140, s79, v[44:45]
	v_mad_i64_i32 v[142:143], s[28:29], v142, s79, v[44:45]
	v_mad_i64_i32 v[144:145], s[28:29], v144, s79, v[44:45]
	v_mad_i64_i32 v[146:147], s[28:29], v146, s79, v[44:45]
	v_mad_i64_i32 v[148:149], s[28:29], v148, s79, v[44:45]
	v_mad_i64_i32 v[150:151], s[28:29], v150, s79, v[44:45]
	v_mad_i64_i32 v[152:153], s[28:29], v152, s79, v[44:45]
	v_mad_i64_i32 v[154:155], s[28:29], v154, s79, v[44:45]
	v_mad_i64_i32 v[156:157], s[28:29], v156, s79, v[44:45]
	v_mad_i64_i32 v[158:159], s[28:29], v158, s79, v[44:45]
	v_mad_i64_i32 v[160:161], s[28:29], v160, s79, v[44:45]
	global_load_dword v108, v[130:131], off
	global_load_dword v109, v[132:133], off
	global_load_dword v124, v[134:135], off
	global_load_dword v125, v[136:137], off
	global_load_dword v126, v[138:139], off
	global_load_dword v127, v[140:141], off
	global_load_dword v162, v[142:143], off
	global_load_dword v163, v[144:145], off
	global_load_dword v164, v[146:147], off
	global_load_dword v165, v[148:149], off
	global_load_dword v166, v[150:151], off
	global_load_dword v167, v[152:153], off
	global_load_dword v168, v[154:155], off
	global_load_dword v169, v[156:157], off
	global_load_dword v170, v[158:159], off
	global_load_dword v171, v[160:161], off
	v_mad_u64_u32 v[46:47], s[28:29], v9, s78, v[6:7]
	v_mad_u64_u32 v[48:49], s[28:29], v7, s78, v[6:7]
	v_mad_u64_u32 v[50:51], s[28:29], v17, s78, v[6:7]
	v_mad_u64_u32 v[52:53], s[28:29], v15, s78, v[6:7]
	v_mad_u64_u32 v[54:55], s[28:29], v35, s78, v[6:7]
	v_mad_u64_u32 v[56:57], s[28:29], v21, s78, v[6:7]
	v_mad_u64_u32 v[58:59], s[28:29], v39, s78, v[6:7]
	v_mad_u64_u32 v[60:61], s[28:29], v37, s78, v[6:7]
	v_mad_u64_u32 v[62:63], s[28:29], v43, s78, v[6:7]
	v_mad_u64_u32 v[64:65], s[28:29], v41, s78, v[6:7]
	v_mad_u64_u32 v[66:67], s[28:29], v79, s78, v[6:7]
	v_mad_u64_u32 v[68:69], s[28:29], v78, s78, v[6:7]
	v_mad_u64_u32 v[70:71], s[28:29], v81, s78, v[6:7]
	v_mad_u64_u32 v[72:73], s[28:29], v80, s78, v[6:7]
	v_mad_u64_u32 v[74:75], s[28:29], v83, s78, v[6:7]
	v_mad_u64_u32 v[76:77], s[28:29], v82, s78, v[6:7]
	s_waitcnt vmcnt(31)
	ds_write_b32 v46, v11
	s_waitcnt vmcnt(30)
	ds_write_b32 v48, v13
	s_waitcnt vmcnt(29)
	ds_write_b32 v50, v84
	s_waitcnt vmcnt(28)
	ds_write_b32 v52, v85
	s_waitcnt vmcnt(27)
	ds_write_b32 v54, v86
	s_waitcnt vmcnt(26)
	ds_write_b32 v56, v87
	s_waitcnt vmcnt(25)
	ds_write_b32 v58, v88
	s_waitcnt vmcnt(24)
	ds_write_b32 v60, v89
	s_waitcnt vmcnt(23)
	ds_write_b32 v62, v90
	s_waitcnt vmcnt(22)
	ds_write_b32 v64, v91
	s_waitcnt vmcnt(21)
	ds_write_b32 v66, v92
	s_waitcnt vmcnt(20)
	ds_write_b32 v68, v93
	s_waitcnt vmcnt(19)
	ds_write_b32 v70, v94
	s_waitcnt vmcnt(18)
	ds_write_b32 v72, v95
	s_waitcnt vmcnt(17)
	ds_write_b32 v74, v96
	s_waitcnt vmcnt(16)
	ds_write_b32 v76, v97
	v_mad_u64_u32 v[130:131], s[28:29], v107, s78, v[6:7]
	v_mad_u64_u32 v[132:133], s[28:29], v106, s78, v[6:7]
	v_mad_u64_u32 v[134:135], s[28:29], v111, s78, v[6:7]
	v_mad_u64_u32 v[136:137], s[28:29], v110, s78, v[6:7]
	v_mad_u64_u32 v[138:139], s[28:29], v113, s78, v[6:7]
	v_mad_u64_u32 v[140:141], s[28:29], v112, s78, v[6:7]
	v_mad_u64_u32 v[142:143], s[28:29], v115, s78, v[6:7]
	v_mad_u64_u32 v[144:145], s[28:29], v114, s78, v[6:7]
	v_mad_u64_u32 v[146:147], s[28:29], v117, s78, v[6:7]
	v_mad_u64_u32 v[148:149], s[28:29], v116, s78, v[6:7]
	v_mad_u64_u32 v[150:151], s[28:29], v119, s78, v[6:7]
	v_mad_u64_u32 v[152:153], s[28:29], v118, s78, v[6:7]
	v_mad_u64_u32 v[154:155], s[28:29], v121, s78, v[6:7]
	v_mad_u64_u32 v[156:157], s[28:29], v120, s78, v[6:7]
	v_mad_u64_u32 v[158:159], s[28:29], v123, s78, v[6:7]
	v_mad_u64_u32 v[160:161], s[28:29], v122, s78, v[6:7]
	s_waitcnt vmcnt(15)
	ds_write_b32 v130, v108
	s_waitcnt vmcnt(14)
	ds_write_b32 v132, v109
	s_waitcnt vmcnt(13)
	ds_write_b32 v134, v124
	s_waitcnt vmcnt(12)
	ds_write_b32 v136, v125
	s_waitcnt vmcnt(11)
	ds_write_b32 v138, v126
	s_waitcnt vmcnt(10)
	ds_write_b32 v140, v127
	s_waitcnt vmcnt(9)
	ds_write_b32 v142, v162
	s_waitcnt vmcnt(8)
	ds_write_b32 v144, v163
	s_waitcnt vmcnt(7)
	ds_write_b32 v146, v164
	s_waitcnt vmcnt(6)
	ds_write_b32 v148, v165
	s_waitcnt vmcnt(5)
	ds_write_b32 v150, v166
	s_waitcnt vmcnt(4)
	ds_write_b32 v152, v167
	s_waitcnt vmcnt(3)
	ds_write_b32 v154, v168
	s_waitcnt vmcnt(2)
	ds_write_b32 v156, v169
	s_waitcnt vmcnt(1)
	ds_write_b32 v158, v170
	s_waitcnt vmcnt(0)
	ds_write_b32 v160, v171
	s_add_i32 s5, s5, 16
	s_add_i32 s1, s1, 16
	s_add_i32 s9, s9, -16
	s_add_i32 s9, s9, -16
	s_cmp_lg_u32 s9, 0
	s_waitcnt lgkmcnt(0)
	ds_read2_b32 v[48:49], v3 offset1:8
	ds_read2_b32 v[52:53], v3 offset0:33 offset1:41
	ds_read2_b32 v[54:55], v3 offset0:66 offset1:74
	ds_read2_b32 v[56:57], v3 offset0:99 offset1:107
	ds_read2_b32 v[58:59], v3 offset0:132 offset1:140
	s_waitcnt lgkmcnt(4)
	s_waitcnt lgkmcnt(3)
	v_cvt_pk_bf16_f32 v9, v48, v52
	ds_read2_b32 v[60:61], v3 offset0:165 offset1:173
	v_mov_b32_e32 v44, v9
	s_waitcnt lgkmcnt(3)
	s_waitcnt lgkmcnt(2)
	ds_read2_b32 v[62:63], v3 offset0:198 offset1:206
	v_cvt_pk_bf16_f32 v9, v54, v56
	ds_read2_b32 v[64:65], v3 offset0:231 offset1:239
	v_mov_b32_e32 v45, v9
	s_waitcnt lgkmcnt(3)
	s_lshl_b64 s[0:1], s[10:11], 11
	s_waitcnt lgkmcnt(2)
	s_add_u32 s5, s16, s0
	v_cvt_pk_bf16_f32 v9, v58, v60
	s_addc_u32 s10, s17, s1
	s_ashr_i32 s9, s8, 31
	v_mov_b32_e32 v46, v9
	s_waitcnt lgkmcnt(1)
	s_lshl_b64 s[0:1], s[8:9], 1
	s_waitcnt lgkmcnt(0)
	s_add_u32 s0, s5, s0
	v_cvt_pk_bf16_f32 v9, v62, v64
	s_addc_u32 s1, s10, s1
	v_lshlrev_b32_e32 v128, 1, v8
	v_mov_b32_e32 v47, v9
	v_lshl_add_u64 v[50:51], s[0:1], 0, v[128:129]
	v_lshlrev_b32_e32 v128, 1, v10
	v_lshl_add_u64 v[66:67], v[50:51], 0, v[128:129]
	v_cvt_pk_bf16_f32 v9, v49, v53
	global_store_dwordx4 v[66:67], v[44:47], off
	v_lshlrev_b32_e32 v128, 1, v12
	ds_read2_b32 v[48:49], v3 offset0:16 offset1:24
	v_mov_b32_e32 v44, v9
	v_cvt_pk_bf16_f32 v9, v55, v57
	v_mov_b32_e32 v45, v9
	v_cvt_pk_bf16_f32 v9, v59, v61
	v_mov_b32_e32 v46, v9
	v_cvt_pk_bf16_f32 v9, v63, v65
	v_mov_b32_e32 v47, v9
	v_lshl_add_u64 v[52:53], v[50:51], 0, v[128:129]
	global_store_dwordx4 v[52:53], v[44:47], off
	ds_read2_b32 v[52:53], v3 offset0:49 offset1:57
	ds_read2_b32 v[54:55], v3 offset0:82 offset1:90
	ds_read2_b32 v[56:57], v3 offset0:115 offset1:123
	s_waitcnt lgkmcnt(3)
	s_waitcnt lgkmcnt(2)
	ds_read2_b32 v[58:59], v3 offset0:148 offset1:156
	v_cvt_pk_bf16_f32 v9, v48, v52
	ds_read2_b32 v[60:61], v3 offset0:181 offset1:189
	v_mov_b32_e32 v44, v9
	s_waitcnt lgkmcnt(3)
	s_waitcnt lgkmcnt(2)
	ds_read2_b32 v[62:63], v3 offset0:214 offset1:222
	v_cvt_pk_bf16_f32 v9, v54, v56
	ds_read2_b32 v[64:65], v3 offset0:247 offset1:255
	v_mov_b32_e32 v45, v9
	s_waitcnt lgkmcnt(3)
	s_waitcnt lgkmcnt(2)
	v_cvt_pk_bf16_f32 v9, v58, v60
	v_mov_b32_e32 v46, v9
	s_waitcnt lgkmcnt(1)
	s_waitcnt lgkmcnt(0)
	v_cvt_pk_bf16_f32 v9, v62, v64
	v_mov_b32_e32 v47, v9
	v_lshlrev_b32_e32 v128, 1, v14
	v_lshl_add_u64 v[66:67], v[50:51], 0, v[128:129]
	v_cvt_pk_bf16_f32 v9, v49, v53
	global_store_dwordx4 v[66:67], v[44:47], off
	v_lshlrev_b32_e32 v128, 1, v16
	v_lshl_add_u64 v[48:49], v[50:51], 0, v[128:129]
	v_mov_b32_e32 v44, v9
	v_cvt_pk_bf16_f32 v9, v55, v57
	v_mov_b32_e32 v45, v9
	v_cvt_pk_bf16_f32 v9, v59, v61
	v_mov_b32_e32 v46, v9
	v_cvt_pk_bf16_f32 v9, v63, v65
	v_mov_b32_e32 v47, v9
	global_store_dwordx4 v[48:49], v[44:47], off
	s_waitcnt lgkmcnt(0)
	s_mov_b32 s1, s4
	s_andn2_b64 vcc, exec, s[6:7]
	s_mov_b64 s[6:7], -1
	s_cbranch_vccnz .LBB0_832

.LBB0_819:
	s_lshl_b32 s11, s4, 1
	s_lshl_b32 s28, s5, 1
	v_or_b32_e32 v7, s11, v1
	v_or_b32_e32 v9, s28, v2
	s_add_i32 s29, s11, 4
	s_add_i32 s30, s28, 4
	s_add_i32 s36, s11, 8
	s_add_i32 s37, s28, 8
	s_add_i32 s38, s11, 12
	s_add_i32 s39, s28, 12
	s_add_i32 s40, s11, 16
	s_add_i32 s41, s28, 16
	s_add_i32 s42, s11, 20
	s_add_i32 s43, s28, 20
	s_add_i32 s44, s11, 24
	s_add_i32 s45, s28, 24
	s_add_i32 s11, s11, 28
	s_add_i32 s28, s28, 28
	v_add_u32_e32 v11, s0, v7
	v_add_u32_e32 v13, s8, v9
	v_or_b32_e32 v15, s29, v1
	v_or_b32_e32 v17, s30, v2
	v_or_b32_e32 v21, s36, v1
	v_or_b32_e32 v35, s37, v2
	v_or_b32_e32 v37, s38, v1
	v_or_b32_e32 v39, s39, v2
	v_or_b32_e32 v41, s40, v1
	v_or_b32_e32 v43, s41, v2
	v_or_b32_e32 v78, s42, v1
	v_or_b32_e32 v79, s43, v2
	v_or_b32_e32 v80, s44, v1
	v_or_b32_e32 v81, s45, v2
	v_or_b32_e32 v82, s11, v1
	v_or_b32_e32 v83, s28, v2
	v_mad_i64_i32 v[46:47], s[28:29], v13, s68, v[44:45]
	v_mad_i64_i32 v[48:49], s[28:29], v11, s68, v[44:45]
	v_add_u32_e32 v11, s0, v15
	v_add_u32_e32 v13, s8, v17
	v_add_u32_e32 v56, s0, v21
	v_add_u32_e32 v54, s8, v35
	v_add_u32_e32 v60, s0, v37
	v_add_u32_e32 v58, s8, v39
	v_add_u32_e32 v64, s0, v41
	v_add_u32_e32 v62, s8, v43
	v_add_u32_e32 v68, s0, v78
	v_add_u32_e32 v66, s8, v79
	v_add_u32_e32 v72, s0, v80
	v_add_u32_e32 v70, s8, v81
	v_add_u32_e32 v76, s0, v82
	v_add_u32_e32 v74, s8, v83
	v_mad_i64_i32 v[50:51], s[28:29], v13, s68, v[44:45]
	v_mad_i64_i32 v[52:53], s[28:29], v11, s68, v[44:45]
	v_mad_i64_i32 v[54:55], s[28:29], v54, s68, v[44:45]
	v_mad_i64_i32 v[56:57], s[28:29], v56, s68, v[44:45]
	v_mad_i64_i32 v[58:59], s[28:29], v58, s68, v[44:45]
	v_mad_i64_i32 v[60:61], s[28:29], v60, s68, v[44:45]
	v_mad_i64_i32 v[62:63], s[28:29], v62, s68, v[44:45]
	v_mad_i64_i32 v[64:65], s[28:29], v64, s68, v[44:45]
	v_mad_i64_i32 v[66:67], s[28:29], v66, s68, v[44:45]
	v_mad_i64_i32 v[68:69], s[28:29], v68, s68, v[44:45]
	v_mad_i64_i32 v[70:71], s[28:29], v70, s68, v[44:45]
	v_mad_i64_i32 v[72:73], s[28:29], v72, s68, v[44:45]
	v_mad_i64_i32 v[74:75], s[28:29], v74, s68, v[44:45]
	v_mad_i64_i32 v[76:77], s[28:29], v76, s68, v[44:45]
	global_load_dword v11, v[46:47], off
	global_load_dword v13, v[48:49], off
	global_load_dword v84, v[50:51], off
	global_load_dword v85, v[52:53], off
	global_load_dword v86, v[54:55], off
	global_load_dword v87, v[56:57], off
	global_load_dword v88, v[58:59], off
	global_load_dword v89, v[60:61], off
	global_load_dword v90, v[62:63], off
	global_load_dword v91, v[64:65], off
	global_load_dword v92, v[66:67], off
	global_load_dword v93, v[68:69], off
	global_load_dword v94, v[70:71], off
	global_load_dword v95, v[72:73], off
	global_load_dword v96, v[74:75], off
	global_load_dword v97, v[76:77], off
	s_add_i32 s5, s5, 16
	s_add_i32 s4, s4, 16
	s_lshl_b32 s11, s4, 1
	s_lshl_b32 s28, s5, 1
	v_or_b32_e32 v106, s11, v1
	v_or_b32_e32 v107, s28, v2
	s_add_i32 s29, s11, 4
	s_add_i32 s30, s28, 4
	s_add_i32 s36, s11, 8
	s_add_i32 s37, s28, 8
	s_add_i32 s38, s11, 12
	s_add_i32 s39, s28, 12
	s_add_i32 s40, s11, 16
	s_add_i32 s41, s28, 16
	s_add_i32 s42, s11, 20
	s_add_i32 s43, s28, 20
	s_add_i32 s44, s11, 24
	s_add_i32 s45, s28, 24
	s_add_i32 s11, s11, 28
	s_add_i32 s28, s28, 28
	v_add_u32_e32 v108, s0, v106
	v_add_u32_e32 v109, s8, v107
	v_or_b32_e32 v110, s29, v1
	v_or_b32_e32 v111, s30, v2
	v_or_b32_e32 v112, s36, v1
	v_or_b32_e32 v113, s37, v2
	v_or_b32_e32 v114, s38, v1
	v_or_b32_e32 v115, s39, v2
	v_or_b32_e32 v116, s40, v1
	v_or_b32_e32 v117, s41, v2
	v_or_b32_e32 v118, s42, v1
	v_or_b32_e32 v119, s43, v2
	v_or_b32_e32 v120, s44, v1
	v_or_b32_e32 v121, s45, v2
	v_or_b32_e32 v122, s11, v1
	v_or_b32_e32 v123, s28, v2
	v_mad_i64_i32 v[130:131], s[28:29], v109, s68, v[44:45]
	v_mad_i64_i32 v[132:133], s[28:29], v108, s68, v[44:45]
	v_add_u32_e32 v108, s0, v110
	v_add_u32_e32 v109, s8, v111
	v_add_u32_e32 v140, s0, v112
	v_add_u32_e32 v138, s8, v113
	v_add_u32_e32 v144, s0, v114
	v_add_u32_e32 v142, s8, v115
	v_add_u32_e32 v148, s0, v116
	v_add_u32_e32 v146, s8, v117
	v_add_u32_e32 v152, s0, v118
	v_add_u32_e32 v150, s8, v119
	v_add_u32_e32 v156, s0, v120
	v_add_u32_e32 v154, s8, v121
	v_add_u32_e32 v160, s0, v122
	v_add_u32_e32 v158, s8, v123
	v_mad_i64_i32 v[134:135], s[28:29], v109, s68, v[44:45]
	v_mad_i64_i32 v[136:137], s[28:29], v108, s68, v[44:45]
	v_mad_i64_i32 v[138:139], s[28:29], v138, s68, v[44:45]
	v_mad_i64_i32 v[140:141], s[28:29], v140, s68, v[44:45]
	v_mad_i64_i32 v[142:143], s[28:29], v142, s68, v[44:45]
	v_mad_i64_i32 v[144:145], s[28:29], v144, s68, v[44:45]
	v_mad_i64_i32 v[146:147], s[28:29], v146, s68, v[44:45]
	v_mad_i64_i32 v[148:149], s[28:29], v148, s68, v[44:45]
	v_mad_i64_i32 v[150:151], s[28:29], v150, s68, v[44:45]
	v_mad_i64_i32 v[152:153], s[28:29], v152, s68, v[44:45]
	v_mad_i64_i32 v[154:155], s[28:29], v154, s68, v[44:45]
	v_mad_i64_i32 v[156:157], s[28:29], v156, s68, v[44:45]
	v_mad_i64_i32 v[158:159], s[28:29], v158, s68, v[44:45]
	v_mad_i64_i32 v[160:161], s[28:29], v160, s68, v[44:45]
	global_load_dword v108, v[130:131], off
	global_load_dword v109, v[132:133], off
	global_load_dword v124, v[134:135], off
	global_load_dword v125, v[136:137], off
	global_load_dword v126, v[138:139], off
	global_load_dword v127, v[140:141], off
	global_load_dword v162, v[142:143], off
	global_load_dword v163, v[144:145], off
	global_load_dword v164, v[146:147], off
	global_load_dword v165, v[148:149], off
	global_load_dword v166, v[150:151], off
	global_load_dword v167, v[152:153], off
	global_load_dword v168, v[154:155], off
	global_load_dword v169, v[156:157], off
	global_load_dword v170, v[158:159], off
	global_load_dword v171, v[160:161], off
	v_mad_u64_u32 v[46:47], s[28:29], v9, s78, v[6:7]
	v_mad_u64_u32 v[48:49], s[28:29], v7, s78, v[6:7]
	v_mad_u64_u32 v[50:51], s[28:29], v17, s78, v[6:7]
	v_mad_u64_u32 v[52:53], s[28:29], v15, s78, v[6:7]
	v_mad_u64_u32 v[54:55], s[28:29], v35, s78, v[6:7]
	v_mad_u64_u32 v[56:57], s[28:29], v21, s78, v[6:7]
	v_mad_u64_u32 v[58:59], s[28:29], v39, s78, v[6:7]
	v_mad_u64_u32 v[60:61], s[28:29], v37, s78, v[6:7]
	v_mad_u64_u32 v[62:63], s[28:29], v43, s78, v[6:7]
	v_mad_u64_u32 v[64:65], s[28:29], v41, s78, v[6:7]
	v_mad_u64_u32 v[66:67], s[28:29], v79, s78, v[6:7]
	v_mad_u64_u32 v[68:69], s[28:29], v78, s78, v[6:7]
	v_mad_u64_u32 v[70:71], s[28:29], v81, s78, v[6:7]
	v_mad_u64_u32 v[72:73], s[28:29], v80, s78, v[6:7]
	v_mad_u64_u32 v[74:75], s[28:29], v83, s78, v[6:7]
	v_mad_u64_u32 v[76:77], s[28:29], v82, s78, v[6:7]
	s_waitcnt vmcnt(31)
	ds_write_b32 v46, v11
	s_waitcnt vmcnt(30)
	ds_write_b32 v48, v13
	s_waitcnt vmcnt(29)
	ds_write_b32 v50, v84
	s_waitcnt vmcnt(28)
	ds_write_b32 v52, v85
	s_waitcnt vmcnt(27)
	ds_write_b32 v54, v86
	s_waitcnt vmcnt(26)
	ds_write_b32 v56, v87
	s_waitcnt vmcnt(25)
	ds_write_b32 v58, v88
	s_waitcnt vmcnt(24)
	ds_write_b32 v60, v89
	s_waitcnt vmcnt(23)
	ds_write_b32 v62, v90
	s_waitcnt vmcnt(22)
	ds_write_b32 v64, v91
	s_waitcnt vmcnt(21)
	ds_write_b32 v66, v92
	s_waitcnt vmcnt(20)
	ds_write_b32 v68, v93
	s_waitcnt vmcnt(19)
	ds_write_b32 v70, v94
	s_waitcnt vmcnt(18)
	ds_write_b32 v72, v95
	s_waitcnt vmcnt(17)
	ds_write_b32 v74, v96
	s_waitcnt vmcnt(16)
	ds_write_b32 v76, v97
	v_mad_u64_u32 v[130:131], s[28:29], v107, s78, v[6:7]
	v_mad_u64_u32 v[132:133], s[28:29], v106, s78, v[6:7]
	v_mad_u64_u32 v[134:135], s[28:29], v111, s78, v[6:7]
	v_mad_u64_u32 v[136:137], s[28:29], v110, s78, v[6:7]
	v_mad_u64_u32 v[138:139], s[28:29], v113, s78, v[6:7]
	v_mad_u64_u32 v[140:141], s[28:29], v112, s78, v[6:7]
	v_mad_u64_u32 v[142:143], s[28:29], v115, s78, v[6:7]
	v_mad_u64_u32 v[144:145], s[28:29], v114, s78, v[6:7]
	v_mad_u64_u32 v[146:147], s[28:29], v117, s78, v[6:7]
	v_mad_u64_u32 v[148:149], s[28:29], v116, s78, v[6:7]
	v_mad_u64_u32 v[150:151], s[28:29], v119, s78, v[6:7]
	v_mad_u64_u32 v[152:153], s[28:29], v118, s78, v[6:7]
	v_mad_u64_u32 v[154:155], s[28:29], v121, s78, v[6:7]
	v_mad_u64_u32 v[156:157], s[28:29], v120, s78, v[6:7]
	v_mad_u64_u32 v[158:159], s[28:29], v123, s78, v[6:7]
	v_mad_u64_u32 v[160:161], s[28:29], v122, s78, v[6:7]
	s_waitcnt vmcnt(15)
	ds_write_b32 v130, v108
	s_waitcnt vmcnt(14)
	ds_write_b32 v132, v109
	s_waitcnt vmcnt(13)
	ds_write_b32 v134, v124
	s_waitcnt vmcnt(12)
	ds_write_b32 v136, v125
	s_waitcnt vmcnt(11)
	ds_write_b32 v138, v126
	s_waitcnt vmcnt(10)
	ds_write_b32 v140, v127
	s_waitcnt vmcnt(9)
	ds_write_b32 v142, v162
	s_waitcnt vmcnt(8)
	ds_write_b32 v144, v163
	s_waitcnt vmcnt(7)
	ds_write_b32 v146, v164
	s_waitcnt vmcnt(6)
	ds_write_b32 v148, v165
	s_waitcnt vmcnt(5)
	ds_write_b32 v150, v166
	s_waitcnt vmcnt(4)
	ds_write_b32 v152, v167
	s_waitcnt vmcnt(3)
	ds_write_b32 v154, v168
	s_waitcnt vmcnt(2)
	ds_write_b32 v156, v169
	s_waitcnt vmcnt(1)
	ds_write_b32 v158, v170
	s_waitcnt vmcnt(0)
	ds_write_b32 v160, v171
	s_add_i32 s5, s5, 16
	s_add_i32 s4, s4, 16
	s_add_i32 s9, s9, -16
	s_add_i32 s9, s9, -16
	s_cmp_lg_u32 s9, 0
	s_waitcnt lgkmcnt(0)
	ds_read2_b32 v[48:49], v3 offset1:8
	ds_read2_b32 v[52:53], v3 offset0:33 offset1:41
	ds_read2_b32 v[54:55], v3 offset0:66 offset1:74
	ds_read2_b32 v[56:57], v3 offset0:99 offset1:107
	ds_read2_b32 v[58:59], v3 offset0:132 offset1:140
	s_waitcnt lgkmcnt(4)
	s_waitcnt lgkmcnt(3)
	v_cvt_pk_bf16_f32 v9, v48, v52
	ds_read2_b32 v[60:61], v3 offset0:165 offset1:173
	v_mov_b32_e32 v44, v9
	s_waitcnt lgkmcnt(3)
	s_waitcnt lgkmcnt(2)
	ds_read2_b32 v[62:63], v3 offset0:198 offset1:206
	v_cvt_pk_bf16_f32 v9, v54, v56
	ds_read2_b32 v[64:65], v3 offset0:231 offset1:239
	v_mov_b32_e32 v45, v9
	s_waitcnt lgkmcnt(3)
	s_mul_i32 s4, s10, 0x300
	s_waitcnt lgkmcnt(2)
	s_mul_hi_i32 s0, s10, 0x300
	s_add_u32 s10, s24, s4
	v_cvt_pk_bf16_f32 v9, v58, v60
	s_addc_u32 s0, s25, s0
	s_ashr_i32 s9, s8, 31
	v_mov_b32_e32 v46, v9
	s_waitcnt lgkmcnt(1)
	s_lshl_b64 s[4:5], s[8:9], 1
	s_waitcnt lgkmcnt(0)
	s_add_u32 s4, s10, s4
	v_cvt_pk_bf16_f32 v9, v62, v64
	s_addc_u32 s5, s0, s5
	v_lshlrev_b32_e32 v128, 1, v8
	v_mov_b32_e32 v47, v9
	v_lshl_add_u64 v[50:51], s[4:5], 0, v[128:129]
	v_mov_b32_e32 v35, v129
	v_lshl_add_u64 v[50:51], v[50:51], 0, v[34:35]
	v_cvt_pk_bf16_f32 v9, v49, v53
	global_store_dwordx4 v[50:51], v[44:47], off
	s_movk_i32 s0, 0x1000
	v_add_co_u32_e32 v52, vcc, s0, v50
	v_mov_b32_e32 v44, v9
	v_cvt_pk_bf16_f32 v9, v55, v57
	v_mov_b32_e32 v45, v9
	v_cvt_pk_bf16_f32 v9, v59, v61
	v_mov_b32_e32 v46, v9
	v_cvt_pk_bf16_f32 v9, v63, v65
	v_mov_b32_e32 v47, v9
	ds_read2_b32 v[48:49], v3 offset0:16 offset1:24
	v_addc_co_u32_e32 v53, vcc, 0, v51, vcc
	global_store_dwordx4 v[52:53], v[44:47], off offset:2048
	ds_read2_b32 v[52:53], v3 offset0:49 offset1:57
	ds_read2_b32 v[54:55], v3 offset0:82 offset1:90
	ds_read2_b32 v[56:57], v3 offset0:115 offset1:123
	s_waitcnt lgkmcnt(3)
	s_waitcnt lgkmcnt(2)
	ds_read2_b32 v[58:59], v3 offset0:148 offset1:156
	v_cvt_pk_bf16_f32 v9, v48, v52
	ds_read2_b32 v[60:61], v3 offset0:181 offset1:189
	v_mov_b32_e32 v44, v9
	s_waitcnt lgkmcnt(3)
	s_waitcnt lgkmcnt(2)
	ds_read2_b32 v[62:63], v3 offset0:214 offset1:222
	v_cvt_pk_bf16_f32 v9, v54, v56
	ds_read2_b32 v[64:65], v3 offset0:247 offset1:255
	v_mov_b32_e32 v45, v9
	s_waitcnt lgkmcnt(3)
	s_waitcnt lgkmcnt(2)
	v_cvt_pk_bf16_f32 v9, v58, v60
	v_mov_b32_e32 v46, v9
	s_waitcnt lgkmcnt(1)
	s_waitcnt lgkmcnt(0)
	v_cvt_pk_bf16_f32 v9, v62, v64
	v_mov_b32_e32 v47, v9
	s_movk_i32 s0, 0x3000
	v_add_co_u32_e32 v66, vcc, s0, v50
	v_addc_co_u32_e32 v67, vcc, 0, v51, vcc
	v_cvt_pk_bf16_f32 v9, v49, v53
	global_store_dwordx4 v[66:67], v[44:47], off
	v_add_co_u32_e32 v48, vcc, 0x4000, v50
	s_nop 0
	v_mov_b32_e32 v44, v9
	v_cvt_pk_bf16_f32 v9, v55, v57
	v_mov_b32_e32 v45, v9
	v_cvt_pk_bf16_f32 v9, v59, v61
	v_mov_b32_e32 v46, v9
	v_cvt_pk_bf16_f32 v9, v63, v65
	v_mov_b32_e32 v47, v9
	v_addc_co_u32_e32 v49, vcc, 0, v51, vcc
	global_store_dwordx4 v[48:49], v[44:47], off offset:2048
	s_waitcnt lgkmcnt(0)
	s_mov_b32 s0, s1
	s_andn2_b64 vcc, exec, s[6:7]
	s_mov_b64 s[6:7], -1
	s_cbranch_vccnz .LBB0_832

.LBB0_826:
	s_lshl_b32 s28, s5, 1
	s_lshl_b32 s29, s9, 1
	v_or_b32_e32 v7, s28, v1
	v_or_b32_e32 v9, s29, v2
	s_add_i32 s30, s28, 4
	s_add_i32 s36, s29, 4
	s_add_i32 s37, s28, 8
	s_add_i32 s38, s29, 8
	s_add_i32 s39, s28, 12
	s_add_i32 s40, s29, 12
	s_add_i32 s41, s28, 16
	s_add_i32 s42, s29, 16
	s_add_i32 s43, s28, 20
	s_add_i32 s44, s29, 20
	s_add_i32 s45, s28, 24
	s_add_i32 s46, s29, 24
	s_add_i32 s28, s28, 28
	s_add_i32 s29, s29, 28
	v_add_u32_e32 v48, s8, v9
	v_or_b32_e32 v11, s30, v1
	v_or_b32_e32 v13, s36, v2
	v_or_b32_e32 v15, s37, v1
	v_or_b32_e32 v17, s38, v2
	v_or_b32_e32 v21, s39, v1
	v_or_b32_e32 v35, s40, v2
	v_or_b32_e32 v37, s41, v1
	v_or_b32_e32 v39, s42, v2
	v_or_b32_e32 v41, s43, v1
	v_or_b32_e32 v43, s44, v2
	v_or_b32_e32 v78, s45, v1
	v_or_b32_e32 v79, s46, v2
	v_or_b32_e32 v80, s28, v1
	v_or_b32_e32 v81, s29, v2
	v_add_u32_e32 v46, s4, v7
	v_ashrrev_i32_e32 v49, 31, v48
	v_add_u32_e32 v50, s4, v11
	v_add_u32_e32 v52, s8, v13
	v_add_u32_e32 v54, s4, v15
	v_add_u32_e32 v56, s8, v17
	v_add_u32_e32 v58, s4, v21
	v_add_u32_e32 v60, s8, v35
	v_add_u32_e32 v62, s4, v37
	v_add_u32_e32 v64, s8, v39
	v_add_u32_e32 v66, s4, v41
	v_add_u32_e32 v68, s8, v43
	v_add_u32_e32 v70, s4, v78
	v_add_u32_e32 v72, s8, v79
	v_add_u32_e32 v74, s4, v80
	v_add_u32_e32 v76, s8, v81
	v_ashrrev_i32_e32 v47, 31, v46
	v_lshlrev_b64 v[48:49], 13, v[48:49]
	v_ashrrev_i32_e32 v53, 31, v52
	v_ashrrev_i32_e32 v51, 31, v50
	v_ashrrev_i32_e32 v57, 31, v56
	v_ashrrev_i32_e32 v55, 31, v54
	v_ashrrev_i32_e32 v61, 31, v60
	v_ashrrev_i32_e32 v59, 31, v58
	v_ashrrev_i32_e32 v65, 31, v64
	v_ashrrev_i32_e32 v63, 31, v62
	v_ashrrev_i32_e32 v69, 31, v68
	v_ashrrev_i32_e32 v67, 31, v66
	v_ashrrev_i32_e32 v73, 31, v72
	v_ashrrev_i32_e32 v71, 31, v70
	v_ashrrev_i32_e32 v77, 31, v76
	v_ashrrev_i32_e32 v75, 31, v74
	v_lshlrev_b64 v[46:47], 13, v[46:47]
	v_lshl_add_u64 v[48:49], v[44:45], 0, v[48:49]
	v_lshlrev_b64 v[50:51], 13, v[50:51]
	v_lshlrev_b64 v[52:53], 13, v[52:53]
	v_lshlrev_b64 v[54:55], 13, v[54:55]
	v_lshlrev_b64 v[56:57], 13, v[56:57]
	v_lshlrev_b64 v[58:59], 13, v[58:59]
	v_lshlrev_b64 v[60:61], 13, v[60:61]
	v_lshlrev_b64 v[62:63], 13, v[62:63]
	v_lshlrev_b64 v[64:65], 13, v[64:65]
	v_lshlrev_b64 v[66:67], 13, v[66:67]
	v_lshlrev_b64 v[68:69], 13, v[68:69]
	v_lshlrev_b64 v[70:71], 13, v[70:71]
	v_lshlrev_b64 v[72:73], 13, v[72:73]
	v_lshlrev_b64 v[74:75], 13, v[74:75]
	v_lshlrev_b64 v[76:77], 13, v[76:77]
	v_lshl_add_u64 v[46:47], v[44:45], 0, v[46:47]
	v_lshl_add_u64 v[52:53], v[44:45], 0, v[52:53]
	v_lshl_add_u64 v[50:51], v[44:45], 0, v[50:51]
	v_lshl_add_u64 v[56:57], v[44:45], 0, v[56:57]
	v_lshl_add_u64 v[54:55], v[44:45], 0, v[54:55]
	v_lshl_add_u64 v[60:61], v[44:45], 0, v[60:61]
	v_lshl_add_u64 v[58:59], v[44:45], 0, v[58:59]
	v_lshl_add_u64 v[64:65], v[44:45], 0, v[64:65]
	v_lshl_add_u64 v[62:63], v[44:45], 0, v[62:63]
	v_lshl_add_u64 v[68:69], v[44:45], 0, v[68:69]
	v_lshl_add_u64 v[66:67], v[44:45], 0, v[66:67]
	v_lshl_add_u64 v[72:73], v[44:45], 0, v[72:73]
	v_lshl_add_u64 v[70:71], v[44:45], 0, v[70:71]
	v_lshl_add_u64 v[76:77], v[44:45], 0, v[76:77]
	v_lshl_add_u64 v[74:75], v[44:45], 0, v[74:75]
	global_load_dword v82, v[48:49], off
	global_load_dword v83, v[46:47], off
	global_load_dword v84, v[52:53], off
	global_load_dword v85, v[50:51], off
	global_load_dword v86, v[56:57], off
	global_load_dword v87, v[54:55], off
	global_load_dword v88, v[60:61], off
	global_load_dword v89, v[58:59], off
	global_load_dword v90, v[64:65], off
	global_load_dword v91, v[62:63], off
	global_load_dword v92, v[68:69], off
	global_load_dword v93, v[66:67], off
	global_load_dword v94, v[72:73], off
	global_load_dword v95, v[70:71], off
	global_load_dword v96, v[76:77], off
	global_load_dword v97, v[74:75], off
	s_add_i32 s9, s9, 16
	s_add_i32 s5, s5, 16
	s_lshl_b32 s28, s5, 1
	s_lshl_b32 s29, s9, 1
	v_or_b32_e32 v106, s28, v1
	v_or_b32_e32 v107, s29, v2
	s_add_i32 s30, s28, 4
	s_add_i32 s36, s29, 4
	s_add_i32 s37, s28, 8
	s_add_i32 s38, s29, 8
	s_add_i32 s39, s28, 12
	s_add_i32 s40, s29, 12
	s_add_i32 s41, s28, 16
	s_add_i32 s42, s29, 16
	s_add_i32 s43, s28, 20
	s_add_i32 s44, s29, 20
	s_add_i32 s45, s28, 24
	s_add_i32 s46, s29, 24
	s_add_i32 s28, s28, 28
	s_add_i32 s29, s29, 28
	v_add_u32_e32 v132, s8, v107
	v_or_b32_e32 v108, s30, v1
	v_or_b32_e32 v109, s36, v2
	v_or_b32_e32 v110, s37, v1
	v_or_b32_e32 v111, s38, v2
	v_or_b32_e32 v112, s39, v1
	v_or_b32_e32 v113, s40, v2
	v_or_b32_e32 v114, s41, v1
	v_or_b32_e32 v115, s42, v2
	v_or_b32_e32 v116, s43, v1
	v_or_b32_e32 v117, s44, v2
	v_or_b32_e32 v118, s45, v1
	v_or_b32_e32 v119, s46, v2
	v_or_b32_e32 v120, s28, v1
	v_or_b32_e32 v121, s29, v2
	v_add_u32_e32 v130, s4, v106
	v_ashrrev_i32_e32 v133, 31, v132
	v_add_u32_e32 v134, s4, v108
	v_add_u32_e32 v136, s8, v109
	v_add_u32_e32 v138, s4, v110
	v_add_u32_e32 v140, s8, v111
	v_add_u32_e32 v142, s4, v112
	v_add_u32_e32 v144, s8, v113
	v_add_u32_e32 v146, s4, v114
	v_add_u32_e32 v148, s8, v115
	v_add_u32_e32 v150, s4, v116
	v_add_u32_e32 v152, s8, v117
	v_add_u32_e32 v154, s4, v118
	v_add_u32_e32 v156, s8, v119
	v_add_u32_e32 v158, s4, v120
	v_add_u32_e32 v160, s8, v121
	v_ashrrev_i32_e32 v131, 31, v130
	v_lshlrev_b64 v[132:133], 13, v[132:133]
	v_ashrrev_i32_e32 v137, 31, v136
	v_ashrrev_i32_e32 v135, 31, v134
	v_ashrrev_i32_e32 v141, 31, v140
	v_ashrrev_i32_e32 v139, 31, v138
	v_ashrrev_i32_e32 v145, 31, v144
	v_ashrrev_i32_e32 v143, 31, v142
	v_ashrrev_i32_e32 v149, 31, v148
	v_ashrrev_i32_e32 v147, 31, v146
	v_ashrrev_i32_e32 v153, 31, v152
	v_ashrrev_i32_e32 v151, 31, v150
	v_ashrrev_i32_e32 v157, 31, v156
	v_ashrrev_i32_e32 v155, 31, v154
	v_ashrrev_i32_e32 v161, 31, v160
	v_ashrrev_i32_e32 v159, 31, v158
	v_lshlrev_b64 v[130:131], 13, v[130:131]
	v_lshl_add_u64 v[132:133], v[44:45], 0, v[132:133]
	v_lshlrev_b64 v[134:135], 13, v[134:135]
	v_lshlrev_b64 v[136:137], 13, v[136:137]
	v_lshlrev_b64 v[138:139], 13, v[138:139]
	v_lshlrev_b64 v[140:141], 13, v[140:141]
	v_lshlrev_b64 v[142:143], 13, v[142:143]
	v_lshlrev_b64 v[144:145], 13, v[144:145]
	v_lshlrev_b64 v[146:147], 13, v[146:147]
	v_lshlrev_b64 v[148:149], 13, v[148:149]
	v_lshlrev_b64 v[150:151], 13, v[150:151]
	v_lshlrev_b64 v[152:153], 13, v[152:153]
	v_lshlrev_b64 v[154:155], 13, v[154:155]
	v_lshlrev_b64 v[156:157], 13, v[156:157]
	v_lshlrev_b64 v[158:159], 13, v[158:159]
	v_lshlrev_b64 v[160:161], 13, v[160:161]
	v_lshl_add_u64 v[130:131], v[44:45], 0, v[130:131]
	v_lshl_add_u64 v[136:137], v[44:45], 0, v[136:137]
	v_lshl_add_u64 v[134:135], v[44:45], 0, v[134:135]
	v_lshl_add_u64 v[140:141], v[44:45], 0, v[140:141]
	v_lshl_add_u64 v[138:139], v[44:45], 0, v[138:139]
	v_lshl_add_u64 v[144:145], v[44:45], 0, v[144:145]
	v_lshl_add_u64 v[142:143], v[44:45], 0, v[142:143]
	v_lshl_add_u64 v[148:149], v[44:45], 0, v[148:149]
	v_lshl_add_u64 v[146:147], v[44:45], 0, v[146:147]
	v_lshl_add_u64 v[152:153], v[44:45], 0, v[152:153]
	v_lshl_add_u64 v[150:151], v[44:45], 0, v[150:151]
	v_lshl_add_u64 v[156:157], v[44:45], 0, v[156:157]
	v_lshl_add_u64 v[154:155], v[44:45], 0, v[154:155]
	v_lshl_add_u64 v[160:161], v[44:45], 0, v[160:161]
	v_lshl_add_u64 v[158:159], v[44:45], 0, v[158:159]
	global_load_dword v122, v[132:133], off
	global_load_dword v123, v[130:131], off
	global_load_dword v124, v[136:137], off
	global_load_dword v125, v[134:135], off
	global_load_dword v126, v[140:141], off
	global_load_dword v127, v[138:139], off
	global_load_dword v162, v[144:145], off
	global_load_dword v163, v[142:143], off
	global_load_dword v164, v[148:149], off
	global_load_dword v165, v[146:147], off
	global_load_dword v166, v[152:153], off
	global_load_dword v167, v[150:151], off
	global_load_dword v168, v[156:157], off
	global_load_dword v169, v[154:155], off
	global_load_dword v170, v[160:161], off
	global_load_dword v171, v[158:159], off
	v_mad_u64_u32 v[46:47], s[28:29], v9, s78, v[6:7]
	v_mad_u64_u32 v[48:49], s[28:29], v7, s78, v[6:7]
	v_mad_u64_u32 v[50:51], s[28:29], v13, s78, v[6:7]
	v_mad_u64_u32 v[52:53], s[28:29], v11, s78, v[6:7]
	v_mad_u64_u32 v[54:55], s[28:29], v17, s78, v[6:7]
	v_mad_u64_u32 v[56:57], s[28:29], v15, s78, v[6:7]
	v_mad_u64_u32 v[58:59], s[28:29], v35, s78, v[6:7]
	v_mad_u64_u32 v[60:61], s[28:29], v21, s78, v[6:7]
	v_mad_u64_u32 v[62:63], s[28:29], v39, s78, v[6:7]
	v_mad_u64_u32 v[64:65], s[28:29], v37, s78, v[6:7]
	v_mad_u64_u32 v[66:67], s[28:29], v43, s78, v[6:7]
	v_mad_u64_u32 v[68:69], s[28:29], v41, s78, v[6:7]
	v_mad_u64_u32 v[70:71], s[28:29], v79, s78, v[6:7]
	v_mad_u64_u32 v[72:73], s[28:29], v78, s78, v[6:7]
	v_mad_u64_u32 v[74:75], s[28:29], v81, s78, v[6:7]
	v_mad_u64_u32 v[76:77], s[28:29], v80, s78, v[6:7]
	s_waitcnt vmcnt(31)
	ds_write_b32 v46, v82
	s_waitcnt vmcnt(30)
	ds_write_b32 v48, v83
	s_waitcnt vmcnt(29)
	ds_write_b32 v50, v84
	s_waitcnt vmcnt(28)
	ds_write_b32 v52, v85
	s_waitcnt vmcnt(27)
	ds_write_b32 v54, v86
	s_waitcnt vmcnt(26)
	ds_write_b32 v56, v87
	s_waitcnt vmcnt(25)
	ds_write_b32 v58, v88
	s_waitcnt vmcnt(24)
	ds_write_b32 v60, v89
	s_waitcnt vmcnt(23)
	ds_write_b32 v62, v90
	s_waitcnt vmcnt(22)
	ds_write_b32 v64, v91
	s_waitcnt vmcnt(21)
	ds_write_b32 v66, v92
	s_waitcnt vmcnt(20)
	ds_write_b32 v68, v93
	s_waitcnt vmcnt(19)
	ds_write_b32 v70, v94
	s_waitcnt vmcnt(18)
	ds_write_b32 v72, v95
	s_waitcnt vmcnt(17)
	ds_write_b32 v74, v96
	s_waitcnt vmcnt(16)
	ds_write_b32 v76, v97
	v_mad_u64_u32 v[130:131], s[28:29], v107, s78, v[6:7]
	v_mad_u64_u32 v[132:133], s[28:29], v106, s78, v[6:7]
	v_mad_u64_u32 v[134:135], s[28:29], v109, s78, v[6:7]
	v_mad_u64_u32 v[136:137], s[28:29], v108, s78, v[6:7]
	v_mad_u64_u32 v[138:139], s[28:29], v111, s78, v[6:7]
	v_mad_u64_u32 v[140:141], s[28:29], v110, s78, v[6:7]
	v_mad_u64_u32 v[142:143], s[28:29], v113, s78, v[6:7]
	v_mad_u64_u32 v[144:145], s[28:29], v112, s78, v[6:7]
	v_mad_u64_u32 v[146:147], s[28:29], v115, s78, v[6:7]
	v_mad_u64_u32 v[148:149], s[28:29], v114, s78, v[6:7]
	v_mad_u64_u32 v[150:151], s[28:29], v117, s78, v[6:7]
	v_mad_u64_u32 v[152:153], s[28:29], v116, s78, v[6:7]
	v_mad_u64_u32 v[154:155], s[28:29], v119, s78, v[6:7]
	v_mad_u64_u32 v[156:157], s[28:29], v118, s78, v[6:7]
	v_mad_u64_u32 v[158:159], s[28:29], v121, s78, v[6:7]
	v_mad_u64_u32 v[160:161], s[28:29], v120, s78, v[6:7]
	s_waitcnt vmcnt(15)
	ds_write_b32 v130, v122
	s_waitcnt vmcnt(14)
	ds_write_b32 v132, v123
	s_waitcnt vmcnt(13)
	ds_write_b32 v134, v124
	s_waitcnt vmcnt(12)
	ds_write_b32 v136, v125
	s_waitcnt vmcnt(11)
	ds_write_b32 v138, v126
	s_waitcnt vmcnt(10)
	ds_write_b32 v140, v127
	s_waitcnt vmcnt(9)
	ds_write_b32 v142, v162
	s_waitcnt vmcnt(8)
	ds_write_b32 v144, v163
	s_waitcnt vmcnt(7)
	ds_write_b32 v146, v164
	s_waitcnt vmcnt(6)
	ds_write_b32 v148, v165
	s_waitcnt vmcnt(5)
	ds_write_b32 v150, v166
	s_waitcnt vmcnt(4)
	ds_write_b32 v152, v167
	s_waitcnt vmcnt(3)
	ds_write_b32 v154, v168
	s_waitcnt vmcnt(2)
	ds_write_b32 v156, v169
	s_waitcnt vmcnt(1)
	ds_write_b32 v158, v170
	s_waitcnt vmcnt(0)
	ds_write_b32 v160, v171
	s_add_i32 s9, s9, 16
	s_add_i32 s5, s5, 16
	s_add_i32 s11, s11, -16
	s_add_i32 s11, s11, -16
	s_cmp_lg_u32 s11, 0
	s_bfe_i32 s4, s1, 0x80000
	s_bfe_u32 s4, s4, 0x3000c
	s_waitcnt lgkmcnt(0)
	s_add_i32 s1, s1, s4
	s_bfe_u32 s4, s10, 0x80017
	ds_read2_b32 v[48:49], v3 offset1:8
	s_bfe_i32 s1, s1, 0x80000
	s_add_i32 s4, s10, s4
	ds_read2_b32 v[52:53], v3 offset0:33 offset1:41
	s_sext_i32_i16 s1, s1
	s_and_b32 s4, s4, 0xff00
	s_sub_i32 s4, s10, s4
	s_lshl_b32 s1, s1, 4
	ds_read2_b32 v[54:55], v3 offset0:66 offset1:74
	s_sext_i32_i16 s4, s4
	s_and_b32 s1, s1, 0xffffff80
	ds_read2_b32 v[56:57], v3 offset0:99 offset1:107
	s_add_i32 s1, s1, s4
	s_waitcnt lgkmcnt(3)
	s_add_i32 s5, s1, 0xffffff80
	s_waitcnt lgkmcnt(2)
	ds_read2_b32 v[58:59], v3 offset0:132 offset1:140
	s_cmpk_lt_i32 s4, 0x80
	v_cvt_pk_bf16_f32 v9, v48, v52
	ds_read2_b32 v[60:61], v3 offset0:165 offset1:173
	s_cselect_b32 s4, s1, s5
	s_mov_b32 s1, 0x23a0000
	v_mov_b32_e32 v44, v9
	s_waitcnt lgkmcnt(3)
	s_cselect_b32 s1, s1, 0x2420000
	s_ashr_i32 s5, s4, 31
	s_waitcnt lgkmcnt(2)
	ds_read2_b32 v[62:63], v3 offset0:198 offset1:206
	s_lshl_b64 s[4:5], s[4:5], 9
	v_cvt_pk_bf16_f32 v9, v54, v56
	ds_read2_b32 v[64:65], v3 offset0:231 offset1:239
	s_add_u32 s1, s13, s1
	v_mov_b32_e32 v45, v9
	s_waitcnt lgkmcnt(3)
	s_addc_u32 s9, s14, 0
	s_waitcnt lgkmcnt(2)
	s_add_u32 s1, s1, s4
	v_cvt_pk_bf16_f32 v9, v58, v60
	s_addc_u32 s10, s9, s5
	s_ashr_i32 s9, s8, 31
	v_mov_b32_e32 v46, v9
	s_waitcnt lgkmcnt(1)
	s_lshl_b64 s[4:5], s[8:9], 1
	s_waitcnt lgkmcnt(0)
	s_add_u32 s4, s1, s4
	v_cvt_pk_bf16_f32 v9, v62, v64
	s_addc_u32 s5, s10, s5
	v_lshlrev_b32_e32 v128, 1, v8
	v_mov_b32_e32 v47, v9
	v_lshl_add_u64 v[50:51], s[4:5], 0, v[128:129]
	v_mov_b32_e32 v37, v129
	v_lshl_add_u64 v[66:67], v[50:51], 0, v[36:37]
	v_cvt_pk_bf16_f32 v9, v49, v53
	global_store_dwordx4 v[66:67], v[44:47], off
	v_mov_b32_e32 v39, v129
	ds_read2_b32 v[48:49], v3 offset0:16 offset1:24
	v_mov_b32_e32 v44, v9
	v_cvt_pk_bf16_f32 v9, v55, v57
	v_mov_b32_e32 v45, v9
	v_cvt_pk_bf16_f32 v9, v59, v61
	v_mov_b32_e32 v46, v9
	v_cvt_pk_bf16_f32 v9, v63, v65
	v_mov_b32_e32 v47, v9
	v_lshl_add_u64 v[52:53], v[50:51], 0, v[38:39]
	global_store_dwordx4 v[52:53], v[44:47], off
	ds_read2_b32 v[52:53], v3 offset0:49 offset1:57
	ds_read2_b32 v[54:55], v3 offset0:82 offset1:90
	ds_read2_b32 v[56:57], v3 offset0:115 offset1:123
	s_waitcnt lgkmcnt(3)
	s_waitcnt lgkmcnt(2)
	ds_read2_b32 v[58:59], v3 offset0:148 offset1:156
	v_cvt_pk_bf16_f32 v9, v48, v52
	ds_read2_b32 v[60:61], v3 offset0:181 offset1:189
	v_mov_b32_e32 v44, v9
	s_waitcnt lgkmcnt(3)
	s_waitcnt lgkmcnt(2)
	ds_read2_b32 v[62:63], v3 offset0:214 offset1:222
	v_cvt_pk_bf16_f32 v9, v54, v56
	ds_read2_b32 v[64:65], v3 offset0:247 offset1:255
	v_mov_b32_e32 v45, v9
	s_waitcnt lgkmcnt(3)
	s_waitcnt lgkmcnt(2)
	v_cvt_pk_bf16_f32 v9, v58, v60
	v_mov_b32_e32 v46, v9
	s_waitcnt lgkmcnt(1)
	s_waitcnt lgkmcnt(0)
	v_cvt_pk_bf16_f32 v9, v62, v64
	v_mov_b32_e32 v47, v9
	v_mov_b32_e32 v41, v129
	v_lshl_add_u64 v[66:67], v[50:51], 0, v[40:41]
	v_cvt_pk_bf16_f32 v9, v49, v53
	global_store_dwordx4 v[66:67], v[44:47], off
	v_mov_b32_e32 v43, v129
	v_lshl_add_u64 v[48:49], v[50:51], 0, v[42:43]
	v_mov_b32_e32 v44, v9
	v_cvt_pk_bf16_f32 v9, v55, v57
	v_mov_b32_e32 v45, v9
	v_cvt_pk_bf16_f32 v9, v59, v61
	v_mov_b32_e32 v46, v9
	v_cvt_pk_bf16_f32 v9, v63, v65
	v_mov_b32_e32 v47, v9
	global_store_dwordx4 v[48:49], v[44:47], off
	s_waitcnt lgkmcnt(0)
	s_mov_b32 s1, s0
	s_andn2_b64 vcc, exec, s[6:7]
	s_mov_b64 s[6:7], -1
	s_cbranch_vccnz .LBB0_832

.LBB0_830:
	s_lshl_b32 s7, s0, 1
	s_lshl_b32 s10, s4, 1
	v_or_b32_e32 v7, s7, v1
	v_or_b32_e32 v9, s10, v2
	s_add_i32 s11, s7, 4
	s_add_i32 s28, s10, 4
	s_add_i32 s29, s7, 8
	s_add_i32 s30, s10, 8
	s_add_i32 s36, s7, 12
	s_add_i32 s37, s10, 12
	s_add_i32 s38, s7, 16
	s_add_i32 s39, s10, 16
	s_add_i32 s40, s7, 20
	s_add_i32 s41, s10, 20
	s_add_i32 s42, s7, 24
	s_add_i32 s43, s10, 24
	s_add_i32 s7, s7, 28
	s_add_i32 s10, s10, 28
	v_add_u32_e32 v48, s6, v9
	v_or_b32_e32 v11, s11, v1
	v_or_b32_e32 v13, s28, v2
	v_or_b32_e32 v15, s29, v1
	v_or_b32_e32 v17, s30, v2
	v_or_b32_e32 v21, s36, v1
	v_or_b32_e32 v35, s37, v2
	v_or_b32_e32 v37, s38, v1
	v_or_b32_e32 v39, s39, v2
	v_or_b32_e32 v41, s40, v1
	v_or_b32_e32 v43, s41, v2
	v_or_b32_e32 v78, s42, v1
	v_or_b32_e32 v79, s43, v2
	v_or_b32_e32 v80, s7, v1
	v_or_b32_e32 v81, s10, v2
	v_add_u32_e32 v46, s1, v7
	v_ashrrev_i32_e32 v49, 31, v48
	v_add_u32_e32 v50, s1, v11
	v_add_u32_e32 v52, s6, v13
	v_add_u32_e32 v54, s1, v15
	v_add_u32_e32 v56, s6, v17
	v_add_u32_e32 v58, s1, v21
	v_add_u32_e32 v60, s6, v35
	v_add_u32_e32 v62, s1, v37
	v_add_u32_e32 v64, s6, v39
	v_add_u32_e32 v66, s1, v41
	v_add_u32_e32 v68, s6, v43
	v_add_u32_e32 v70, s1, v78
	v_add_u32_e32 v72, s6, v79
	v_add_u32_e32 v74, s1, v80
	v_add_u32_e32 v76, s6, v81
	v_ashrrev_i32_e32 v47, 31, v46
	v_lshlrev_b64 v[48:49], 12, v[48:49]
	v_ashrrev_i32_e32 v53, 31, v52
	v_ashrrev_i32_e32 v51, 31, v50
	v_ashrrev_i32_e32 v57, 31, v56
	v_ashrrev_i32_e32 v55, 31, v54
	v_ashrrev_i32_e32 v61, 31, v60
	v_ashrrev_i32_e32 v59, 31, v58
	v_ashrrev_i32_e32 v65, 31, v64
	v_ashrrev_i32_e32 v63, 31, v62
	v_ashrrev_i32_e32 v69, 31, v68
	v_ashrrev_i32_e32 v67, 31, v66
	v_ashrrev_i32_e32 v73, 31, v72
	v_ashrrev_i32_e32 v71, 31, v70
	v_ashrrev_i32_e32 v77, 31, v76
	v_ashrrev_i32_e32 v75, 31, v74
	v_lshlrev_b64 v[46:47], 12, v[46:47]
	v_lshl_add_u64 v[48:49], v[44:45], 0, v[48:49]
	v_lshlrev_b64 v[50:51], 12, v[50:51]
	v_lshlrev_b64 v[52:53], 12, v[52:53]
	v_lshlrev_b64 v[54:55], 12, v[54:55]
	v_lshlrev_b64 v[56:57], 12, v[56:57]
	v_lshlrev_b64 v[58:59], 12, v[58:59]
	v_lshlrev_b64 v[60:61], 12, v[60:61]
	v_lshlrev_b64 v[62:63], 12, v[62:63]
	v_lshlrev_b64 v[64:65], 12, v[64:65]
	v_lshlrev_b64 v[66:67], 12, v[66:67]
	v_lshlrev_b64 v[68:69], 12, v[68:69]
	v_lshlrev_b64 v[70:71], 12, v[70:71]
	v_lshlrev_b64 v[72:73], 12, v[72:73]
	v_lshlrev_b64 v[74:75], 12, v[74:75]
	v_lshlrev_b64 v[76:77], 12, v[76:77]
	v_lshl_add_u64 v[46:47], v[44:45], 0, v[46:47]
	v_lshl_add_u64 v[52:53], v[44:45], 0, v[52:53]
	v_lshl_add_u64 v[50:51], v[44:45], 0, v[50:51]
	v_lshl_add_u64 v[56:57], v[44:45], 0, v[56:57]
	v_lshl_add_u64 v[54:55], v[44:45], 0, v[54:55]
	v_lshl_add_u64 v[60:61], v[44:45], 0, v[60:61]
	v_lshl_add_u64 v[58:59], v[44:45], 0, v[58:59]
	v_lshl_add_u64 v[64:65], v[44:45], 0, v[64:65]
	v_lshl_add_u64 v[62:63], v[44:45], 0, v[62:63]
	v_lshl_add_u64 v[68:69], v[44:45], 0, v[68:69]
	v_lshl_add_u64 v[66:67], v[44:45], 0, v[66:67]
	v_lshl_add_u64 v[72:73], v[44:45], 0, v[72:73]
	v_lshl_add_u64 v[70:71], v[44:45], 0, v[70:71]
	v_lshl_add_u64 v[76:77], v[44:45], 0, v[76:77]
	v_lshl_add_u64 v[74:75], v[44:45], 0, v[74:75]
	global_load_dword v82, v[48:49], off
	global_load_dword v83, v[46:47], off
	global_load_dword v84, v[52:53], off
	global_load_dword v85, v[50:51], off
	global_load_dword v86, v[56:57], off
	global_load_dword v87, v[54:55], off
	global_load_dword v88, v[60:61], off
	global_load_dword v89, v[58:59], off
	global_load_dword v90, v[64:65], off
	global_load_dword v91, v[62:63], off
	global_load_dword v92, v[68:69], off
	global_load_dword v93, v[66:67], off
	global_load_dword v94, v[72:73], off
	global_load_dword v95, v[70:71], off
	global_load_dword v96, v[76:77], off
	global_load_dword v97, v[74:75], off
	s_add_i32 s4, s4, 16
	s_add_i32 s0, s0, 16
	s_lshl_b32 s7, s0, 1
	s_lshl_b32 s10, s4, 1
	v_or_b32_e32 v106, s7, v1
	v_or_b32_e32 v107, s10, v2
	s_add_i32 s11, s7, 4
	s_add_i32 s28, s10, 4
	s_add_i32 s29, s7, 8
	s_add_i32 s30, s10, 8
	s_add_i32 s36, s7, 12
	s_add_i32 s37, s10, 12
	s_add_i32 s38, s7, 16
	s_add_i32 s39, s10, 16
	s_add_i32 s40, s7, 20
	s_add_i32 s41, s10, 20
	s_add_i32 s42, s7, 24
	s_add_i32 s43, s10, 24
	s_add_i32 s7, s7, 28
	s_add_i32 s10, s10, 28
	v_add_u32_e32 v132, s6, v107
	v_or_b32_e32 v108, s11, v1
	v_or_b32_e32 v109, s28, v2
	v_or_b32_e32 v110, s29, v1
	v_or_b32_e32 v111, s30, v2
	v_or_b32_e32 v112, s36, v1
	v_or_b32_e32 v113, s37, v2
	v_or_b32_e32 v114, s38, v1
	v_or_b32_e32 v115, s39, v2
	v_or_b32_e32 v116, s40, v1
	v_or_b32_e32 v117, s41, v2
	v_or_b32_e32 v118, s42, v1
	v_or_b32_e32 v119, s43, v2
	v_or_b32_e32 v120, s7, v1
	v_or_b32_e32 v121, s10, v2
	v_add_u32_e32 v130, s1, v106
	v_ashrrev_i32_e32 v133, 31, v132
	v_add_u32_e32 v134, s1, v108
	v_add_u32_e32 v136, s6, v109
	v_add_u32_e32 v138, s1, v110
	v_add_u32_e32 v140, s6, v111
	v_add_u32_e32 v142, s1, v112
	v_add_u32_e32 v144, s6, v113
	v_add_u32_e32 v146, s1, v114
	v_add_u32_e32 v148, s6, v115
	v_add_u32_e32 v150, s1, v116
	v_add_u32_e32 v152, s6, v117
	v_add_u32_e32 v154, s1, v118
	v_add_u32_e32 v156, s6, v119
	v_add_u32_e32 v158, s1, v120
	v_add_u32_e32 v160, s6, v121
	v_ashrrev_i32_e32 v131, 31, v130
	v_lshlrev_b64 v[132:133], 12, v[132:133]
	v_ashrrev_i32_e32 v137, 31, v136
	v_ashrrev_i32_e32 v135, 31, v134
	v_ashrrev_i32_e32 v141, 31, v140
	v_ashrrev_i32_e32 v139, 31, v138
	v_ashrrev_i32_e32 v145, 31, v144
	v_ashrrev_i32_e32 v143, 31, v142
	v_ashrrev_i32_e32 v149, 31, v148
	v_ashrrev_i32_e32 v147, 31, v146
	v_ashrrev_i32_e32 v153, 31, v152
	v_ashrrev_i32_e32 v151, 31, v150
	v_ashrrev_i32_e32 v157, 31, v156
	v_ashrrev_i32_e32 v155, 31, v154
	v_ashrrev_i32_e32 v161, 31, v160
	v_ashrrev_i32_e32 v159, 31, v158
	v_lshlrev_b64 v[130:131], 12, v[130:131]
	v_lshl_add_u64 v[132:133], v[44:45], 0, v[132:133]
	v_lshlrev_b64 v[134:135], 12, v[134:135]
	v_lshlrev_b64 v[136:137], 12, v[136:137]
	v_lshlrev_b64 v[138:139], 12, v[138:139]
	v_lshlrev_b64 v[140:141], 12, v[140:141]
	v_lshlrev_b64 v[142:143], 12, v[142:143]
	v_lshlrev_b64 v[144:145], 12, v[144:145]
	v_lshlrev_b64 v[146:147], 12, v[146:147]
	v_lshlrev_b64 v[148:149], 12, v[148:149]
	v_lshlrev_b64 v[150:151], 12, v[150:151]
	v_lshlrev_b64 v[152:153], 12, v[152:153]
	v_lshlrev_b64 v[154:155], 12, v[154:155]
	v_lshlrev_b64 v[156:157], 12, v[156:157]
	v_lshlrev_b64 v[158:159], 12, v[158:159]
	v_lshlrev_b64 v[160:161], 12, v[160:161]
	v_lshl_add_u64 v[130:131], v[44:45], 0, v[130:131]
	v_lshl_add_u64 v[136:137], v[44:45], 0, v[136:137]
	v_lshl_add_u64 v[134:135], v[44:45], 0, v[134:135]
	v_lshl_add_u64 v[140:141], v[44:45], 0, v[140:141]
	v_lshl_add_u64 v[138:139], v[44:45], 0, v[138:139]
	v_lshl_add_u64 v[144:145], v[44:45], 0, v[144:145]
	v_lshl_add_u64 v[142:143], v[44:45], 0, v[142:143]
	v_lshl_add_u64 v[148:149], v[44:45], 0, v[148:149]
	v_lshl_add_u64 v[146:147], v[44:45], 0, v[146:147]
	v_lshl_add_u64 v[152:153], v[44:45], 0, v[152:153]
	v_lshl_add_u64 v[150:151], v[44:45], 0, v[150:151]
	v_lshl_add_u64 v[156:157], v[44:45], 0, v[156:157]
	v_lshl_add_u64 v[154:155], v[44:45], 0, v[154:155]
	v_lshl_add_u64 v[160:161], v[44:45], 0, v[160:161]
	v_lshl_add_u64 v[158:159], v[44:45], 0, v[158:159]
	global_load_dword v122, v[132:133], off
	global_load_dword v123, v[130:131], off
	global_load_dword v124, v[136:137], off
	global_load_dword v125, v[134:135], off
	global_load_dword v126, v[140:141], off
	global_load_dword v127, v[138:139], off
	global_load_dword v162, v[144:145], off
	global_load_dword v163, v[142:143], off
	global_load_dword v164, v[148:149], off
	global_load_dword v165, v[146:147], off
	global_load_dword v166, v[152:153], off
	global_load_dword v167, v[150:151], off
	global_load_dword v168, v[156:157], off
	global_load_dword v169, v[154:155], off
	global_load_dword v170, v[160:161], off
	global_load_dword v171, v[158:159], off
	v_mad_u64_u32 v[46:47], s[10:11], v9, s78, v[6:7]
	v_mad_u64_u32 v[48:49], s[10:11], v7, s78, v[6:7]
	v_mad_u64_u32 v[50:51], s[10:11], v13, s78, v[6:7]
	v_mad_u64_u32 v[52:53], s[10:11], v11, s78, v[6:7]
	v_mad_u64_u32 v[54:55], s[10:11], v17, s78, v[6:7]
	v_mad_u64_u32 v[56:57], s[10:11], v15, s78, v[6:7]
	v_mad_u64_u32 v[58:59], s[10:11], v35, s78, v[6:7]
	v_mad_u64_u32 v[60:61], s[10:11], v21, s78, v[6:7]
	v_mad_u64_u32 v[62:63], s[10:11], v39, s78, v[6:7]
	v_mad_u64_u32 v[64:65], s[10:11], v37, s78, v[6:7]
	v_mad_u64_u32 v[66:67], s[10:11], v43, s78, v[6:7]
	v_mad_u64_u32 v[68:69], s[10:11], v41, s78, v[6:7]
	v_mad_u64_u32 v[70:71], s[10:11], v79, s78, v[6:7]
	v_mad_u64_u32 v[72:73], s[10:11], v78, s78, v[6:7]
	v_mad_u64_u32 v[74:75], s[10:11], v81, s78, v[6:7]
	v_mad_u64_u32 v[76:77], s[10:11], v80, s78, v[6:7]
	s_waitcnt vmcnt(31)
	ds_write_b32 v46, v82
	s_waitcnt vmcnt(30)
	ds_write_b32 v48, v83
	s_waitcnt vmcnt(29)
	ds_write_b32 v50, v84
	s_waitcnt vmcnt(28)
	ds_write_b32 v52, v85
	s_waitcnt vmcnt(27)
	ds_write_b32 v54, v86
	s_waitcnt vmcnt(26)
	ds_write_b32 v56, v87
	s_waitcnt vmcnt(25)
	ds_write_b32 v58, v88
	s_waitcnt vmcnt(24)
	ds_write_b32 v60, v89
	s_waitcnt vmcnt(23)
	ds_write_b32 v62, v90
	s_waitcnt vmcnt(22)
	ds_write_b32 v64, v91
	s_waitcnt vmcnt(21)
	ds_write_b32 v66, v92
	s_waitcnt vmcnt(20)
	ds_write_b32 v68, v93
	s_waitcnt vmcnt(19)
	ds_write_b32 v70, v94
	s_waitcnt vmcnt(18)
	ds_write_b32 v72, v95
	s_waitcnt vmcnt(17)
	ds_write_b32 v74, v96
	s_waitcnt vmcnt(16)
	ds_write_b32 v76, v97
	v_mad_u64_u32 v[130:131], s[10:11], v107, s78, v[6:7]
	v_mad_u64_u32 v[132:133], s[10:11], v106, s78, v[6:7]
	v_mad_u64_u32 v[134:135], s[10:11], v109, s78, v[6:7]
	v_mad_u64_u32 v[136:137], s[10:11], v108, s78, v[6:7]
	v_mad_u64_u32 v[138:139], s[10:11], v111, s78, v[6:7]
	v_mad_u64_u32 v[140:141], s[10:11], v110, s78, v[6:7]
	v_mad_u64_u32 v[142:143], s[10:11], v113, s78, v[6:7]
	v_mad_u64_u32 v[144:145], s[10:11], v112, s78, v[6:7]
	v_mad_u64_u32 v[146:147], s[10:11], v115, s78, v[6:7]
	v_mad_u64_u32 v[148:149], s[10:11], v114, s78, v[6:7]
	v_mad_u64_u32 v[150:151], s[10:11], v117, s78, v[6:7]
	v_mad_u64_u32 v[152:153], s[10:11], v116, s78, v[6:7]
	v_mad_u64_u32 v[154:155], s[10:11], v119, s78, v[6:7]
	v_mad_u64_u32 v[156:157], s[10:11], v118, s78, v[6:7]
	v_mad_u64_u32 v[158:159], s[10:11], v121, s78, v[6:7]
	v_mad_u64_u32 v[160:161], s[10:11], v120, s78, v[6:7]
	s_waitcnt vmcnt(15)
	ds_write_b32 v130, v122
	s_waitcnt vmcnt(14)
	ds_write_b32 v132, v123
	s_waitcnt vmcnt(13)
	ds_write_b32 v134, v124
	s_waitcnt vmcnt(12)
	ds_write_b32 v136, v125
	s_waitcnt vmcnt(11)
	ds_write_b32 v138, v126
	s_waitcnt vmcnt(10)
	ds_write_b32 v140, v127
	s_waitcnt vmcnt(9)
	ds_write_b32 v142, v162
	s_waitcnt vmcnt(8)
	ds_write_b32 v144, v163
	s_waitcnt vmcnt(7)
	ds_write_b32 v146, v164
	s_waitcnt vmcnt(6)
	ds_write_b32 v148, v165
	s_waitcnt vmcnt(5)
	ds_write_b32 v150, v166
	s_waitcnt vmcnt(4)
	ds_write_b32 v152, v167
	s_waitcnt vmcnt(3)
	ds_write_b32 v154, v168
	s_waitcnt vmcnt(2)
	ds_write_b32 v156, v169
	s_waitcnt vmcnt(1)
	ds_write_b32 v158, v170
	s_waitcnt vmcnt(0)
	ds_write_b32 v160, v171
	s_add_i32 s4, s4, 16
	s_add_i32 s0, s0, 16
	s_add_i32 s5, s5, -16
	s_add_i32 s5, s5, -16
	s_cmp_lg_u32 s5, 0
	s_waitcnt lgkmcnt(0)
	ds_read2_b32 v[48:49], v3 offset1:8
	ds_read2_b32 v[52:53], v3 offset0:33 offset1:41
	ds_read2_b32 v[54:55], v3 offset0:66 offset1:74
	ds_read2_b32 v[56:57], v3 offset0:99 offset1:107
	ds_read2_b32 v[58:59], v3 offset0:132 offset1:140
	s_waitcnt lgkmcnt(4)
	s_waitcnt lgkmcnt(3)
	v_cvt_pk_bf16_f32 v9, v48, v52
	ds_read2_b32 v[60:61], v3 offset0:165 offset1:173
	v_mov_b32_e32 v44, v9
	s_waitcnt lgkmcnt(3)
	s_waitcnt lgkmcnt(2)
	ds_read2_b32 v[62:63], v3 offset0:198 offset1:206
	v_cvt_pk_bf16_f32 v9, v54, v56
	ds_read2_b32 v[64:65], v3 offset0:231 offset1:239
	v_mov_b32_e32 v45, v9
	s_waitcnt lgkmcnt(3)
	s_lshl_b64 s[0:1], s[8:9], 11
	s_waitcnt lgkmcnt(2)
	s_add_u32 s4, s26, s0
	v_cvt_pk_bf16_f32 v9, v58, v60
	s_addc_u32 s5, s27, s1
	s_ashr_i32 s7, s6, 31
	v_mov_b32_e32 v46, v9
	s_waitcnt lgkmcnt(1)
	s_lshl_b64 s[0:1], s[6:7], 1
	s_waitcnt lgkmcnt(0)
	s_add_u32 s0, s4, s0
	v_cvt_pk_bf16_f32 v9, v62, v64
	s_addc_u32 s1, s5, s1
	v_lshlrev_b32_e32 v128, 1, v8
	v_mov_b32_e32 v47, v9
	v_lshl_add_u64 v[50:51], s[0:1], 0, v[128:129]
	v_lshlrev_b32_e32 v128, 1, v10
	v_lshl_add_u64 v[66:67], v[50:51], 0, v[128:129]
	v_cvt_pk_bf16_f32 v9, v49, v53
	global_store_dwordx4 v[66:67], v[44:47], off
	v_lshlrev_b32_e32 v128, 1, v12
	ds_read2_b32 v[48:49], v3 offset0:16 offset1:24
	v_mov_b32_e32 v44, v9
	v_cvt_pk_bf16_f32 v9, v55, v57
	v_mov_b32_e32 v45, v9
	v_cvt_pk_bf16_f32 v9, v59, v61
	v_mov_b32_e32 v46, v9
	v_cvt_pk_bf16_f32 v9, v63, v65
	v_mov_b32_e32 v47, v9
	v_lshl_add_u64 v[52:53], v[50:51], 0, v[128:129]
	global_store_dwordx4 v[52:53], v[44:47], off
	ds_read2_b32 v[52:53], v3 offset0:49 offset1:57
	ds_read2_b32 v[54:55], v3 offset0:82 offset1:90
	ds_read2_b32 v[56:57], v3 offset0:115 offset1:123
	s_waitcnt lgkmcnt(3)
	s_waitcnt lgkmcnt(2)
	ds_read2_b32 v[58:59], v3 offset0:148 offset1:156
	v_cvt_pk_bf16_f32 v9, v48, v52
	ds_read2_b32 v[60:61], v3 offset0:181 offset1:189
	v_mov_b32_e32 v44, v9
	s_waitcnt lgkmcnt(3)
	s_waitcnt lgkmcnt(2)
	ds_read2_b32 v[62:63], v3 offset0:214 offset1:222
	v_cvt_pk_bf16_f32 v9, v54, v56
	ds_read2_b32 v[64:65], v3 offset0:247 offset1:255
	v_mov_b32_e32 v45, v9
	s_waitcnt lgkmcnt(3)
	s_waitcnt lgkmcnt(2)
	v_cvt_pk_bf16_f32 v9, v58, v60
	v_mov_b32_e32 v46, v9
	s_waitcnt lgkmcnt(1)
	s_waitcnt lgkmcnt(0)
	v_cvt_pk_bf16_f32 v9, v62, v64
	v_mov_b32_e32 v47, v9
	v_lshlrev_b32_e32 v128, 1, v14
	v_lshl_add_u64 v[66:67], v[50:51], 0, v[128:129]
	v_cvt_pk_bf16_f32 v9, v49, v53
	global_store_dwordx4 v[66:67], v[44:47], off
	v_lshlrev_b32_e32 v128, 1, v16
	v_lshl_add_u64 v[48:49], v[50:51], 0, v[128:129]
	v_mov_b32_e32 v44, v9
	v_cvt_pk_bf16_f32 v9, v55, v57
	v_mov_b32_e32 v45, v9
	v_cvt_pk_bf16_f32 v9, v59, v61
	v_mov_b32_e32 v46, v9
	v_cvt_pk_bf16_f32 v9, v63, v65
	v_mov_b32_e32 v47, v9
	global_store_dwordx4 v[48:49], v[44:47], off
	s_waitcnt lgkmcnt(0)
	s_mov_b64 s[6:7], -1
